# baseline (speedup 1.0000x reference)
.LBB0_91:
	v_mul_lo_u32 v64, v71, s82
	v_lshlrev_b32_e32 v66, 4, v68
	v_add_u32_e32 v64, 0x20000, v64
	v_and_b32_e32 v66, 0x70, v66
	v_mul_u32_u24_e32 v67, 0x90, v69
	v_bfe_u32 v65, v68, 3, 3
	v_add3_u32 v67, v64, v67, v72
	v_or_b32_e32 v64, v64, v66
	v_or3_b32 v68, v70, s64, v65
	v_mad_u32_u24 v69, v65, s83, v64
	s_waitcnt vmcnt(0)
	v_pk_mul_f32 v[62:63], v[172:173], v[62:63] op_sel_hi:[0,1]
	v_pk_mul_f32 v[60:61], v[172:173], v[60:61] op_sel_hi:[0,1]
	v_pk_mul_f32 v[64:65], v[172:173], v[58:59] op_sel_hi:[0,1]
	v_pk_mul_f32 v[58:59], v[172:173], v[56:57] op_sel_hi:[0,1]
	v_cvt_pk_bf16_f32 v56, v60, v61
	v_cvt_pk_bf16_f32 v57, v62, v63
	v_cvt_pk_bf16_f32 v58, v58, v59
	v_cvt_pk_bf16_f32 v59, v64, v65
	ds_write_b128 v67, v[56:59]
	v_pk_mul_f32 v[56:57], v[172:173], v[50:51] op_sel_hi:[0,1]
	v_pk_mul_f32 v[50:51], v[172:173], v[48:49] op_sel_hi:[0,1]
	v_pk_mul_f32 v[54:55], v[172:173], v[54:55] op_sel_hi:[0,1]
	v_pk_mul_f32 v[52:53], v[172:173], v[52:53] op_sel_hi:[0,1]
	v_cvt_pk_bf16_f32 v48, v52, v53
	v_cvt_pk_bf16_f32 v49, v54, v55
	v_cvt_pk_bf16_f32 v50, v50, v51
	v_cvt_pk_bf16_f32 v51, v56, v57
	ds_write_b128 v67, v[48:51] offset:64
	ds_read_b128 v[48:51], v69
	s_lshl_b32 s62, s89, 9
	v_or3_b32 v52, v73, s62, v66
	v_lshl_add_u32 v56, v68, 12, v52
	v_add_u32_e32 v57, 0x80000, v56
	ds_read_b128 v[52:55], v69 offset:1152
	s_waitcnt lgkmcnt(0)
	global_store_dwordx4 v57, v[48:51], s[6:7] sc0 sc1
	v_pk_mul_f32 v[46:47], v[170:171], v[46:47] op_sel_hi:[0,1]
	v_pk_mul_f32 v[44:45], v[170:171], v[44:45] op_sel_hi:[0,1]
	v_pk_mul_f32 v[48:49], v[170:171], v[42:43] op_sel_hi:[0,1]
	v_pk_mul_f32 v[42:43], v[170:171], v[40:41] op_sel_hi:[0,1]
	v_cvt_pk_bf16_f32 v40, v44, v45
	v_cvt_pk_bf16_f32 v41, v46, v47
	v_cvt_pk_bf16_f32 v42, v42, v43
	v_cvt_pk_bf16_f32 v43, v48, v49
	ds_write_b128 v67, v[40:43]
	v_pk_mul_f32 v[40:41], v[170:171], v[34:35] op_sel_hi:[0,1]
	v_pk_mul_f32 v[34:35], v[170:171], v[32:33] op_sel_hi:[0,1]
	v_pk_mul_f32 v[38:39], v[170:171], v[38:39] op_sel_hi:[0,1]
	v_pk_mul_f32 v[36:37], v[170:171], v[36:37] op_sel_hi:[0,1]
	v_cvt_pk_bf16_f32 v32, v36, v37
	v_cvt_pk_bf16_f32 v33, v38, v39
	v_cvt_pk_bf16_f32 v34, v34, v35
	v_cvt_pk_bf16_f32 v35, v40, v41
	ds_write_b128 v67, v[32:35] offset:64
	ds_read_b128 v[32:35], v69
	v_add_u32_e32 v36, 0x88000, v56
	v_add_u32_e32 v40, 0x90000, v56
	global_store_dwordx4 v36, v[52:55], s[6:7] sc0 sc1
	ds_read_b128 v[36:39], v69 offset:1152
	s_waitcnt lgkmcnt(1)
	global_store_dwordx4 v40, v[32:35], s[6:7] sc0 sc1
	v_pk_mul_f32 v[30:31], v[168:169], v[30:31] op_sel_hi:[0,1]
	v_pk_mul_f32 v[28:29], v[168:169], v[28:29] op_sel_hi:[0,1]
	v_pk_mul_f32 v[32:33], v[168:169], v[26:27] op_sel_hi:[0,1]
	v_pk_mul_f32 v[26:27], v[168:169], v[24:25] op_sel_hi:[0,1]
	v_cvt_pk_bf16_f32 v24, v28, v29
	v_cvt_pk_bf16_f32 v25, v30, v31
	v_cvt_pk_bf16_f32 v26, v26, v27
	v_cvt_pk_bf16_f32 v27, v32, v33
	ds_write_b128 v67, v[24:27]
	v_pk_mul_f32 v[24:25], v[168:169], v[18:19] op_sel_hi:[0,1]
	v_pk_mul_f32 v[18:19], v[168:169], v[16:17] op_sel_hi:[0,1]
	v_pk_mul_f32 v[22:23], v[168:169], v[22:23] op_sel_hi:[0,1]
	v_pk_mul_f32 v[20:21], v[168:169], v[20:21] op_sel_hi:[0,1]
	v_cvt_pk_bf16_f32 v16, v20, v21
	v_cvt_pk_bf16_f32 v17, v22, v23
	v_cvt_pk_bf16_f32 v18, v18, v19
	v_cvt_pk_bf16_f32 v19, v24, v25
	ds_write_b128 v67, v[16:19] offset:64
	ds_read_b128 v[16:19], v69
	v_add_u32_e32 v20, 0x98000, v56
	v_add_u32_e32 v24, 0xa0000, v56
	s_waitcnt lgkmcnt(3)
	global_store_dwordx4 v20, v[36:39], s[6:7] sc0 sc1
	ds_read_b128 v[20:23], v69 offset:1152
	s_waitcnt lgkmcnt(1)
	global_store_dwordx4 v24, v[16:19], s[6:7] sc0 sc1
	v_pk_mul_f32 v[14:15], v[166:167], v[14:15] op_sel_hi:[0,1]
	v_pk_mul_f32 v[12:13], v[166:167], v[12:13] op_sel_hi:[0,1]
	v_pk_mul_f32 v[16:17], v[166:167], v[10:11] op_sel_hi:[0,1]
	v_pk_mul_f32 v[10:11], v[166:167], v[8:9] op_sel_hi:[0,1]
	v_cvt_pk_bf16_f32 v8, v12, v13
	v_cvt_pk_bf16_f32 v9, v14, v15
	v_cvt_pk_bf16_f32 v10, v10, v11
	v_cvt_pk_bf16_f32 v11, v16, v17
	ds_write_b128 v67, v[8:11]
	v_pk_mul_f32 v[8:9], v[166:167], v[2:3] op_sel_hi:[0,1]
	v_pk_mul_f32 v[2:3], v[166:167], v[0:1] op_sel_hi:[0,1]
	v_pk_mul_f32 v[6:7], v[166:167], v[6:7] op_sel_hi:[0,1]
	v_pk_mul_f32 v[4:5], v[166:167], v[4:5] op_sel_hi:[0,1]
	v_cvt_pk_bf16_f32 v0, v4, v5
	v_cvt_pk_bf16_f32 v1, v6, v7
	v_cvt_pk_bf16_f32 v2, v2, v3
	v_cvt_pk_bf16_f32 v3, v8, v9
	ds_write_b128 v67, v[0:3] offset:64
	ds_read_b128 v[0:3], v69
	ds_read_b128 v[64:67], v69 offset:1152
	v_add_u32_e32 v4, 0xa8000, v56
	s_waitcnt lgkmcnt(4)
	global_store_dwordx4 v4, v[20:23], s[6:7] sc0 sc1
	v_add_u32_e32 v4, 0xb0000, v56
	v_add_u32_e32 v74, 0xb8000, v56
	s_waitcnt lgkmcnt(1)
	global_store_dwordx4 v4, v[0:3], s[6:7] sc0 sc1
.LBB0_92:
	s_cmp_eq_u32 s74, 2
	s_cselect_b32 s72, 4, 8
	s_waitcnt lgkmcnt(0)
	global_store_dwordx4 v74, v[64:67], s[6:7] sc0 sc1
	s_add_i32 s75, s75, 1
	s_andn2_b64 vcc, exec, s[70:71]
	s_mov_b64 s[6:7], s[68:69]
	s_mov_b32 s74, s65
	s_cbranch_vccz .LBB0_134

.LBB0_110:
	ds_read_b128 v[140:143], v138
	ds_read_b128 v[144:147], v138 offset:1024
	ds_read_b128 v[148:151], v138 offset:2048
	ds_read_b128 v[152:155], v138 offset:3072
	v_readfirstlane_b32 s63, v137
	v_lshl_add_u64 v[218:219], v[128:129], 0, s[22:23]
	s_mov_b32 m0, s63
	v_readfirstlane_b32 s63, v136
	ds_read_b128 v[156:159], v192
	ds_read_b128 v[160:163], v192 offset:1024
	ds_read_b128 v[194:197], v191
	ds_read_b128 v[198:201], v191 offset:1024
	ds_read_b128 v[202:205], v190
	ds_read_b128 v[206:209], v190 offset:1024
	ds_read_b128 v[210:213], v189
	ds_read_b128 v[214:217], v189 offset:1024
	global_load_lds_dwordx4 v[218:219], off
	v_lshl_add_u64 v[218:219], v[128:129], 0, s[24:25]
	s_mov_b32 m0, s63
	s_nop 0
	global_load_lds_dwordx4 v[218:219], off
	s_waitcnt lgkmcnt(8)
	s_barrier
	s_waitcnt lgkmcnt(0)
	s_setprio 1
	s_waitcnt lgkmcnt(0)
	v_mfma_f32_16x16x32_bf16 v[124:127], v[140:143], v[156:159], v[124:127]
	v_mfma_f32_16x16x32_bf16 v[120:123], v[148:151], v[156:159], v[120:123]
	v_mfma_f32_16x16x32_bf16 v[116:119], v[140:143], v[194:197], v[116:119]
	v_mfma_f32_16x16x32_bf16 v[112:115], v[148:151], v[194:197], v[112:115]
	v_mfma_f32_16x16x32_bf16 v[108:111], v[140:143], v[202:205], v[108:111]
	v_mfma_f32_16x16x32_bf16 v[104:107], v[148:151], v[202:205], v[104:107]
	v_mfma_f32_16x16x32_bf16 v[100:103], v[140:143], v[210:213], v[100:103]
	v_mfma_f32_16x16x32_bf16 v[96:99], v[148:151], v[210:213], v[96:99]
	v_mfma_f32_16x16x32_bf16 v[124:127], v[144:147], v[160:163], v[124:127]
	v_mfma_f32_16x16x32_bf16 v[120:123], v[152:155], v[160:163], v[120:123]
	v_mfma_f32_16x16x32_bf16 v[116:119], v[144:147], v[198:201], v[116:119]
	v_mfma_f32_16x16x32_bf16 v[112:115], v[152:155], v[198:201], v[112:115]
	v_mfma_f32_16x16x32_bf16 v[108:111], v[144:147], v[206:209], v[108:111]
	v_mfma_f32_16x16x32_bf16 v[104:107], v[152:155], v[206:209], v[104:107]
	v_mfma_f32_16x16x32_bf16 v[100:103], v[144:147], v[214:217], v[100:103]
	v_mfma_f32_16x16x32_bf16 v[96:99], v[152:155], v[214:217], v[96:99]
	s_setprio 0
	s_barrier
	v_readfirstlane_b32 s63, v188
	v_lshl_add_u64 v[234:235], s[66:67], 0, v[164:165]
	s_mov_b32 m0, s63
	v_readfirstlane_b32 s63, v187
	ds_read_b128 v[218:221], v135
	ds_read_b128 v[222:225], v135 offset:1024
	ds_read_b128 v[226:229], v135 offset:2048
	ds_read_b128 v[230:233], v135 offset:3072
	global_load_lds_dwordx4 v[234:235], off
	v_lshl_add_u64 v[236:237], v[234:235], 0, s[10:11]
	s_mov_b32 m0, s63
	s_nop 0
	global_load_lds_dwordx4 v[236:237], off
	s_barrier
	s_waitcnt lgkmcnt(0)
	s_setprio 1
	s_waitcnt lgkmcnt(0)
	v_mfma_f32_16x16x32_bf16 v[92:95], v[218:221], v[156:159], v[92:95]
	v_mfma_f32_16x16x32_bf16 v[88:91], v[226:229], v[156:159], v[88:91]
	v_mfma_f32_16x16x32_bf16 v[84:87], v[218:221], v[194:197], v[84:87]
	v_mfma_f32_16x16x32_bf16 v[80:83], v[226:229], v[194:197], v[80:83]
	v_mfma_f32_16x16x32_bf16 v[76:79], v[218:221], v[202:205], v[76:79]
	v_mfma_f32_16x16x32_bf16 v[72:75], v[226:229], v[202:205], v[72:75]
	v_mfma_f32_16x16x32_bf16 v[68:71], v[218:221], v[210:213], v[68:71]
	v_mfma_f32_16x16x32_bf16 v[64:67], v[226:229], v[210:213], v[64:67]
	v_mfma_f32_16x16x32_bf16 v[92:95], v[222:225], v[160:163], v[92:95]
	v_mfma_f32_16x16x32_bf16 v[88:91], v[230:233], v[160:163], v[88:91]
	v_mfma_f32_16x16x32_bf16 v[84:87], v[222:225], v[198:201], v[84:87]
	v_mfma_f32_16x16x32_bf16 v[80:83], v[230:233], v[198:201], v[80:83]
	v_mfma_f32_16x16x32_bf16 v[76:79], v[222:225], v[206:209], v[76:79]
	v_mfma_f32_16x16x32_bf16 v[72:75], v[230:233], v[206:209], v[72:75]
	v_mfma_f32_16x16x32_bf16 v[68:71], v[222:225], v[214:217], v[68:71]
	v_mfma_f32_16x16x32_bf16 v[64:67], v[230:233], v[214:217], v[64:67]
	s_setprio 0
	v_readfirstlane_b32 s63, v169
	v_lshl_add_u64 v[236:237], v[128:129], 0, s[26:27]
	s_mov_b32 m0, s63
	v_readfirstlane_b32 s63, v186
	s_barrier
	ds_read_b128 v[156:159], v192 offset:16384
	ds_read_b128 v[160:163], v192 offset:17408
	ds_read_b128 v[194:197], v191 offset:16384
	ds_read_b128 v[198:201], v191 offset:17408
	ds_read_b128 v[202:205], v190 offset:16384
	ds_read_b128 v[206:209], v190 offset:17408
	ds_read_b128 v[210:213], v189 offset:16384
	ds_read_b128 v[214:217], v189 offset:17408
	global_load_lds_dwordx4 v[236:237], off
	v_lshl_add_u64 v[236:237], v[128:129], 0, s[28:29]
	s_mov_b32 m0, s63
	s_nop 0
	global_load_lds_dwordx4 v[236:237], off
	s_barrier
	s_waitcnt lgkmcnt(0)
	s_setprio 1
	s_waitcnt lgkmcnt(0)
	v_mfma_f32_16x16x32_bf16 v[60:63], v[140:143], v[156:159], v[60:63]
	v_mfma_f32_16x16x32_bf16 v[56:59], v[148:151], v[156:159], v[56:59]
	v_mfma_f32_16x16x32_bf16 v[52:55], v[140:143], v[194:197], v[52:55]
	v_mfma_f32_16x16x32_bf16 v[48:51], v[148:151], v[194:197], v[48:51]
	v_mfma_f32_16x16x32_bf16 v[44:47], v[140:143], v[202:205], v[44:47]
	v_mfma_f32_16x16x32_bf16 v[40:43], v[148:151], v[202:205], v[40:43]
	v_mfma_f32_16x16x32_bf16 v[36:39], v[140:143], v[210:213], v[36:39]
	v_mfma_f32_16x16x32_bf16 v[32:35], v[148:151], v[210:213], v[32:35]
	v_mfma_f32_16x16x32_bf16 v[60:63], v[144:147], v[160:163], v[60:63]
	v_mfma_f32_16x16x32_bf16 v[56:59], v[152:155], v[160:163], v[56:59]
	v_mfma_f32_16x16x32_bf16 v[52:55], v[144:147], v[198:201], v[52:55]
	v_mfma_f32_16x16x32_bf16 v[48:51], v[152:155], v[198:201], v[48:51]
	v_mfma_f32_16x16x32_bf16 v[44:47], v[144:147], v[206:209], v[44:47]
	v_mfma_f32_16x16x32_bf16 v[40:43], v[152:155], v[206:209], v[40:43]
	v_mfma_f32_16x16x32_bf16 v[36:39], v[144:147], v[214:217], v[36:39]
	v_mfma_f32_16x16x32_bf16 v[32:35], v[152:155], v[214:217], v[32:35]
	s_setprio 0
	s_barrier
	v_readfirstlane_b32 s63, v185
	v_lshl_add_u64 v[140:141], v[234:235], 0, s[30:31]
	s_mov_b32 m0, s63
	v_readfirstlane_b32 s63, v184
	global_load_lds_dwordx4 v[140:141], off
	v_lshl_add_u64 v[140:141], v[234:235], 0, s[34:35]
	s_mov_b32 m0, s63
	s_nop 0
	global_load_lds_dwordx4 v[140:141], off
	s_waitcnt vmcnt(6)
	s_barrier
	s_setprio 1
	v_mfma_f32_16x16x32_bf16 v[28:31], v[218:221], v[156:159], v[28:31]
	v_mfma_f32_16x16x32_bf16 v[24:27], v[226:229], v[156:159], v[24:27]
	v_mfma_f32_16x16x32_bf16 v[20:23], v[218:221], v[194:197], v[20:23]
	v_mfma_f32_16x16x32_bf16 v[16:19], v[226:229], v[194:197], v[16:19]
	v_mfma_f32_16x16x32_bf16 v[12:15], v[218:221], v[202:205], v[12:15]
	v_mfma_f32_16x16x32_bf16 v[8:11], v[226:229], v[202:205], v[8:11]
	v_mfma_f32_16x16x32_bf16 v[4:7], v[218:221], v[210:213], v[4:7]
	v_mfma_f32_16x16x32_bf16 v[0:3], v[226:229], v[210:213], v[0:3]
	v_mfma_f32_16x16x32_bf16 v[28:31], v[222:225], v[160:163], v[28:31]
	v_mfma_f32_16x16x32_bf16 v[24:27], v[230:233], v[160:163], v[24:27]
	v_mfma_f32_16x16x32_bf16 v[20:23], v[222:225], v[198:201], v[20:23]
	v_mfma_f32_16x16x32_bf16 v[16:19], v[230:233], v[198:201], v[16:19]
	v_mfma_f32_16x16x32_bf16 v[12:15], v[222:225], v[206:209], v[12:15]
	v_mfma_f32_16x16x32_bf16 v[8:11], v[230:233], v[206:209], v[8:11]
	v_mfma_f32_16x16x32_bf16 v[4:7], v[222:225], v[214:217], v[4:7]
	v_mfma_f32_16x16x32_bf16 v[0:3], v[230:233], v[214:217], v[0:3]
	s_setprio 0
	s_barrier
	ds_read_b128 v[140:143], v130
	ds_read_b128 v[144:147], v130 offset:1024
	ds_read_b128 v[148:151], v130 offset:2048
	ds_read_b128 v[152:155], v130 offset:3072
	v_readfirstlane_b32 s63, v183
	v_lshl_add_u64 v[218:219], v[128:129], 0, s[40:41]
	s_mov_b32 m0, s63
	v_readfirstlane_b32 s63, v182
	ds_read_b128 v[156:159], v192 offset:32768
	ds_read_b128 v[160:163], v192 offset:33792
	ds_read_b128 v[194:197], v191 offset:32768
	ds_read_b128 v[198:201], v191 offset:33792
	ds_read_b128 v[202:205], v190 offset:32768
	ds_read_b128 v[206:209], v190 offset:33792
	ds_read_b128 v[210:213], v189 offset:32768
	ds_read_b128 v[214:217], v189 offset:33792
	global_load_lds_dwordx4 v[218:219], off
	s_mov_b32 m0, s63
	s_nop 0
	global_load_lds_dwordx4 v[128:129], off
	s_waitcnt lgkmcnt(8)
	s_barrier
	s_waitcnt lgkmcnt(0)
	s_setprio 1
	s_waitcnt lgkmcnt(0)
	v_mfma_f32_16x16x32_bf16 v[124:127], v[140:143], v[156:159], v[124:127]
	v_mfma_f32_16x16x32_bf16 v[120:123], v[148:151], v[156:159], v[120:123]
	v_mfma_f32_16x16x32_bf16 v[116:119], v[140:143], v[194:197], v[116:119]
	v_mfma_f32_16x16x32_bf16 v[112:115], v[148:151], v[194:197], v[112:115]
	v_mfma_f32_16x16x32_bf16 v[108:111], v[140:143], v[202:205], v[108:111]
	v_mfma_f32_16x16x32_bf16 v[104:107], v[148:151], v[202:205], v[104:107]
	v_mfma_f32_16x16x32_bf16 v[100:103], v[140:143], v[210:213], v[100:103]
	v_mfma_f32_16x16x32_bf16 v[96:99], v[148:151], v[210:213], v[96:99]
	v_mfma_f32_16x16x32_bf16 v[124:127], v[144:147], v[160:163], v[124:127]
	v_mfma_f32_16x16x32_bf16 v[120:123], v[152:155], v[160:163], v[120:123]
	v_mfma_f32_16x16x32_bf16 v[116:119], v[144:147], v[198:201], v[116:119]
	v_mfma_f32_16x16x32_bf16 v[112:115], v[152:155], v[198:201], v[112:115]
	v_mfma_f32_16x16x32_bf16 v[108:111], v[144:147], v[206:209], v[108:111]
	v_mfma_f32_16x16x32_bf16 v[104:107], v[152:155], v[206:209], v[104:107]
	v_mfma_f32_16x16x32_bf16 v[100:103], v[144:147], v[214:217], v[100:103]
	v_mfma_f32_16x16x32_bf16 v[96:99], v[152:155], v[214:217], v[96:99]
	s_setprio 0
	s_barrier
	v_readfirstlane_b32 s63, v181
	v_lshl_add_u64 v[234:235], s[64:65], 0, v[164:165]
	s_mov_b32 m0, s63
	v_readfirstlane_b32 s63, v180
	ds_read_b128 v[218:221], v132
	ds_read_b128 v[222:225], v132 offset:1024
	ds_read_b128 v[226:229], v132 offset:2048
	ds_read_b128 v[230:233], v132 offset:3072
	global_load_lds_dwordx4 v[234:235], off
	v_lshl_add_u64 v[236:237], v[234:235], 0, s[10:11]
	s_mov_b32 m0, s63
	s_nop 0
	global_load_lds_dwordx4 v[236:237], off
	s_barrier
	s_waitcnt lgkmcnt(0)
	s_setprio 1
	s_waitcnt lgkmcnt(0)
	v_mfma_f32_16x16x32_bf16 v[92:95], v[218:221], v[156:159], v[92:95]
	v_mfma_f32_16x16x32_bf16 v[88:91], v[226:229], v[156:159], v[88:91]
	v_mfma_f32_16x16x32_bf16 v[84:87], v[218:221], v[194:197], v[84:87]
	v_mfma_f32_16x16x32_bf16 v[80:83], v[226:229], v[194:197], v[80:83]
	v_mfma_f32_16x16x32_bf16 v[76:79], v[218:221], v[202:205], v[76:79]
	v_mfma_f32_16x16x32_bf16 v[72:75], v[226:229], v[202:205], v[72:75]
	v_mfma_f32_16x16x32_bf16 v[68:71], v[218:221], v[210:213], v[68:71]
	v_mfma_f32_16x16x32_bf16 v[64:67], v[226:229], v[210:213], v[64:67]
	v_mfma_f32_16x16x32_bf16 v[92:95], v[222:225], v[160:163], v[92:95]
	v_mfma_f32_16x16x32_bf16 v[88:91], v[230:233], v[160:163], v[88:91]
	v_mfma_f32_16x16x32_bf16 v[84:87], v[222:225], v[198:201], v[84:87]
	v_mfma_f32_16x16x32_bf16 v[80:83], v[230:233], v[198:201], v[80:83]
	v_mfma_f32_16x16x32_bf16 v[76:79], v[222:225], v[206:209], v[76:79]
	v_mfma_f32_16x16x32_bf16 v[72:75], v[230:233], v[206:209], v[72:75]
	v_mfma_f32_16x16x32_bf16 v[68:71], v[222:225], v[214:217], v[68:71]
	v_mfma_f32_16x16x32_bf16 v[64:67], v[230:233], v[214:217], v[64:67]
	s_setprio 0
	v_readfirstlane_b32 s63, v179
	v_lshl_add_u64 v[236:237], v[128:129], 0, s[44:45]
	s_mov_b32 m0, s63
	v_readfirstlane_b32 s63, v177
	s_barrier
	ds_read_b128 v[156:159], v192 offset:49152
	ds_read_b128 v[160:163], v192 offset:50176
	ds_read_b128 v[194:197], v191 offset:49152
	ds_read_b128 v[198:201], v191 offset:50176
	ds_read_b128 v[202:205], v190 offset:49152
	ds_read_b128 v[206:209], v190 offset:50176
	ds_read_b128 v[210:213], v189 offset:49152
	ds_read_b128 v[214:217], v189 offset:50176
	global_load_lds_dwordx4 v[236:237], off
	v_lshl_add_u64 v[236:237], v[128:129], 0, s[46:47]
	s_mov_b32 m0, s63
	s_nop 0
	global_load_lds_dwordx4 v[236:237], off
	s_barrier
	s_waitcnt lgkmcnt(0)
	s_setprio 1
	s_waitcnt lgkmcnt(0)
	v_mfma_f32_16x16x32_bf16 v[60:63], v[140:143], v[156:159], v[60:63]
	v_mfma_f32_16x16x32_bf16 v[56:59], v[148:151], v[156:159], v[56:59]
	v_mfma_f32_16x16x32_bf16 v[52:55], v[140:143], v[194:197], v[52:55]
	v_mfma_f32_16x16x32_bf16 v[48:51], v[148:151], v[194:197], v[48:51]
	v_mfma_f32_16x16x32_bf16 v[44:47], v[140:143], v[202:205], v[44:47]
	v_mfma_f32_16x16x32_bf16 v[40:43], v[148:151], v[202:205], v[40:43]
	v_mfma_f32_16x16x32_bf16 v[36:39], v[140:143], v[210:213], v[36:39]
	v_mfma_f32_16x16x32_bf16 v[32:35], v[148:151], v[210:213], v[32:35]
	v_mfma_f32_16x16x32_bf16 v[60:63], v[144:147], v[160:163], v[60:63]
	v_mfma_f32_16x16x32_bf16 v[56:59], v[152:155], v[160:163], v[56:59]
	v_mfma_f32_16x16x32_bf16 v[52:55], v[144:147], v[198:201], v[52:55]
	v_mfma_f32_16x16x32_bf16 v[48:51], v[152:155], v[198:201], v[48:51]
	v_mfma_f32_16x16x32_bf16 v[44:47], v[144:147], v[206:209], v[44:47]
	v_mfma_f32_16x16x32_bf16 v[40:43], v[152:155], v[206:209], v[40:43]
	v_mfma_f32_16x16x32_bf16 v[36:39], v[144:147], v[214:217], v[36:39]
	v_mfma_f32_16x16x32_bf16 v[32:35], v[152:155], v[214:217], v[32:35]
	s_setprio 0
	s_barrier
	v_readfirstlane_b32 s63, v175
	v_lshl_add_u64 v[140:141], v[234:235], 0, s[30:31]
	s_mov_b32 m0, s63
	v_readfirstlane_b32 s63, v173
	global_load_lds_dwordx4 v[140:141], off
	v_lshl_add_u64 v[140:141], v[234:235], 0, s[34:35]
	s_mov_b32 m0, s63
	s_nop 0
	global_load_lds_dwordx4 v[140:141], off
	s_waitcnt vmcnt(6)
	s_barrier
	s_setprio 1
	v_mfma_f32_16x16x32_bf16 v[28:31], v[218:221], v[156:159], v[28:31]
	v_mfma_f32_16x16x32_bf16 v[24:27], v[226:229], v[156:159], v[24:27]
	v_mfma_f32_16x16x32_bf16 v[20:23], v[218:221], v[194:197], v[20:23]
	v_mfma_f32_16x16x32_bf16 v[16:19], v[226:229], v[194:197], v[16:19]
	v_mfma_f32_16x16x32_bf16 v[12:15], v[218:221], v[202:205], v[12:15]
	v_mfma_f32_16x16x32_bf16 v[8:11], v[226:229], v[202:205], v[8:11]
	v_mfma_f32_16x16x32_bf16 v[4:7], v[218:221], v[210:213], v[4:7]
	v_mfma_f32_16x16x32_bf16 v[0:3], v[226:229], v[210:213], v[0:3]
	v_mfma_f32_16x16x32_bf16 v[28:31], v[222:225], v[160:163], v[28:31]
	v_mfma_f32_16x16x32_bf16 v[24:27], v[230:233], v[160:163], v[24:27]
	v_mfma_f32_16x16x32_bf16 v[20:23], v[222:225], v[198:201], v[20:23]
	v_mfma_f32_16x16x32_bf16 v[16:19], v[230:233], v[198:201], v[16:19]
	v_mfma_f32_16x16x32_bf16 v[12:15], v[222:225], v[206:209], v[12:15]
	v_mfma_f32_16x16x32_bf16 v[8:11], v[230:233], v[206:209], v[8:11]
	v_mfma_f32_16x16x32_bf16 v[4:7], v[222:225], v[214:217], v[4:7]
	v_mfma_f32_16x16x32_bf16 v[0:3], v[230:233], v[214:217], v[0:3]
	s_setprio 0
	s_add_i32 s4, s4, 2
	s_add_u32 s64, s64, s68
	s_addc_u32 s65, s65, s69
	s_add_u32 s66, s66, s68
	s_addc_u32 s67, s67, s69
	s_cmp_lt_u32 s4, 28
	v_lshl_add_u64 v[128:129], v[128:129], 0, s[56:57]
	s_barrier
	s_cbranch_scc1 .LBB0_110
	s_lshl_b32 s4, s70, 11
	s_or_b32 s64, s71, s4
	s_or_b32 s66, s64, 0x80
	v_lshlrev_b32_e32 v128, 3, v131
	v_lshlrev_b32_e32 v129, 5, v131
	s_ashr_i32 s67, s66, 31
	v_and_b32_e32 v128, 0xffff0, v128
	v_and_b32_e32 v129, 32, v129
	s_lshl_b64 s[66:67], s[66:67], 12
	v_add_u32_e32 v129, v129, v134
	v_add_lshl_u32 v128, v133, v128, 12
	s_add_u32 s66, s54, s66
	v_lshl_add_u32 v164, v129, 1, v128
	s_addc_u32 s67, s55, s67
	v_lshl_add_u64 v[128:129], s[66:67], 0, v[164:165]
	v_readfirstlane_b32 s4, v137
	ds_read_b128 v[140:143], v138
	ds_read_b128 v[144:147], v138 offset:1024
	ds_read_b128 v[148:151], v138 offset:2048
	ds_read_b128 v[152:155], v138 offset:3072
	ds_read_b128 v[156:159], v192
	ds_read_b128 v[160:163], v192 offset:1024
	ds_read_b128 v[194:197], v191
	ds_read_b128 v[198:201], v191 offset:1024
	ds_read_b128 v[202:205], v190
	ds_read_b128 v[206:209], v190 offset:1024
	ds_read_b128 v[210:213], v189
	ds_read_b128 v[214:217], v189 offset:1024
	v_lshl_add_u64 v[138:139], v[128:129], 0, s[58:59]
	s_mov_b32 m0, s4
	v_readfirstlane_b32 s4, v136
	global_load_lds_dwordx4 v[138:139], off
	v_lshl_add_u64 v[128:129], v[128:129], 0, s[60:61]
	s_mov_b32 m0, s4
	s_ashr_i32 s65, s64, 31
	global_load_lds_dwordx4 v[128:129], off
	s_barrier
	s_waitcnt lgkmcnt(0)
	s_setprio 1
	s_waitcnt lgkmcnt(0)
	v_mfma_f32_16x16x32_bf16 v[124:127], v[140:143], v[156:159], v[124:127]
	v_mfma_f32_16x16x32_bf16 v[120:123], v[148:151], v[156:159], v[120:123]
	v_mfma_f32_16x16x32_bf16 v[116:119], v[140:143], v[194:197], v[116:119]
	v_mfma_f32_16x16x32_bf16 v[112:115], v[148:151], v[194:197], v[112:115]
	v_mfma_f32_16x16x32_bf16 v[108:111], v[140:143], v[202:205], v[108:111]
	v_mfma_f32_16x16x32_bf16 v[104:107], v[148:151], v[202:205], v[104:107]
	v_mfma_f32_16x16x32_bf16 v[100:103], v[140:143], v[210:213], v[100:103]
	v_mfma_f32_16x16x32_bf16 v[96:99], v[148:151], v[210:213], v[96:99]
	v_mfma_f32_16x16x32_bf16 v[124:127], v[144:147], v[160:163], v[124:127]
	v_mfma_f32_16x16x32_bf16 v[120:123], v[152:155], v[160:163], v[120:123]
	v_mfma_f32_16x16x32_bf16 v[116:119], v[144:147], v[198:201], v[116:119]
	v_mfma_f32_16x16x32_bf16 v[112:115], v[152:155], v[198:201], v[112:115]
	v_mfma_f32_16x16x32_bf16 v[108:111], v[144:147], v[206:209], v[108:111]
	v_mfma_f32_16x16x32_bf16 v[104:107], v[152:155], v[206:209], v[104:107]
	v_mfma_f32_16x16x32_bf16 v[100:103], v[144:147], v[214:217], v[100:103]
	v_mfma_f32_16x16x32_bf16 v[96:99], v[152:155], v[214:217], v[96:99]
	s_setprio 0
	s_barrier
	ds_read_b128 v[136:139], v135
	ds_read_b128 v[218:221], v135 offset:1024
	ds_read_b128 v[222:225], v135 offset:2048
	ds_read_b128 v[226:229], v135 offset:3072
	s_barrier
	s_waitcnt lgkmcnt(0)
	s_setprio 1
	s_waitcnt lgkmcnt(0)
	v_mfma_f32_16x16x32_bf16 v[92:95], v[136:139], v[156:159], v[92:95]
	v_mfma_f32_16x16x32_bf16 v[88:91], v[222:225], v[156:159], v[88:91]
	v_mfma_f32_16x16x32_bf16 v[84:87], v[136:139], v[194:197], v[84:87]
	v_mfma_f32_16x16x32_bf16 v[80:83], v[222:225], v[194:197], v[80:83]
	v_mfma_f32_16x16x32_bf16 v[76:79], v[136:139], v[202:205], v[76:79]
	v_mfma_f32_16x16x32_bf16 v[72:75], v[222:225], v[202:205], v[72:75]
	v_mfma_f32_16x16x32_bf16 v[68:71], v[136:139], v[210:213], v[68:71]
	v_mfma_f32_16x16x32_bf16 v[64:67], v[222:225], v[210:213], v[64:67]
	v_mfma_f32_16x16x32_bf16 v[156:159], v[218:221], v[160:163], v[92:95]
	v_mfma_f32_16x16x32_bf16 v[160:163], v[226:229], v[160:163], v[88:91]
	v_mfma_f32_16x16x32_bf16 v[194:197], v[218:221], v[198:201], v[84:87]
	v_mfma_f32_16x16x32_bf16 v[198:201], v[226:229], v[198:201], v[80:83]
	v_mfma_f32_16x16x32_bf16 v[202:205], v[218:221], v[206:209], v[76:79]
	v_mfma_f32_16x16x32_bf16 v[206:209], v[226:229], v[206:209], v[72:75]
	v_mfma_f32_16x16x32_bf16 v[210:213], v[218:221], v[214:217], v[68:71]
	v_mfma_f32_16x16x32_bf16 v[214:217], v[226:229], v[214:217], v[64:67]
	s_setprio 0
	s_barrier
	s_nop 0
	ds_read_b128 v[64:67], v192 offset:16384
	ds_read_b128 v[68:71], v192 offset:17408
	ds_read_b128 v[72:75], v191 offset:16384
	ds_read_b128 v[76:79], v191 offset:17408
	ds_read_b128 v[80:83], v190 offset:16384
	ds_read_b128 v[84:87], v190 offset:17408
	ds_read_b128 v[88:91], v189 offset:16384
	ds_read_b128 v[92:95], v189 offset:17408
	s_waitcnt vmcnt(4)
	s_barrier
	s_waitcnt lgkmcnt(0)
	s_setprio 1
	s_waitcnt lgkmcnt(0)
	v_mfma_f32_16x16x32_bf16 v[60:63], v[140:143], v[64:67], v[60:63]
	v_mfma_f32_16x16x32_bf16 v[56:59], v[148:151], v[64:67], v[56:59]
	v_mfma_f32_16x16x32_bf16 v[52:55], v[140:143], v[72:75], v[52:55]
	v_mfma_f32_16x16x32_bf16 v[48:51], v[148:151], v[72:75], v[48:51]
	v_mfma_f32_16x16x32_bf16 v[230:233], v[140:143], v[80:83], v[44:47]
	v_mfma_f32_16x16x32_bf16 v[234:237], v[148:151], v[80:83], v[40:43]
	v_mfma_f32_16x16x32_bf16 v[140:143], v[140:143], v[88:91], v[36:39]
	v_mfma_f32_16x16x32_bf16 v[148:151], v[148:151], v[88:91], v[32:35]
	v_mfma_f32_16x16x32_bf16 v[32:35], v[144:147], v[68:71], v[60:63]
	v_mfma_f32_16x16x32_bf16 v[36:39], v[152:155], v[68:71], v[56:59]
	v_mfma_f32_16x16x32_bf16 v[40:43], v[144:147], v[76:79], v[52:55]
	v_mfma_f32_16x16x32_bf16 v[44:47], v[152:155], v[76:79], v[48:51]
	v_mfma_f32_16x16x32_bf16 v[48:51], v[144:147], v[84:87], v[230:233]
	v_mfma_f32_16x16x32_bf16 v[52:55], v[152:155], v[84:87], v[234:237]
	v_mfma_f32_16x16x32_bf16 v[56:59], v[144:147], v[92:95], v[140:143]
	v_mfma_f32_16x16x32_bf16 v[60:63], v[152:155], v[92:95], v[148:151]
	s_setprio 0
	s_setprio 1
	v_mfma_f32_16x16x32_bf16 v[28:31], v[136:139], v[64:67], v[28:31]
	v_mfma_f32_16x16x32_bf16 v[24:27], v[222:225], v[64:67], v[24:27]
	v_mfma_f32_16x16x32_bf16 v[20:23], v[136:139], v[72:75], v[20:23]
	v_mfma_f32_16x16x32_bf16 v[64:67], v[222:225], v[72:75], v[16:19]
	v_mfma_f32_16x16x32_bf16 v[12:15], v[136:139], v[80:83], v[12:15]
	v_mfma_f32_16x16x32_bf16 v[8:11], v[222:225], v[80:83], v[8:11]
	v_mfma_f32_16x16x32_bf16 v[72:75], v[136:139], v[88:91], v[4:7]
	v_mfma_f32_16x16x32_bf16 v[80:83], v[222:225], v[88:91], v[0:3]
	v_mfma_f32_16x16x32_bf16 v[0:3], v[218:221], v[68:71], v[28:31]
	v_mfma_f32_16x16x32_bf16 v[4:7], v[226:229], v[68:71], v[24:27]
	v_mfma_f32_16x16x32_bf16 v[16:19], v[218:221], v[76:79], v[20:23]
	v_mfma_f32_16x16x32_bf16 v[20:23], v[226:229], v[76:79], v[64:67]
	v_mfma_f32_16x16x32_bf16 v[64:67], v[218:221], v[84:87], v[12:15]
	v_mfma_f32_16x16x32_bf16 v[68:71], v[226:229], v[84:87], v[8:11]
	v_mfma_f32_16x16x32_bf16 v[72:75], v[218:221], v[92:95], v[72:75]
	v_mfma_f32_16x16x32_bf16 v[76:79], v[226:229], v[92:95], v[80:83]
	s_setprio 0
	s_barrier
	ds_read_b128 v[12:15], v130
	ds_read_b128 v[8:11], v130 offset:1024
	ds_read_b128 v[24:27], v130 offset:2048
	ds_read_b128 v[80:83], v130 offset:3072
	ds_read_b128 v[140:143], v192 offset:32768
	ds_read_b128 v[148:151], v192 offset:33792
	ds_read_b128 v[218:221], v191 offset:32768
	ds_read_b128 v[222:225], v191 offset:33792
	ds_read_b128 v[226:229], v190 offset:32768
	ds_read_b128 v[230:233], v190 offset:33792
	ds_read_b128 v[234:237], v189 offset:32768
	ds_read_b128 v[238:241], v189 offset:33792
	s_waitcnt vmcnt(2)
	s_barrier
	s_waitcnt lgkmcnt(0)
	s_setprio 1
	s_waitcnt lgkmcnt(0)
	v_mfma_f32_16x16x32_bf16 v[28:31], v[12:15], v[140:143], v[124:127]
	v_mfma_f32_16x16x32_bf16 v[84:87], v[24:27], v[140:143], v[120:123]
	v_mfma_f32_16x16x32_bf16 v[88:91], v[12:15], v[218:221], v[116:119]
	v_mfma_f32_16x16x32_bf16 v[92:95], v[24:27], v[218:221], v[112:115]
	v_mfma_f32_16x16x32_bf16 v[108:111], v[12:15], v[226:229], v[108:111]
	v_mfma_f32_16x16x32_bf16 v[104:107], v[24:27], v[226:229], v[104:107]
	v_mfma_f32_16x16x32_bf16 v[100:103], v[12:15], v[234:237], v[100:103]
	v_mfma_f32_16x16x32_bf16 v[96:99], v[24:27], v[234:237], v[96:99]
	v_mfma_f32_16x16x32_bf16 v[152:155], v[8:11], v[148:151], v[28:31]
	v_mfma_f32_16x16x32_bf16 v[144:147], v[80:83], v[148:151], v[84:87]
	v_mfma_f32_16x16x32_bf16 v[136:139], v[8:11], v[222:225], v[88:91]
	v_mfma_f32_16x16x32_bf16 v[128:131], v[80:83], v[222:225], v[92:95]
	v_mfma_f32_16x16x32_bf16 v[120:123], v[8:11], v[230:233], v[108:111]
	v_mfma_f32_16x16x32_bf16 v[112:115], v[80:83], v[230:233], v[104:107]
	v_mfma_f32_16x16x32_bf16 v[104:107], v[8:11], v[238:241], v[100:103]
	v_mfma_f32_16x16x32_bf16 v[28:31], v[80:83], v[238:241], v[96:99]
	s_setprio 0
	s_barrier
	ds_read_b128 v[92:95], v132
	ds_read_b128 v[84:87], v132 offset:1024
	ds_read_b128 v[96:99], v132 offset:2048
	ds_read_b128 v[88:91], v132 offset:3072
	s_waitcnt vmcnt(0)
	s_barrier
	s_waitcnt lgkmcnt(0)
	s_setprio 1
	s_waitcnt lgkmcnt(0)
	v_mfma_f32_16x16x32_bf16 v[100:103], v[92:95], v[140:143], v[156:159]
	v_mfma_f32_16x16x32_bf16 v[108:111], v[96:99], v[140:143], v[160:163]
	v_mfma_f32_16x16x32_bf16 v[116:119], v[92:95], v[218:221], v[194:197]
	v_mfma_f32_16x16x32_bf16 v[124:127], v[96:99], v[218:221], v[198:201]
	v_mfma_f32_16x16x32_bf16 v[160:163], v[92:95], v[226:229], v[202:205]
	v_mfma_f32_16x16x32_bf16 v[194:197], v[96:99], v[226:229], v[206:209]
	v_mfma_f32_16x16x32_bf16 v[198:201], v[92:95], v[234:237], v[210:213]
	v_mfma_f32_16x16x32_bf16 v[202:205], v[96:99], v[234:237], v[214:217]
	v_mfma_f32_16x16x32_bf16 v[156:159], v[84:87], v[148:151], v[100:103]
	v_mfma_f32_16x16x32_bf16 v[148:151], v[88:91], v[148:151], v[108:111]
	v_mfma_f32_16x16x32_bf16 v[140:143], v[84:87], v[222:225], v[116:119]
	v_mfma_f32_16x16x32_bf16 v[132:135], v[88:91], v[222:225], v[124:127]
	v_mfma_f32_16x16x32_bf16 v[124:127], v[84:87], v[230:233], v[160:163]
	v_mfma_f32_16x16x32_bf16 v[116:119], v[88:91], v[230:233], v[194:197]
	v_mfma_f32_16x16x32_bf16 v[108:111], v[84:87], v[238:241], v[198:201]
	v_mfma_f32_16x16x32_bf16 v[100:103], v[88:91], v[238:241], v[202:205]
	s_setprio 0
	s_lshl_b64 s[66:67], s[64:65], 2
	s_barrier
	v_mbcnt_lo_u32_b32 v162, -1, 0
	v_mbcnt_hi_u32_b32 v162, -1, v162
	s_add_u32 s66, s87, s66
	v_add_u32_e32 v160, s76, v162
	s_addc_u32 s67, s88, s67
	v_and_b32_e32 v164, 0x100, v160
	v_and_b32_e32 v162, 15, v162
	v_lshl_add_u64 v[160:161], s[66:67], 0, v[164:165]
	v_lshlrev_b32_e32 v164, 2, v162
	v_lshl_add_u64 v[160:161], v[160:161], 0, v[164:165]
	global_load_dword v178, v[160:161], off
	global_load_dword v176, v[160:161], off offset:64
	global_load_dword v174, v[160:161], off offset:128
	global_load_dword v164, v[160:161], off offset:192
	global_load_dword v172, v[160:161], off offset:512
	global_load_dword v170, v[160:161], off offset:576
	global_load_dword v168, v[160:161], off offset:640
	global_load_dword v166, v[160:161], off offset:704
	v_mbcnt_lo_u32_b32 v194, -1, 0
	v_mbcnt_hi_u32_b32 v194, -1, v194
	s_mov_b64 s[66:67], -1
	v_add_u32_e32 v160, s76, v194
	v_bfe_u32 v161, v160, 8, 1
	v_ashrrev_i32_e32 v196, 6, v160
	v_bfe_u32 v160, v194, 4, 2
	v_and_b32_e32 v198, 3, v196
	v_and_b32_e32 v195, 15, v194
	s_cmp_gt_i32 s74, 1
	v_lshlrev_b32_e32 v193, 6, v161
	v_lshlrev_b32_e32 v197, 4, v160
	s_cbranch_scc0 .LBB0_113
	v_lshlrev_b32_e32 v161, 6, v198
	v_or3_b32 v160, v193, v195, s64
	v_or3_b32 v161, v161, v197, s62
	v_lshl_add_u32 v199, v160, 12, v161
	s_waitcnt vmcnt(0)
	v_mul_f32_e32 v160, v178, v178
	v_pk_mul_f32 v[200:201], v[152:153], v[160:161] op_sel_hi:[1,0]
	v_pk_mul_f32 v[162:163], v[154:155], v[160:161] op_sel_hi:[1,0]
	v_pk_mul_f32 v[202:203], v[158:159], v[160:161] op_sel_hi:[1,0]
	v_pk_mul_f32 v[204:205], v[156:157], v[160:161] op_sel_hi:[1,0]
	v_mul_f32_e32 v160, v144, v200
	v_mul_f32_e32 v161, v145, v201
	v_cvt_pk_bf16_f32 v160, v160, v161
	v_mul_f32_e32 v161, v146, v162
	v_mul_f32_e32 v162, v147, v163
	v_cvt_pk_bf16_f32 v161, v161, v162
	v_mul_f32_e32 v162, v148, v204
	v_mul_f32_e32 v163, v149, v205
	v_cvt_pk_bf16_f32 v162, v162, v163
	v_mul_f32_e32 v163, v150, v202
	v_mul_f32_e32 v200, v151, v203
	v_cvt_pk_bf16_f32 v163, v163, v200
	global_store_dwordx4 v199, v[160:163], s[6:7] sc0 sc1
	v_add_u32_e32 v206, 0x10000, v199
	s_mov_b64 s[66:67], 0
	v_mul_f32_e32 v160, v176, v176
	v_pk_mul_f32 v[200:201], v[136:137], v[160:161] op_sel_hi:[1,0]
	v_pk_mul_f32 v[162:163], v[138:139], v[160:161] op_sel_hi:[1,0]
	v_pk_mul_f32 v[202:203], v[142:143], v[160:161] op_sel_hi:[1,0]
	v_pk_mul_f32 v[204:205], v[140:141], v[160:161] op_sel_hi:[1,0]
	v_mul_f32_e32 v160, v128, v200
	v_mul_f32_e32 v161, v129, v201
	v_cvt_pk_bf16_f32 v160, v160, v161
	v_mul_f32_e32 v161, v130, v162
	v_mul_f32_e32 v162, v131, v163
	v_cvt_pk_bf16_f32 v161, v161, v162
	v_mul_f32_e32 v162, v132, v204
	v_mul_f32_e32 v163, v133, v205
	v_cvt_pk_bf16_f32 v162, v162, v163
	v_mul_f32_e32 v163, v134, v202
	v_mul_f32_e32 v200, v135, v203
	v_cvt_pk_bf16_f32 v163, v163, v200
	global_store_dwordx4 v206, v[160:163], s[6:7] sc0 sc1
	v_add_u32_e32 v206, 0x20000, v199
	v_add_u32_e32 v199, 0x30000, v199
	v_mul_f32_e32 v160, v174, v174
	v_pk_mul_f32 v[200:201], v[120:121], v[160:161] op_sel_hi:[1,0]
	v_pk_mul_f32 v[162:163], v[122:123], v[160:161] op_sel_hi:[1,0]
	v_pk_mul_f32 v[202:203], v[126:127], v[160:161] op_sel_hi:[1,0]
	v_pk_mul_f32 v[204:205], v[124:125], v[160:161] op_sel_hi:[1,0]
	v_mul_f32_e32 v160, v112, v200
	v_mul_f32_e32 v161, v113, v201
	v_cvt_pk_bf16_f32 v160, v160, v161
	v_mul_f32_e32 v161, v114, v162
	v_mul_f32_e32 v162, v115, v163
	v_cvt_pk_bf16_f32 v161, v161, v162
	v_mul_f32_e32 v162, v116, v204
	v_mul_f32_e32 v163, v117, v205
	v_cvt_pk_bf16_f32 v162, v162, v163
	v_mul_f32_e32 v163, v118, v202
	v_mul_f32_e32 v200, v119, v203
	v_cvt_pk_bf16_f32 v163, v163, v200
	global_store_dwordx4 v206, v[160:163], s[6:7] sc0 sc1
	s_nop 1
	v_mul_f32_e32 v160, v164, v164
	v_pk_mul_f32 v[200:201], v[104:105], v[160:161] op_sel_hi:[1,0]
	v_pk_mul_f32 v[162:163], v[106:107], v[160:161] op_sel_hi:[1,0]
	v_pk_mul_f32 v[202:203], v[110:111], v[160:161] op_sel_hi:[1,0]
	v_pk_mul_f32 v[204:205], v[108:109], v[160:161] op_sel_hi:[1,0]
	v_mul_f32_e32 v160, v28, v200
	v_mul_f32_e32 v161, v29, v201
	v_cvt_pk_bf16_f32 v160, v160, v161
	v_mul_f32_e32 v161, v30, v162
	v_mul_f32_e32 v162, v31, v163
	v_cvt_pk_bf16_f32 v161, v161, v162
	v_mul_f32_e32 v162, v100, v204
	v_mul_f32_e32 v163, v101, v205
	v_cvt_pk_bf16_f32 v162, v162, v163
	v_mul_f32_e32 v163, v102, v202
	v_mul_f32_e32 v200, v103, v203
	v_cvt_pk_bf16_f32 v163, v163, v200
.LBB0_113:
	s_andn2_b64 vcc, exec, s[66:67]
	s_cbranch_vccnz .LBB0_117
	s_cmp_lg_u32 s74, 0
	v_lshlrev_b32_e32 v198, 7, v198
	s_cbranch_scc0 .LBB0_132
	s_lshl_b32 s4, s89, 9
	v_or3_b32 v160, v193, v195, s64
	v_or3_b32 v161, v197, s4, v198
	v_lshl_add_u32 v199, v160, 12, v161
	s_waitcnt vmcnt(0)
	v_pk_mul_f32 v[162:163], v[154:155], v[178:179] op_sel_hi:[1,0]
	v_pk_mul_f32 v[160:161], v[152:153], v[178:179] op_sel_hi:[1,0]
	v_pk_mul_f32 v[200:201], v[146:147], v[178:179] op_sel_hi:[1,0]
	v_pk_mul_f32 v[202:203], v[144:145], v[178:179] op_sel_hi:[1,0]
	v_cvt_pk_bf16_f32 v160, v160, v161
	v_cvt_pk_bf16_f32 v161, v162, v163
	v_cvt_pk_bf16_f32 v163, v200, v201
	v_pk_mul_f32 v[200:201], v[150:151], v[178:179] op_sel_hi:[1,0]
	v_cvt_pk_bf16_f32 v162, v202, v203
	global_store_dwordx4 v199, v[160:163], s[6:7] sc0 sc1
	v_pk_mul_f32 v[202:203], v[148:149], v[178:179] op_sel_hi:[1,0]
	v_add_u32_e32 v204, 0x10000, v199
	v_pk_mul_f32 v[162:163], v[158:159], v[178:179] op_sel_hi:[1,0]
	v_pk_mul_f32 v[160:161], v[156:157], v[178:179] op_sel_hi:[1,0]
	s_nop 0
	v_cvt_pk_bf16_f32 v160, v160, v161
	v_cvt_pk_bf16_f32 v161, v162, v163
	v_cvt_pk_bf16_f32 v162, v202, v203
	v_cvt_pk_bf16_f32 v163, v200, v201
	global_store_dwordx4 v199, v[160:163], s[6:7] offset:64 sc0 sc1
	v_pk_mul_f32 v[200:201], v[130:131], v[176:177] op_sel_hi:[1,0]
	v_pk_mul_f32 v[202:203], v[128:129], v[176:177] op_sel_hi:[1,0]
	v_pk_mul_f32 v[162:163], v[138:139], v[176:177] op_sel_hi:[1,0]
	v_pk_mul_f32 v[160:161], v[136:137], v[176:177] op_sel_hi:[1,0]
	s_nop 0
	v_cvt_pk_bf16_f32 v160, v160, v161
	v_cvt_pk_bf16_f32 v161, v162, v163
	v_cvt_pk_bf16_f32 v162, v202, v203
	v_cvt_pk_bf16_f32 v163, v200, v201
	global_store_dwordx4 v204, v[160:163], s[6:7] sc0 sc1
	v_pk_mul_f32 v[200:201], v[134:135], v[176:177] op_sel_hi:[1,0]
	v_pk_mul_f32 v[202:203], v[132:133], v[176:177] op_sel_hi:[1,0]
	v_pk_mul_f32 v[162:163], v[142:143], v[176:177] op_sel_hi:[1,0]
	v_pk_mul_f32 v[160:161], v[140:141], v[176:177] op_sel_hi:[1,0]
	v_add_u32_e32 v204, 0x20000, v199
	v_cvt_pk_bf16_f32 v160, v160, v161
	v_cvt_pk_bf16_f32 v161, v162, v163
	v_cvt_pk_bf16_f32 v162, v202, v203
	v_cvt_pk_bf16_f32 v163, v200, v201
	v_add_u32_e32 v200, 0x10040, v199
	global_store_dwordx4 v200, v[160:163], s[6:7] sc0 sc1
	v_pk_mul_f32 v[200:201], v[114:115], v[174:175] op_sel_hi:[1,0]
	v_pk_mul_f32 v[202:203], v[112:113], v[174:175] op_sel_hi:[1,0]
	v_pk_mul_f32 v[162:163], v[122:123], v[174:175] op_sel_hi:[1,0]
	v_pk_mul_f32 v[160:161], v[120:121], v[174:175] op_sel_hi:[1,0]
	s_nop 0
	v_cvt_pk_bf16_f32 v160, v160, v161
	v_cvt_pk_bf16_f32 v161, v162, v163
	v_cvt_pk_bf16_f32 v162, v202, v203
	v_cvt_pk_bf16_f32 v163, v200, v201
	global_store_dwordx4 v204, v[160:163], s[6:7] sc0 sc1
	v_pk_mul_f32 v[200:201], v[118:119], v[174:175] op_sel_hi:[1,0]
	v_pk_mul_f32 v[202:203], v[116:117], v[174:175] op_sel_hi:[1,0]
	v_pk_mul_f32 v[162:163], v[126:127], v[174:175] op_sel_hi:[1,0]
	v_pk_mul_f32 v[160:161], v[124:125], v[174:175] op_sel_hi:[1,0]
	v_add_u32_e32 v204, 0x30000, v199
	v_cvt_pk_bf16_f32 v160, v160, v161
	v_cvt_pk_bf16_f32 v161, v162, v163
	v_cvt_pk_bf16_f32 v162, v202, v203
	v_cvt_pk_bf16_f32 v163, v200, v201
	v_add_u32_e32 v200, 0x20040, v199
	global_store_dwordx4 v200, v[160:163], s[6:7] sc0 sc1
	v_pk_mul_f32 v[200:201], v[30:31], v[164:165] op_sel_hi:[1,0]
	v_pk_mul_f32 v[202:203], v[28:29], v[164:165] op_sel_hi:[1,0]
	v_pk_mul_f32 v[162:163], v[106:107], v[164:165] op_sel_hi:[1,0]
	v_pk_mul_f32 v[160:161], v[104:105], v[164:165] op_sel_hi:[1,0]
	v_add_u32_e32 v199, 0x30040, v199
	v_cvt_pk_bf16_f32 v160, v160, v161
	v_cvt_pk_bf16_f32 v161, v162, v163
	v_cvt_pk_bf16_f32 v162, v202, v203
	v_cvt_pk_bf16_f32 v163, v200, v201
	global_store_dwordx4 v204, v[160:163], s[6:7] sc0 sc1
	v_pk_mul_f32 v[200:201], v[102:103], v[164:165] op_sel_hi:[1,0]
	v_pk_mul_f32 v[202:203], v[100:101], v[164:165] op_sel_hi:[1,0]
	v_pk_mul_f32 v[162:163], v[110:111], v[164:165] op_sel_hi:[1,0]
	v_pk_mul_f32 v[160:161], v[108:109], v[164:165] op_sel_hi:[1,0]
	s_nop 0
	v_cvt_pk_bf16_f32 v160, v160, v161
	v_cvt_pk_bf16_f32 v161, v162, v163
	v_cvt_pk_bf16_f32 v162, v202, v203
	v_cvt_pk_bf16_f32 v163, v200, v201
	s_cbranch_execnz .LBB0_117
.LBB0_116:
	v_mul_lo_u32 v160, v196, s82
	v_lshlrev_b32_e32 v161, 4, v194
	v_add_u32_e32 v160, 0x20000, v160
	v_and_b32_e32 v163, 0x70, v161
	v_mul_u32_u24_e32 v161, 0x90, v195
	v_bfe_u32 v162, v194, 3, 3
	v_add3_u32 v194, v160, v161, v197
	v_or_b32_e32 v160, v160, v163
	v_mad_u32_u24 v195, v162, s83, v160
	s_waitcnt vmcnt(0)
	v_pk_mul_f32 v[160:161], v[146:147], v[178:179] op_sel_hi:[1,0]
	v_pk_mul_f32 v[146:147], v[144:145], v[178:179] op_sel_hi:[1,0]
	v_pk_mul_f32 v[154:155], v[154:155], v[178:179] op_sel_hi:[1,0]
	v_pk_mul_f32 v[152:153], v[152:153], v[178:179] op_sel_hi:[1,0]
	v_cvt_pk_bf16_f32 v145, v154, v155
	v_cvt_pk_bf16_f32 v146, v146, v147
	v_cvt_pk_bf16_f32 v147, v160, v161
	v_pk_mul_f32 v[150:151], v[150:151], v[178:179] op_sel_hi:[1,0]
	v_cvt_pk_bf16_f32 v144, v152, v153
	ds_write_b128 v194, v[144:147]
	v_pk_mul_f32 v[146:147], v[158:159], v[178:179] op_sel_hi:[1,0]
	v_pk_mul_f32 v[144:145], v[156:157], v[178:179] op_sel_hi:[1,0]
	v_pk_mul_f32 v[148:149], v[148:149], v[178:179] op_sel_hi:[1,0]
	v_cvt_pk_bf16_f32 v144, v144, v145
	v_cvt_pk_bf16_f32 v145, v146, v147
	v_cvt_pk_bf16_f32 v147, v150, v151
	s_lshl_b32 s4, s89, 9
	v_cvt_pk_bf16_f32 v146, v148, v149
	ds_write_b128 v194, v[144:147] offset:64
	ds_read_b128 v[144:147], v195
	v_or3_b32 v148, v193, v162, s64
	v_or3_b32 v149, v198, s4, v163
	v_lshl_add_u32 v152, v148, 12, v149
	ds_read_b128 v[148:151], v195 offset:1152
	s_waitcnt lgkmcnt(1)
	global_store_dwordx4 v152, v[144:147], s[6:7] sc0 sc1
	v_pk_mul_f32 v[138:139], v[138:139], v[176:177] op_sel_hi:[1,0]
	v_pk_mul_f32 v[136:137], v[136:137], v[176:177] op_sel_hi:[1,0]
	v_pk_mul_f32 v[144:145], v[130:131], v[176:177] op_sel_hi:[1,0]
	v_pk_mul_f32 v[130:131], v[128:129], v[176:177] op_sel_hi:[1,0]
	v_cvt_pk_bf16_f32 v128, v136, v137
	v_cvt_pk_bf16_f32 v129, v138, v139
	v_pk_mul_f32 v[134:135], v[134:135], v[176:177] op_sel_hi:[1,0]
	v_cvt_pk_bf16_f32 v130, v130, v131
	v_cvt_pk_bf16_f32 v131, v144, v145
	ds_write_b128 v194, v[128:131]
	v_pk_mul_f32 v[130:131], v[142:143], v[176:177] op_sel_hi:[1,0]
	v_pk_mul_f32 v[128:129], v[140:141], v[176:177] op_sel_hi:[1,0]
	v_pk_mul_f32 v[132:133], v[132:133], v[176:177] op_sel_hi:[1,0]
	v_cvt_pk_bf16_f32 v128, v128, v129
	v_cvt_pk_bf16_f32 v129, v130, v131
	v_cvt_pk_bf16_f32 v131, v134, v135
	v_add_u32_e32 v136, 0x10000, v152
	v_cvt_pk_bf16_f32 v130, v132, v133
	ds_write_b128 v194, v[128:131] offset:64
	ds_read_b128 v[128:131], v195
	v_add_u32_e32 v132, 0x8000, v152
	s_waitcnt lgkmcnt(3)
	global_store_dwordx4 v132, v[148:151], s[6:7] sc0 sc1
	ds_read_b128 v[132:135], v195 offset:1152
	v_pk_mul_f32 v[122:123], v[122:123], v[174:175] op_sel_hi:[1,0]
	s_waitcnt lgkmcnt(1)
	global_store_dwordx4 v136, v[128:131], s[6:7] sc0 sc1
	v_pk_mul_f32 v[120:121], v[120:121], v[174:175] op_sel_hi:[1,0]
	v_pk_mul_f32 v[118:119], v[118:119], v[174:175] op_sel_hi:[1,0]
	v_pk_mul_f32 v[128:129], v[114:115], v[174:175] op_sel_hi:[1,0]
	v_pk_mul_f32 v[114:115], v[112:113], v[174:175] op_sel_hi:[1,0]
	v_cvt_pk_bf16_f32 v112, v120, v121
	v_cvt_pk_bf16_f32 v113, v122, v123
	v_pk_mul_f32 v[116:117], v[116:117], v[174:175] op_sel_hi:[1,0]
	v_cvt_pk_bf16_f32 v114, v114, v115
	v_cvt_pk_bf16_f32 v115, v128, v129
	ds_write_b128 v194, v[112:115]
	v_pk_mul_f32 v[114:115], v[126:127], v[174:175] op_sel_hi:[1,0]
	v_pk_mul_f32 v[112:113], v[124:125], v[174:175] op_sel_hi:[1,0]
	v_add_u32_e32 v120, 0x20000, v152
	v_cvt_pk_bf16_f32 v112, v112, v113
	v_cvt_pk_bf16_f32 v113, v114, v115
	v_cvt_pk_bf16_f32 v114, v116, v117
	v_cvt_pk_bf16_f32 v115, v118, v119
	ds_write_b128 v194, v[112:115] offset:64
	ds_read_b128 v[112:115], v195
	v_add_u32_e32 v116, 0x18000, v152
	s_waitcnt lgkmcnt(3)
	global_store_dwordx4 v116, v[132:135], s[6:7] sc0 sc1
	ds_read_b128 v[116:119], v195 offset:1152
	v_pk_mul_f32 v[106:107], v[106:107], v[164:165] op_sel_hi:[1,0]
	s_waitcnt lgkmcnt(1)
	global_store_dwordx4 v120, v[112:115], s[6:7] sc0 sc1
	v_pk_mul_f32 v[104:105], v[104:105], v[164:165] op_sel_hi:[1,0]
	v_pk_mul_f32 v[102:103], v[102:103], v[164:165] op_sel_hi:[1,0]
	v_pk_mul_f32 v[112:113], v[30:31], v[164:165] op_sel_hi:[1,0]
	v_pk_mul_f32 v[30:31], v[28:29], v[164:165] op_sel_hi:[1,0]
	v_cvt_pk_bf16_f32 v28, v104, v105
	v_cvt_pk_bf16_f32 v29, v106, v107
	v_pk_mul_f32 v[100:101], v[100:101], v[164:165] op_sel_hi:[1,0]
	v_cvt_pk_bf16_f32 v30, v30, v31
	v_cvt_pk_bf16_f32 v31, v112, v113
	ds_write_b128 v194, v[28:31]
	v_pk_mul_f32 v[30:31], v[110:111], v[164:165] op_sel_hi:[1,0]
	v_pk_mul_f32 v[28:29], v[108:109], v[164:165] op_sel_hi:[1,0]
	v_add_u32_e32 v199, 0x38000, v152
	v_cvt_pk_bf16_f32 v28, v28, v29
	v_cvt_pk_bf16_f32 v29, v30, v31
	v_cvt_pk_bf16_f32 v30, v100, v101
	v_cvt_pk_bf16_f32 v31, v102, v103
	ds_write_b128 v194, v[28:31] offset:64
	ds_read_b128 v[28:31], v195
	ds_read_b128 v[160:163], v195 offset:1152
	v_add_u32_e32 v100, 0x28000, v152
	s_waitcnt lgkmcnt(4)
	global_store_dwordx4 v100, v[116:119], s[6:7] sc0 sc1
	v_add_u32_e32 v100, 0x30000, v152
	s_waitcnt lgkmcnt(1)
	global_store_dwordx4 v100, v[28:31], s[6:7] sc0 sc1
.LBB0_117:
	s_waitcnt lgkmcnt(0)
	global_store_dwordx4 v199, v[160:163], s[6:7] sc0 sc1
	ds_read_b128 v[100:103], v192 offset:49152
	ds_read_b128 v[104:107], v192 offset:50176
	ds_read_b128 v[108:111], v191 offset:49152
	ds_read_b128 v[112:115], v191 offset:50176
	ds_read_b128 v[116:119], v190 offset:49152
	ds_read_b128 v[120:123], v190 offset:50176
	ds_read_b128 v[124:127], v189 offset:49152
	ds_read_b128 v[128:131], v189 offset:50176
	s_barrier
	s_waitcnt lgkmcnt(0)
	s_setprio 1
	s_waitcnt lgkmcnt(0)
	v_mfma_f32_16x16x32_bf16 v[28:31], v[12:15], v[100:103], v[32:35]
	v_mfma_f32_16x16x32_bf16 v[32:35], v[24:27], v[100:103], v[36:39]
	v_mfma_f32_16x16x32_bf16 v[36:39], v[12:15], v[108:111], v[40:43]
	v_mfma_f32_16x16x32_bf16 v[40:43], v[24:27], v[108:111], v[44:47]
	v_mfma_f32_16x16x32_bf16 v[48:51], v[12:15], v[116:119], v[48:51]
	v_mfma_f32_16x16x32_bf16 v[52:55], v[24:27], v[116:119], v[52:55]
	v_mfma_f32_16x16x32_bf16 v[12:15], v[12:15], v[124:127], v[56:59]
	v_mfma_f32_16x16x32_bf16 v[132:135], v[24:27], v[124:127], v[60:63]
	v_mfma_f32_16x16x32_bf16 v[60:63], v[8:11], v[104:107], v[28:31]
	v_mfma_f32_16x16x32_bf16 v[56:59], v[80:83], v[104:107], v[32:35]
	v_mfma_f32_16x16x32_bf16 v[44:47], v[8:11], v[112:115], v[36:39]
	v_mfma_f32_16x16x32_bf16 v[40:43], v[80:83], v[112:115], v[40:43]
	v_mfma_f32_16x16x32_bf16 v[28:31], v[8:11], v[120:123], v[48:51]
	v_mfma_f32_16x16x32_bf16 v[24:27], v[80:83], v[120:123], v[52:55]
	v_mfma_f32_16x16x32_bf16 v[12:15], v[8:11], v[128:131], v[12:15]
	v_mfma_f32_16x16x32_bf16 v[8:11], v[80:83], v[128:131], v[132:135]
	s_setprio 0
	s_setprio 1
	v_mfma_f32_16x16x32_bf16 v[0:3], v[92:95], v[100:103], v[0:3]
	v_mfma_f32_16x16x32_bf16 v[4:7], v[96:99], v[100:103], v[4:7]
	v_mfma_f32_16x16x32_bf16 v[16:19], v[92:95], v[108:111], v[16:19]
	v_mfma_f32_16x16x32_bf16 v[20:23], v[96:99], v[108:111], v[20:23]
	v_mfma_f32_16x16x32_bf16 v[64:67], v[92:95], v[116:119], v[64:67]
	v_mfma_f32_16x16x32_bf16 v[68:71], v[96:99], v[116:119], v[68:71]
	v_mfma_f32_16x16x32_bf16 v[72:75], v[92:95], v[124:127], v[72:75]
	v_mfma_f32_16x16x32_bf16 v[76:79], v[96:99], v[124:127], v[76:79]
	v_mfma_f32_16x16x32_bf16 v[52:55], v[84:87], v[104:107], v[0:3]
	v_mfma_f32_16x16x32_bf16 v[48:51], v[88:91], v[104:107], v[4:7]
	v_mfma_f32_16x16x32_bf16 v[36:39], v[84:87], v[112:115], v[16:19]
	v_mfma_f32_16x16x32_bf16 v[32:35], v[88:91], v[112:115], v[20:23]
	v_mfma_f32_16x16x32_bf16 v[20:23], v[84:87], v[120:123], v[64:67]
	v_mfma_f32_16x16x32_bf16 v[16:19], v[88:91], v[120:123], v[68:71]
	v_mfma_f32_16x16x32_bf16 v[4:7], v[84:87], v[128:131], v[72:75]
	v_mfma_f32_16x16x32_bf16 v[0:3], v[88:91], v[128:131], v[76:79]
	s_setprio 0
	v_cmp_gt_u32_e32 vcc, s81, v171
	s_barrier
	s_and_saveexec_b64 s[66:67], vcc
	s_cbranch_execz .LBB0_119
	s_barrier

.LBB0_125:
	v_mbcnt_lo_u32_b32 v68, -1, 0
	v_mbcnt_hi_u32_b32 v68, -1, v68
	s_mov_b64 s[72:73], -1
	v_add_u32_e32 v64, s76, v68
	v_bfe_u32 v65, v64, 8, 1
	v_ashrrev_i32_e32 v71, 6, v64
	v_bfe_u32 v64, v68, 4, 2
	v_and_b32_e32 v73, 3, v71
	v_and_b32_e32 v69, 15, v68
	s_cmp_gt_i32 s74, 1
	v_lshlrev_b32_e32 v70, 6, v65
	v_lshlrev_b32_e32 v72, 4, v64
	s_cbranch_scc0 .LBB0_127
	v_lshlrev_b32_e32 v64, 6, v73
	v_or3_b32 v65, v70, s64, v69
	v_or3_b32 v64, v64, v72, s62
	v_lshl_add_u32 v80, v65, 12, v64
	s_waitcnt vmcnt(0)
	v_mul_f32_e32 v64, v172, v172
	v_pk_mul_f32 v[74:75], v[64:65], v[60:61] op_sel_hi:[0,1]
	v_pk_mul_f32 v[66:67], v[64:65], v[62:63] op_sel_hi:[0,1]
	v_pk_mul_f32 v[76:77], v[64:65], v[54:55] op_sel_hi:[0,1]
	v_pk_mul_f32 v[78:79], v[64:65], v[52:53] op_sel_hi:[0,1]
	v_mul_f32_e32 v64, v56, v74
	v_mul_f32_e32 v65, v57, v75
	v_cvt_pk_bf16_f32 v64, v64, v65
	v_mul_f32_e32 v65, v58, v66
	v_mul_f32_e32 v66, v59, v67
	v_cvt_pk_bf16_f32 v65, v65, v66
	v_mul_f32_e32 v66, v48, v78
	v_mul_f32_e32 v67, v49, v79
	v_add_u32_e32 v81, 0x80000, v80
	v_cvt_pk_bf16_f32 v66, v66, v67
	v_mul_f32_e32 v67, v50, v76
	v_mul_f32_e32 v74, v51, v77
	v_cvt_pk_bf16_f32 v67, v67, v74
	global_store_dwordx4 v81, v[64:67], s[6:7] sc0 sc1
	v_add_u32_e32 v81, 0x90000, v80
	s_mov_b64 s[72:73], 0
	v_mul_f32_e32 v64, v170, v170
	v_pk_mul_f32 v[74:75], v[64:65], v[44:45] op_sel_hi:[0,1]
	v_pk_mul_f32 v[66:67], v[64:65], v[46:47] op_sel_hi:[0,1]
	v_pk_mul_f32 v[76:77], v[64:65], v[38:39] op_sel_hi:[0,1]
	v_pk_mul_f32 v[78:79], v[64:65], v[36:37] op_sel_hi:[0,1]
	v_mul_f32_e32 v64, v40, v74
	v_mul_f32_e32 v65, v41, v75
	v_cvt_pk_bf16_f32 v64, v64, v65
	v_mul_f32_e32 v65, v42, v66
	v_mul_f32_e32 v66, v43, v67
	v_cvt_pk_bf16_f32 v65, v65, v66
	v_mul_f32_e32 v66, v32, v78
	v_mul_f32_e32 v67, v33, v79
	v_cvt_pk_bf16_f32 v66, v66, v67
	v_mul_f32_e32 v67, v34, v76
	v_mul_f32_e32 v74, v35, v77
	v_cvt_pk_bf16_f32 v67, v67, v74
	global_store_dwordx4 v81, v[64:67], s[6:7] sc0 sc1
	v_add_u32_e32 v81, 0xa0000, v80
	s_nop 0
	v_mul_f32_e32 v64, v168, v168
	v_pk_mul_f32 v[74:75], v[64:65], v[28:29] op_sel_hi:[0,1]
	v_pk_mul_f32 v[66:67], v[64:65], v[30:31] op_sel_hi:[0,1]
	v_pk_mul_f32 v[76:77], v[64:65], v[22:23] op_sel_hi:[0,1]
	v_pk_mul_f32 v[78:79], v[64:65], v[20:21] op_sel_hi:[0,1]
	v_mul_f32_e32 v64, v24, v74
	v_mul_f32_e32 v65, v25, v75
	v_cvt_pk_bf16_f32 v64, v64, v65
	v_mul_f32_e32 v65, v26, v66
	v_mul_f32_e32 v66, v27, v67
	v_cvt_pk_bf16_f32 v65, v65, v66
	v_mul_f32_e32 v66, v16, v78
	v_mul_f32_e32 v67, v17, v79
	v_cvt_pk_bf16_f32 v66, v66, v67
	v_mul_f32_e32 v67, v18, v76
	v_mul_f32_e32 v74, v19, v77
	v_cvt_pk_bf16_f32 v67, v67, v74
	global_store_dwordx4 v81, v[64:67], s[6:7] sc0 sc1
	v_add_u32_e32 v74, 0xb0000, v80
	s_nop 0
	v_mul_f32_e32 v64, v166, v166
	v_pk_mul_f32 v[76:77], v[64:65], v[12:13] op_sel_hi:[0,1]
	v_pk_mul_f32 v[66:67], v[64:65], v[14:15] op_sel_hi:[0,1]
	v_pk_mul_f32 v[78:79], v[64:65], v[6:7] op_sel_hi:[0,1]
	v_pk_mul_f32 v[80:81], v[64:65], v[4:5] op_sel_hi:[0,1]
	v_mul_f32_e32 v64, v8, v76
	v_mul_f32_e32 v65, v9, v77
	v_cvt_pk_bf16_f32 v64, v64, v65
	v_mul_f32_e32 v65, v10, v66
	v_mul_f32_e32 v66, v11, v67
	v_cvt_pk_bf16_f32 v65, v65, v66
	v_mul_f32_e32 v66, v0, v80
	v_mul_f32_e32 v67, v1, v81
	v_cvt_pk_bf16_f32 v66, v66, v67
	v_mul_f32_e32 v67, v2, v78
	v_mul_f32_e32 v75, v3, v79
	v_cvt_pk_bf16_f32 v67, v67, v75
.LBB0_127:
	s_andn2_b64 vcc, exec, s[72:73]
	s_cbranch_vccnz .LBB0_92
	s_cmp_lg_u32 s74, 0
	v_lshlrev_b32_e32 v73, 7, v73
	s_cbranch_scc0 .LBB0_133
	s_lshl_b32 s62, s89, 9
	v_or3_b32 v64, v70, v69, s64
	v_or3_b32 v65, v72, s62, v73
	v_lshl_add_u32 v78, v64, 12, v65
	s_waitcnt vmcnt(0)
	v_pk_mul_f32 v[66:67], v[172:173], v[62:63] op_sel_hi:[0,1]
	v_pk_mul_f32 v[64:65], v[172:173], v[60:61] op_sel_hi:[0,1]
	v_add_u32_e32 v79, 0x80000, v78
	v_pk_mul_f32 v[74:75], v[172:173], v[58:59] op_sel_hi:[0,1]
	v_pk_mul_f32 v[76:77], v[172:173], v[56:57] op_sel_hi:[0,1]
	v_cvt_pk_bf16_f32 v64, v64, v65
	v_cvt_pk_bf16_f32 v65, v66, v67
	v_cvt_pk_bf16_f32 v66, v76, v77
	v_cvt_pk_bf16_f32 v67, v74, v75
	global_store_dwordx4 v79, v[64:67], s[6:7] sc0 sc1
	v_pk_mul_f32 v[74:75], v[172:173], v[50:51] op_sel_hi:[0,1]
	v_pk_mul_f32 v[76:77], v[172:173], v[48:49] op_sel_hi:[0,1]
	v_pk_mul_f32 v[66:67], v[172:173], v[54:55] op_sel_hi:[0,1]
	v_pk_mul_f32 v[64:65], v[172:173], v[52:53] op_sel_hi:[0,1]
	v_cvt_pk_bf16_f32 v64, v64, v65
	v_cvt_pk_bf16_f32 v65, v66, v67
	v_cvt_pk_bf16_f32 v66, v76, v77
	v_cvt_pk_bf16_f32 v67, v74, v75
	v_add_u32_e32 v74, 0x80040, v78
	global_store_dwordx4 v74, v[64:67], s[6:7] sc0 sc1
	v_add_u32_e32 v79, 0x90000, v78
	v_pk_mul_f32 v[74:75], v[170:171], v[42:43] op_sel_hi:[0,1]
	v_pk_mul_f32 v[66:67], v[170:171], v[46:47] op_sel_hi:[0,1]
	v_pk_mul_f32 v[64:65], v[170:171], v[44:45] op_sel_hi:[0,1]
	v_pk_mul_f32 v[76:77], v[170:171], v[40:41] op_sel_hi:[0,1]
	v_cvt_pk_bf16_f32 v64, v64, v65
	v_cvt_pk_bf16_f32 v65, v66, v67
	v_cvt_pk_bf16_f32 v66, v76, v77
	v_cvt_pk_bf16_f32 v67, v74, v75
	global_store_dwordx4 v79, v[64:67], s[6:7] sc0 sc1
	v_pk_mul_f32 v[74:75], v[170:171], v[34:35] op_sel_hi:[0,1]
	v_pk_mul_f32 v[76:77], v[170:171], v[32:33] op_sel_hi:[0,1]
	v_pk_mul_f32 v[66:67], v[170:171], v[38:39] op_sel_hi:[0,1]
	v_pk_mul_f32 v[64:65], v[170:171], v[36:37] op_sel_hi:[0,1]
	v_cvt_pk_bf16_f32 v64, v64, v65
	v_cvt_pk_bf16_f32 v65, v66, v67
	v_cvt_pk_bf16_f32 v66, v76, v77
	v_cvt_pk_bf16_f32 v67, v74, v75
	v_add_u32_e32 v74, 0x90040, v78
	global_store_dwordx4 v74, v[64:67], s[6:7] sc0 sc1
	v_add_u32_e32 v79, 0xa0000, v78
	v_pk_mul_f32 v[74:75], v[168:169], v[26:27] op_sel_hi:[0,1]
	v_pk_mul_f32 v[66:67], v[168:169], v[30:31] op_sel_hi:[0,1]
	v_pk_mul_f32 v[64:65], v[168:169], v[28:29] op_sel_hi:[0,1]
	v_pk_mul_f32 v[76:77], v[168:169], v[24:25] op_sel_hi:[0,1]
	v_cvt_pk_bf16_f32 v64, v64, v65
	v_cvt_pk_bf16_f32 v65, v66, v67
	v_cvt_pk_bf16_f32 v66, v76, v77
	v_cvt_pk_bf16_f32 v67, v74, v75
	global_store_dwordx4 v79, v[64:67], s[6:7] sc0 sc1
	v_pk_mul_f32 v[74:75], v[168:169], v[18:19] op_sel_hi:[0,1]
	v_pk_mul_f32 v[76:77], v[168:169], v[16:17] op_sel_hi:[0,1]
	v_pk_mul_f32 v[66:67], v[168:169], v[22:23] op_sel_hi:[0,1]
	v_pk_mul_f32 v[64:65], v[168:169], v[20:21] op_sel_hi:[0,1]
	v_cvt_pk_bf16_f32 v64, v64, v65
	v_cvt_pk_bf16_f32 v65, v66, v67
	v_cvt_pk_bf16_f32 v66, v76, v77
	v_cvt_pk_bf16_f32 v67, v74, v75
	v_add_u32_e32 v74, 0xa0040, v78
	global_store_dwordx4 v74, v[64:67], s[6:7] sc0 sc1
	v_add_u32_e32 v79, 0xb0000, v78
	v_pk_mul_f32 v[74:75], v[166:167], v[10:11] op_sel_hi:[0,1]
	v_pk_mul_f32 v[66:67], v[166:167], v[14:15] op_sel_hi:[0,1]
	v_pk_mul_f32 v[64:65], v[166:167], v[12:13] op_sel_hi:[0,1]
	v_pk_mul_f32 v[76:77], v[166:167], v[8:9] op_sel_hi:[0,1]
	v_cvt_pk_bf16_f32 v64, v64, v65
	v_cvt_pk_bf16_f32 v65, v66, v67
	v_cvt_pk_bf16_f32 v66, v76, v77
	v_cvt_pk_bf16_f32 v67, v74, v75
	global_store_dwordx4 v79, v[64:67], s[6:7] sc0 sc1
	v_pk_mul_f32 v[74:75], v[166:167], v[2:3] op_sel_hi:[0,1]
	v_pk_mul_f32 v[76:77], v[166:167], v[0:1] op_sel_hi:[0,1]
	v_pk_mul_f32 v[66:67], v[166:167], v[6:7] op_sel_hi:[0,1]
	v_pk_mul_f32 v[64:65], v[166:167], v[4:5] op_sel_hi:[0,1]
	v_cvt_pk_bf16_f32 v64, v64, v65
	v_cvt_pk_bf16_f32 v65, v66, v67
	v_cvt_pk_bf16_f32 v66, v76, v77
	v_cvt_pk_bf16_f32 v67, v74, v75
	v_add_u32_e32 v74, 0xb0040, v78
	s_cbranch_execnz .LBB0_92
	s_branch .LBB0_91

.LBB0_166:
	v_mbcnt_lo_u32_b32 v64, -1, 0
	v_mbcnt_hi_u32_b32 v64, -1, v64
	v_cvt_pk_bf16_f32 v56, v56, v57
	v_cvt_pk_bf16_f32 v57, v58, v59
	v_cvt_pk_bf16_f32 v58, v48, v49
	v_cvt_pk_bf16_f32 v59, v50, v51
	v_cvt_pk_bf16_f32 v48, v60, v61
	s_nop 0
	v_add_u32_e32 v65, s72, v64
	v_ashrrev_i32_e32 v66, 6, v65
	v_and_b32_e32 v67, 15, v64
	v_and_b32_e32 v68, 48, v64
	v_mul_lo_u32 v69, v66, s77
	v_lshrrev_b32_e32 v65, 2, v65
	v_bfe_u32 v70, v64, 3, 3
	v_lshlrev_b32_e32 v64, 4, v64
	v_add_u32_e32 v69, 0x20000, v69
	v_and_b32_e32 v65, 64, v65
	v_and_b32_e32 v64, 0x70, v64
	v_mul_u32_u24_e32 v67, 0x90, v67
	v_add3_u32 v67, v69, v67, v68
	v_or_b32_e32 v68, v69, v64
	v_or3_b32 v65, s24, v65, v70
	v_lshlrev_b32_e32 v66, 7, v66
	v_mad_u32_u24 v68, v70, s78, v68
	ds_write_b128 v67, v[56:59]
	v_cvt_pk_bf16_f32 v49, v62, v63
	v_cvt_pk_bf16_f32 v50, v52, v53
	v_cvt_pk_bf16_f32 v51, v54, v55
	ds_write_b128 v67, v[48:51] offset:64
	v_lshlrev_b32_e32 v52, 12, v65
	ds_read_b128 v[48:51], v68
	v_and_or_b32 v52, v66, s79, v52
	v_or3_b32 v128, v52, s66, v64
	v_lshl_add_u64 v[56:57], s[0:1], 0, v[128:129]
	v_add_co_u32_e32 v58, vcc, s92, v56
	ds_read_b128 v[52:55], v68 offset:1152
	v_cvt_pk_bf16_f32 v44, v44, v45
	v_cvt_pk_bf16_f32 v45, v46, v47
	v_cvt_pk_bf16_f32 v46, v40, v41
	v_cvt_pk_bf16_f32 v47, v42, v43
	ds_write_b128 v67, v[44:47]
	v_cvt_pk_bf16_f32 v28, v28, v29
	v_cvt_pk_bf16_f32 v29, v30, v31
	v_cvt_pk_bf16_f32 v30, v24, v25
	v_cvt_pk_bf16_f32 v31, v26, v27
	ds_write_b128 v67, v[28:31] offset:64
	v_addc_co_u32_e32 v59, vcc, 0, v57, vcc
	ds_read_b128 v[24:27], v68
	ds_read_b128 v[28:31], v68 offset:1152
	s_waitcnt lgkmcnt(0)
	global_store_dwordx4 v[58:59], v[48:51], off sc0 sc1
	v_cvt_pk_bf16_f32 v20, v20, v21
	v_cvt_pk_bf16_f32 v21, v22, v23
	v_cvt_pk_bf16_f32 v22, v16, v17
	v_cvt_pk_bf16_f32 v23, v18, v19
	ds_write_b128 v67, v[20:23] offset:64
	s_nop 0
	v_add_co_u32_e32 v48, vcc, s93, v56
	v_cvt_pk_bf16_f32 v8, v8, v9
	v_cvt_pk_bf16_f32 v9, v10, v11
	v_cvt_pk_bf16_f32 v10, v0, v1
	v_cvt_pk_bf16_f32 v11, v2, v3
	s_nop 1
	v_addc_co_u32_e32 v49, vcc, 0, v57, vcc
	v_add_co_u32_e32 v40, vcc, s94, v56
	v_cvt_pk_bf16_f32 v0, v12, v13
	v_cvt_pk_bf16_f32 v1, v14, v15
	v_cvt_pk_bf16_f32 v2, v4, v5
	v_cvt_pk_bf16_f32 v3, v6, v7
	s_nop 1
	v_addc_co_u32_e32 v41, vcc, 0, v57, vcc
	global_store_dwordx4 v[40:41], v[24:27], off sc0 sc1
	s_add_i32 s73, s73, 1
	global_store_dwordx4 v[48:49], v[52:55], off sc0 sc1
	v_add_co_u32_e32 v24, vcc, s95, v56
	v_cvt_pk_bf16_f32 v26, v32, v33
	v_cvt_pk_bf16_f32 v27, v34, v35
	s_nop 1
	v_addc_co_u32_e32 v25, vcc, 0, v57, vcc
	global_store_dwordx4 v[24:25], v[28:31], off sc0 sc1
	v_cvt_pk_bf16_f32 v24, v36, v37
	v_cvt_pk_bf16_f32 v25, v38, v39
	ds_write_b128 v67, v[24:27]
	ds_read_b128 v[16:19], v68
	ds_read_b128 v[20:23], v68 offset:1152
	v_add_co_u32_e32 v24, vcc, s96, v56
	ds_write_b128 v67, v[8:11]
	ds_write_b128 v67, v[0:3] offset:64
	v_addc_co_u32_e32 v25, vcc, 0, v57, vcc
	ds_read_b128 v[0:3], v68
	ds_read_b128 v[4:7], v68 offset:1152
	s_waitcnt lgkmcnt(0)
	global_store_dwordx4 v[24:25], v[16:19], off sc0 sc1
	s_nop 1
	v_add_co_u32_e32 v16, vcc, s97, v56
	s_nop 1
	v_addc_co_u32_e32 v17, vcc, 0, v57, vcc
	v_add_co_u32_e32 v8, vcc, 0xb0000, v56
	global_store_dwordx4 v[16:17], v[20:23], off sc0 sc1
	s_nop 0
	v_addc_co_u32_e32 v9, vcc, 0, v57, vcc
	global_store_dwordx4 v[8:9], v[0:3], off sc0 sc1
	s_nop 1
	v_add_co_u32_e32 v0, vcc, 0xb8000, v56
	s_nop 1
	v_addc_co_u32_e32 v1, vcc, 0, v57, vcc
	s_andn2_b64 vcc, exec, s[64:65]
	s_mov_b64 s[64:65], 0
	global_store_dwordx4 v[0:1], v[4:7], off sc0 sc1
	s_cbranch_vccz .LBB0_183

.LBB0_178:
	ds_read_b128 v[164:167], v162
	ds_read_b128 v[168:171], v162 offset:1024
	ds_read_b128 v[172:175], v162 offset:2048
	ds_read_b128 v[176:179], v162 offset:3072
	v_lshl_add_u64 v[228:229], s[50:51], 0, v[132:133]
	s_mov_b64 s[66:67], 0xe080080
	v_readfirstlane_b32 s65, v161
	v_lshl_add_u64 v[212:213], v[228:229], 0, s[66:67]
	s_mov_b32 m0, s65
	s_mov_b64 s[66:67], 0xe0c0080
	v_readfirstlane_b32 s65, v160
	ds_read_b128 v[180:183], v153
	ds_read_b128 v[184:187], v153 offset:1024
	ds_read_b128 v[188:191], v152
	ds_read_b128 v[192:195], v152 offset:1024
	ds_read_b128 v[196:199], v151
	ds_read_b128 v[200:203], v151 offset:1024
	ds_read_b128 v[204:207], v150
	ds_read_b128 v[208:211], v150 offset:1024
	global_load_lds_dwordx4 v[212:213], off
	v_lshl_add_u64 v[212:213], v[228:229], 0, s[66:67]
	s_mov_b32 m0, s65
	s_nop 0
	global_load_lds_dwordx4 v[212:213], off
	s_waitcnt lgkmcnt(8)
	s_barrier
	s_waitcnt lgkmcnt(0)
	s_setprio 1
	s_waitcnt lgkmcnt(0)
	v_mfma_f32_16x16x32_bf16 v[124:127], v[164:167], v[180:183], v[124:127]
	v_mfma_f32_16x16x32_bf16 v[120:123], v[172:175], v[180:183], v[120:123]
	v_mfma_f32_16x16x32_bf16 v[116:119], v[164:167], v[188:191], v[116:119]
	v_mfma_f32_16x16x32_bf16 v[112:115], v[172:175], v[188:191], v[112:115]
	v_mfma_f32_16x16x32_bf16 v[108:111], v[164:167], v[196:199], v[108:111]
	v_mfma_f32_16x16x32_bf16 v[104:107], v[172:175], v[196:199], v[104:107]
	v_mfma_f32_16x16x32_bf16 v[100:103], v[164:167], v[204:207], v[100:103]
	v_mfma_f32_16x16x32_bf16 v[96:99], v[172:175], v[204:207], v[96:99]
	v_mfma_f32_16x16x32_bf16 v[124:127], v[168:171], v[184:187], v[124:127]
	v_mfma_f32_16x16x32_bf16 v[120:123], v[176:179], v[184:187], v[120:123]
	v_mfma_f32_16x16x32_bf16 v[116:119], v[168:171], v[192:195], v[116:119]
	v_mfma_f32_16x16x32_bf16 v[112:115], v[176:179], v[192:195], v[112:115]
	v_mfma_f32_16x16x32_bf16 v[108:111], v[168:171], v[200:203], v[108:111]
	v_mfma_f32_16x16x32_bf16 v[104:107], v[176:179], v[200:203], v[104:107]
	v_mfma_f32_16x16x32_bf16 v[100:103], v[168:171], v[208:211], v[100:103]
	v_mfma_f32_16x16x32_bf16 v[96:99], v[176:179], v[208:211], v[96:99]
	s_setprio 0
	s_barrier
	v_lshl_add_u64 v[230:231], s[50:51], 0, v[130:131]
	s_mov_b64 s[66:67], 0x1880000
	v_readfirstlane_b32 s65, v149
	v_lshl_add_u64 v[232:233], v[230:231], 0, s[66:67]
	s_mov_b32 m0, s65
	s_mov_b64 s[66:67], 0x1881000
	v_readfirstlane_b32 s65, v148
	ds_read_b128 v[212:215], v159
	ds_read_b128 v[216:219], v159 offset:1024
	ds_read_b128 v[220:223], v159 offset:2048
	ds_read_b128 v[224:227], v159 offset:3072
	global_load_lds_dwordx4 v[232:233], off
	v_lshl_add_u64 v[232:233], v[230:231], 0, s[66:67]
	s_mov_b32 m0, s65
	s_nop 0
	global_load_lds_dwordx4 v[232:233], off
	s_barrier
	s_waitcnt lgkmcnt(0)
	s_setprio 1
	s_waitcnt lgkmcnt(0)
	v_mfma_f32_16x16x32_bf16 v[92:95], v[212:215], v[180:183], v[92:95]
	v_mfma_f32_16x16x32_bf16 v[88:91], v[220:223], v[180:183], v[88:91]
	v_mfma_f32_16x16x32_bf16 v[84:87], v[212:215], v[188:191], v[84:87]
	v_mfma_f32_16x16x32_bf16 v[80:83], v[220:223], v[188:191], v[80:83]
	v_mfma_f32_16x16x32_bf16 v[76:79], v[212:215], v[196:199], v[76:79]
	v_mfma_f32_16x16x32_bf16 v[72:75], v[220:223], v[196:199], v[72:75]
	v_mfma_f32_16x16x32_bf16 v[68:71], v[212:215], v[204:207], v[68:71]
	v_mfma_f32_16x16x32_bf16 v[64:67], v[220:223], v[204:207], v[64:67]
	v_mfma_f32_16x16x32_bf16 v[92:95], v[216:219], v[184:187], v[92:95]
	v_mfma_f32_16x16x32_bf16 v[88:91], v[224:227], v[184:187], v[88:91]
	v_mfma_f32_16x16x32_bf16 v[84:87], v[216:219], v[192:195], v[84:87]
	v_mfma_f32_16x16x32_bf16 v[80:83], v[224:227], v[192:195], v[80:83]
	v_mfma_f32_16x16x32_bf16 v[76:79], v[216:219], v[200:203], v[76:79]
	v_mfma_f32_16x16x32_bf16 v[72:75], v[224:227], v[200:203], v[72:75]
	v_mfma_f32_16x16x32_bf16 v[68:71], v[216:219], v[208:211], v[68:71]
	v_mfma_f32_16x16x32_bf16 v[64:67], v[224:227], v[208:211], v[64:67]
	s_setprio 0
	s_mov_b64 s[66:67], 0xe000100
	v_readfirstlane_b32 s65, v135
	v_lshl_add_u64 v[232:233], v[228:229], 0, s[66:67]
	s_mov_b32 m0, s65
	s_mov_b64 s[66:67], 0xe040100
	v_readfirstlane_b32 s65, v147
	s_barrier
	ds_read_b128 v[180:183], v153 offset:16384
	ds_read_b128 v[184:187], v153 offset:17408
	ds_read_b128 v[188:191], v152 offset:16384
	ds_read_b128 v[192:195], v152 offset:17408
	ds_read_b128 v[196:199], v151 offset:16384
	ds_read_b128 v[200:203], v151 offset:17408
	ds_read_b128 v[204:207], v150 offset:16384
	ds_read_b128 v[208:211], v150 offset:17408
	global_load_lds_dwordx4 v[232:233], off
	v_lshl_add_u64 v[232:233], v[228:229], 0, s[66:67]
	s_mov_b32 m0, s65
	s_nop 0
	global_load_lds_dwordx4 v[232:233], off
	s_barrier
	s_waitcnt lgkmcnt(0)
	s_setprio 1
	s_waitcnt lgkmcnt(0)
	v_mfma_f32_16x16x32_bf16 v[60:63], v[164:167], v[180:183], v[60:63]
	v_mfma_f32_16x16x32_bf16 v[56:59], v[172:175], v[180:183], v[56:59]
	v_mfma_f32_16x16x32_bf16 v[52:55], v[164:167], v[188:191], v[52:55]
	v_mfma_f32_16x16x32_bf16 v[48:51], v[172:175], v[188:191], v[48:51]
	v_mfma_f32_16x16x32_bf16 v[44:47], v[164:167], v[196:199], v[44:47]
	v_mfma_f32_16x16x32_bf16 v[40:43], v[172:175], v[196:199], v[40:43]
	v_mfma_f32_16x16x32_bf16 v[36:39], v[164:167], v[204:207], v[36:39]
	v_mfma_f32_16x16x32_bf16 v[32:35], v[172:175], v[204:207], v[32:35]
	v_mfma_f32_16x16x32_bf16 v[60:63], v[168:171], v[184:187], v[60:63]
	v_mfma_f32_16x16x32_bf16 v[56:59], v[176:179], v[184:187], v[56:59]
	v_mfma_f32_16x16x32_bf16 v[52:55], v[168:171], v[192:195], v[52:55]
	v_mfma_f32_16x16x32_bf16 v[48:51], v[176:179], v[192:195], v[48:51]
	v_mfma_f32_16x16x32_bf16 v[44:47], v[168:171], v[200:203], v[44:47]
	v_mfma_f32_16x16x32_bf16 v[40:43], v[176:179], v[200:203], v[40:43]
	v_mfma_f32_16x16x32_bf16 v[36:39], v[168:171], v[208:211], v[36:39]
	v_mfma_f32_16x16x32_bf16 v[32:35], v[176:179], v[208:211], v[32:35]
	s_setprio 0
	s_barrier
	s_mov_b64 s[66:67], 0x1882000
	v_readfirstlane_b32 s65, v146
	v_lshl_add_u64 v[164:165], v[230:231], 0, s[66:67]
	s_mov_b32 m0, s65
	s_mov_b64 s[66:67], 0x1883000
	v_readfirstlane_b32 s65, v145
	global_load_lds_dwordx4 v[164:165], off
	v_lshl_add_u64 v[164:165], v[230:231], 0, s[66:67]
	s_mov_b32 m0, s65
	s_nop 0
	global_load_lds_dwordx4 v[164:165], off
	s_waitcnt vmcnt(6)
	s_barrier
	s_setprio 1
	v_mfma_f32_16x16x32_bf16 v[28:31], v[212:215], v[180:183], v[28:31]
	v_mfma_f32_16x16x32_bf16 v[24:27], v[220:223], v[180:183], v[24:27]
	v_mfma_f32_16x16x32_bf16 v[20:23], v[212:215], v[188:191], v[20:23]
	v_mfma_f32_16x16x32_bf16 v[16:19], v[220:223], v[188:191], v[16:19]
	v_mfma_f32_16x16x32_bf16 v[12:15], v[212:215], v[196:199], v[12:15]
	v_mfma_f32_16x16x32_bf16 v[8:11], v[220:223], v[196:199], v[8:11]
	v_mfma_f32_16x16x32_bf16 v[4:7], v[212:215], v[204:207], v[4:7]
	v_mfma_f32_16x16x32_bf16 v[0:3], v[220:223], v[204:207], v[0:3]
	v_mfma_f32_16x16x32_bf16 v[28:31], v[216:219], v[184:187], v[28:31]
	v_mfma_f32_16x16x32_bf16 v[24:27], v[224:227], v[184:187], v[24:27]
	v_mfma_f32_16x16x32_bf16 v[20:23], v[216:219], v[192:195], v[20:23]
	v_mfma_f32_16x16x32_bf16 v[16:19], v[224:227], v[192:195], v[16:19]
	v_mfma_f32_16x16x32_bf16 v[12:15], v[216:219], v[200:203], v[12:15]
	v_mfma_f32_16x16x32_bf16 v[8:11], v[224:227], v[200:203], v[8:11]
	v_mfma_f32_16x16x32_bf16 v[4:7], v[216:219], v[208:211], v[4:7]
	v_mfma_f32_16x16x32_bf16 v[0:3], v[224:227], v[208:211], v[0:3]
	s_setprio 0
	s_barrier
	ds_read_b128 v[164:167], v155
	ds_read_b128 v[168:171], v155 offset:1024
	ds_read_b128 v[172:175], v155 offset:2048
	ds_read_b128 v[176:179], v155 offset:3072
	v_readfirstlane_b32 s65, v144
	v_lshl_add_u64 v[212:213], v[228:229], 0, s[26:27]
	s_mov_b32 m0, s65
	v_readfirstlane_b32 s65, v143
	ds_read_b128 v[180:183], v153 offset:32768
	ds_read_b128 v[184:187], v153 offset:33792
	ds_read_b128 v[188:191], v152 offset:32768
	ds_read_b128 v[192:195], v152 offset:33792
	ds_read_b128 v[196:199], v151 offset:32768
	ds_read_b128 v[200:203], v151 offset:33792
	ds_read_b128 v[204:207], v150 offset:32768
	ds_read_b128 v[208:211], v150 offset:33792
	global_load_lds_dwordx4 v[212:213], off
	v_lshl_add_u64 v[212:213], v[228:229], 0, s[28:29]
	s_mov_b32 m0, s65
	s_nop 0
	global_load_lds_dwordx4 v[212:213], off
	s_waitcnt lgkmcnt(8)
	s_barrier
	s_waitcnt lgkmcnt(0)
	s_setprio 1
	s_waitcnt lgkmcnt(0)
	v_mfma_f32_16x16x32_bf16 v[124:127], v[164:167], v[180:183], v[124:127]
	v_mfma_f32_16x16x32_bf16 v[120:123], v[172:175], v[180:183], v[120:123]
	v_mfma_f32_16x16x32_bf16 v[116:119], v[164:167], v[188:191], v[116:119]
	v_mfma_f32_16x16x32_bf16 v[112:115], v[172:175], v[188:191], v[112:115]
	v_mfma_f32_16x16x32_bf16 v[108:111], v[164:167], v[196:199], v[108:111]
	v_mfma_f32_16x16x32_bf16 v[104:107], v[172:175], v[196:199], v[104:107]
	v_mfma_f32_16x16x32_bf16 v[100:103], v[164:167], v[204:207], v[100:103]
	v_mfma_f32_16x16x32_bf16 v[96:99], v[172:175], v[204:207], v[96:99]
	v_mfma_f32_16x16x32_bf16 v[124:127], v[168:171], v[184:187], v[124:127]
	v_mfma_f32_16x16x32_bf16 v[120:123], v[176:179], v[184:187], v[120:123]
	v_mfma_f32_16x16x32_bf16 v[116:119], v[168:171], v[192:195], v[116:119]
	v_mfma_f32_16x16x32_bf16 v[112:115], v[176:179], v[192:195], v[112:115]
	v_mfma_f32_16x16x32_bf16 v[108:111], v[168:171], v[200:203], v[108:111]
	v_mfma_f32_16x16x32_bf16 v[104:107], v[176:179], v[200:203], v[104:107]
	v_mfma_f32_16x16x32_bf16 v[100:103], v[168:171], v[208:211], v[100:103]
	v_mfma_f32_16x16x32_bf16 v[96:99], v[176:179], v[208:211], v[96:99]
	s_setprio 0
	s_barrier
	v_readfirstlane_b32 s65, v142
	v_lshl_add_u64 v[232:233], v[230:231], 0, s[30:31]
	s_mov_b32 m0, s65
	v_readfirstlane_b32 s65, v141
	ds_read_b128 v[212:215], v154
	ds_read_b128 v[216:219], v154 offset:1024
	ds_read_b128 v[220:223], v154 offset:2048
	ds_read_b128 v[224:227], v154 offset:3072
	global_load_lds_dwordx4 v[232:233], off
	v_lshl_add_u64 v[232:233], v[230:231], 0, s[34:35]
	s_mov_b32 m0, s65
	s_nop 0
	global_load_lds_dwordx4 v[232:233], off
	s_barrier
	s_waitcnt lgkmcnt(0)
	s_setprio 1
	s_waitcnt lgkmcnt(0)
	v_mfma_f32_16x16x32_bf16 v[92:95], v[212:215], v[180:183], v[92:95]
	v_mfma_f32_16x16x32_bf16 v[88:91], v[220:223], v[180:183], v[88:91]
	v_mfma_f32_16x16x32_bf16 v[84:87], v[212:215], v[188:191], v[84:87]
	v_mfma_f32_16x16x32_bf16 v[80:83], v[220:223], v[188:191], v[80:83]
	v_mfma_f32_16x16x32_bf16 v[76:79], v[212:215], v[196:199], v[76:79]
	v_mfma_f32_16x16x32_bf16 v[72:75], v[220:223], v[196:199], v[72:75]
	v_mfma_f32_16x16x32_bf16 v[68:71], v[212:215], v[204:207], v[68:71]
	v_mfma_f32_16x16x32_bf16 v[64:67], v[220:223], v[204:207], v[64:67]
	v_mfma_f32_16x16x32_bf16 v[92:95], v[216:219], v[184:187], v[92:95]
	v_mfma_f32_16x16x32_bf16 v[88:91], v[224:227], v[184:187], v[88:91]
	v_mfma_f32_16x16x32_bf16 v[84:87], v[216:219], v[192:195], v[84:87]
	v_mfma_f32_16x16x32_bf16 v[80:83], v[224:227], v[192:195], v[80:83]
	v_mfma_f32_16x16x32_bf16 v[76:79], v[216:219], v[200:203], v[76:79]
	v_mfma_f32_16x16x32_bf16 v[72:75], v[224:227], v[200:203], v[72:75]
	v_mfma_f32_16x16x32_bf16 v[68:71], v[216:219], v[208:211], v[68:71]
	v_mfma_f32_16x16x32_bf16 v[64:67], v[224:227], v[208:211], v[64:67]
	s_setprio 0
	v_readfirstlane_b32 s65, v140
	v_lshl_add_u64 v[232:233], v[228:229], 0, s[40:41]
	s_mov_b32 m0, s65
	v_readfirstlane_b32 s65, v139
	s_barrier
	ds_read_b128 v[180:183], v153 offset:49152
	ds_read_b128 v[184:187], v153 offset:50176
	ds_read_b128 v[188:191], v152 offset:49152
	ds_read_b128 v[192:195], v152 offset:50176
	ds_read_b128 v[196:199], v151 offset:49152
	ds_read_b128 v[200:203], v151 offset:50176
	ds_read_b128 v[204:207], v150 offset:49152
	ds_read_b128 v[208:211], v150 offset:50176
	global_load_lds_dwordx4 v[232:233], off
	v_lshl_add_u64 v[228:229], v[228:229], 0, s[44:45]
	s_mov_b32 m0, s65
	s_nop 0
	global_load_lds_dwordx4 v[228:229], off
	s_barrier
	s_waitcnt lgkmcnt(0)
	s_setprio 1
	s_waitcnt lgkmcnt(0)
	v_mfma_f32_16x16x32_bf16 v[60:63], v[164:167], v[180:183], v[60:63]
	v_mfma_f32_16x16x32_bf16 v[56:59], v[172:175], v[180:183], v[56:59]
	v_mfma_f32_16x16x32_bf16 v[52:55], v[164:167], v[188:191], v[52:55]
	v_mfma_f32_16x16x32_bf16 v[48:51], v[172:175], v[188:191], v[48:51]
	v_mfma_f32_16x16x32_bf16 v[44:47], v[164:167], v[196:199], v[44:47]
	v_mfma_f32_16x16x32_bf16 v[40:43], v[172:175], v[196:199], v[40:43]
	v_mfma_f32_16x16x32_bf16 v[36:39], v[164:167], v[204:207], v[36:39]
	v_mfma_f32_16x16x32_bf16 v[32:35], v[172:175], v[204:207], v[32:35]
	v_mfma_f32_16x16x32_bf16 v[60:63], v[168:171], v[184:187], v[60:63]
	v_mfma_f32_16x16x32_bf16 v[56:59], v[176:179], v[184:187], v[56:59]
	v_mfma_f32_16x16x32_bf16 v[52:55], v[168:171], v[192:195], v[52:55]
	v_mfma_f32_16x16x32_bf16 v[48:51], v[176:179], v[192:195], v[48:51]
	v_mfma_f32_16x16x32_bf16 v[44:47], v[168:171], v[200:203], v[44:47]
	v_mfma_f32_16x16x32_bf16 v[40:43], v[176:179], v[200:203], v[40:43]
	v_mfma_f32_16x16x32_bf16 v[36:39], v[168:171], v[208:211], v[36:39]
	v_mfma_f32_16x16x32_bf16 v[32:35], v[176:179], v[208:211], v[32:35]
	s_setprio 0
	s_barrier
	v_readfirstlane_b32 s65, v138
	v_lshl_add_u64 v[164:165], v[230:231], 0, s[46:47]
	s_mov_b32 m0, s65
	v_readfirstlane_b32 s65, v137
	global_load_lds_dwordx4 v[164:165], off
	v_lshl_add_u64 v[164:165], v[230:231], 0, s[56:57]
	s_mov_b32 m0, s65
	s_nop 0
	global_load_lds_dwordx4 v[164:165], off
	s_waitcnt vmcnt(6)
	s_barrier
	s_setprio 1
	v_mfma_f32_16x16x32_bf16 v[28:31], v[212:215], v[180:183], v[28:31]
	v_mfma_f32_16x16x32_bf16 v[24:27], v[220:223], v[180:183], v[24:27]
	v_mfma_f32_16x16x32_bf16 v[20:23], v[212:215], v[188:191], v[20:23]
	v_mfma_f32_16x16x32_bf16 v[16:19], v[220:223], v[188:191], v[16:19]
	v_mfma_f32_16x16x32_bf16 v[12:15], v[212:215], v[196:199], v[12:15]
	v_mfma_f32_16x16x32_bf16 v[8:11], v[220:223], v[196:199], v[8:11]
	v_mfma_f32_16x16x32_bf16 v[4:7], v[212:215], v[204:207], v[4:7]
	v_mfma_f32_16x16x32_bf16 v[0:3], v[220:223], v[204:207], v[0:3]
	v_mfma_f32_16x16x32_bf16 v[28:31], v[216:219], v[184:187], v[28:31]
	v_mfma_f32_16x16x32_bf16 v[24:27], v[224:227], v[184:187], v[24:27]
	v_mfma_f32_16x16x32_bf16 v[20:23], v[216:219], v[192:195], v[20:23]
	v_mfma_f32_16x16x32_bf16 v[16:19], v[224:227], v[192:195], v[16:19]
	v_mfma_f32_16x16x32_bf16 v[12:15], v[216:219], v[200:203], v[12:15]
	v_mfma_f32_16x16x32_bf16 v[8:11], v[224:227], v[200:203], v[8:11]
	v_mfma_f32_16x16x32_bf16 v[4:7], v[216:219], v[208:211], v[4:7]
	v_mfma_f32_16x16x32_bf16 v[0:3], v[224:227], v[208:211], v[0:3]
	s_setprio 0
	s_add_i32 s24, s24, 2
	v_lshl_add_u64 v[130:131], v[130:131], 0, s[10:11]
	s_cmp_lt_u32 s24, 28
	v_lshl_add_u64 v[132:133], v[132:133], 0, s[58:59]
	s_barrier
	s_cbranch_scc1 .LBB0_178
	s_lshl_b32 s24, s85, 5
	s_lshl_b32 s65, s85, 8
	s_and_b32 s24, s24, 0x1800
	s_and_b32 s65, s65, 0x700
	s_or_b32 s24, s65, s24
	v_lshlrev_b32_e32 v128, 3, v156
	v_lshlrev_b32_e32 v130, 5, v156
	v_and_b32_e32 v128, 0xffff0, v128
	v_and_b32_e32 v130, 32, v130
	s_lshl_b32 s65, s24, 12
	v_add_u32_e32 v130, v130, v158
	v_add_lshl_u32 v128, v157, v128, 12
	s_add_u32 s66, s68, s65
	v_lshl_add_u32 v128, v130, 1, v128
	s_addc_u32 s67, s69, 0
	v_lshl_add_u64 v[156:157], s[66:67], 0, v[128:129]
	v_readfirstlane_b32 s65, v161
	ds_read_b128 v[130:133], v162
	ds_read_b128 v[164:167], v162 offset:1024
	ds_read_b128 v[168:171], v162 offset:2048
	ds_read_b128 v[172:175], v162 offset:3072
	ds_read_b128 v[176:179], v153
	ds_read_b128 v[180:183], v153 offset:1024
	ds_read_b128 v[184:187], v152
	ds_read_b128 v[188:191], v152 offset:1024
	ds_read_b128 v[192:195], v151
	ds_read_b128 v[196:199], v151 offset:1024
	ds_read_b128 v[200:203], v150
	ds_read_b128 v[204:207], v150 offset:1024
	v_lshl_add_u64 v[162:163], v[156:157], 0, s[60:61]
	s_mov_b32 m0, s65
	v_readfirstlane_b32 s65, v160
	global_load_lds_dwordx4 v[162:163], off
	v_lshl_add_u64 v[156:157], v[156:157], 0, s[62:63]
	s_mov_b32 m0, s65
	s_nop 0
	global_load_lds_dwordx4 v[156:157], off
	s_barrier
	s_waitcnt lgkmcnt(0)
	s_setprio 1
	s_waitcnt lgkmcnt(0)
	v_mfma_f32_16x16x32_bf16 v[124:127], v[130:133], v[176:179], v[124:127]
	v_mfma_f32_16x16x32_bf16 v[120:123], v[168:171], v[176:179], v[120:123]
	v_mfma_f32_16x16x32_bf16 v[116:119], v[130:133], v[184:187], v[116:119]
	v_mfma_f32_16x16x32_bf16 v[112:115], v[168:171], v[184:187], v[112:115]
	v_mfma_f32_16x16x32_bf16 v[108:111], v[130:133], v[192:195], v[108:111]
	v_mfma_f32_16x16x32_bf16 v[104:107], v[168:171], v[192:195], v[104:107]
	v_mfma_f32_16x16x32_bf16 v[100:103], v[130:133], v[200:203], v[100:103]
	v_mfma_f32_16x16x32_bf16 v[96:99], v[168:171], v[200:203], v[96:99]
	v_mfma_f32_16x16x32_bf16 v[124:127], v[164:167], v[180:183], v[124:127]
	v_mfma_f32_16x16x32_bf16 v[120:123], v[172:175], v[180:183], v[120:123]
	v_mfma_f32_16x16x32_bf16 v[116:119], v[164:167], v[188:191], v[116:119]
	v_mfma_f32_16x16x32_bf16 v[112:115], v[172:175], v[188:191], v[112:115]
	v_mfma_f32_16x16x32_bf16 v[108:111], v[164:167], v[196:199], v[108:111]
	v_mfma_f32_16x16x32_bf16 v[104:107], v[172:175], v[196:199], v[104:107]
	v_mfma_f32_16x16x32_bf16 v[100:103], v[164:167], v[204:207], v[100:103]
	v_mfma_f32_16x16x32_bf16 v[96:99], v[172:175], v[204:207], v[96:99]
	s_setprio 0
	s_barrier
	ds_read_b128 v[160:163], v159
	ds_read_b128 v[208:211], v159 offset:1024
	ds_read_b128 v[212:215], v159 offset:2048
	ds_read_b128 v[156:159], v159 offset:3072
	s_barrier
	s_waitcnt lgkmcnt(0)
	s_setprio 1
	s_waitcnt lgkmcnt(0)
	v_mfma_f32_16x16x32_bf16 v[92:95], v[160:163], v[176:179], v[92:95]
	v_mfma_f32_16x16x32_bf16 v[88:91], v[212:215], v[176:179], v[88:91]
	v_mfma_f32_16x16x32_bf16 v[84:87], v[160:163], v[184:187], v[84:87]
	v_mfma_f32_16x16x32_bf16 v[80:83], v[212:215], v[184:187], v[80:83]
	v_mfma_f32_16x16x32_bf16 v[76:79], v[160:163], v[192:195], v[76:79]
	v_mfma_f32_16x16x32_bf16 v[72:75], v[212:215], v[192:195], v[72:75]
	v_mfma_f32_16x16x32_bf16 v[68:71], v[160:163], v[200:203], v[68:71]
	v_mfma_f32_16x16x32_bf16 v[64:67], v[212:215], v[200:203], v[64:67]
	v_mfma_f32_16x16x32_bf16 v[176:179], v[208:211], v[180:183], v[92:95]
	v_mfma_f32_16x16x32_bf16 v[180:183], v[156:159], v[180:183], v[88:91]
	v_mfma_f32_16x16x32_bf16 v[184:187], v[208:211], v[188:191], v[84:87]
	v_mfma_f32_16x16x32_bf16 v[188:191], v[156:159], v[188:191], v[80:83]
	v_mfma_f32_16x16x32_bf16 v[192:195], v[208:211], v[196:199], v[76:79]
	v_mfma_f32_16x16x32_bf16 v[196:199], v[156:159], v[196:199], v[72:75]
	v_mfma_f32_16x16x32_bf16 v[200:203], v[208:211], v[204:207], v[68:71]
	v_mfma_f32_16x16x32_bf16 v[204:207], v[156:159], v[204:207], v[64:67]
	s_setprio 0
	s_barrier
	s_nop 0
	ds_read_b128 v[64:67], v153 offset:16384
	ds_read_b128 v[68:71], v153 offset:17408
	ds_read_b128 v[72:75], v152 offset:16384
	ds_read_b128 v[76:79], v152 offset:17408
	ds_read_b128 v[80:83], v151 offset:16384
	ds_read_b128 v[84:87], v151 offset:17408
	ds_read_b128 v[88:91], v150 offset:16384
	ds_read_b128 v[92:95], v150 offset:17408
	s_waitcnt vmcnt(4)
	s_barrier
	s_waitcnt lgkmcnt(0)
	s_setprio 1
	s_waitcnt lgkmcnt(0)
	v_mfma_f32_16x16x32_bf16 v[60:63], v[130:133], v[64:67], v[60:63]
	v_mfma_f32_16x16x32_bf16 v[56:59], v[168:171], v[64:67], v[56:59]
	v_mfma_f32_16x16x32_bf16 v[52:55], v[130:133], v[72:75], v[52:55]
	v_mfma_f32_16x16x32_bf16 v[48:51], v[168:171], v[72:75], v[48:51]
	v_mfma_f32_16x16x32_bf16 v[216:219], v[130:133], v[80:83], v[44:47]
	v_mfma_f32_16x16x32_bf16 v[220:223], v[168:171], v[80:83], v[40:43]
	v_mfma_f32_16x16x32_bf16 v[130:133], v[130:133], v[88:91], v[36:39]
	v_mfma_f32_16x16x32_bf16 v[168:171], v[168:171], v[88:91], v[32:35]
	v_mfma_f32_16x16x32_bf16 v[32:35], v[164:167], v[68:71], v[60:63]
	v_mfma_f32_16x16x32_bf16 v[36:39], v[172:175], v[68:71], v[56:59]
	v_mfma_f32_16x16x32_bf16 v[40:43], v[164:167], v[76:79], v[52:55]
	v_mfma_f32_16x16x32_bf16 v[44:47], v[172:175], v[76:79], v[48:51]
	v_mfma_f32_16x16x32_bf16 v[48:51], v[164:167], v[84:87], v[216:219]
	v_mfma_f32_16x16x32_bf16 v[52:55], v[172:175], v[84:87], v[220:223]
	v_mfma_f32_16x16x32_bf16 v[56:59], v[164:167], v[92:95], v[130:133]
	v_mfma_f32_16x16x32_bf16 v[60:63], v[172:175], v[92:95], v[168:171]
	s_setprio 0
	s_setprio 1
	v_mfma_f32_16x16x32_bf16 v[28:31], v[160:163], v[64:67], v[28:31]
	v_mfma_f32_16x16x32_bf16 v[24:27], v[212:215], v[64:67], v[24:27]
	v_mfma_f32_16x16x32_bf16 v[20:23], v[160:163], v[72:75], v[20:23]
	v_mfma_f32_16x16x32_bf16 v[64:67], v[212:215], v[72:75], v[16:19]
	v_mfma_f32_16x16x32_bf16 v[72:75], v[160:163], v[80:83], v[12:15]
	v_mfma_f32_16x16x32_bf16 v[8:11], v[212:215], v[80:83], v[8:11]
	v_mfma_f32_16x16x32_bf16 v[80:83], v[160:163], v[88:91], v[4:7]
	v_mfma_f32_16x16x32_bf16 v[0:3], v[212:215], v[88:91], v[0:3]
	v_mfma_f32_16x16x32_bf16 v[4:7], v[208:211], v[68:71], v[28:31]
	v_mfma_f32_16x16x32_bf16 v[12:15], v[156:159], v[68:71], v[24:27]
	v_mfma_f32_16x16x32_bf16 v[16:19], v[208:211], v[76:79], v[20:23]
	v_mfma_f32_16x16x32_bf16 v[20:23], v[156:159], v[76:79], v[64:67]
	v_mfma_f32_16x16x32_bf16 v[24:27], v[208:211], v[84:87], v[72:75]
	v_mfma_f32_16x16x32_bf16 v[28:31], v[156:159], v[84:87], v[8:11]
	v_mfma_f32_16x16x32_bf16 v[64:67], v[208:211], v[92:95], v[80:83]
	v_mfma_f32_16x16x32_bf16 v[68:71], v[156:159], v[92:95], v[0:3]
	s_setprio 0
	s_barrier
	ds_read_b128 v[8:11], v155
	ds_read_b128 v[0:3], v155 offset:1024
	ds_read_b128 v[76:79], v155 offset:2048
	ds_read_b128 v[72:75], v155 offset:3072
	ds_read_b128 v[130:133], v153 offset:32768
	ds_read_b128 v[156:159], v153 offset:33792
	ds_read_b128 v[160:163], v152 offset:32768
	ds_read_b128 v[164:167], v152 offset:33792
	ds_read_b128 v[168:171], v151 offset:32768
	ds_read_b128 v[172:175], v151 offset:33792
	ds_read_b128 v[208:211], v150 offset:32768
	ds_read_b128 v[212:215], v150 offset:33792
	s_waitcnt vmcnt(2)
	s_barrier
	s_waitcnt lgkmcnt(0)
	s_setprio 1
	s_waitcnt lgkmcnt(0)
	v_mfma_f32_16x16x32_bf16 v[80:83], v[8:11], v[130:133], v[124:127]
	v_mfma_f32_16x16x32_bf16 v[84:87], v[76:79], v[130:133], v[120:123]
	v_mfma_f32_16x16x32_bf16 v[88:91], v[8:11], v[160:163], v[116:119]
	v_mfma_f32_16x16x32_bf16 v[92:95], v[76:79], v[160:163], v[112:115]
	v_mfma_f32_16x16x32_bf16 v[108:111], v[8:11], v[168:171], v[108:111]
	v_mfma_f32_16x16x32_bf16 v[104:107], v[76:79], v[168:171], v[104:107]
	v_mfma_f32_16x16x32_bf16 v[100:103], v[8:11], v[208:211], v[100:103]
	v_mfma_f32_16x16x32_bf16 v[96:99], v[76:79], v[208:211], v[96:99]
	v_mfma_f32_16x16x32_bf16 v[112:115], v[0:3], v[156:159], v[80:83]
	v_mfma_f32_16x16x32_bf16 v[116:119], v[72:75], v[156:159], v[84:87]
	v_mfma_f32_16x16x32_bf16 v[120:123], v[0:3], v[164:167], v[88:91]
	v_mfma_f32_16x16x32_bf16 v[124:127], v[72:75], v[164:167], v[92:95]
	v_mfma_f32_16x16x32_bf16 v[108:111], v[0:3], v[172:175], v[108:111]
	v_mfma_f32_16x16x32_bf16 v[104:107], v[72:75], v[172:175], v[104:107]
	v_mfma_f32_16x16x32_bf16 v[100:103], v[0:3], v[212:215], v[100:103]
	v_mfma_f32_16x16x32_bf16 v[96:99], v[72:75], v[212:215], v[96:99]
	s_setprio 0
	s_barrier
	ds_read_b128 v[88:91], v154
	ds_read_b128 v[80:83], v154 offset:1024
	ds_read_b128 v[92:95], v154 offset:2048
	ds_read_b128 v[84:87], v154 offset:3072
	s_waitcnt vmcnt(0)
	s_barrier
	s_waitcnt lgkmcnt(0)
	s_setprio 1
	s_waitcnt lgkmcnt(0)
	v_mfma_f32_16x16x32_bf16 v[176:179], v[88:91], v[130:133], v[176:179]
	v_mfma_f32_16x16x32_bf16 v[130:133], v[92:95], v[130:133], v[180:183]
	v_mfma_f32_16x16x32_bf16 v[180:183], v[88:91], v[160:163], v[184:187]
	v_mfma_f32_16x16x32_bf16 v[160:163], v[92:95], v[160:163], v[188:191]
	v_mfma_f32_16x16x32_bf16 v[184:187], v[88:91], v[168:171], v[192:195]
	v_mfma_f32_16x16x32_bf16 v[168:171], v[92:95], v[168:171], v[196:199]
	v_mfma_f32_16x16x32_bf16 v[188:191], v[88:91], v[208:211], v[200:203]
	v_mfma_f32_16x16x32_bf16 v[192:195], v[92:95], v[208:211], v[204:207]
	v_mfma_f32_16x16x32_bf16 v[176:179], v[80:83], v[156:159], v[176:179]
	v_mfma_f32_16x16x32_bf16 v[130:133], v[84:87], v[156:159], v[130:133]
	v_mfma_f32_16x16x32_bf16 v[154:157], v[80:83], v[164:167], v[180:183]
	v_mfma_f32_16x16x32_bf16 v[158:161], v[84:87], v[164:167], v[160:163]
	v_mfma_f32_16x16x32_bf16 v[162:165], v[80:83], v[172:175], v[184:187]
	v_mfma_f32_16x16x32_bf16 v[166:169], v[84:87], v[172:175], v[168:171]
	v_mfma_f32_16x16x32_bf16 v[170:173], v[80:83], v[212:215], v[188:191]
	v_mfma_f32_16x16x32_bf16 v[180:183], v[84:87], v[212:215], v[192:195]
	s_setprio 0
	s_barrier
	v_mbcnt_lo_u32_b32 v128, -1, 0
	v_mbcnt_hi_u32_b32 v128, -1, v128
	v_cvt_pk_bf16_f32 v112, v112, v113
	v_cvt_pk_bf16_f32 v113, v114, v115
	v_cvt_pk_bf16_f32 v114, v116, v117
	v_cvt_pk_bf16_f32 v115, v118, v119
	s_lshl_b32 s66, s64, 9
	v_add_u32_e32 v174, s72, v128
	v_ashrrev_i32_e32 v175, 6, v174
	v_and_b32_e32 v184, 15, v128
	v_and_b32_e32 v185, 48, v128
	v_mul_lo_u32 v186, v175, s77
	v_bfe_u32 v187, v128, 3, 3
	v_lshlrev_b32_e32 v128, 4, v128
	v_add_u32_e32 v186, 0x20000, v186
	v_lshrrev_b32_e32 v174, 2, v174
	v_and_b32_e32 v128, 0x70, v128
	v_mul_u32_u24_e32 v184, 0x90, v184
	v_and_b32_e32 v174, 64, v174
	v_add3_u32 v184, v186, v184, v185
	v_or_b32_e32 v185, v186, v128
	v_or3_b32 v174, s24, v174, v187
	v_mad_u32_u24 v185, v187, s78, v185
	ds_write_b128 v184, v[112:115]
	v_cvt_pk_bf16_f32 v112, v176, v177
	v_cvt_pk_bf16_f32 v113, v178, v179
	v_cvt_pk_bf16_f32 v114, v130, v131
	v_cvt_pk_bf16_f32 v115, v132, v133
	ds_write_b128 v184, v[112:115] offset:64
	v_lshlrev_b32_e32 v175, 7, v175
	ds_read_b128 v[112:115], v185
	v_lshlrev_b32_e32 v116, 12, v174
	v_and_or_b32 v116, v175, s79, v116
	v_or3_b32 v128, v116, s66, v128
	ds_read_b128 v[116:119], v185 offset:1152
	v_lshl_add_u64 v[130:131], s[0:1], 0, v[128:129]
	s_mov_b32 s64, 0x8000
	s_waitcnt lgkmcnt(0)
	global_store_dwordx4 v128, v[112:115], s[0:1] sc0 sc1
	v_cvt_pk_bf16_f32 v108, v108, v109
	v_cvt_pk_bf16_f32 v109, v110, v111
	v_cvt_pk_bf16_f32 v110, v104, v105
	v_cvt_pk_bf16_f32 v111, v106, v107
	v_cvt_pk_bf16_f32 v104, v162, v163
	s_nop 1
	v_add_co_u32_e32 v112, vcc, s64, v130
	v_cvt_pk_bf16_f32 v114, v124, v125
	v_cvt_pk_bf16_f32 v115, v126, v127
	v_cvt_pk_bf16_f32 v105, v164, v165
	v_cvt_pk_bf16_f32 v106, v166, v167
	s_nop 1
	v_addc_co_u32_e32 v113, vcc, 0, v131, vcc
	global_store_dwordx4 v[112:113], v[116:119], off sc0 sc1
	v_cvt_pk_bf16_f32 v112, v120, v121
	v_cvt_pk_bf16_f32 v113, v122, v123
	ds_write_b128 v184, v[112:115]
	v_cvt_pk_bf16_f32 v112, v154, v155
	v_cvt_pk_bf16_f32 v113, v156, v157
	v_cvt_pk_bf16_f32 v114, v158, v159
	v_cvt_pk_bf16_f32 v115, v160, v161
	ds_write_b128 v184, v[112:115] offset:64
	ds_read_b128 v[112:115], v185
	ds_read_b128 v[116:119], v185 offset:1152
	v_add_co_u32_e32 v120, vcc, s74, v130
	ds_write_b128 v184, v[108:111]
	v_cvt_pk_bf16_f32 v107, v168, v169
	ds_write_b128 v184, v[104:107] offset:64
	v_addc_co_u32_e32 v121, vcc, 0, v131, vcc
	ds_read_b128 v[104:107], v185
	ds_read_b128 v[108:111], v185 offset:1152
	s_waitcnt lgkmcnt(0)
	global_store_dwordx4 v[120:121], v[112:115], off sc0 sc1
	v_cvt_pk_bf16_f32 v100, v100, v101
	v_cvt_pk_bf16_f32 v101, v102, v103
	v_cvt_pk_bf16_f32 v102, v96, v97
	v_cvt_pk_bf16_f32 v103, v98, v99
	ds_write_b128 v184, v[100:103]
	s_nop 0
	v_add_co_u32_e32 v112, vcc, s75, v130
	v_cvt_pk_bf16_f32 v96, v170, v171
	v_cvt_pk_bf16_f32 v97, v172, v173
	v_cvt_pk_bf16_f32 v98, v180, v181
	v_cvt_pk_bf16_f32 v99, v182, v183
	s_nop 1
	v_addc_co_u32_e32 v113, vcc, 0, v131, vcc
	global_store_dwordx4 v[112:113], v[116:119], off sc0 sc1
	v_add_co_u32_e32 v112, vcc, s76, v130
	ds_write_b128 v184, v[96:99] offset:64
	s_nop 0
	v_addc_co_u32_e32 v113, vcc, 0, v131, vcc
	ds_read_b128 v[96:99], v185
	ds_read_b128 v[100:103], v185 offset:1152
	global_store_dwordx4 v[112:113], v[104:107], off sc0 sc1
	s_nop 1
	v_add_co_u32_e32 v104, vcc, s80, v130
	s_nop 1
	v_addc_co_u32_e32 v105, vcc, 0, v131, vcc
	global_store_dwordx4 v[104:105], v[108:111], off sc0 sc1
	v_add_co_u32_e32 v104, vcc, s81, v130
	s_nop 1
	v_addc_co_u32_e32 v105, vcc, 0, v131, vcc
	s_waitcnt lgkmcnt(0)
	global_store_dwordx4 v[104:105], v[96:99], off sc0 sc1
	s_nop 1
	v_add_co_u32_e32 v96, vcc, s82, v130
	s_nop 1
	v_addc_co_u32_e32 v97, vcc, 0, v131, vcc
	global_store_dwordx4 v[96:97], v[100:103], off sc0 sc1
	ds_read_b128 v[96:99], v153 offset:49152
	ds_read_b128 v[100:103], v153 offset:50176
	ds_read_b128 v[104:107], v152 offset:49152
	ds_read_b128 v[108:111], v152 offset:50176
	ds_read_b128 v[112:115], v151 offset:49152
	ds_read_b128 v[116:119], v151 offset:50176
	ds_read_b128 v[120:123], v150 offset:49152
	ds_read_b128 v[124:127], v150 offset:50176
	s_barrier
	s_waitcnt lgkmcnt(0)
	s_setprio 1
	s_waitcnt lgkmcnt(0)
	v_mfma_f32_16x16x32_bf16 v[32:35], v[8:11], v[96:99], v[32:35]
	v_mfma_f32_16x16x32_bf16 v[36:39], v[76:79], v[96:99], v[36:39]
	v_mfma_f32_16x16x32_bf16 v[40:43], v[8:11], v[104:107], v[40:43]
	v_mfma_f32_16x16x32_bf16 v[130:133], v[76:79], v[104:107], v[44:47]
	v_mfma_f32_16x16x32_bf16 v[150:153], v[8:11], v[112:115], v[48:51]
	v_mfma_f32_16x16x32_bf16 v[52:55], v[76:79], v[112:115], v[52:55]
	v_mfma_f32_16x16x32_bf16 v[8:11], v[8:11], v[120:123], v[56:59]
	v_mfma_f32_16x16x32_bf16 v[60:63], v[76:79], v[120:123], v[60:63]
	v_mfma_f32_16x16x32_bf16 v[56:59], v[0:3], v[100:103], v[32:35]
	v_mfma_f32_16x16x32_bf16 v[48:51], v[72:75], v[100:103], v[36:39]
	v_mfma_f32_16x16x32_bf16 v[44:47], v[0:3], v[108:111], v[40:43]
	v_mfma_f32_16x16x32_bf16 v[40:43], v[72:75], v[108:111], v[130:133]
	v_mfma_f32_16x16x32_bf16 v[36:39], v[0:3], v[116:119], v[150:153]
	v_mfma_f32_16x16x32_bf16 v[32:35], v[72:75], v[116:119], v[52:55]
	v_mfma_f32_16x16x32_bf16 v[8:11], v[0:3], v[124:127], v[8:11]
	v_mfma_f32_16x16x32_bf16 v[0:3], v[72:75], v[124:127], v[60:63]
	s_setprio 0
	s_setprio 1
	v_mfma_f32_16x16x32_bf16 v[4:7], v[88:91], v[96:99], v[4:7]
	v_mfma_f32_16x16x32_bf16 v[12:15], v[92:95], v[96:99], v[12:15]
	v_mfma_f32_16x16x32_bf16 v[16:19], v[88:91], v[104:107], v[16:19]
	v_mfma_f32_16x16x32_bf16 v[20:23], v[92:95], v[104:107], v[20:23]
	v_mfma_f32_16x16x32_bf16 v[72:75], v[88:91], v[112:115], v[24:27]
	v_mfma_f32_16x16x32_bf16 v[76:79], v[92:95], v[112:115], v[28:31]
	v_mfma_f32_16x16x32_bf16 v[64:67], v[88:91], v[120:123], v[64:67]
	v_mfma_f32_16x16x32_bf16 v[68:71], v[92:95], v[120:123], v[68:71]
	v_mfma_f32_16x16x32_bf16 v[60:63], v[80:83], v[100:103], v[4:7]
	v_mfma_f32_16x16x32_bf16 v[52:55], v[84:87], v[100:103], v[12:15]
	v_mfma_f32_16x16x32_bf16 v[28:31], v[80:83], v[108:111], v[16:19]
	v_mfma_f32_16x16x32_bf16 v[24:27], v[84:87], v[108:111], v[20:23]
	v_mfma_f32_16x16x32_bf16 v[20:23], v[80:83], v[116:119], v[72:75]
	v_mfma_f32_16x16x32_bf16 v[16:19], v[84:87], v[116:119], v[76:79]
	v_mfma_f32_16x16x32_bf16 v[12:15], v[80:83], v[124:127], v[64:67]
	v_mfma_f32_16x16x32_bf16 v[4:7], v[84:87], v[124:127], v[68:71]
	s_setprio 0
	v_cmp_gt_u32_e32 vcc, s83, v136
	s_barrier
	s_and_saveexec_b64 s[64:65], vcc
	s_cbranch_execz .LBB0_181
	s_barrier

.LBB0_221:
	v_mul_lo_u32 v64, v73, s75
	v_lshlrev_b32_e32 v67, 4, v69
	v_add_u32_e32 v64, 0x20000, v64
	v_bfe_u32 v65, v69, 3, 3
	v_and_b32_e32 v67, 0x70, v67
	v_mul_u32_u24_e32 v69, 0x90, v70
	v_add3_u32 v69, v64, v69, v72
	v_lshl_or_b32 v68, v68, 6, s56
	v_or_b32_e32 v64, v64, v67
	v_or3_b32 v68, v68, v65, s72
	v_mad_u32_u24 v70, v65, s76, v64
	s_waitcnt vmcnt(0)
	v_pk_mul_f32 v[62:63], v[172:173], v[62:63] op_sel_hi:[0,1]
	v_pk_mul_f32 v[60:61], v[172:173], v[60:61] op_sel_hi:[0,1]
	v_pk_mul_f32 v[64:65], v[172:173], v[58:59] op_sel_hi:[0,1]
	v_pk_mul_f32 v[58:59], v[172:173], v[56:57] op_sel_hi:[0,1]
	v_cvt_pk_bf16_f32 v56, v60, v61
	v_cvt_pk_bf16_f32 v57, v62, v63
	v_cvt_pk_bf16_f32 v58, v58, v59
	v_cvt_pk_bf16_f32 v59, v64, v65
	ds_write_b128 v69, v[56:59]
	v_pk_mul_f32 v[56:57], v[172:173], v[50:51] op_sel_hi:[0,1]
	v_pk_mul_f32 v[50:51], v[172:173], v[48:49] op_sel_hi:[0,1]
	v_pk_mul_f32 v[54:55], v[172:173], v[54:55] op_sel_hi:[0,1]
	v_pk_mul_f32 v[52:53], v[172:173], v[52:53] op_sel_hi:[0,1]
	v_cvt_pk_bf16_f32 v48, v52, v53
	v_cvt_pk_bf16_f32 v49, v54, v55
	v_cvt_pk_bf16_f32 v50, v50, v51
	v_cvt_pk_bf16_f32 v51, v56, v57
	ds_write_b128 v69, v[48:51] offset:64
	ds_read_b128 v[48:51], v70
	v_lshlrev_b32_e32 v66, 7, v71
	s_lshl_b32 s57, s80, 9
	v_or3_b32 v52, v66, s57, v67
	v_mad_u64_u32 v[56:57], s[56:57], v68, s79, v[52:53]
	ds_read_b128 v[52:55], v70 offset:1152
	s_waitcnt lgkmcnt(0)
	global_store_dwordx4 v56, v[48:51], s[0:1] sc0 sc1
	v_pk_mul_f32 v[46:47], v[170:171], v[46:47] op_sel_hi:[0,1]
	v_pk_mul_f32 v[44:45], v[170:171], v[44:45] op_sel_hi:[0,1]
	v_pk_mul_f32 v[48:49], v[170:171], v[42:43] op_sel_hi:[0,1]
	v_pk_mul_f32 v[42:43], v[170:171], v[40:41] op_sel_hi:[0,1]
	v_cvt_pk_bf16_f32 v40, v44, v45
	v_cvt_pk_bf16_f32 v41, v46, v47
	v_cvt_pk_bf16_f32 v42, v42, v43
	v_cvt_pk_bf16_f32 v43, v48, v49
	ds_write_b128 v69, v[40:43]
	v_pk_mul_f32 v[40:41], v[170:171], v[26:27] op_sel_hi:[0,1]
	v_pk_mul_f32 v[26:27], v[170:171], v[24:25] op_sel_hi:[0,1]
	v_pk_mul_f32 v[30:31], v[170:171], v[30:31] op_sel_hi:[0,1]
	v_pk_mul_f32 v[28:29], v[170:171], v[28:29] op_sel_hi:[0,1]
	v_cvt_pk_bf16_f32 v24, v28, v29
	v_cvt_pk_bf16_f32 v25, v30, v31
	v_cvt_pk_bf16_f32 v26, v26, v27
	v_cvt_pk_bf16_f32 v27, v40, v41
	ds_write_b128 v69, v[24:27] offset:64
	ds_read_b128 v[24:27], v70
	s_lshl_b32 s56, s79, 3
	v_add_u32_e32 v28, s56, v56
	v_add_u32_e32 v40, s56, v28
	global_store_dwordx4 v28, v[52:55], s[0:1] sc0 sc1
	ds_read_b128 v[28:31], v70 offset:1152
	s_waitcnt lgkmcnt(1)
	global_store_dwordx4 v40, v[24:27], s[0:1] sc0 sc1
	v_pk_mul_f32 v[34:35], v[168:169], v[34:35] op_sel_hi:[0,1]
	v_pk_mul_f32 v[32:33], v[168:169], v[32:33] op_sel_hi:[0,1]
	v_pk_mul_f32 v[24:25], v[168:169], v[36:37] op_sel_hi:[0,1]
	v_pk_mul_f32 v[26:27], v[168:169], v[38:39] op_sel_hi:[0,1]
	v_cvt_pk_bf16_f32 v24, v24, v25
	v_cvt_pk_bf16_f32 v25, v26, v27
	v_cvt_pk_bf16_f32 v26, v32, v33
	v_cvt_pk_bf16_f32 v27, v34, v35
	ds_write_b128 v69, v[24:27]
	v_pk_mul_f32 v[24:25], v[168:169], v[18:19] op_sel_hi:[0,1]
	v_pk_mul_f32 v[18:19], v[168:169], v[16:17] op_sel_hi:[0,1]
	v_pk_mul_f32 v[22:23], v[168:169], v[22:23] op_sel_hi:[0,1]
	v_pk_mul_f32 v[20:21], v[168:169], v[20:21] op_sel_hi:[0,1]
	v_cvt_pk_bf16_f32 v16, v20, v21
	v_cvt_pk_bf16_f32 v17, v22, v23
	v_cvt_pk_bf16_f32 v18, v18, v19
	v_cvt_pk_bf16_f32 v19, v24, v25
	ds_write_b128 v69, v[16:19] offset:64
	ds_read_b128 v[16:19], v70
	v_add_u32_e32 v20, s56, v40
	v_add_u32_e32 v24, s56, v20
	s_waitcnt lgkmcnt(3)
	global_store_dwordx4 v20, v[28:31], s[0:1] sc0 sc1
	ds_read_b128 v[20:23], v70 offset:1152
	s_waitcnt lgkmcnt(1)
	global_store_dwordx4 v24, v[16:19], s[0:1] sc0 sc1
	v_pk_mul_f32 v[14:15], v[166:167], v[14:15] op_sel_hi:[0,1]
	v_pk_mul_f32 v[12:13], v[166:167], v[12:13] op_sel_hi:[0,1]
	v_pk_mul_f32 v[16:17], v[166:167], v[10:11] op_sel_hi:[0,1]
	v_pk_mul_f32 v[10:11], v[166:167], v[8:9] op_sel_hi:[0,1]
	v_cvt_pk_bf16_f32 v8, v12, v13
	v_cvt_pk_bf16_f32 v9, v14, v15
	v_cvt_pk_bf16_f32 v10, v10, v11
	v_cvt_pk_bf16_f32 v11, v16, v17
	ds_write_b128 v69, v[8:11]
	v_pk_mul_f32 v[8:9], v[166:167], v[2:3] op_sel_hi:[0,1]
	v_pk_mul_f32 v[2:3], v[166:167], v[0:1] op_sel_hi:[0,1]
	v_pk_mul_f32 v[6:7], v[166:167], v[6:7] op_sel_hi:[0,1]
	v_pk_mul_f32 v[4:5], v[166:167], v[4:5] op_sel_hi:[0,1]
	v_cvt_pk_bf16_f32 v0, v4, v5
	v_cvt_pk_bf16_f32 v1, v6, v7
	v_cvt_pk_bf16_f32 v2, v2, v3
	v_cvt_pk_bf16_f32 v3, v8, v9
	ds_write_b128 v69, v[0:3] offset:64
	ds_read_b128 v[0:3], v70
	ds_read_b128 v[64:67], v70 offset:1152
	v_add_u32_e32 v4, s56, v24
	s_waitcnt lgkmcnt(4)
	global_store_dwordx4 v4, v[20:23], s[0:1] sc0 sc1
	v_add_u32_e32 v4, s56, v4
	v_add_u32_e32 v74, s56, v4
	s_waitcnt lgkmcnt(1)
	global_store_dwordx4 v4, v[0:3], s[0:1] sc0 sc1
.LBB0_222:
	s_add_i32 s78, s78, 1
	s_mov_b64 s[56:57], 0
	s_andn2_b64 vcc, exec, s[60:61]
	s_mov_b32 s79, s86
	s_waitcnt lgkmcnt(0)
	global_store_dwordx4 v74, v[64:67], s[0:1] sc0 sc1
	s_cbranch_vccz .LBB0_248

.LBB0_234:
	ds_read_b128 v[140:143], v138
	ds_read_b128 v[144:147], v138 offset:1024
	ds_read_b128 v[148:151], v138 offset:2048
	ds_read_b128 v[152:155], v138 offset:3072
	v_readfirstlane_b32 s82, v137
	v_lshl_add_u64 v[218:219], v[128:129], 0, s[18:19]
	s_mov_b32 m0, s82
	v_readfirstlane_b32 s82, v136
	ds_read_b128 v[156:159], v193
	ds_read_b128 v[160:163], v193 offset:1024
	ds_read_b128 v[194:197], v192
	ds_read_b128 v[198:201], v192 offset:1024
	ds_read_b128 v[202:205], v191
	ds_read_b128 v[206:209], v191 offset:1024
	ds_read_b128 v[210:213], v190
	ds_read_b128 v[214:217], v190 offset:1024
	global_load_lds_dwordx4 v[218:219], off
	v_lshl_add_u64 v[218:219], v[128:129], 0, s[20:21]
	s_mov_b32 m0, s82
	s_nop 0
	global_load_lds_dwordx4 v[218:219], off
	s_waitcnt lgkmcnt(8)
	s_barrier
	s_waitcnt lgkmcnt(0)
	s_setprio 1
	s_waitcnt lgkmcnt(0)
	v_mfma_f32_16x16x32_bf16 v[124:127], v[140:143], v[156:159], v[124:127]
	v_mfma_f32_16x16x32_bf16 v[120:123], v[148:151], v[156:159], v[120:123]
	v_mfma_f32_16x16x32_bf16 v[116:119], v[140:143], v[194:197], v[116:119]
	v_mfma_f32_16x16x32_bf16 v[112:115], v[148:151], v[194:197], v[112:115]
	v_mfma_f32_16x16x32_bf16 v[108:111], v[140:143], v[202:205], v[108:111]
	v_mfma_f32_16x16x32_bf16 v[104:107], v[148:151], v[202:205], v[104:107]
	v_mfma_f32_16x16x32_bf16 v[100:103], v[140:143], v[210:213], v[100:103]
	v_mfma_f32_16x16x32_bf16 v[96:99], v[148:151], v[210:213], v[96:99]
	v_mfma_f32_16x16x32_bf16 v[124:127], v[144:147], v[160:163], v[124:127]
	v_mfma_f32_16x16x32_bf16 v[120:123], v[152:155], v[160:163], v[120:123]
	v_mfma_f32_16x16x32_bf16 v[116:119], v[144:147], v[198:201], v[116:119]
	v_mfma_f32_16x16x32_bf16 v[112:115], v[152:155], v[198:201], v[112:115]
	v_mfma_f32_16x16x32_bf16 v[108:111], v[144:147], v[206:209], v[108:111]
	v_mfma_f32_16x16x32_bf16 v[104:107], v[152:155], v[206:209], v[104:107]
	v_mfma_f32_16x16x32_bf16 v[100:103], v[144:147], v[214:217], v[100:103]
	v_mfma_f32_16x16x32_bf16 v[96:99], v[152:155], v[214:217], v[96:99]
	s_setprio 0
	s_barrier
	v_readfirstlane_b32 s82, v189
	v_lshl_add_u64 v[234:235], s[60:61], 0, v[164:165]
	s_mov_b32 m0, s82
	v_readfirstlane_b32 s82, v188
	ds_read_b128 v[218:221], v135
	ds_read_b128 v[222:225], v135 offset:1024
	ds_read_b128 v[226:229], v135 offset:2048
	ds_read_b128 v[230:233], v135 offset:3072
	global_load_lds_dwordx4 v[234:235], off
	v_lshl_add_u64 v[236:237], v[234:235], 0, s[2:3]
	s_mov_b32 m0, s82
	s_nop 0
	global_load_lds_dwordx4 v[236:237], off
	s_barrier
	s_waitcnt lgkmcnt(0)
	s_setprio 1
	s_waitcnt lgkmcnt(0)
	v_mfma_f32_16x16x32_bf16 v[92:95], v[218:221], v[156:159], v[92:95]
	v_mfma_f32_16x16x32_bf16 v[88:91], v[226:229], v[156:159], v[88:91]
	v_mfma_f32_16x16x32_bf16 v[84:87], v[218:221], v[194:197], v[84:87]
	v_mfma_f32_16x16x32_bf16 v[80:83], v[226:229], v[194:197], v[80:83]
	v_mfma_f32_16x16x32_bf16 v[76:79], v[218:221], v[202:205], v[76:79]
	v_mfma_f32_16x16x32_bf16 v[72:75], v[226:229], v[202:205], v[72:75]
	v_mfma_f32_16x16x32_bf16 v[68:71], v[218:221], v[210:213], v[68:71]
	v_mfma_f32_16x16x32_bf16 v[64:67], v[226:229], v[210:213], v[64:67]
	v_mfma_f32_16x16x32_bf16 v[92:95], v[222:225], v[160:163], v[92:95]
	v_mfma_f32_16x16x32_bf16 v[88:91], v[230:233], v[160:163], v[88:91]
	v_mfma_f32_16x16x32_bf16 v[84:87], v[222:225], v[198:201], v[84:87]
	v_mfma_f32_16x16x32_bf16 v[80:83], v[230:233], v[198:201], v[80:83]
	v_mfma_f32_16x16x32_bf16 v[76:79], v[222:225], v[206:209], v[76:79]
	v_mfma_f32_16x16x32_bf16 v[72:75], v[230:233], v[206:209], v[72:75]
	v_mfma_f32_16x16x32_bf16 v[68:71], v[222:225], v[214:217], v[68:71]
	v_mfma_f32_16x16x32_bf16 v[64:67], v[230:233], v[214:217], v[64:67]
	s_setprio 0
	v_readfirstlane_b32 s82, v169
	v_lshl_add_u64 v[236:237], v[128:129], 0, s[22:23]
	s_mov_b32 m0, s82
	v_readfirstlane_b32 s82, v187
	s_barrier
	ds_read_b128 v[156:159], v193 offset:16384
	ds_read_b128 v[160:163], v193 offset:17408
	ds_read_b128 v[194:197], v192 offset:16384
	ds_read_b128 v[198:201], v192 offset:17408
	ds_read_b128 v[202:205], v191 offset:16384
	ds_read_b128 v[206:209], v191 offset:17408
	ds_read_b128 v[210:213], v190 offset:16384
	ds_read_b128 v[214:217], v190 offset:17408
	global_load_lds_dwordx4 v[236:237], off
	v_lshl_add_u64 v[236:237], v[128:129], 0, s[24:25]
	s_mov_b32 m0, s82
	s_nop 0
	global_load_lds_dwordx4 v[236:237], off
	s_barrier
	s_waitcnt lgkmcnt(0)
	s_setprio 1
	s_waitcnt lgkmcnt(0)
	v_mfma_f32_16x16x32_bf16 v[60:63], v[140:143], v[156:159], v[60:63]
	v_mfma_f32_16x16x32_bf16 v[56:59], v[148:151], v[156:159], v[56:59]
	v_mfma_f32_16x16x32_bf16 v[52:55], v[140:143], v[194:197], v[52:55]
	v_mfma_f32_16x16x32_bf16 v[48:51], v[148:151], v[194:197], v[48:51]
	v_mfma_f32_16x16x32_bf16 v[44:47], v[140:143], v[202:205], v[44:47]
	v_mfma_f32_16x16x32_bf16 v[40:43], v[148:151], v[202:205], v[40:43]
	v_mfma_f32_16x16x32_bf16 v[36:39], v[140:143], v[210:213], v[36:39]
	v_mfma_f32_16x16x32_bf16 v[32:35], v[148:151], v[210:213], v[32:35]
	v_mfma_f32_16x16x32_bf16 v[60:63], v[144:147], v[160:163], v[60:63]
	v_mfma_f32_16x16x32_bf16 v[56:59], v[152:155], v[160:163], v[56:59]
	v_mfma_f32_16x16x32_bf16 v[52:55], v[144:147], v[198:201], v[52:55]
	v_mfma_f32_16x16x32_bf16 v[48:51], v[152:155], v[198:201], v[48:51]
	v_mfma_f32_16x16x32_bf16 v[44:47], v[144:147], v[206:209], v[44:47]
	v_mfma_f32_16x16x32_bf16 v[40:43], v[152:155], v[206:209], v[40:43]
	v_mfma_f32_16x16x32_bf16 v[36:39], v[144:147], v[214:217], v[36:39]
	v_mfma_f32_16x16x32_bf16 v[32:35], v[152:155], v[214:217], v[32:35]
	s_setprio 0
	s_barrier
	v_readfirstlane_b32 s82, v186
	v_lshl_add_u64 v[140:141], v[234:235], 0, s[6:7]
	s_mov_b32 m0, s82
	v_readfirstlane_b32 s82, v185
	global_load_lds_dwordx4 v[140:141], off
	v_lshl_add_u64 v[140:141], v[234:235], 0, s[8:9]
	s_mov_b32 m0, s82
	s_nop 0
	global_load_lds_dwordx4 v[140:141], off
	s_waitcnt vmcnt(6)
	s_barrier
	s_setprio 1
	v_mfma_f32_16x16x32_bf16 v[28:31], v[218:221], v[156:159], v[28:31]
	v_mfma_f32_16x16x32_bf16 v[24:27], v[226:229], v[156:159], v[24:27]
	v_mfma_f32_16x16x32_bf16 v[20:23], v[218:221], v[194:197], v[20:23]
	v_mfma_f32_16x16x32_bf16 v[16:19], v[226:229], v[194:197], v[16:19]
	v_mfma_f32_16x16x32_bf16 v[12:15], v[218:221], v[202:205], v[12:15]
	v_mfma_f32_16x16x32_bf16 v[8:11], v[226:229], v[202:205], v[8:11]
	v_mfma_f32_16x16x32_bf16 v[4:7], v[218:221], v[210:213], v[4:7]
	v_mfma_f32_16x16x32_bf16 v[0:3], v[226:229], v[210:213], v[0:3]
	v_mfma_f32_16x16x32_bf16 v[28:31], v[222:225], v[160:163], v[28:31]
	v_mfma_f32_16x16x32_bf16 v[24:27], v[230:233], v[160:163], v[24:27]
	v_mfma_f32_16x16x32_bf16 v[20:23], v[222:225], v[198:201], v[20:23]
	v_mfma_f32_16x16x32_bf16 v[16:19], v[230:233], v[198:201], v[16:19]
	v_mfma_f32_16x16x32_bf16 v[12:15], v[222:225], v[206:209], v[12:15]
	v_mfma_f32_16x16x32_bf16 v[8:11], v[230:233], v[206:209], v[8:11]
	v_mfma_f32_16x16x32_bf16 v[4:7], v[222:225], v[214:217], v[4:7]
	v_mfma_f32_16x16x32_bf16 v[0:3], v[230:233], v[214:217], v[0:3]
	s_setprio 0
	s_barrier
	ds_read_b128 v[140:143], v130
	ds_read_b128 v[144:147], v130 offset:1024
	ds_read_b128 v[148:151], v130 offset:2048
	ds_read_b128 v[152:155], v130 offset:3072
	v_readfirstlane_b32 s82, v184
	v_lshl_add_u64 v[218:219], v[128:129], 0, s[26:27]
	s_mov_b32 m0, s82
	v_readfirstlane_b32 s82, v183
	ds_read_b128 v[156:159], v193 offset:32768
	ds_read_b128 v[160:163], v193 offset:33792
	ds_read_b128 v[194:197], v192 offset:32768
	ds_read_b128 v[198:201], v192 offset:33792
	ds_read_b128 v[202:205], v191 offset:32768
	ds_read_b128 v[206:209], v191 offset:33792
	ds_read_b128 v[210:213], v190 offset:32768
	ds_read_b128 v[214:217], v190 offset:33792
	global_load_lds_dwordx4 v[218:219], off
	s_mov_b32 m0, s82
	s_nop 0
	global_load_lds_dwordx4 v[128:129], off
	s_waitcnt lgkmcnt(8)
	s_barrier
	s_waitcnt lgkmcnt(0)
	s_setprio 1
	s_waitcnt lgkmcnt(0)
	v_mfma_f32_16x16x32_bf16 v[124:127], v[140:143], v[156:159], v[124:127]
	v_mfma_f32_16x16x32_bf16 v[120:123], v[148:151], v[156:159], v[120:123]
	v_mfma_f32_16x16x32_bf16 v[116:119], v[140:143], v[194:197], v[116:119]
	v_mfma_f32_16x16x32_bf16 v[112:115], v[148:151], v[194:197], v[112:115]
	v_mfma_f32_16x16x32_bf16 v[108:111], v[140:143], v[202:205], v[108:111]
	v_mfma_f32_16x16x32_bf16 v[104:107], v[148:151], v[202:205], v[104:107]
	v_mfma_f32_16x16x32_bf16 v[100:103], v[140:143], v[210:213], v[100:103]
	v_mfma_f32_16x16x32_bf16 v[96:99], v[148:151], v[210:213], v[96:99]
	v_mfma_f32_16x16x32_bf16 v[124:127], v[144:147], v[160:163], v[124:127]
	v_mfma_f32_16x16x32_bf16 v[120:123], v[152:155], v[160:163], v[120:123]
	v_mfma_f32_16x16x32_bf16 v[116:119], v[144:147], v[198:201], v[116:119]
	v_mfma_f32_16x16x32_bf16 v[112:115], v[152:155], v[198:201], v[112:115]
	v_mfma_f32_16x16x32_bf16 v[108:111], v[144:147], v[206:209], v[108:111]
	v_mfma_f32_16x16x32_bf16 v[104:107], v[152:155], v[206:209], v[104:107]
	v_mfma_f32_16x16x32_bf16 v[100:103], v[144:147], v[214:217], v[100:103]
	v_mfma_f32_16x16x32_bf16 v[96:99], v[152:155], v[214:217], v[96:99]
	s_setprio 0
	s_barrier
	v_readfirstlane_b32 s82, v182
	v_lshl_add_u64 v[234:235], s[56:57], 0, v[164:165]
	s_mov_b32 m0, s82
	v_readfirstlane_b32 s82, v181
	ds_read_b128 v[218:221], v132
	ds_read_b128 v[222:225], v132 offset:1024
	ds_read_b128 v[226:229], v132 offset:2048
	ds_read_b128 v[230:233], v132 offset:3072
	global_load_lds_dwordx4 v[234:235], off
	v_lshl_add_u64 v[236:237], v[234:235], 0, s[2:3]
	s_mov_b32 m0, s82
	s_nop 0
	global_load_lds_dwordx4 v[236:237], off
	s_barrier
	s_waitcnt lgkmcnt(0)
	s_setprio 1
	s_waitcnt lgkmcnt(0)
	v_mfma_f32_16x16x32_bf16 v[92:95], v[218:221], v[156:159], v[92:95]
	v_mfma_f32_16x16x32_bf16 v[88:91], v[226:229], v[156:159], v[88:91]
	v_mfma_f32_16x16x32_bf16 v[84:87], v[218:221], v[194:197], v[84:87]
	v_mfma_f32_16x16x32_bf16 v[80:83], v[226:229], v[194:197], v[80:83]
	v_mfma_f32_16x16x32_bf16 v[76:79], v[218:221], v[202:205], v[76:79]
	v_mfma_f32_16x16x32_bf16 v[72:75], v[226:229], v[202:205], v[72:75]
	v_mfma_f32_16x16x32_bf16 v[68:71], v[218:221], v[210:213], v[68:71]
	v_mfma_f32_16x16x32_bf16 v[64:67], v[226:229], v[210:213], v[64:67]
	v_mfma_f32_16x16x32_bf16 v[92:95], v[222:225], v[160:163], v[92:95]
	v_mfma_f32_16x16x32_bf16 v[88:91], v[230:233], v[160:163], v[88:91]
	v_mfma_f32_16x16x32_bf16 v[84:87], v[222:225], v[198:201], v[84:87]
	v_mfma_f32_16x16x32_bf16 v[80:83], v[230:233], v[198:201], v[80:83]
	v_mfma_f32_16x16x32_bf16 v[76:79], v[222:225], v[206:209], v[76:79]
	v_mfma_f32_16x16x32_bf16 v[72:75], v[230:233], v[206:209], v[72:75]
	v_mfma_f32_16x16x32_bf16 v[68:71], v[222:225], v[214:217], v[68:71]
	v_mfma_f32_16x16x32_bf16 v[64:67], v[230:233], v[214:217], v[64:67]
	s_setprio 0
	v_readfirstlane_b32 s82, v177
	v_lshl_add_u64 v[236:237], v[128:129], 0, s[28:29]
	s_mov_b32 m0, s82
	v_readfirstlane_b32 s82, v175
	s_barrier
	ds_read_b128 v[156:159], v193 offset:49152
	ds_read_b128 v[160:163], v193 offset:50176
	ds_read_b128 v[194:197], v192 offset:49152
	ds_read_b128 v[198:201], v192 offset:50176
	ds_read_b128 v[202:205], v191 offset:49152
	ds_read_b128 v[206:209], v191 offset:50176
	ds_read_b128 v[210:213], v190 offset:49152
	ds_read_b128 v[214:217], v190 offset:50176
	global_load_lds_dwordx4 v[236:237], off
	v_lshl_add_u64 v[236:237], v[128:129], 0, s[30:31]
	s_mov_b32 m0, s82
	s_nop 0
	global_load_lds_dwordx4 v[236:237], off
	s_barrier
	s_waitcnt lgkmcnt(0)
	s_setprio 1
	s_waitcnt lgkmcnt(0)
	v_mfma_f32_16x16x32_bf16 v[60:63], v[140:143], v[156:159], v[60:63]
	v_mfma_f32_16x16x32_bf16 v[56:59], v[148:151], v[156:159], v[56:59]
	v_mfma_f32_16x16x32_bf16 v[52:55], v[140:143], v[194:197], v[52:55]
	v_mfma_f32_16x16x32_bf16 v[48:51], v[148:151], v[194:197], v[48:51]
	v_mfma_f32_16x16x32_bf16 v[44:47], v[140:143], v[202:205], v[44:47]
	v_mfma_f32_16x16x32_bf16 v[40:43], v[148:151], v[202:205], v[40:43]
	v_mfma_f32_16x16x32_bf16 v[36:39], v[140:143], v[210:213], v[36:39]
	v_mfma_f32_16x16x32_bf16 v[32:35], v[148:151], v[210:213], v[32:35]
	v_mfma_f32_16x16x32_bf16 v[60:63], v[144:147], v[160:163], v[60:63]
	v_mfma_f32_16x16x32_bf16 v[56:59], v[152:155], v[160:163], v[56:59]
	v_mfma_f32_16x16x32_bf16 v[52:55], v[144:147], v[198:201], v[52:55]
	v_mfma_f32_16x16x32_bf16 v[48:51], v[152:155], v[198:201], v[48:51]
	v_mfma_f32_16x16x32_bf16 v[44:47], v[144:147], v[206:209], v[44:47]
	v_mfma_f32_16x16x32_bf16 v[40:43], v[152:155], v[206:209], v[40:43]
	v_mfma_f32_16x16x32_bf16 v[36:39], v[144:147], v[214:217], v[36:39]
	v_mfma_f32_16x16x32_bf16 v[32:35], v[152:155], v[214:217], v[32:35]
	s_setprio 0
	s_barrier
	v_readfirstlane_b32 s82, v173
	v_lshl_add_u64 v[140:141], v[234:235], 0, s[6:7]
	s_mov_b32 m0, s82
	v_readfirstlane_b32 s82, v171
	global_load_lds_dwordx4 v[140:141], off
	v_lshl_add_u64 v[140:141], v[234:235], 0, s[8:9]
	s_mov_b32 m0, s82
	s_nop 0
	global_load_lds_dwordx4 v[140:141], off
	s_waitcnt vmcnt(6)
	s_barrier
	s_setprio 1
	v_mfma_f32_16x16x32_bf16 v[28:31], v[218:221], v[156:159], v[28:31]
	v_mfma_f32_16x16x32_bf16 v[24:27], v[226:229], v[156:159], v[24:27]
	v_mfma_f32_16x16x32_bf16 v[20:23], v[218:221], v[194:197], v[20:23]
	v_mfma_f32_16x16x32_bf16 v[16:19], v[226:229], v[194:197], v[16:19]
	v_mfma_f32_16x16x32_bf16 v[12:15], v[218:221], v[202:205], v[12:15]
	v_mfma_f32_16x16x32_bf16 v[8:11], v[226:229], v[202:205], v[8:11]
	v_mfma_f32_16x16x32_bf16 v[4:7], v[218:221], v[210:213], v[4:7]
	v_mfma_f32_16x16x32_bf16 v[0:3], v[226:229], v[210:213], v[0:3]
	v_mfma_f32_16x16x32_bf16 v[28:31], v[222:225], v[160:163], v[28:31]
	v_mfma_f32_16x16x32_bf16 v[24:27], v[230:233], v[160:163], v[24:27]
	v_mfma_f32_16x16x32_bf16 v[20:23], v[222:225], v[198:201], v[20:23]
	v_mfma_f32_16x16x32_bf16 v[16:19], v[230:233], v[198:201], v[16:19]
	v_mfma_f32_16x16x32_bf16 v[12:15], v[222:225], v[206:209], v[12:15]
	v_mfma_f32_16x16x32_bf16 v[8:11], v[230:233], v[206:209], v[8:11]
	v_mfma_f32_16x16x32_bf16 v[4:7], v[222:225], v[214:217], v[4:7]
	v_mfma_f32_16x16x32_bf16 v[0:3], v[230:233], v[214:217], v[0:3]
	s_setprio 0
	s_add_i32 s14, s14, 2
	s_add_u32 s56, s56, s58
	s_addc_u32 s57, s57, s59
	s_add_u32 s60, s60, s58
	s_addc_u32 s61, s61, s59
	s_cmp_lt_u32 s14, 28
	v_lshl_add_u64 v[128:129], v[128:129], 0, s[34:35]
	s_barrier
	s_cbranch_scc1 .LBB0_234
	s_lshl_b32 s14, s62, 3
	s_or_b32 s82, s63, s14
	s_lshl_b32 s56, s82, 8
	v_lshlrev_b32_e32 v128, 3, v131
	v_lshlrev_b32_e32 v129, 5, v131
	s_or_b32 s14, s56, 0x80
	v_and_b32_e32 v128, 0x7fff0, v128
	v_and_b32_e32 v129, 32, v129
	s_lshl_b64 s[58:59], s[14:15], 13
	v_add_u32_e32 v129, v129, v134
	v_add_lshl_u32 v128, v133, v128, 13
	s_add_u32 s58, s40, s58
	v_lshl_add_u32 v164, v129, 1, v128
	s_addc_u32 s59, s41, s59
	v_lshl_add_u64 v[128:129], s[58:59], 0, v[164:165]
	v_readfirstlane_b32 s14, v137
	ds_read_b128 v[140:143], v138
	ds_read_b128 v[144:147], v138 offset:1024
	ds_read_b128 v[148:151], v138 offset:2048
	ds_read_b128 v[152:155], v138 offset:3072
	ds_read_b128 v[156:159], v193
	ds_read_b128 v[160:163], v193 offset:1024
	ds_read_b128 v[194:197], v192
	ds_read_b128 v[198:201], v192 offset:1024
	ds_read_b128 v[202:205], v191
	ds_read_b128 v[206:209], v191 offset:1024
	ds_read_b128 v[210:213], v190
	ds_read_b128 v[214:217], v190 offset:1024
	v_lshl_add_u64 v[138:139], v[128:129], 0, s[44:45]
	s_mov_b32 m0, s14
	v_readfirstlane_b32 s14, v136
	global_load_lds_dwordx4 v[138:139], off
	v_lshl_add_u64 v[128:129], v[128:129], 0, s[46:47]
	s_mov_b32 m0, s14
	s_mov_b32 s57, s15
	global_load_lds_dwordx4 v[128:129], off
	s_barrier
	s_waitcnt lgkmcnt(0)
	s_setprio 1
	s_waitcnt lgkmcnt(0)
	v_mfma_f32_16x16x32_bf16 v[124:127], v[140:143], v[156:159], v[124:127]
	v_mfma_f32_16x16x32_bf16 v[120:123], v[148:151], v[156:159], v[120:123]
	v_mfma_f32_16x16x32_bf16 v[116:119], v[140:143], v[194:197], v[116:119]
	v_mfma_f32_16x16x32_bf16 v[112:115], v[148:151], v[194:197], v[112:115]
	v_mfma_f32_16x16x32_bf16 v[108:111], v[140:143], v[202:205], v[108:111]
	v_mfma_f32_16x16x32_bf16 v[104:107], v[148:151], v[202:205], v[104:107]
	v_mfma_f32_16x16x32_bf16 v[100:103], v[140:143], v[210:213], v[100:103]
	v_mfma_f32_16x16x32_bf16 v[96:99], v[148:151], v[210:213], v[96:99]
	v_mfma_f32_16x16x32_bf16 v[124:127], v[144:147], v[160:163], v[124:127]
	v_mfma_f32_16x16x32_bf16 v[120:123], v[152:155], v[160:163], v[120:123]
	v_mfma_f32_16x16x32_bf16 v[116:119], v[144:147], v[198:201], v[116:119]
	v_mfma_f32_16x16x32_bf16 v[112:115], v[152:155], v[198:201], v[112:115]
	v_mfma_f32_16x16x32_bf16 v[108:111], v[144:147], v[206:209], v[108:111]
	v_mfma_f32_16x16x32_bf16 v[104:107], v[152:155], v[206:209], v[104:107]
	v_mfma_f32_16x16x32_bf16 v[100:103], v[144:147], v[214:217], v[100:103]
	v_mfma_f32_16x16x32_bf16 v[96:99], v[152:155], v[214:217], v[96:99]
	s_setprio 0
	s_barrier
	ds_read_b128 v[136:139], v135
	ds_read_b128 v[218:221], v135 offset:1024
	ds_read_b128 v[222:225], v135 offset:2048
	ds_read_b128 v[226:229], v135 offset:3072
	s_barrier
	s_waitcnt lgkmcnt(0)
	s_setprio 1
	s_waitcnt lgkmcnt(0)
	v_mfma_f32_16x16x32_bf16 v[92:95], v[136:139], v[156:159], v[92:95]
	v_mfma_f32_16x16x32_bf16 v[84:87], v[136:139], v[194:197], v[84:87]
	v_mfma_f32_16x16x32_bf16 v[80:83], v[222:225], v[194:197], v[80:83]
	v_mfma_f32_16x16x32_bf16 v[88:91], v[222:225], v[156:159], v[88:91]
	v_mfma_f32_16x16x32_bf16 v[76:79], v[136:139], v[202:205], v[76:79]
	v_mfma_f32_16x16x32_bf16 v[72:75], v[222:225], v[202:205], v[72:75]
	v_mfma_f32_16x16x32_bf16 v[68:71], v[136:139], v[210:213], v[68:71]
	v_mfma_f32_16x16x32_bf16 v[64:67], v[222:225], v[210:213], v[64:67]
	v_mfma_f32_16x16x32_bf16 v[156:159], v[218:221], v[160:163], v[92:95]
	v_mfma_f32_16x16x32_bf16 v[194:197], v[218:221], v[198:201], v[84:87]
	v_mfma_f32_16x16x32_bf16 v[198:201], v[226:229], v[198:201], v[80:83]
	v_mfma_f32_16x16x32_bf16 v[160:163], v[226:229], v[160:163], v[88:91]
	v_mfma_f32_16x16x32_bf16 v[202:205], v[218:221], v[206:209], v[76:79]
	v_mfma_f32_16x16x32_bf16 v[206:209], v[226:229], v[206:209], v[72:75]
	v_mfma_f32_16x16x32_bf16 v[210:213], v[218:221], v[214:217], v[68:71]
	v_mfma_f32_16x16x32_bf16 v[214:217], v[226:229], v[214:217], v[64:67]
	s_setprio 0
	s_barrier
	s_nop 0
	ds_read_b128 v[64:67], v193 offset:16384
	ds_read_b128 v[68:71], v193 offset:17408
	ds_read_b128 v[72:75], v192 offset:16384
	ds_read_b128 v[76:79], v192 offset:17408
	ds_read_b128 v[80:83], v191 offset:16384
	ds_read_b128 v[84:87], v191 offset:17408
	ds_read_b128 v[88:91], v190 offset:16384
	ds_read_b128 v[92:95], v190 offset:17408
	s_waitcnt vmcnt(4)
	s_barrier
	s_waitcnt lgkmcnt(0)
	s_setprio 1
	s_waitcnt lgkmcnt(0)
	v_mfma_f32_16x16x32_bf16 v[60:63], v[140:143], v[64:67], v[60:63]
	v_mfma_f32_16x16x32_bf16 v[56:59], v[148:151], v[64:67], v[56:59]
	v_mfma_f32_16x16x32_bf16 v[52:55], v[140:143], v[72:75], v[52:55]
	v_mfma_f32_16x16x32_bf16 v[48:51], v[148:151], v[72:75], v[48:51]
	v_mfma_f32_16x16x32_bf16 v[230:233], v[140:143], v[80:83], v[44:47]
	v_mfma_f32_16x16x32_bf16 v[234:237], v[148:151], v[80:83], v[40:43]
	v_mfma_f32_16x16x32_bf16 v[140:143], v[140:143], v[88:91], v[36:39]
	v_mfma_f32_16x16x32_bf16 v[148:151], v[148:151], v[88:91], v[32:35]
	v_mfma_f32_16x16x32_bf16 v[32:35], v[144:147], v[68:71], v[60:63]
	v_mfma_f32_16x16x32_bf16 v[36:39], v[152:155], v[68:71], v[56:59]
	v_mfma_f32_16x16x32_bf16 v[40:43], v[144:147], v[76:79], v[52:55]
	v_mfma_f32_16x16x32_bf16 v[44:47], v[152:155], v[76:79], v[48:51]
	v_mfma_f32_16x16x32_bf16 v[48:51], v[144:147], v[84:87], v[230:233]
	v_mfma_f32_16x16x32_bf16 v[52:55], v[152:155], v[84:87], v[234:237]
	v_mfma_f32_16x16x32_bf16 v[56:59], v[144:147], v[92:95], v[140:143]
	v_mfma_f32_16x16x32_bf16 v[60:63], v[152:155], v[92:95], v[148:151]
	s_setprio 0
	s_setprio 1
	v_mfma_f32_16x16x32_bf16 v[28:31], v[136:139], v[64:67], v[28:31]
	v_mfma_f32_16x16x32_bf16 v[24:27], v[222:225], v[64:67], v[24:27]
	v_mfma_f32_16x16x32_bf16 v[20:23], v[136:139], v[72:75], v[20:23]
	v_mfma_f32_16x16x32_bf16 v[64:67], v[222:225], v[72:75], v[16:19]
	v_mfma_f32_16x16x32_bf16 v[12:15], v[136:139], v[80:83], v[12:15]
	v_mfma_f32_16x16x32_bf16 v[8:11], v[222:225], v[80:83], v[8:11]
	v_mfma_f32_16x16x32_bf16 v[72:75], v[136:139], v[88:91], v[4:7]
	v_mfma_f32_16x16x32_bf16 v[80:83], v[222:225], v[88:91], v[0:3]
	v_mfma_f32_16x16x32_bf16 v[0:3], v[218:221], v[68:71], v[28:31]
	v_mfma_f32_16x16x32_bf16 v[4:7], v[226:229], v[68:71], v[24:27]
	v_mfma_f32_16x16x32_bf16 v[16:19], v[218:221], v[76:79], v[20:23]
	v_mfma_f32_16x16x32_bf16 v[20:23], v[226:229], v[76:79], v[64:67]
	v_mfma_f32_16x16x32_bf16 v[24:27], v[218:221], v[84:87], v[12:15]
	v_mfma_f32_16x16x32_bf16 v[28:31], v[226:229], v[84:87], v[8:11]
	v_mfma_f32_16x16x32_bf16 v[64:67], v[218:221], v[92:95], v[72:75]
	v_mfma_f32_16x16x32_bf16 v[68:71], v[226:229], v[92:95], v[80:83]
	s_setprio 0
	s_barrier
	ds_read_b128 v[12:15], v130
	ds_read_b128 v[8:11], v130 offset:1024
	ds_read_b128 v[76:79], v130 offset:2048
	ds_read_b128 v[72:75], v130 offset:3072
	ds_read_b128 v[140:143], v193 offset:32768
	ds_read_b128 v[148:151], v193 offset:33792
	ds_read_b128 v[218:221], v192 offset:32768
	ds_read_b128 v[222:225], v192 offset:33792
	ds_read_b128 v[226:229], v191 offset:32768
	ds_read_b128 v[230:233], v191 offset:33792
	ds_read_b128 v[234:237], v190 offset:32768
	ds_read_b128 v[238:241], v190 offset:33792
	s_waitcnt vmcnt(2)
	s_barrier
	s_waitcnt lgkmcnt(0)
	s_setprio 1
	s_waitcnt lgkmcnt(0)
	v_mfma_f32_16x16x32_bf16 v[80:83], v[12:15], v[140:143], v[124:127]
	v_mfma_f32_16x16x32_bf16 v[84:87], v[76:79], v[140:143], v[120:123]
	v_mfma_f32_16x16x32_bf16 v[88:91], v[12:15], v[218:221], v[116:119]
	v_mfma_f32_16x16x32_bf16 v[92:95], v[76:79], v[218:221], v[112:115]
	v_mfma_f32_16x16x32_bf16 v[108:111], v[12:15], v[226:229], v[108:111]
	v_mfma_f32_16x16x32_bf16 v[104:107], v[76:79], v[226:229], v[104:107]
	v_mfma_f32_16x16x32_bf16 v[100:103], v[12:15], v[234:237], v[100:103]
	v_mfma_f32_16x16x32_bf16 v[96:99], v[76:79], v[234:237], v[96:99]
	v_mfma_f32_16x16x32_bf16 v[152:155], v[8:11], v[148:151], v[80:83]
	v_mfma_f32_16x16x32_bf16 v[144:147], v[72:75], v[148:151], v[84:87]
	v_mfma_f32_16x16x32_bf16 v[136:139], v[8:11], v[222:225], v[88:91]
	v_mfma_f32_16x16x32_bf16 v[128:131], v[72:75], v[222:225], v[92:95]
	v_mfma_f32_16x16x32_bf16 v[120:123], v[8:11], v[230:233], v[108:111]
	v_mfma_f32_16x16x32_bf16 v[112:115], v[72:75], v[230:233], v[104:107]
	v_mfma_f32_16x16x32_bf16 v[104:107], v[8:11], v[238:241], v[100:103]
	v_mfma_f32_16x16x32_bf16 v[96:99], v[72:75], v[238:241], v[96:99]
	s_setprio 0
	s_barrier
	ds_read_b128 v[88:91], v132
	ds_read_b128 v[80:83], v132 offset:1024
	ds_read_b128 v[92:95], v132 offset:2048
	ds_read_b128 v[84:87], v132 offset:3072
	s_waitcnt vmcnt(0)
	s_barrier
	s_waitcnt lgkmcnt(0)
	s_setprio 1
	s_waitcnt lgkmcnt(0)
	v_mfma_f32_16x16x32_bf16 v[100:103], v[88:91], v[140:143], v[156:159]
	v_mfma_f32_16x16x32_bf16 v[108:111], v[92:95], v[140:143], v[160:163]
	v_mfma_f32_16x16x32_bf16 v[116:119], v[88:91], v[218:221], v[194:197]
	v_mfma_f32_16x16x32_bf16 v[124:127], v[92:95], v[218:221], v[198:201]
	v_mfma_f32_16x16x32_bf16 v[160:163], v[88:91], v[226:229], v[202:205]
	v_mfma_f32_16x16x32_bf16 v[194:197], v[92:95], v[226:229], v[206:209]
	v_mfma_f32_16x16x32_bf16 v[198:201], v[88:91], v[234:237], v[210:213]
	v_mfma_f32_16x16x32_bf16 v[202:205], v[92:95], v[234:237], v[214:217]
	v_mfma_f32_16x16x32_bf16 v[156:159], v[80:83], v[148:151], v[100:103]
	v_mfma_f32_16x16x32_bf16 v[148:151], v[84:87], v[148:151], v[108:111]
	v_mfma_f32_16x16x32_bf16 v[140:143], v[80:83], v[222:225], v[116:119]
	v_mfma_f32_16x16x32_bf16 v[132:135], v[84:87], v[222:225], v[124:127]
	v_mfma_f32_16x16x32_bf16 v[124:127], v[80:83], v[230:233], v[160:163]
	v_mfma_f32_16x16x32_bf16 v[116:119], v[84:87], v[230:233], v[194:197]
	v_mfma_f32_16x16x32_bf16 v[108:111], v[80:83], v[238:241], v[198:201]
	v_mfma_f32_16x16x32_bf16 v[100:103], v[84:87], v[238:241], v[202:205]
	s_setprio 0
	s_lshl_b64 s[58:59], s[56:57], 2
	s_barrier
	v_mbcnt_lo_u32_b32 v162, -1, 0
	v_mbcnt_hi_u32_b32 v162, -1, v162
	s_add_u32 s58, s87, s58
	v_add_u32_e32 v160, s64, v162
	s_addc_u32 s59, s88, s59
	v_and_b32_e32 v164, 0x100, v160
	v_and_b32_e32 v162, 15, v162
	v_lshl_add_u64 v[160:161], s[58:59], 0, v[164:165]
	v_lshlrev_b32_e32 v164, 2, v162
	v_lshl_add_u64 v[160:161], v[160:161], 0, v[164:165]
	global_load_dword v180, v[160:161], off
	global_load_dword v178, v[160:161], off offset:64
	global_load_dword v176, v[160:161], off offset:128
	global_load_dword v174, v[160:161], off offset:192
	global_load_dword v172, v[160:161], off offset:512
	global_load_dword v170, v[160:161], off offset:576
	global_load_dword v168, v[160:161], off offset:640
	global_load_dword v166, v[160:161], off offset:704
	v_mbcnt_lo_u32_b32 v194, -1, 0
	v_mbcnt_hi_u32_b32 v194, -1, v194
	s_cmp_lg_u32 s81, 0
	v_add_u32_e32 v160, s64, v194
	v_bfe_u32 v196, v160, 8, 1
	v_ashrrev_i32_e32 v199, 6, v160
	v_bfe_u32 v160, v194, 4, 2
	s_cselect_b64 s[58:59], -1, 0
	v_and_b32_e32 v197, 3, v199
	v_and_b32_e32 v195, 15, v194
	s_and_b64 vcc, exec, s[58:59]
	v_lshlrev_b32_e32 v198, 4, v160
	s_cbranch_vccz .LBB0_246
	s_lshl_b32 s14, s80, 22
	s_lshl_b32 s57, s82, 14
	s_add_i32 s57, s57, s14
	v_lshlrev_b32_e32 v160, 6, v195
	v_or3_b32 v160, s57, v160, v198
	v_lshl_add_u32 v160, v197, 20, v160
	v_lshl_or_b32 v164, v196, 12, v160
	s_waitcnt vmcnt(0)
	v_pk_mul_f32 v[160:161], v[154:155], v[180:181] op_sel_hi:[1,0]
	v_pk_mul_f32 v[200:201], v[146:147], v[180:181] op_sel_hi:[1,0]
	v_max_f32_e32 v160, 0, v160
	v_mul_f32_e32 v204, v160, v160
	v_max_f32_e32 v160, 0, v200
	v_pk_mul_f32 v[162:163], v[152:153], v[180:181] op_sel_hi:[1,0]
	v_mul_f32_e32 v200, v160, v160
	v_max_f32_e32 v160, 0, v161
	v_pk_mul_f32 v[202:203], v[144:145], v[180:181] op_sel_hi:[1,0]
	v_max_f32_e32 v162, 0, v162
	v_max_f32_e32 v163, 0, v163
	v_mul_f32_e32 v161, v160, v160
	v_max_f32_e32 v160, 0, v201
	v_mul_f32_e32 v162, v162, v162
	v_max_f32_e32 v202, 0, v202
	v_mul_f32_e32 v163, v163, v163
	v_max_f32_e32 v203, 0, v203
	v_mul_f32_e32 v201, v160, v160
	v_cvt_pk_bf16_f32 v160, v162, v163
	v_cvt_pk_bf16_f32 v161, v204, v161
	v_mul_f32_e32 v202, v202, v202
	v_mul_f32_e32 v203, v203, v203
	v_cvt_pk_bf16_f32 v162, v202, v203
	v_cvt_pk_bf16_f32 v163, v200, v201
	global_store_dwordx4 v164, v[160:163], s[0:1] sc0 sc1
	v_pk_mul_f32 v[202:203], v[150:151], v[180:181] op_sel_hi:[1,0]
	v_lshl_add_u64 v[200:201], s[0:1], 0, v[164:165]
	v_pk_mul_f32 v[160:161], v[158:159], v[180:181] op_sel_hi:[1,0]
	v_pk_mul_f32 v[162:163], v[156:157], v[180:181] op_sel_hi:[1,0]
	v_max_f32_e32 v160, 0, v160
	v_mul_f32_e32 v206, v160, v160
	v_max_f32_e32 v160, 0, v202
	v_mul_f32_e32 v202, v160, v160
	v_max_f32_e32 v160, 0, v161
	v_pk_mul_f32 v[204:205], v[148:149], v[180:181] op_sel_hi:[1,0]
	v_max_f32_e32 v162, 0, v162
	v_max_f32_e32 v163, 0, v163
	v_mul_f32_e32 v161, v160, v160
	v_max_f32_e32 v160, 0, v203
	v_add_co_u32_e32 v200, vcc, s74, v200
	v_mul_f32_e32 v162, v162, v162
	v_max_f32_e32 v204, 0, v204
	v_mul_f32_e32 v163, v163, v163
	v_max_f32_e32 v205, 0, v205
	v_mul_f32_e32 v203, v160, v160
	v_cvt_pk_bf16_f32 v160, v162, v163
	v_cvt_pk_bf16_f32 v161, v206, v161
	v_addc_co_u32_e32 v201, vcc, 0, v201, vcc
	v_mul_f32_e32 v204, v204, v204
	v_mul_f32_e32 v205, v205, v205
	v_cvt_pk_bf16_f32 v162, v204, v205
	v_cvt_pk_bf16_f32 v163, v202, v203
	global_store_dwordx4 v[200:201], v[160:163], off sc0 sc1
	v_pk_mul_f32 v[202:203], v[130:131], v[178:179] op_sel_hi:[1,0]
	v_pk_mul_f32 v[204:205], v[128:129], v[178:179] op_sel_hi:[1,0]
	v_pk_mul_f32 v[160:161], v[138:139], v[178:179] op_sel_hi:[1,0]
	v_pk_mul_f32 v[162:163], v[136:137], v[178:179] op_sel_hi:[1,0]
	v_max_f32_e32 v160, 0, v160
	v_mul_f32_e32 v206, v160, v160
	v_max_f32_e32 v160, 0, v202
	v_mul_f32_e32 v202, v160, v160
	v_max_f32_e32 v160, 0, v161
	v_max_f32_e32 v162, 0, v162
	v_max_f32_e32 v163, 0, v163
	v_mul_f32_e32 v161, v160, v160
	v_max_f32_e32 v160, 0, v203
	v_mul_f32_e32 v162, v162, v162
	v_max_f32_e32 v204, 0, v204
	v_mul_f32_e32 v163, v163, v163
	v_max_f32_e32 v205, 0, v205
	v_mul_f32_e32 v203, v160, v160
	v_cvt_pk_bf16_f32 v160, v162, v163
	v_cvt_pk_bf16_f32 v161, v206, v161
	v_mul_f32_e32 v204, v204, v204
	v_mul_f32_e32 v205, v205, v205
	v_cvt_pk_bf16_f32 v162, v204, v205
	v_cvt_pk_bf16_f32 v163, v202, v203
	global_store_dwordx4 v164, v[160:163], s[0:1] offset:1024 sc0 sc1
	v_pk_mul_f32 v[202:203], v[134:135], v[178:179] op_sel_hi:[1,0]
	v_pk_mul_f32 v[204:205], v[132:133], v[178:179] op_sel_hi:[1,0]
	v_pk_mul_f32 v[160:161], v[142:143], v[178:179] op_sel_hi:[1,0]
	v_pk_mul_f32 v[162:163], v[140:141], v[178:179] op_sel_hi:[1,0]
	v_max_f32_e32 v160, 0, v160
	v_mul_f32_e32 v206, v160, v160
	v_max_f32_e32 v160, 0, v202
	v_mul_f32_e32 v202, v160, v160
	v_max_f32_e32 v160, 0, v161
	v_max_f32_e32 v162, 0, v162
	v_max_f32_e32 v163, 0, v163
	v_mul_f32_e32 v161, v160, v160
	v_max_f32_e32 v160, 0, v203
	v_mul_f32_e32 v162, v162, v162
	v_max_f32_e32 v204, 0, v204
	v_mul_f32_e32 v163, v163, v163
	v_max_f32_e32 v205, 0, v205
	v_mul_f32_e32 v203, v160, v160
	v_cvt_pk_bf16_f32 v160, v162, v163
	v_cvt_pk_bf16_f32 v161, v206, v161
	v_mul_f32_e32 v204, v204, v204
	v_mul_f32_e32 v205, v205, v205
	v_cvt_pk_bf16_f32 v162, v204, v205
	v_cvt_pk_bf16_f32 v163, v202, v203
	global_store_dwordx4 v[200:201], v[160:163], off offset:1024 sc0 sc1
	v_pk_mul_f32 v[202:203], v[114:115], v[176:177] op_sel_hi:[1,0]
	v_pk_mul_f32 v[204:205], v[112:113], v[176:177] op_sel_hi:[1,0]
	v_pk_mul_f32 v[160:161], v[122:123], v[176:177] op_sel_hi:[1,0]
	v_pk_mul_f32 v[162:163], v[120:121], v[176:177] op_sel_hi:[1,0]
	v_max_f32_e32 v160, 0, v160
	v_mul_f32_e32 v206, v160, v160
	v_max_f32_e32 v160, 0, v202
	v_mul_f32_e32 v202, v160, v160
	v_max_f32_e32 v160, 0, v161
	v_max_f32_e32 v162, 0, v162
	v_max_f32_e32 v163, 0, v163
	v_mul_f32_e32 v161, v160, v160
	v_max_f32_e32 v160, 0, v203
	v_mul_f32_e32 v162, v162, v162
	v_max_f32_e32 v204, 0, v204
	v_mul_f32_e32 v163, v163, v163
	v_max_f32_e32 v205, 0, v205
	v_mul_f32_e32 v203, v160, v160
	v_cvt_pk_bf16_f32 v160, v162, v163
	v_cvt_pk_bf16_f32 v161, v206, v161
	v_mul_f32_e32 v204, v204, v204
	v_mul_f32_e32 v205, v205, v205
	v_cvt_pk_bf16_f32 v162, v204, v205
	v_cvt_pk_bf16_f32 v163, v202, v203
	global_store_dwordx4 v164, v[160:163], s[0:1] offset:2048 sc0 sc1
	v_pk_mul_f32 v[202:203], v[118:119], v[176:177] op_sel_hi:[1,0]
	v_pk_mul_f32 v[204:205], v[116:117], v[176:177] op_sel_hi:[1,0]
	v_pk_mul_f32 v[160:161], v[126:127], v[176:177] op_sel_hi:[1,0]
	v_pk_mul_f32 v[162:163], v[124:125], v[176:177] op_sel_hi:[1,0]
	v_max_f32_e32 v160, 0, v160
	v_mul_f32_e32 v206, v160, v160
	v_max_f32_e32 v160, 0, v202
	v_mul_f32_e32 v202, v160, v160
	v_max_f32_e32 v160, 0, v161
	v_max_f32_e32 v162, 0, v162
	v_max_f32_e32 v163, 0, v163
	v_mul_f32_e32 v161, v160, v160
	v_max_f32_e32 v160, 0, v203
	v_mul_f32_e32 v162, v162, v162
	v_max_f32_e32 v204, 0, v204
	v_mul_f32_e32 v163, v163, v163
	v_max_f32_e32 v205, 0, v205
	v_mul_f32_e32 v203, v160, v160
	v_cvt_pk_bf16_f32 v160, v162, v163
	v_cvt_pk_bf16_f32 v161, v206, v161
	v_mul_f32_e32 v204, v204, v204
	v_mul_f32_e32 v205, v205, v205
	v_cvt_pk_bf16_f32 v162, v204, v205
	v_cvt_pk_bf16_f32 v163, v202, v203
	global_store_dwordx4 v[200:201], v[160:163], off offset:2048 sc0 sc1
	v_pk_mul_f32 v[200:201], v[98:99], v[174:175] op_sel_hi:[1,0]
	v_pk_mul_f32 v[202:203], v[96:97], v[174:175] op_sel_hi:[1,0]
	v_pk_mul_f32 v[160:161], v[106:107], v[174:175] op_sel_hi:[1,0]
	v_pk_mul_f32 v[162:163], v[104:105], v[174:175] op_sel_hi:[1,0]
	v_max_f32_e32 v160, 0, v160
	v_mul_f32_e32 v204, v160, v160
	v_max_f32_e32 v160, 0, v200
	v_mul_f32_e32 v200, v160, v160
	v_max_f32_e32 v160, 0, v161
	v_max_f32_e32 v162, 0, v162
	v_max_f32_e32 v163, 0, v163
	v_mul_f32_e32 v161, v160, v160
	v_max_f32_e32 v160, 0, v201
	v_mul_f32_e32 v162, v162, v162
	v_max_f32_e32 v202, 0, v202
	v_mul_f32_e32 v163, v163, v163
	v_max_f32_e32 v203, 0, v203
	v_mul_f32_e32 v201, v160, v160
	v_cvt_pk_bf16_f32 v160, v162, v163
	v_cvt_pk_bf16_f32 v161, v204, v161
	v_mul_f32_e32 v202, v202, v202
	v_mul_f32_e32 v203, v203, v203
	v_cvt_pk_bf16_f32 v162, v202, v203
	v_cvt_pk_bf16_f32 v163, v200, v201
	global_store_dwordx4 v164, v[160:163], s[0:1] offset:3072 sc0 sc1
	v_pk_mul_f32 v[200:201], v[102:103], v[174:175] op_sel_hi:[1,0]
	v_pk_mul_f32 v[202:203], v[100:101], v[174:175] op_sel_hi:[1,0]
	v_pk_mul_f32 v[160:161], v[110:111], v[174:175] op_sel_hi:[1,0]
	v_pk_mul_f32 v[162:163], v[108:109], v[174:175] op_sel_hi:[1,0]
	v_max_f32_e32 v160, 0, v160
	v_mul_f32_e32 v204, v160, v160
	v_max_f32_e32 v160, 0, v200
	v_max_f32_e32 v162, 0, v162
	v_max_f32_e32 v163, 0, v163
	v_mul_f32_e32 v200, v160, v160
	v_max_f32_e32 v160, 0, v161
	v_mul_f32_e32 v162, v162, v162
	v_max_f32_e32 v202, 0, v202
	v_mul_f32_e32 v163, v163, v163
	v_max_f32_e32 v203, 0, v203
	v_mul_f32_e32 v161, v160, v160
	v_max_f32_e32 v160, 0, v201
	v_mul_f32_e32 v202, v202, v202
	v_mul_f32_e32 v203, v203, v203
	v_mul_f32_e32 v201, v160, v160
	v_cvt_pk_bf16_f32 v160, v162, v163
	v_cvt_pk_bf16_f32 v161, v204, v161
	v_cvt_pk_bf16_f32 v162, v202, v203
	v_cvt_pk_bf16_f32 v163, v200, v201
	v_add_u32_e32 v164, 0x80c00, v164
	s_cbranch_execnz .LBB0_238
.LBB0_237:
	v_mul_lo_u32 v160, v199, s75
	v_lshlrev_b32_e32 v164, 4, v194
	v_add_u32_e32 v160, 0x20000, v160
	v_bfe_u32 v162, v194, 3, 3
	v_and_b32_e32 v164, 0x70, v164
	v_mul_u32_u24_e32 v194, 0x90, v195
	v_lshlrev_b32_e32 v161, 6, v196
	v_add3_u32 v194, v160, v194, v198
	v_or_b32_e32 v160, v160, v164
	v_or3_b32 v195, v161, v162, s56
	v_mad_u32_u24 v162, v162, s76, v160
	s_waitcnt vmcnt(0)
	v_pk_mul_f32 v[160:161], v[146:147], v[180:181] op_sel_hi:[1,0]
	v_pk_mul_f32 v[146:147], v[144:145], v[180:181] op_sel_hi:[1,0]
	v_pk_mul_f32 v[154:155], v[154:155], v[180:181] op_sel_hi:[1,0]
	v_pk_mul_f32 v[152:153], v[152:153], v[180:181] op_sel_hi:[1,0]
	v_cvt_pk_bf16_f32 v145, v154, v155
	v_cvt_pk_bf16_f32 v146, v146, v147
	v_cvt_pk_bf16_f32 v147, v160, v161
	v_pk_mul_f32 v[150:151], v[150:151], v[180:181] op_sel_hi:[1,0]
	v_cvt_pk_bf16_f32 v144, v152, v153
	ds_write_b128 v194, v[144:147]
	v_pk_mul_f32 v[146:147], v[158:159], v[180:181] op_sel_hi:[1,0]
	v_pk_mul_f32 v[144:145], v[156:157], v[180:181] op_sel_hi:[1,0]
	v_pk_mul_f32 v[148:149], v[148:149], v[180:181] op_sel_hi:[1,0]
	v_cvt_pk_bf16_f32 v144, v144, v145
	v_cvt_pk_bf16_f32 v145, v146, v147
	v_cvt_pk_bf16_f32 v147, v150, v151
	v_lshlrev_b32_e32 v163, 7, v197
	v_cvt_pk_bf16_f32 v146, v148, v149
	ds_write_b128 v194, v[144:147] offset:64
	ds_read_b128 v[144:147], v162
	s_lshl_b32 s14, s80, 9
	v_or3_b32 v148, v163, s14, v164
	v_mad_u64_u32 v[152:153], s[60:61], v195, s79, v[148:149]
	ds_read_b128 v[148:151], v162 offset:1152
	s_waitcnt lgkmcnt(1)
	global_store_dwordx4 v152, v[144:147], s[0:1] sc0 sc1
	v_pk_mul_f32 v[138:139], v[138:139], v[178:179] op_sel_hi:[1,0]
	v_pk_mul_f32 v[136:137], v[136:137], v[178:179] op_sel_hi:[1,0]
	v_pk_mul_f32 v[144:145], v[130:131], v[178:179] op_sel_hi:[1,0]
	v_pk_mul_f32 v[130:131], v[128:129], v[178:179] op_sel_hi:[1,0]
	v_cvt_pk_bf16_f32 v128, v136, v137
	v_cvt_pk_bf16_f32 v129, v138, v139
	v_pk_mul_f32 v[134:135], v[134:135], v[178:179] op_sel_hi:[1,0]
	v_cvt_pk_bf16_f32 v130, v130, v131
	v_cvt_pk_bf16_f32 v131, v144, v145
	ds_write_b128 v194, v[128:131]
	v_pk_mul_f32 v[130:131], v[142:143], v[178:179] op_sel_hi:[1,0]
	v_pk_mul_f32 v[128:129], v[140:141], v[178:179] op_sel_hi:[1,0]
	v_pk_mul_f32 v[132:133], v[132:133], v[178:179] op_sel_hi:[1,0]
	v_cvt_pk_bf16_f32 v128, v128, v129
	v_cvt_pk_bf16_f32 v129, v130, v131
	v_cvt_pk_bf16_f32 v131, v134, v135
	s_lshl_b32 s14, s79, 3
	v_cvt_pk_bf16_f32 v130, v132, v133
	ds_write_b128 v194, v[128:131] offset:64
	ds_read_b128 v[128:131], v162
	v_add_u32_e32 v132, s14, v152
	v_add_u32_e32 v136, s14, v132
	s_waitcnt lgkmcnt(3)
	global_store_dwordx4 v132, v[148:151], s[0:1] sc0 sc1
	ds_read_b128 v[132:135], v162 offset:1152
	s_waitcnt lgkmcnt(1)
	global_store_dwordx4 v136, v[128:131], s[0:1] sc0 sc1
	v_pk_mul_f32 v[122:123], v[122:123], v[176:177] op_sel_hi:[1,0]
	v_pk_mul_f32 v[120:121], v[120:121], v[176:177] op_sel_hi:[1,0]
	v_pk_mul_f32 v[128:129], v[114:115], v[176:177] op_sel_hi:[1,0]
	v_pk_mul_f32 v[114:115], v[112:113], v[176:177] op_sel_hi:[1,0]
	v_cvt_pk_bf16_f32 v112, v120, v121
	v_cvt_pk_bf16_f32 v113, v122, v123
	v_pk_mul_f32 v[118:119], v[118:119], v[176:177] op_sel_hi:[1,0]
	v_cvt_pk_bf16_f32 v114, v114, v115
	v_cvt_pk_bf16_f32 v115, v128, v129
	ds_write_b128 v194, v[112:115]
	v_pk_mul_f32 v[114:115], v[126:127], v[176:177] op_sel_hi:[1,0]
	v_pk_mul_f32 v[112:113], v[124:125], v[176:177] op_sel_hi:[1,0]
	v_pk_mul_f32 v[116:117], v[116:117], v[176:177] op_sel_hi:[1,0]
	v_cvt_pk_bf16_f32 v112, v112, v113
	v_cvt_pk_bf16_f32 v113, v114, v115
	v_cvt_pk_bf16_f32 v115, v118, v119
	v_pk_mul_f32 v[106:107], v[106:107], v[174:175] op_sel_hi:[1,0]
	v_cvt_pk_bf16_f32 v114, v116, v117
	ds_write_b128 v194, v[112:115] offset:64
	ds_read_b128 v[112:115], v162
	v_add_u32_e32 v116, s14, v136
	v_add_u32_e32 v120, s14, v116
	s_waitcnt lgkmcnt(3)
	global_store_dwordx4 v116, v[132:135], s[0:1] sc0 sc1
	ds_read_b128 v[116:119], v162 offset:1152
	s_waitcnt lgkmcnt(1)
	global_store_dwordx4 v120, v[112:115], s[0:1] sc0 sc1
	v_pk_mul_f32 v[104:105], v[104:105], v[174:175] op_sel_hi:[1,0]
	v_pk_mul_f32 v[102:103], v[102:103], v[174:175] op_sel_hi:[1,0]
	v_pk_mul_f32 v[112:113], v[98:99], v[174:175] op_sel_hi:[1,0]
	v_pk_mul_f32 v[98:99], v[96:97], v[174:175] op_sel_hi:[1,0]
	v_cvt_pk_bf16_f32 v96, v104, v105
	v_cvt_pk_bf16_f32 v97, v106, v107
	v_pk_mul_f32 v[100:101], v[100:101], v[174:175] op_sel_hi:[1,0]
	v_cvt_pk_bf16_f32 v98, v98, v99
	v_cvt_pk_bf16_f32 v99, v112, v113
	ds_write_b128 v194, v[96:99]
	v_pk_mul_f32 v[98:99], v[110:111], v[174:175] op_sel_hi:[1,0]
	v_pk_mul_f32 v[96:97], v[108:109], v[174:175] op_sel_hi:[1,0]
	s_nop 0
	v_cvt_pk_bf16_f32 v96, v96, v97
	v_cvt_pk_bf16_f32 v97, v98, v99
	v_cvt_pk_bf16_f32 v98, v100, v101
	v_cvt_pk_bf16_f32 v99, v102, v103
	ds_write_b128 v194, v[96:99] offset:64
	ds_read_b128 v[96:99], v162
	ds_read_b128 v[160:163], v162 offset:1152
	v_add_u32_e32 v100, s14, v120
	s_waitcnt lgkmcnt(4)
	global_store_dwordx4 v100, v[116:119], s[0:1] sc0 sc1
	v_add_u32_e32 v100, s14, v100
	v_add_u32_e32 v164, s14, v100
	s_waitcnt lgkmcnt(1)
	global_store_dwordx4 v100, v[96:99], s[0:1] sc0 sc1
.LBB0_238:
	s_waitcnt lgkmcnt(0)
	global_store_dwordx4 v164, v[160:163], s[0:1] sc0 sc1
	ds_read_b128 v[96:99], v193 offset:49152
	ds_read_b128 v[100:103], v193 offset:50176
	ds_read_b128 v[104:107], v192 offset:49152
	ds_read_b128 v[108:111], v192 offset:50176
	ds_read_b128 v[112:115], v191 offset:49152
	ds_read_b128 v[116:119], v191 offset:50176
	ds_read_b128 v[120:123], v190 offset:49152
	ds_read_b128 v[124:127], v190 offset:50176
	s_barrier
	s_waitcnt lgkmcnt(0)
	s_setprio 1
	s_waitcnt lgkmcnt(0)
	v_mfma_f32_16x16x32_bf16 v[32:35], v[12:15], v[96:99], v[32:35]
	v_mfma_f32_16x16x32_bf16 v[36:39], v[76:79], v[96:99], v[36:39]
	v_mfma_f32_16x16x32_bf16 v[40:43], v[12:15], v[104:107], v[40:43]
	v_mfma_f32_16x16x32_bf16 v[128:131], v[76:79], v[104:107], v[44:47]
	v_mfma_f32_16x16x32_bf16 v[48:51], v[12:15], v[112:115], v[48:51]
	v_mfma_f32_16x16x32_bf16 v[52:55], v[76:79], v[112:115], v[52:55]
	v_mfma_f32_16x16x32_bf16 v[12:15], v[12:15], v[120:123], v[56:59]
	v_mfma_f32_16x16x32_bf16 v[76:79], v[76:79], v[120:123], v[60:63]
	v_mfma_f32_16x16x32_bf16 v[60:63], v[8:11], v[100:103], v[32:35]
	v_mfma_f32_16x16x32_bf16 v[56:59], v[72:75], v[100:103], v[36:39]
	v_mfma_f32_16x16x32_bf16 v[44:47], v[8:11], v[108:111], v[40:43]
	v_mfma_f32_16x16x32_bf16 v[40:43], v[72:75], v[108:111], v[128:131]
	v_mfma_f32_16x16x32_bf16 v[36:39], v[8:11], v[116:119], v[48:51]
	v_mfma_f32_16x16x32_bf16 v[32:35], v[72:75], v[116:119], v[52:55]
	v_mfma_f32_16x16x32_bf16 v[12:15], v[8:11], v[124:127], v[12:15]
	v_mfma_f32_16x16x32_bf16 v[8:11], v[72:75], v[124:127], v[76:79]
	s_setprio 0
	s_setprio 1
	v_mfma_f32_16x16x32_bf16 v[0:3], v[88:91], v[96:99], v[0:3]
	v_mfma_f32_16x16x32_bf16 v[4:7], v[92:95], v[96:99], v[4:7]
	v_mfma_f32_16x16x32_bf16 v[16:19], v[88:91], v[104:107], v[16:19]
	v_mfma_f32_16x16x32_bf16 v[20:23], v[92:95], v[104:107], v[20:23]
	v_mfma_f32_16x16x32_bf16 v[72:75], v[88:91], v[112:115], v[24:27]
	v_mfma_f32_16x16x32_bf16 v[76:79], v[92:95], v[112:115], v[28:31]
	v_mfma_f32_16x16x32_bf16 v[64:67], v[88:91], v[120:123], v[64:67]
	v_mfma_f32_16x16x32_bf16 v[68:71], v[92:95], v[120:123], v[68:71]
	v_mfma_f32_16x16x32_bf16 v[52:55], v[80:83], v[100:103], v[0:3]
	v_mfma_f32_16x16x32_bf16 v[48:51], v[84:87], v[100:103], v[4:7]
	v_mfma_f32_16x16x32_bf16 v[28:31], v[80:83], v[108:111], v[16:19]
	v_mfma_f32_16x16x32_bf16 v[24:27], v[84:87], v[108:111], v[20:23]
	v_mfma_f32_16x16x32_bf16 v[20:23], v[80:83], v[116:119], v[72:75]
	v_mfma_f32_16x16x32_bf16 v[16:19], v[84:87], v[116:119], v[76:79]
	v_mfma_f32_16x16x32_bf16 v[4:7], v[80:83], v[124:127], v[64:67]
	v_mfma_f32_16x16x32_bf16 v[0:3], v[84:87], v[124:127], v[68:71]
	s_setprio 0
	v_cmp_gt_u32_e32 vcc, s73, v179
	s_barrier
	s_and_saveexec_b64 s[60:61], vcc
	s_cbranch_execz .LBB0_240
	s_barrier

.LBB0_244:
	v_mbcnt_lo_u32_b32 v69, -1, 0
	v_mbcnt_hi_u32_b32 v69, -1, v69
	s_and_b64 vcc, exec, s[58:59]
	v_add_u32_e32 v64, s64, v69
	v_bfe_u32 v68, v64, 8, 1
	v_ashrrev_i32_e32 v73, 6, v64
	v_bfe_u32 v64, v69, 4, 2
	v_and_b32_e32 v71, 3, v73
	v_and_b32_e32 v70, 15, v69
	v_lshlrev_b32_e32 v72, 4, v64
	s_cbranch_vccz .LBB0_247
	s_lshl_b32 s57, s82, 14
	s_lshl_b32 s58, s80, 22
	s_add_i32 s57, s57, s58
	v_lshlrev_b32_e32 v64, 6, v70
	v_or3_b32 v64, s57, v64, v72
	v_lshl_add_u32 v64, v71, 20, v64
	v_lshl_or_b32 v164, v68, 12, v64
	s_waitcnt vmcnt(0)
	v_pk_mul_f32 v[64:65], v[172:173], v[58:59] op_sel_hi:[0,1]
	v_pk_mul_f32 v[66:67], v[172:173], v[56:57] op_sel_hi:[0,1]
	v_max_f32_e32 v66, 0, v66
	v_max_f32_e32 v64, 0, v64
	v_mul_f32_e32 v74, v66, v66
	v_max_f32_e32 v66, 0, v67
	v_mul_f32_e32 v76, v64, v64
	v_max_f32_e32 v64, 0, v65
	v_mul_f32_e32 v75, v66, v66
	v_mul_f32_e32 v77, v64, v64
	v_pk_mul_f32 v[64:65], v[172:173], v[62:63] op_sel_hi:[0,1]
	v_pk_mul_f32 v[66:67], v[172:173], v[60:61] op_sel_hi:[0,1]
	v_max_f32_e32 v66, 0, v66
	v_max_f32_e32 v64, 0, v64
	v_mul_f32_e32 v66, v66, v66
	v_max_f32_e32 v67, 0, v67
	v_mul_f32_e32 v78, v64, v64
	v_max_f32_e32 v64, 0, v65
	v_mul_f32_e32 v67, v67, v67
	v_mul_f32_e32 v65, v64, v64
	v_cvt_pk_bf16_f32 v64, v66, v67
	v_cvt_pk_bf16_f32 v66, v74, v75
	v_lshl_add_u64 v[74:75], s[0:1], 0, v[164:165]
	v_cvt_pk_bf16_f32 v67, v76, v77
	v_add_co_u32_e32 v76, vcc, s68, v74
	v_cvt_pk_bf16_f32 v65, v78, v65
	s_nop 1
	v_addc_co_u32_e32 v77, vcc, 0, v75, vcc
	global_store_dwordx4 v[76:77], v[64:67], off sc0 sc1
	v_add_co_u32_e32 v74, vcc, s77, v74
	s_nop 0
	v_pk_mul_f32 v[64:65], v[172:173], v[50:51] op_sel_hi:[0,1]
	v_max_f32_e32 v64, 0, v64
	v_pk_mul_f32 v[66:67], v[172:173], v[48:49] op_sel_hi:[0,1]
	v_mul_f32_e32 v80, v64, v64
	v_max_f32_e32 v64, 0, v65
	v_max_f32_e32 v66, 0, v66
	v_mul_f32_e32 v81, v64, v64
	v_pk_mul_f32 v[64:65], v[172:173], v[54:55] op_sel_hi:[0,1]
	v_mul_f32_e32 v78, v66, v66
	v_max_f32_e32 v66, 0, v67
	v_max_f32_e32 v64, 0, v64
	v_mul_f32_e32 v79, v66, v66
	v_pk_mul_f32 v[66:67], v[172:173], v[52:53] op_sel_hi:[0,1]
	v_mul_f32_e32 v82, v64, v64
	v_max_f32_e32 v64, 0, v65
	v_max_f32_e32 v66, 0, v66
	v_max_f32_e32 v67, 0, v67
	v_mul_f32_e32 v65, v64, v64
	v_mul_f32_e32 v66, v66, v66
	v_mul_f32_e32 v67, v67, v67
	v_cvt_pk_bf16_f32 v64, v66, v67
	v_cvt_pk_bf16_f32 v65, v82, v65
	v_addc_co_u32_e32 v75, vcc, 0, v75, vcc
	v_cvt_pk_bf16_f32 v66, v78, v79
	v_cvt_pk_bf16_f32 v67, v80, v81
	global_store_dwordx4 v[74:75], v[64:67], off sc0 sc1
	s_nop 1
	v_pk_mul_f32 v[64:65], v[170:171], v[42:43] op_sel_hi:[0,1]
	v_max_f32_e32 v64, 0, v64
	v_pk_mul_f32 v[66:67], v[170:171], v[40:41] op_sel_hi:[0,1]
	v_mul_f32_e32 v80, v64, v64
	v_max_f32_e32 v64, 0, v65
	v_max_f32_e32 v66, 0, v66
	v_mul_f32_e32 v81, v64, v64
	v_pk_mul_f32 v[64:65], v[170:171], v[46:47] op_sel_hi:[0,1]
	v_mul_f32_e32 v78, v66, v66
	v_max_f32_e32 v66, 0, v67
	v_max_f32_e32 v64, 0, v64
	v_mul_f32_e32 v79, v66, v66
	v_pk_mul_f32 v[66:67], v[170:171], v[44:45] op_sel_hi:[0,1]
	v_mul_f32_e32 v82, v64, v64
	v_max_f32_e32 v64, 0, v65
	v_max_f32_e32 v66, 0, v66
	v_max_f32_e32 v67, 0, v67
	v_mul_f32_e32 v65, v64, v64
	v_mul_f32_e32 v66, v66, v66
	v_mul_f32_e32 v67, v67, v67
	v_cvt_pk_bf16_f32 v64, v66, v67
	v_cvt_pk_bf16_f32 v65, v82, v65
	v_cvt_pk_bf16_f32 v66, v78, v79
	v_cvt_pk_bf16_f32 v67, v80, v81
	global_store_dwordx4 v[76:77], v[64:67], off offset:1024 sc0 sc1
	s_nop 1
	v_pk_mul_f32 v[64:65], v[170:171], v[26:27] op_sel_hi:[0,1]
	v_max_f32_e32 v64, 0, v64
	v_pk_mul_f32 v[66:67], v[170:171], v[24:25] op_sel_hi:[0,1]
	v_mul_f32_e32 v80, v64, v64
	v_max_f32_e32 v64, 0, v65
	v_max_f32_e32 v66, 0, v66
	v_mul_f32_e32 v81, v64, v64
	v_pk_mul_f32 v[64:65], v[170:171], v[30:31] op_sel_hi:[0,1]
	v_mul_f32_e32 v78, v66, v66
	v_max_f32_e32 v66, 0, v67
	v_max_f32_e32 v64, 0, v64
	v_mul_f32_e32 v79, v66, v66
	v_pk_mul_f32 v[66:67], v[170:171], v[28:29] op_sel_hi:[0,1]
	v_mul_f32_e32 v82, v64, v64
	v_max_f32_e32 v64, 0, v65
	v_max_f32_e32 v66, 0, v66
	v_max_f32_e32 v67, 0, v67
	v_mul_f32_e32 v65, v64, v64
	v_mul_f32_e32 v66, v66, v66
	v_mul_f32_e32 v67, v67, v67
	v_cvt_pk_bf16_f32 v64, v66, v67
	v_cvt_pk_bf16_f32 v65, v82, v65
	v_cvt_pk_bf16_f32 v66, v78, v79
	v_cvt_pk_bf16_f32 v67, v80, v81
	global_store_dwordx4 v[74:75], v[64:67], off offset:1024 sc0 sc1
	s_nop 1
	v_pk_mul_f32 v[64:65], v[168:169], v[34:35] op_sel_hi:[0,1]
	v_max_f32_e32 v64, 0, v64
	v_pk_mul_f32 v[66:67], v[168:169], v[32:33] op_sel_hi:[0,1]
	v_mul_f32_e32 v80, v64, v64
	v_max_f32_e32 v64, 0, v65
	v_max_f32_e32 v66, 0, v66
	v_mul_f32_e32 v81, v64, v64
	v_pk_mul_f32 v[64:65], v[168:169], v[38:39] op_sel_hi:[0,1]
	v_mul_f32_e32 v78, v66, v66
	v_max_f32_e32 v66, 0, v67
	v_max_f32_e32 v64, 0, v64
	v_mul_f32_e32 v79, v66, v66
	v_pk_mul_f32 v[66:67], v[168:169], v[36:37] op_sel_hi:[0,1]
	v_mul_f32_e32 v82, v64, v64
	v_max_f32_e32 v64, 0, v65
	v_max_f32_e32 v66, 0, v66
	v_max_f32_e32 v67, 0, v67
	v_mul_f32_e32 v65, v64, v64
	v_mul_f32_e32 v66, v66, v66
	v_mul_f32_e32 v67, v67, v67
	v_cvt_pk_bf16_f32 v64, v66, v67
	v_cvt_pk_bf16_f32 v65, v82, v65
	v_cvt_pk_bf16_f32 v66, v78, v79
	v_cvt_pk_bf16_f32 v67, v80, v81
	global_store_dwordx4 v[76:77], v[64:67], off offset:2048 sc0 sc1
	s_nop 1
	v_pk_mul_f32 v[64:65], v[168:169], v[18:19] op_sel_hi:[0,1]
	v_max_f32_e32 v64, 0, v64
	v_pk_mul_f32 v[66:67], v[168:169], v[16:17] op_sel_hi:[0,1]
	v_mul_f32_e32 v80, v64, v64
	v_max_f32_e32 v64, 0, v65
	v_max_f32_e32 v66, 0, v66
	v_mul_f32_e32 v81, v64, v64
	v_pk_mul_f32 v[64:65], v[168:169], v[22:23] op_sel_hi:[0,1]
	v_mul_f32_e32 v78, v66, v66
	v_max_f32_e32 v66, 0, v67
	v_max_f32_e32 v64, 0, v64
	v_mul_f32_e32 v79, v66, v66
	v_pk_mul_f32 v[66:67], v[168:169], v[20:21] op_sel_hi:[0,1]
	v_mul_f32_e32 v82, v64, v64
	v_max_f32_e32 v64, 0, v65
	v_max_f32_e32 v66, 0, v66
	v_max_f32_e32 v67, 0, v67
	v_mul_f32_e32 v65, v64, v64
	v_mul_f32_e32 v66, v66, v66
	v_mul_f32_e32 v67, v67, v67
	v_cvt_pk_bf16_f32 v64, v66, v67
	v_cvt_pk_bf16_f32 v65, v82, v65
	v_cvt_pk_bf16_f32 v66, v78, v79
	v_cvt_pk_bf16_f32 v67, v80, v81
	global_store_dwordx4 v[74:75], v[64:67], off offset:2048 sc0 sc1
	s_nop 1
	v_pk_mul_f32 v[64:65], v[166:167], v[10:11] op_sel_hi:[0,1]
	v_max_f32_e32 v64, 0, v64
	v_pk_mul_f32 v[66:67], v[166:167], v[8:9] op_sel_hi:[0,1]
	v_mul_f32_e32 v78, v64, v64
	v_max_f32_e32 v64, 0, v65
	v_max_f32_e32 v66, 0, v66
	v_mul_f32_e32 v79, v64, v64
	v_pk_mul_f32 v[64:65], v[166:167], v[14:15] op_sel_hi:[0,1]
	v_mul_f32_e32 v74, v66, v66
	v_max_f32_e32 v66, 0, v67
	v_max_f32_e32 v64, 0, v64
	v_mul_f32_e32 v75, v66, v66
	v_pk_mul_f32 v[66:67], v[166:167], v[12:13] op_sel_hi:[0,1]
	v_mul_f32_e32 v80, v64, v64
	v_max_f32_e32 v64, 0, v65
	v_max_f32_e32 v66, 0, v66
	v_max_f32_e32 v67, 0, v67
	v_mul_f32_e32 v65, v64, v64
	v_mul_f32_e32 v66, v66, v66
	v_mul_f32_e32 v67, v67, v67
	v_cvt_pk_bf16_f32 v64, v66, v67
	v_cvt_pk_bf16_f32 v65, v80, v65
	v_cvt_pk_bf16_f32 v66, v74, v75
	v_cvt_pk_bf16_f32 v67, v78, v79
	global_store_dwordx4 v[76:77], v[64:67], off offset:3072 sc0 sc1
	s_nop 1
	v_pk_mul_f32 v[64:65], v[166:167], v[2:3] op_sel_hi:[0,1]
	v_pk_mul_f32 v[66:67], v[166:167], v[0:1] op_sel_hi:[0,1]
	v_max_f32_e32 v64, 0, v64
	v_max_f32_e32 v66, 0, v66
	v_mul_f32_e32 v76, v64, v64
	v_max_f32_e32 v64, 0, v65
	v_mul_f32_e32 v74, v66, v66
	v_max_f32_e32 v66, 0, v67
	v_mul_f32_e32 v77, v64, v64
	v_pk_mul_f32 v[64:65], v[166:167], v[6:7] op_sel_hi:[0,1]
	v_mul_f32_e32 v75, v66, v66
	v_pk_mul_f32 v[66:67], v[166:167], v[4:5] op_sel_hi:[0,1]
	v_max_f32_e32 v64, 0, v64
	v_max_f32_e32 v66, 0, v66
	v_max_f32_e32 v67, 0, v67
	v_mul_f32_e32 v78, v64, v64
	v_max_f32_e32 v64, 0, v65
	v_mul_f32_e32 v66, v66, v66
	v_mul_f32_e32 v67, v67, v67
	v_mul_f32_e32 v65, v64, v64
	v_cvt_pk_bf16_f32 v64, v66, v67
	v_cvt_pk_bf16_f32 v65, v78, v65
	v_cvt_pk_bf16_f32 v66, v74, v75
	v_cvt_pk_bf16_f32 v67, v76, v77
	v_add_u32_e32 v74, 0x82c00, v164
	s_cbranch_execnz .LBB0_222
	s_branch .LBB0_221

.LBB0_262:
	v_mbcnt_lo_u32_b32 v64, -1, 0
	v_mbcnt_hi_u32_b32 v64, -1, v64
	v_cvt_pk_bf16_f32 v56, v56, v57
	v_cvt_pk_bf16_f32 v57, v58, v59
	v_cvt_pk_bf16_f32 v58, v48, v49
	v_cvt_pk_bf16_f32 v59, v50, v51
	v_cvt_pk_bf16_f32 v48, v60, v61
	s_nop 0
	v_add_u32_e32 v65, s72, v64
	v_ashrrev_i32_e32 v66, 6, v65
	v_and_b32_e32 v67, 15, v64
	v_and_b32_e32 v68, 48, v64
	v_mul_lo_u32 v69, v66, s77
	v_lshrrev_b32_e32 v65, 2, v65
	v_bfe_u32 v70, v64, 3, 3
	v_lshlrev_b32_e32 v64, 4, v64
	v_add_u32_e32 v69, 0x20000, v69
	v_and_b32_e32 v65, 64, v65
	v_and_b32_e32 v64, 0x70, v64
	v_mul_u32_u24_e32 v67, 0x90, v67
	v_add3_u32 v67, v69, v67, v68
	v_or_b32_e32 v68, v69, v64
	v_or3_b32 v65, s97, v65, v70
	v_lshlrev_b32_e32 v66, 7, v66
	v_mad_u32_u24 v68, v70, s79, v68
	ds_write_b128 v67, v[56:59]
	v_cvt_pk_bf16_f32 v49, v62, v63
	v_cvt_pk_bf16_f32 v50, v52, v53
	v_cvt_pk_bf16_f32 v51, v54, v55
	ds_write_b128 v67, v[48:51] offset:64
	v_lshlrev_b32_e32 v52, 12, v65
	ds_read_b128 v[48:51], v68
	v_and_or_b32 v52, v66, s80, v52
	v_or3_b32 v128, v52, s89, v64
	v_lshl_add_u64 v[56:57], s[0:1], 0, v[128:129]
	v_add_co_u32_e32 v58, vcc, s91, v56
	ds_read_b128 v[52:55], v68 offset:1152
	v_cvt_pk_bf16_f32 v44, v44, v45
	v_cvt_pk_bf16_f32 v45, v46, v47
	v_cvt_pk_bf16_f32 v46, v40, v41
	v_cvt_pk_bf16_f32 v47, v42, v43
	ds_write_b128 v67, v[44:47]
	v_cvt_pk_bf16_f32 v28, v28, v29
	v_cvt_pk_bf16_f32 v29, v30, v31
	v_cvt_pk_bf16_f32 v30, v24, v25
	v_cvt_pk_bf16_f32 v31, v26, v27
	ds_write_b128 v67, v[28:31] offset:64
	v_addc_co_u32_e32 v59, vcc, 0, v57, vcc
	ds_read_b128 v[24:27], v68
	ds_read_b128 v[28:31], v68 offset:1152
	s_waitcnt lgkmcnt(0)
	global_store_dwordx4 v[58:59], v[48:51], off sc0 sc1
	v_cvt_pk_bf16_f32 v20, v20, v21
	v_cvt_pk_bf16_f32 v21, v22, v23
	v_cvt_pk_bf16_f32 v22, v16, v17
	v_cvt_pk_bf16_f32 v23, v18, v19
	ds_write_b128 v67, v[20:23] offset:64
	s_nop 0
	v_add_co_u32_e32 v48, vcc, s92, v56
	v_cvt_pk_bf16_f32 v8, v8, v9
	v_cvt_pk_bf16_f32 v9, v10, v11
	v_cvt_pk_bf16_f32 v10, v0, v1
	v_cvt_pk_bf16_f32 v11, v2, v3
	s_nop 1
	v_addc_co_u32_e32 v49, vcc, 0, v57, vcc
	v_add_co_u32_e32 v40, vcc, s93, v56
	v_cvt_pk_bf16_f32 v0, v12, v13
	v_cvt_pk_bf16_f32 v1, v14, v15
	v_cvt_pk_bf16_f32 v2, v4, v5
	v_cvt_pk_bf16_f32 v3, v6, v7
	s_nop 1
	v_addc_co_u32_e32 v41, vcc, 0, v57, vcc
	global_store_dwordx4 v[40:41], v[24:27], off sc0 sc1
	s_add_i32 s76, s76, 1
	global_store_dwordx4 v[48:49], v[52:55], off sc0 sc1
	v_add_co_u32_e32 v24, vcc, s94, v56
	v_cvt_pk_bf16_f32 v26, v32, v33
	v_cvt_pk_bf16_f32 v27, v34, v35
	s_nop 1
	v_addc_co_u32_e32 v25, vcc, 0, v57, vcc
	global_store_dwordx4 v[24:25], v[28:31], off sc0 sc1
	v_cvt_pk_bf16_f32 v24, v36, v37
	v_cvt_pk_bf16_f32 v25, v38, v39
	ds_write_b128 v67, v[24:27]
	ds_read_b128 v[16:19], v68
	ds_read_b128 v[20:23], v68 offset:1152
	v_add_co_u32_e32 v24, vcc, s95, v56
	ds_write_b128 v67, v[8:11]
	ds_write_b128 v67, v[0:3] offset:64
	v_addc_co_u32_e32 v25, vcc, 0, v57, vcc
	ds_read_b128 v[0:3], v68
	ds_read_b128 v[4:7], v68 offset:1152
	s_waitcnt lgkmcnt(0)
	global_store_dwordx4 v[24:25], v[16:19], off sc0 sc1
	s_nop 1
	v_add_co_u32_e32 v16, vcc, s96, v56
	s_nop 1
	v_addc_co_u32_e32 v17, vcc, 0, v57, vcc
	v_add_co_u32_e32 v8, vcc, 0xb0000, v56
	global_store_dwordx4 v[16:17], v[20:23], off sc0 sc1
	s_nop 0
	v_addc_co_u32_e32 v9, vcc, 0, v57, vcc
	global_store_dwordx4 v[8:9], v[0:3], off sc0 sc1
	s_nop 1
	v_add_co_u32_e32 v0, vcc, 0xb8000, v56
	s_nop 1
	v_addc_co_u32_e32 v1, vcc, 0, v57, vcc
	s_andn2_b64 vcc, exec, s[64:65]
	s_mov_b64 s[64:65], 0
	global_store_dwordx4 v[0:1], v[4:7], off sc0 sc1
	s_cbranch_vccz .LBB0_281

.LBB0_274:
	ds_read_b128 v[162:165], v161
	ds_read_b128 v[166:169], v161 offset:1024
	ds_read_b128 v[170:173], v161 offset:2048
	ds_read_b128 v[174:177], v161 offset:3072
	s_mov_b32 vcc_lo, 0xffe01000
	s_mov_b32 vcc_hi, -1
	v_lshl_add_u64 v[210:211], v[132:133], 0, vcc
	v_readfirstlane_b32 s67, v160
	s_mov_b32 vcc_lo, 0xffe02000
	s_mov_b32 m0, s67
	s_mov_b32 vcc_hi, -1
	v_readfirstlane_b32 s67, v159
	ds_read_b128 v[178:181], v152
	ds_read_b128 v[182:185], v152 offset:1024
	ds_read_b128 v[186:189], v151
	ds_read_b128 v[190:193], v151 offset:1024
	ds_read_b128 v[194:197], v150
	ds_read_b128 v[198:201], v150 offset:1024
	ds_read_b128 v[202:205], v149
	ds_read_b128 v[206:209], v149 offset:1024
	global_load_lds_dwordx4 v[210:211], off
	v_lshl_add_u64 v[210:211], v[132:133], 0, vcc
	s_mov_b32 m0, s67
	s_nop 0
	global_load_lds_dwordx4 v[210:211], off
	s_waitcnt lgkmcnt(8)
	s_barrier
	s_waitcnt lgkmcnt(0)
	s_setprio 1
	s_waitcnt lgkmcnt(0)
	v_mfma_f32_16x16x32_bf16 v[124:127], v[162:165], v[178:181], v[124:127]
	v_mfma_f32_16x16x32_bf16 v[120:123], v[170:173], v[178:181], v[120:123]
	v_mfma_f32_16x16x32_bf16 v[116:119], v[162:165], v[186:189], v[116:119]
	v_mfma_f32_16x16x32_bf16 v[112:115], v[170:173], v[186:189], v[112:115]
	v_mfma_f32_16x16x32_bf16 v[108:111], v[162:165], v[194:197], v[108:111]
	v_mfma_f32_16x16x32_bf16 v[104:107], v[170:173], v[194:197], v[104:107]
	v_mfma_f32_16x16x32_bf16 v[100:103], v[162:165], v[202:205], v[100:103]
	v_mfma_f32_16x16x32_bf16 v[96:99], v[170:173], v[202:205], v[96:99]
	v_mfma_f32_16x16x32_bf16 v[124:127], v[166:169], v[182:185], v[124:127]
	v_mfma_f32_16x16x32_bf16 v[120:123], v[174:177], v[182:185], v[120:123]
	v_mfma_f32_16x16x32_bf16 v[116:119], v[166:169], v[190:193], v[116:119]
	v_mfma_f32_16x16x32_bf16 v[112:115], v[174:177], v[190:193], v[112:115]
	v_mfma_f32_16x16x32_bf16 v[108:111], v[166:169], v[198:201], v[108:111]
	v_mfma_f32_16x16x32_bf16 v[104:107], v[174:177], v[198:201], v[104:107]
	v_mfma_f32_16x16x32_bf16 v[100:103], v[166:169], v[206:209], v[100:103]
	v_mfma_f32_16x16x32_bf16 v[96:99], v[174:177], v[206:209], v[96:99]
	s_setprio 0
	s_barrier
	s_mov_b32 vcc_lo, 0xfffbd000
	s_mov_b32 vcc_hi, -1
	v_readfirstlane_b32 s67, v148
	v_lshl_add_u64 v[226:227], v[130:131], 0, vcc
	s_mov_b32 m0, s67
	v_readfirstlane_b32 s67, v147
	ds_read_b128 v[210:213], v158
	ds_read_b128 v[214:217], v158 offset:1024
	ds_read_b128 v[218:221], v158 offset:2048
	ds_read_b128 v[222:225], v158 offset:3072
	global_load_lds_dwordx4 v[226:227], off
	v_lshl_add_u64 v[226:227], v[130:131], 0, s[22:23]
	s_mov_b32 m0, s67
	s_add_i32 s66, s66, 2
	global_load_lds_dwordx4 v[226:227], off
	s_barrier
	s_waitcnt lgkmcnt(0)
	s_setprio 1
	s_waitcnt lgkmcnt(0)
	v_mfma_f32_16x16x32_bf16 v[92:95], v[210:213], v[178:181], v[92:95]
	v_mfma_f32_16x16x32_bf16 v[88:91], v[218:221], v[178:181], v[88:91]
	v_mfma_f32_16x16x32_bf16 v[84:87], v[210:213], v[186:189], v[84:87]
	v_mfma_f32_16x16x32_bf16 v[80:83], v[218:221], v[186:189], v[80:83]
	v_mfma_f32_16x16x32_bf16 v[76:79], v[210:213], v[194:197], v[76:79]
	v_mfma_f32_16x16x32_bf16 v[72:75], v[218:221], v[194:197], v[72:75]
	v_mfma_f32_16x16x32_bf16 v[68:71], v[210:213], v[202:205], v[68:71]
	v_mfma_f32_16x16x32_bf16 v[64:67], v[218:221], v[202:205], v[64:67]
	v_mfma_f32_16x16x32_bf16 v[92:95], v[214:217], v[182:185], v[92:95]
	v_mfma_f32_16x16x32_bf16 v[88:91], v[222:225], v[182:185], v[88:91]
	v_mfma_f32_16x16x32_bf16 v[84:87], v[214:217], v[190:193], v[84:87]
	v_mfma_f32_16x16x32_bf16 v[80:83], v[222:225], v[190:193], v[80:83]
	v_mfma_f32_16x16x32_bf16 v[76:79], v[214:217], v[198:201], v[76:79]
	v_mfma_f32_16x16x32_bf16 v[72:75], v[222:225], v[198:201], v[72:75]
	v_mfma_f32_16x16x32_bf16 v[68:71], v[214:217], v[206:209], v[68:71]
	v_mfma_f32_16x16x32_bf16 v[64:67], v[222:225], v[206:209], v[64:67]
	s_setprio 0
	v_readfirstlane_b32 s67, v134
	v_lshl_add_u64 v[226:227], v[132:133], 0, s[24:25]
	s_mov_b32 m0, s67
	v_readfirstlane_b32 s67, v146
	s_barrier
	ds_read_b128 v[178:181], v152 offset:16384
	ds_read_b128 v[182:185], v152 offset:17408
	ds_read_b128 v[186:189], v151 offset:16384
	ds_read_b128 v[190:193], v151 offset:17408
	ds_read_b128 v[194:197], v150 offset:16384
	ds_read_b128 v[198:201], v150 offset:17408
	ds_read_b128 v[202:205], v149 offset:16384
	ds_read_b128 v[206:209], v149 offset:17408
	global_load_lds_dwordx4 v[226:227], off
	v_lshl_add_u64 v[226:227], v[132:133], 0, s[26:27]
	s_mov_b32 m0, s67
	s_nop 0
	global_load_lds_dwordx4 v[226:227], off
	s_barrier
	s_waitcnt lgkmcnt(0)
	s_setprio 1
	s_waitcnt lgkmcnt(0)
	v_mfma_f32_16x16x32_bf16 v[60:63], v[162:165], v[178:181], v[60:63]
	v_mfma_f32_16x16x32_bf16 v[56:59], v[170:173], v[178:181], v[56:59]
	v_mfma_f32_16x16x32_bf16 v[52:55], v[162:165], v[186:189], v[52:55]
	v_mfma_f32_16x16x32_bf16 v[48:51], v[170:173], v[186:189], v[48:51]
	v_mfma_f32_16x16x32_bf16 v[44:47], v[162:165], v[194:197], v[44:47]
	v_mfma_f32_16x16x32_bf16 v[40:43], v[170:173], v[194:197], v[40:43]
	v_mfma_f32_16x16x32_bf16 v[36:39], v[162:165], v[202:205], v[36:39]
	v_mfma_f32_16x16x32_bf16 v[32:35], v[170:173], v[202:205], v[32:35]
	v_mfma_f32_16x16x32_bf16 v[60:63], v[166:169], v[182:185], v[60:63]
	v_mfma_f32_16x16x32_bf16 v[56:59], v[174:177], v[182:185], v[56:59]
	v_mfma_f32_16x16x32_bf16 v[52:55], v[166:169], v[190:193], v[52:55]
	v_mfma_f32_16x16x32_bf16 v[48:51], v[174:177], v[190:193], v[48:51]
	v_mfma_f32_16x16x32_bf16 v[44:47], v[166:169], v[198:201], v[44:47]
	v_mfma_f32_16x16x32_bf16 v[40:43], v[174:177], v[198:201], v[40:43]
	v_mfma_f32_16x16x32_bf16 v[36:39], v[166:169], v[206:209], v[36:39]
	v_mfma_f32_16x16x32_bf16 v[32:35], v[174:177], v[206:209], v[32:35]
	s_setprio 0
	s_barrier
	v_readfirstlane_b32 s67, v145
	v_lshl_add_u64 v[162:163], v[130:131], 0, s[28:29]
	s_mov_b32 m0, s67
	v_readfirstlane_b32 s67, v144
	global_load_lds_dwordx4 v[162:163], off
	v_lshl_add_u64 v[162:163], v[130:131], 0, s[30:31]
	s_mov_b32 m0, s67
	s_nop 0
	global_load_lds_dwordx4 v[162:163], off
	s_waitcnt vmcnt(6)
	s_barrier
	s_setprio 1
	v_mfma_f32_16x16x32_bf16 v[28:31], v[210:213], v[178:181], v[28:31]
	v_mfma_f32_16x16x32_bf16 v[24:27], v[218:221], v[178:181], v[24:27]
	v_mfma_f32_16x16x32_bf16 v[20:23], v[210:213], v[186:189], v[20:23]
	v_mfma_f32_16x16x32_bf16 v[16:19], v[218:221], v[186:189], v[16:19]
	v_mfma_f32_16x16x32_bf16 v[12:15], v[210:213], v[194:197], v[12:15]
	v_mfma_f32_16x16x32_bf16 v[8:11], v[218:221], v[194:197], v[8:11]
	v_mfma_f32_16x16x32_bf16 v[4:7], v[210:213], v[202:205], v[4:7]
	v_mfma_f32_16x16x32_bf16 v[0:3], v[218:221], v[202:205], v[0:3]
	v_mfma_f32_16x16x32_bf16 v[28:31], v[214:217], v[182:185], v[28:31]
	v_mfma_f32_16x16x32_bf16 v[24:27], v[222:225], v[182:185], v[24:27]
	v_mfma_f32_16x16x32_bf16 v[20:23], v[214:217], v[190:193], v[20:23]
	v_mfma_f32_16x16x32_bf16 v[16:19], v[222:225], v[190:193], v[16:19]
	v_mfma_f32_16x16x32_bf16 v[12:15], v[214:217], v[198:201], v[12:15]
	v_mfma_f32_16x16x32_bf16 v[8:11], v[222:225], v[198:201], v[8:11]
	v_mfma_f32_16x16x32_bf16 v[4:7], v[214:217], v[206:209], v[4:7]
	v_mfma_f32_16x16x32_bf16 v[0:3], v[222:225], v[206:209], v[0:3]
	s_setprio 0
	s_barrier
	ds_read_b128 v[162:165], v154
	ds_read_b128 v[166:169], v154 offset:1024
	ds_read_b128 v[170:173], v154 offset:2048
	ds_read_b128 v[174:177], v154 offset:3072
	v_readfirstlane_b32 s67, v143
	v_lshl_add_u64 v[210:211], v[132:133], 0, s[34:35]
	s_mov_b32 m0, s67
	v_readfirstlane_b32 s67, v142
	ds_read_b128 v[178:181], v152 offset:32768
	ds_read_b128 v[182:185], v152 offset:33792
	ds_read_b128 v[186:189], v151 offset:32768
	ds_read_b128 v[190:193], v151 offset:33792
	ds_read_b128 v[194:197], v150 offset:32768
	ds_read_b128 v[198:201], v150 offset:33792
	ds_read_b128 v[202:205], v149 offset:32768
	ds_read_b128 v[206:209], v149 offset:33792
	global_load_lds_dwordx4 v[210:211], off
	v_lshl_add_u64 v[210:211], v[132:133], 0, s[44:45]
	s_mov_b32 m0, s67
	s_nop 0
	global_load_lds_dwordx4 v[210:211], off
	s_waitcnt lgkmcnt(8)
	s_barrier
	s_waitcnt lgkmcnt(0)
	s_setprio 1
	s_waitcnt lgkmcnt(0)
	v_mfma_f32_16x16x32_bf16 v[124:127], v[162:165], v[178:181], v[124:127]
	v_mfma_f32_16x16x32_bf16 v[120:123], v[170:173], v[178:181], v[120:123]
	v_mfma_f32_16x16x32_bf16 v[116:119], v[162:165], v[186:189], v[116:119]
	v_mfma_f32_16x16x32_bf16 v[112:115], v[170:173], v[186:189], v[112:115]
	v_mfma_f32_16x16x32_bf16 v[108:111], v[162:165], v[194:197], v[108:111]
	v_mfma_f32_16x16x32_bf16 v[104:107], v[170:173], v[194:197], v[104:107]
	v_mfma_f32_16x16x32_bf16 v[100:103], v[162:165], v[202:205], v[100:103]
	v_mfma_f32_16x16x32_bf16 v[96:99], v[170:173], v[202:205], v[96:99]
	v_mfma_f32_16x16x32_bf16 v[124:127], v[166:169], v[182:185], v[124:127]
	v_mfma_f32_16x16x32_bf16 v[120:123], v[174:177], v[182:185], v[120:123]
	v_mfma_f32_16x16x32_bf16 v[116:119], v[166:169], v[190:193], v[116:119]
	v_mfma_f32_16x16x32_bf16 v[112:115], v[174:177], v[190:193], v[112:115]
	v_mfma_f32_16x16x32_bf16 v[108:111], v[166:169], v[198:201], v[108:111]
	v_mfma_f32_16x16x32_bf16 v[104:107], v[174:177], v[198:201], v[104:107]
	v_mfma_f32_16x16x32_bf16 v[100:103], v[166:169], v[206:209], v[100:103]
	v_mfma_f32_16x16x32_bf16 v[96:99], v[174:177], v[206:209], v[96:99]
	s_setprio 0
	s_barrier
	v_readfirstlane_b32 s67, v141
	v_lshl_add_u64 v[226:227], v[130:131], 0, s[46:47]
	s_mov_b32 m0, s67
	v_readfirstlane_b32 s67, v140
	ds_read_b128 v[210:213], v153
	ds_read_b128 v[214:217], v153 offset:1024
	ds_read_b128 v[218:221], v153 offset:2048
	ds_read_b128 v[222:225], v153 offset:3072
	global_load_lds_dwordx4 v[226:227], off
	v_lshl_add_u64 v[226:227], v[130:131], 0, s[56:57]
	s_mov_b32 m0, s67
	s_nop 0
	global_load_lds_dwordx4 v[226:227], off
	s_barrier
	s_waitcnt lgkmcnt(0)
	s_setprio 1
	s_waitcnt lgkmcnt(0)
	v_mfma_f32_16x16x32_bf16 v[92:95], v[210:213], v[178:181], v[92:95]
	v_mfma_f32_16x16x32_bf16 v[88:91], v[218:221], v[178:181], v[88:91]
	v_mfma_f32_16x16x32_bf16 v[84:87], v[210:213], v[186:189], v[84:87]
	v_mfma_f32_16x16x32_bf16 v[80:83], v[218:221], v[186:189], v[80:83]
	v_mfma_f32_16x16x32_bf16 v[76:79], v[210:213], v[194:197], v[76:79]
	v_mfma_f32_16x16x32_bf16 v[72:75], v[218:221], v[194:197], v[72:75]
	v_mfma_f32_16x16x32_bf16 v[68:71], v[210:213], v[202:205], v[68:71]
	v_mfma_f32_16x16x32_bf16 v[64:67], v[218:221], v[202:205], v[64:67]
	v_mfma_f32_16x16x32_bf16 v[92:95], v[214:217], v[182:185], v[92:95]
	v_mfma_f32_16x16x32_bf16 v[88:91], v[222:225], v[182:185], v[88:91]
	v_mfma_f32_16x16x32_bf16 v[84:87], v[214:217], v[190:193], v[84:87]
	v_mfma_f32_16x16x32_bf16 v[80:83], v[222:225], v[190:193], v[80:83]
	v_mfma_f32_16x16x32_bf16 v[76:79], v[214:217], v[198:201], v[76:79]
	v_mfma_f32_16x16x32_bf16 v[72:75], v[222:225], v[198:201], v[72:75]
	v_mfma_f32_16x16x32_bf16 v[68:71], v[214:217], v[206:209], v[68:71]
	v_mfma_f32_16x16x32_bf16 v[64:67], v[222:225], v[206:209], v[64:67]
	s_setprio 0
	v_readfirstlane_b32 s67, v139
	v_lshl_add_u64 v[226:227], v[132:133], 0, s[58:59]
	s_mov_b32 m0, s67
	v_readfirstlane_b32 s67, v138
	s_barrier
	ds_read_b128 v[178:181], v152 offset:49152
	ds_read_b128 v[182:185], v152 offset:50176
	ds_read_b128 v[186:189], v151 offset:49152
	ds_read_b128 v[190:193], v151 offset:50176
	ds_read_b128 v[194:197], v150 offset:49152
	ds_read_b128 v[198:201], v150 offset:50176
	ds_read_b128 v[202:205], v149 offset:49152
	ds_read_b128 v[206:209], v149 offset:50176
	global_load_lds_dwordx4 v[226:227], off
	s_mov_b32 m0, s67
	s_nop 0
	global_load_lds_dwordx4 v[132:133], off
	s_barrier
	s_waitcnt lgkmcnt(0)
	s_setprio 1
	s_waitcnt lgkmcnt(0)
	v_mfma_f32_16x16x32_bf16 v[60:63], v[162:165], v[178:181], v[60:63]
	v_mfma_f32_16x16x32_bf16 v[56:59], v[170:173], v[178:181], v[56:59]
	v_mfma_f32_16x16x32_bf16 v[52:55], v[162:165], v[186:189], v[52:55]
	v_mfma_f32_16x16x32_bf16 v[48:51], v[170:173], v[186:189], v[48:51]
	v_mfma_f32_16x16x32_bf16 v[44:47], v[162:165], v[194:197], v[44:47]
	v_mfma_f32_16x16x32_bf16 v[40:43], v[170:173], v[194:197], v[40:43]
	v_mfma_f32_16x16x32_bf16 v[36:39], v[162:165], v[202:205], v[36:39]
	v_mfma_f32_16x16x32_bf16 v[32:35], v[170:173], v[202:205], v[32:35]
	v_mfma_f32_16x16x32_bf16 v[60:63], v[166:169], v[182:185], v[60:63]
	v_mfma_f32_16x16x32_bf16 v[56:59], v[174:177], v[182:185], v[56:59]
	v_mfma_f32_16x16x32_bf16 v[52:55], v[166:169], v[190:193], v[52:55]
	v_mfma_f32_16x16x32_bf16 v[48:51], v[174:177], v[190:193], v[48:51]
	v_mfma_f32_16x16x32_bf16 v[44:47], v[166:169], v[198:201], v[44:47]
	v_mfma_f32_16x16x32_bf16 v[40:43], v[174:177], v[198:201], v[40:43]
	v_mfma_f32_16x16x32_bf16 v[36:39], v[166:169], v[206:209], v[36:39]
	v_mfma_f32_16x16x32_bf16 v[32:35], v[174:177], v[206:209], v[32:35]
	s_setprio 0
	s_barrier
	v_readfirstlane_b32 s67, v137
	v_lshl_add_u64 v[162:163], v[130:131], 0, s[58:59]
	s_mov_b32 m0, s67
	v_readfirstlane_b32 s67, v136
	global_load_lds_dwordx4 v[162:163], off
	s_mov_b32 m0, s67
	s_nop 0
	global_load_lds_dwordx4 v[130:131], off
	s_waitcnt vmcnt(6)
	s_barrier
	s_setprio 1
	v_mfma_f32_16x16x32_bf16 v[28:31], v[210:213], v[178:181], v[28:31]
	v_mfma_f32_16x16x32_bf16 v[24:27], v[218:221], v[178:181], v[24:27]
	v_mfma_f32_16x16x32_bf16 v[20:23], v[210:213], v[186:189], v[20:23]
	v_mfma_f32_16x16x32_bf16 v[16:19], v[218:221], v[186:189], v[16:19]
	v_mfma_f32_16x16x32_bf16 v[12:15], v[210:213], v[194:197], v[12:15]
	v_mfma_f32_16x16x32_bf16 v[8:11], v[218:221], v[194:197], v[8:11]
	v_mfma_f32_16x16x32_bf16 v[4:7], v[210:213], v[202:205], v[4:7]
	v_mfma_f32_16x16x32_bf16 v[0:3], v[218:221], v[202:205], v[0:3]
	v_mfma_f32_16x16x32_bf16 v[28:31], v[214:217], v[182:185], v[28:31]
	v_mfma_f32_16x16x32_bf16 v[24:27], v[222:225], v[182:185], v[24:27]
	v_mfma_f32_16x16x32_bf16 v[20:23], v[214:217], v[190:193], v[20:23]
	v_mfma_f32_16x16x32_bf16 v[16:19], v[222:225], v[190:193], v[16:19]
	v_mfma_f32_16x16x32_bf16 v[12:15], v[214:217], v[198:201], v[12:15]
	v_mfma_f32_16x16x32_bf16 v[8:11], v[222:225], v[198:201], v[8:11]
	v_mfma_f32_16x16x32_bf16 v[4:7], v[214:217], v[206:209], v[4:7]
	v_mfma_f32_16x16x32_bf16 v[0:3], v[222:225], v[206:209], v[0:3]
	s_setprio 0
	v_lshl_add_u64 v[130:131], v[130:131], 0, s[60:61]
	s_cmp_lt_u32 s66, s65
	v_lshl_add_u64 v[132:133], v[132:133], 0, s[62:63]
	s_barrier
	s_cbranch_scc1 .LBB0_274
	s_lshl_b32 s65, s86, 5
	s_lshl_b32 s66, s86, 8
	s_and_b32 s65, s65, 0x1800
	s_and_b32 s66, s66, 0x700
	s_or_b32 s97, s66, s65
	s_lshl_b32 s65, s97, 6
	s_add_u32 s65, s68, s65
	s_addc_u32 s86, s69, 0
	s_add_i32 s20, s20, -1
	s_lshl_b64 s[66:67], s[20:21], 20
	v_add_u32_e32 v128, v156, v157
	s_add_u32 s66, s65, s66
	v_or_b32_e32 v128, v128, v155
	s_addc_u32 s67, s86, s67
	v_lshl_add_u64 v[156:157], s[66:67], 0, v[128:129]
	v_readfirstlane_b32 s20, v160
	v_lshl_add_u64 v[206:207], v[156:157], 0, s[4:5]
	s_mov_b32 m0, s20
	v_readfirstlane_b32 s20, v159
	ds_read_b128 v[130:133], v161
	ds_read_b128 v[162:165], v161 offset:1024
	ds_read_b128 v[166:169], v161 offset:2048
	ds_read_b128 v[170:173], v161 offset:3072
	ds_read_b128 v[174:177], v152
	ds_read_b128 v[178:181], v152 offset:1024
	ds_read_b128 v[182:185], v151
	ds_read_b128 v[186:189], v151 offset:1024
	ds_read_b128 v[190:193], v150
	ds_read_b128 v[194:197], v150 offset:1024
	ds_read_b128 v[198:201], v149
	ds_read_b128 v[202:205], v149 offset:1024
	global_load_lds_dwordx4 v[206:207], off
	v_lshl_add_u64 v[156:157], v[156:157], 0, s[6:7]
	s_mov_b32 m0, s20
	s_nop 0
	global_load_lds_dwordx4 v[156:157], off
	s_barrier
	s_waitcnt lgkmcnt(0)
	s_setprio 1
	s_waitcnt lgkmcnt(0)
	v_mfma_f32_16x16x32_bf16 v[124:127], v[130:133], v[174:177], v[124:127]
	v_mfma_f32_16x16x32_bf16 v[120:123], v[166:169], v[174:177], v[120:123]
	v_mfma_f32_16x16x32_bf16 v[116:119], v[130:133], v[182:185], v[116:119]
	v_mfma_f32_16x16x32_bf16 v[112:115], v[166:169], v[182:185], v[112:115]
	v_mfma_f32_16x16x32_bf16 v[108:111], v[130:133], v[190:193], v[108:111]
	v_mfma_f32_16x16x32_bf16 v[104:107], v[166:169], v[190:193], v[104:107]
	v_mfma_f32_16x16x32_bf16 v[100:103], v[130:133], v[198:201], v[100:103]
	v_mfma_f32_16x16x32_bf16 v[96:99], v[166:169], v[198:201], v[96:99]
	v_mfma_f32_16x16x32_bf16 v[124:127], v[162:165], v[178:181], v[124:127]
	v_mfma_f32_16x16x32_bf16 v[120:123], v[170:173], v[178:181], v[120:123]
	v_mfma_f32_16x16x32_bf16 v[116:119], v[162:165], v[186:189], v[116:119]
	v_mfma_f32_16x16x32_bf16 v[112:115], v[170:173], v[186:189], v[112:115]
	v_mfma_f32_16x16x32_bf16 v[108:111], v[162:165], v[194:197], v[108:111]
	v_mfma_f32_16x16x32_bf16 v[104:107], v[170:173], v[194:197], v[104:107]
	v_mfma_f32_16x16x32_bf16 v[100:103], v[162:165], v[202:205], v[100:103]
	v_mfma_f32_16x16x32_bf16 v[96:99], v[170:173], v[202:205], v[96:99]
	s_setprio 0
	s_barrier
	ds_read_b128 v[206:209], v158
	ds_read_b128 v[210:213], v158 offset:1024
	ds_read_b128 v[214:217], v158 offset:2048
	ds_read_b128 v[156:159], v158 offset:3072
	s_barrier
	s_waitcnt lgkmcnt(0)
	s_setprio 1
	s_waitcnt lgkmcnt(0)
	v_mfma_f32_16x16x32_bf16 v[92:95], v[206:209], v[174:177], v[92:95]
	v_mfma_f32_16x16x32_bf16 v[88:91], v[214:217], v[174:177], v[88:91]
	v_mfma_f32_16x16x32_bf16 v[84:87], v[206:209], v[182:185], v[84:87]
	v_mfma_f32_16x16x32_bf16 v[80:83], v[214:217], v[182:185], v[80:83]
	v_mfma_f32_16x16x32_bf16 v[76:79], v[206:209], v[190:193], v[76:79]
	v_mfma_f32_16x16x32_bf16 v[72:75], v[214:217], v[190:193], v[72:75]
	v_mfma_f32_16x16x32_bf16 v[68:71], v[206:209], v[198:201], v[68:71]
	v_mfma_f32_16x16x32_bf16 v[64:67], v[214:217], v[198:201], v[64:67]
	v_mfma_f32_16x16x32_bf16 v[174:177], v[210:213], v[178:181], v[92:95]
	v_mfma_f32_16x16x32_bf16 v[178:181], v[156:159], v[178:181], v[88:91]
	v_mfma_f32_16x16x32_bf16 v[182:185], v[210:213], v[186:189], v[84:87]
	v_mfma_f32_16x16x32_bf16 v[186:189], v[156:159], v[186:189], v[80:83]
	v_mfma_f32_16x16x32_bf16 v[190:193], v[210:213], v[194:197], v[76:79]
	v_mfma_f32_16x16x32_bf16 v[194:197], v[156:159], v[194:197], v[72:75]
	v_mfma_f32_16x16x32_bf16 v[198:201], v[210:213], v[202:205], v[68:71]
	v_mfma_f32_16x16x32_bf16 v[202:205], v[156:159], v[202:205], v[64:67]
	s_setprio 0
	s_barrier
	s_nop 0
	ds_read_b128 v[64:67], v152 offset:16384
	ds_read_b128 v[68:71], v152 offset:17408
	ds_read_b128 v[72:75], v151 offset:16384
	ds_read_b128 v[76:79], v151 offset:17408
	ds_read_b128 v[80:83], v150 offset:16384
	ds_read_b128 v[84:87], v150 offset:17408
	ds_read_b128 v[88:91], v149 offset:16384
	ds_read_b128 v[92:95], v149 offset:17408
	s_waitcnt vmcnt(4)
	s_barrier
	s_waitcnt lgkmcnt(0)
	s_setprio 1
	s_waitcnt lgkmcnt(0)
	v_mfma_f32_16x16x32_bf16 v[60:63], v[130:133], v[64:67], v[60:63]
	v_mfma_f32_16x16x32_bf16 v[56:59], v[166:169], v[64:67], v[56:59]
	v_mfma_f32_16x16x32_bf16 v[52:55], v[130:133], v[72:75], v[52:55]
	v_mfma_f32_16x16x32_bf16 v[48:51], v[166:169], v[72:75], v[48:51]
	v_mfma_f32_16x16x32_bf16 v[218:221], v[130:133], v[80:83], v[44:47]
	v_mfma_f32_16x16x32_bf16 v[222:225], v[166:169], v[80:83], v[40:43]
	v_mfma_f32_16x16x32_bf16 v[130:133], v[130:133], v[88:91], v[36:39]
	v_mfma_f32_16x16x32_bf16 v[166:169], v[166:169], v[88:91], v[32:35]
	v_mfma_f32_16x16x32_bf16 v[32:35], v[162:165], v[68:71], v[60:63]
	v_mfma_f32_16x16x32_bf16 v[36:39], v[170:173], v[68:71], v[56:59]
	v_mfma_f32_16x16x32_bf16 v[40:43], v[162:165], v[76:79], v[52:55]
	v_mfma_f32_16x16x32_bf16 v[44:47], v[170:173], v[76:79], v[48:51]
	v_mfma_f32_16x16x32_bf16 v[48:51], v[162:165], v[84:87], v[218:221]
	v_mfma_f32_16x16x32_bf16 v[52:55], v[170:173], v[84:87], v[222:225]
	v_mfma_f32_16x16x32_bf16 v[56:59], v[162:165], v[92:95], v[130:133]
	v_mfma_f32_16x16x32_bf16 v[60:63], v[170:173], v[92:95], v[166:169]
	s_setprio 0
	s_setprio 1
	v_mfma_f32_16x16x32_bf16 v[28:31], v[206:209], v[64:67], v[28:31]
	v_mfma_f32_16x16x32_bf16 v[24:27], v[214:217], v[64:67], v[24:27]
	v_mfma_f32_16x16x32_bf16 v[20:23], v[206:209], v[72:75], v[20:23]
	v_mfma_f32_16x16x32_bf16 v[64:67], v[214:217], v[72:75], v[16:19]
	v_mfma_f32_16x16x32_bf16 v[72:75], v[206:209], v[80:83], v[12:15]
	v_mfma_f32_16x16x32_bf16 v[8:11], v[214:217], v[80:83], v[8:11]
	v_mfma_f32_16x16x32_bf16 v[80:83], v[206:209], v[88:91], v[4:7]
	v_mfma_f32_16x16x32_bf16 v[0:3], v[214:217], v[88:91], v[0:3]
	v_mfma_f32_16x16x32_bf16 v[4:7], v[210:213], v[68:71], v[28:31]
	v_mfma_f32_16x16x32_bf16 v[12:15], v[156:159], v[68:71], v[24:27]
	v_mfma_f32_16x16x32_bf16 v[16:19], v[210:213], v[76:79], v[20:23]
	v_mfma_f32_16x16x32_bf16 v[20:23], v[156:159], v[76:79], v[64:67]
	v_mfma_f32_16x16x32_bf16 v[24:27], v[210:213], v[84:87], v[72:75]
	v_mfma_f32_16x16x32_bf16 v[28:31], v[156:159], v[84:87], v[8:11]
	v_mfma_f32_16x16x32_bf16 v[64:67], v[210:213], v[92:95], v[80:83]
	v_mfma_f32_16x16x32_bf16 v[68:71], v[156:159], v[92:95], v[0:3]
	s_setprio 0
	s_barrier
	ds_read_b128 v[8:11], v154
	ds_read_b128 v[0:3], v154 offset:1024
	ds_read_b128 v[76:79], v154 offset:2048
	ds_read_b128 v[72:75], v154 offset:3072
	ds_read_b128 v[130:133], v152 offset:32768
	ds_read_b128 v[154:157], v152 offset:33792
	ds_read_b128 v[158:161], v151 offset:32768
	ds_read_b128 v[162:165], v151 offset:33792
	ds_read_b128 v[166:169], v150 offset:32768
	ds_read_b128 v[170:173], v150 offset:33792
	ds_read_b128 v[206:209], v149 offset:32768
	ds_read_b128 v[210:213], v149 offset:33792
	s_waitcnt vmcnt(2)
	s_barrier
	s_waitcnt lgkmcnt(0)
	s_setprio 1
	s_waitcnt lgkmcnt(0)
	v_mfma_f32_16x16x32_bf16 v[80:83], v[8:11], v[130:133], v[124:127]
	v_mfma_f32_16x16x32_bf16 v[84:87], v[76:79], v[130:133], v[120:123]
	v_mfma_f32_16x16x32_bf16 v[88:91], v[8:11], v[158:161], v[116:119]
	v_mfma_f32_16x16x32_bf16 v[92:95], v[76:79], v[158:161], v[112:115]
	v_mfma_f32_16x16x32_bf16 v[108:111], v[8:11], v[166:169], v[108:111]
	v_mfma_f32_16x16x32_bf16 v[104:107], v[76:79], v[166:169], v[104:107]
	v_mfma_f32_16x16x32_bf16 v[100:103], v[8:11], v[206:209], v[100:103]
	v_mfma_f32_16x16x32_bf16 v[96:99], v[76:79], v[206:209], v[96:99]
	v_mfma_f32_16x16x32_bf16 v[112:115], v[0:3], v[154:157], v[80:83]
	v_mfma_f32_16x16x32_bf16 v[116:119], v[72:75], v[154:157], v[84:87]
	v_mfma_f32_16x16x32_bf16 v[120:123], v[0:3], v[162:165], v[88:91]
	v_mfma_f32_16x16x32_bf16 v[124:127], v[72:75], v[162:165], v[92:95]
	v_mfma_f32_16x16x32_bf16 v[108:111], v[0:3], v[170:173], v[108:111]
	v_mfma_f32_16x16x32_bf16 v[104:107], v[72:75], v[170:173], v[104:107]
	v_mfma_f32_16x16x32_bf16 v[100:103], v[0:3], v[210:213], v[100:103]
	v_mfma_f32_16x16x32_bf16 v[96:99], v[72:75], v[210:213], v[96:99]
	s_setprio 0
	s_barrier
	ds_read_b128 v[88:91], v153
	ds_read_b128 v[80:83], v153 offset:1024
	ds_read_b128 v[92:95], v153 offset:2048
	ds_read_b128 v[84:87], v153 offset:3072
	s_waitcnt vmcnt(0)
	s_barrier
	s_waitcnt lgkmcnt(0)
	s_setprio 1
	s_waitcnt lgkmcnt(0)
	v_mfma_f32_16x16x32_bf16 v[174:177], v[88:91], v[130:133], v[174:177]
	v_mfma_f32_16x16x32_bf16 v[130:133], v[92:95], v[130:133], v[178:181]
	v_mfma_f32_16x16x32_bf16 v[178:181], v[88:91], v[158:161], v[182:185]
	v_mfma_f32_16x16x32_bf16 v[158:161], v[92:95], v[158:161], v[186:189]
	v_mfma_f32_16x16x32_bf16 v[182:185], v[88:91], v[166:169], v[190:193]
	v_mfma_f32_16x16x32_bf16 v[166:169], v[92:95], v[166:169], v[194:197]
	v_mfma_f32_16x16x32_bf16 v[186:189], v[88:91], v[206:209], v[198:201]
	v_mfma_f32_16x16x32_bf16 v[190:193], v[92:95], v[206:209], v[202:205]
	v_mfma_f32_16x16x32_bf16 v[174:177], v[80:83], v[154:157], v[174:177]
	v_mfma_f32_16x16x32_bf16 v[130:133], v[84:87], v[154:157], v[130:133]
	v_mfma_f32_16x16x32_bf16 v[154:157], v[80:83], v[162:165], v[178:181]
	v_mfma_f32_16x16x32_bf16 v[158:161], v[84:87], v[162:165], v[158:161]
	v_mfma_f32_16x16x32_bf16 v[162:165], v[80:83], v[170:173], v[182:185]
	v_mfma_f32_16x16x32_bf16 v[166:169], v[84:87], v[170:173], v[166:169]
	v_mfma_f32_16x16x32_bf16 v[170:173], v[80:83], v[210:213], v[186:189]
	v_mfma_f32_16x16x32_bf16 v[178:181], v[84:87], v[210:213], v[190:193]
	s_setprio 0
	s_barrier
	v_mbcnt_lo_u32_b32 v128, -1, 0
	v_mbcnt_hi_u32_b32 v128, -1, v128
	v_cvt_pk_bf16_f32 v112, v112, v113
	v_cvt_pk_bf16_f32 v113, v114, v115
	v_cvt_pk_bf16_f32 v114, v116, v117
	v_cvt_pk_bf16_f32 v115, v118, v119
	s_lshl_b32 s89, s64, 9
	v_add_u32_e32 v153, s72, v128
	v_ashrrev_i32_e32 v182, 6, v153
	v_and_b32_e32 v183, 15, v128
	v_and_b32_e32 v184, 48, v128
	v_mul_lo_u32 v185, v182, s77
	v_bfe_u32 v186, v128, 3, 3
	v_lshlrev_b32_e32 v128, 4, v128
	v_add_u32_e32 v185, 0x20000, v185
	v_lshrrev_b32_e32 v153, 2, v153
	v_and_b32_e32 v128, 0x70, v128
	v_mul_u32_u24_e32 v183, 0x90, v183
	v_and_b32_e32 v153, 64, v153
	v_add3_u32 v183, v185, v183, v184
	v_or_b32_e32 v184, v185, v128
	v_or3_b32 v153, s97, v153, v186
	v_mad_u32_u24 v184, v186, s79, v184
	ds_write_b128 v183, v[112:115]
	v_cvt_pk_bf16_f32 v112, v174, v175
	v_cvt_pk_bf16_f32 v113, v176, v177
	v_cvt_pk_bf16_f32 v114, v130, v131
	v_cvt_pk_bf16_f32 v115, v132, v133
	ds_write_b128 v183, v[112:115] offset:64
	v_lshlrev_b32_e32 v182, 7, v182
	ds_read_b128 v[112:115], v184
	v_lshlrev_b32_e32 v116, 12, v153
	v_and_or_b32 v116, v182, s80, v116
	v_or3_b32 v128, v116, s89, v128
	ds_read_b128 v[116:119], v184 offset:1152
	v_lshl_add_u64 v[130:131], s[0:1], 0, v[128:129]
	s_mov_b32 s20, 0x8000
	s_waitcnt lgkmcnt(0)
	global_store_dwordx4 v128, v[112:115], s[0:1] sc0 sc1
	v_cvt_pk_bf16_f32 v108, v108, v109
	v_cvt_pk_bf16_f32 v109, v110, v111
	v_cvt_pk_bf16_f32 v110, v104, v105
	v_cvt_pk_bf16_f32 v111, v106, v107
	v_cvt_pk_bf16_f32 v104, v162, v163
	s_nop 1
	v_add_co_u32_e32 v112, vcc, s20, v130
	v_cvt_pk_bf16_f32 v114, v124, v125
	v_cvt_pk_bf16_f32 v115, v126, v127
	v_cvt_pk_bf16_f32 v105, v164, v165
	v_cvt_pk_bf16_f32 v106, v166, v167
	s_nop 1
	v_addc_co_u32_e32 v113, vcc, 0, v131, vcc
	global_store_dwordx4 v[112:113], v[116:119], off sc0 sc1
	v_cvt_pk_bf16_f32 v112, v120, v121
	v_cvt_pk_bf16_f32 v113, v122, v123
	ds_write_b128 v183, v[112:115]
	v_cvt_pk_bf16_f32 v112, v154, v155
	v_cvt_pk_bf16_f32 v113, v156, v157
	v_cvt_pk_bf16_f32 v114, v158, v159
	v_cvt_pk_bf16_f32 v115, v160, v161
	ds_write_b128 v183, v[112:115] offset:64
	ds_read_b128 v[112:115], v184
	ds_read_b128 v[116:119], v184 offset:1152
	v_add_co_u32_e32 v120, vcc, s74, v130
	ds_write_b128 v183, v[108:111]
	v_cvt_pk_bf16_f32 v107, v168, v169
	ds_write_b128 v183, v[104:107] offset:64
	v_addc_co_u32_e32 v121, vcc, 0, v131, vcc
	ds_read_b128 v[104:107], v184
	ds_read_b128 v[108:111], v184 offset:1152
	s_waitcnt lgkmcnt(0)
	global_store_dwordx4 v[120:121], v[112:115], off sc0 sc1
	v_cvt_pk_bf16_f32 v100, v100, v101
	v_cvt_pk_bf16_f32 v101, v102, v103
	v_cvt_pk_bf16_f32 v102, v96, v97
	v_cvt_pk_bf16_f32 v103, v98, v99
	ds_write_b128 v183, v[100:103]
	s_nop 0
	v_add_co_u32_e32 v112, vcc, s75, v130
	v_cvt_pk_bf16_f32 v96, v170, v171
	v_cvt_pk_bf16_f32 v97, v172, v173
	v_cvt_pk_bf16_f32 v98, v178, v179
	v_cvt_pk_bf16_f32 v99, v180, v181
	s_nop 1
	v_addc_co_u32_e32 v113, vcc, 0, v131, vcc
	global_store_dwordx4 v[112:113], v[116:119], off sc0 sc1
	v_add_co_u32_e32 v112, vcc, s78, v130
	ds_write_b128 v183, v[96:99] offset:64
	s_nop 0
	v_addc_co_u32_e32 v113, vcc, 0, v131, vcc
	ds_read_b128 v[96:99], v184
	ds_read_b128 v[100:103], v184 offset:1152
	global_store_dwordx4 v[112:113], v[104:107], off sc0 sc1
	s_nop 1
	v_add_co_u32_e32 v104, vcc, s81, v130
	s_nop 1
	v_addc_co_u32_e32 v105, vcc, 0, v131, vcc
	global_store_dwordx4 v[104:105], v[108:111], off sc0 sc1
	v_add_co_u32_e32 v104, vcc, s82, v130
	s_nop 1
	v_addc_co_u32_e32 v105, vcc, 0, v131, vcc
	s_waitcnt lgkmcnt(0)
	global_store_dwordx4 v[104:105], v[96:99], off sc0 sc1
	s_nop 1
	v_add_co_u32_e32 v96, vcc, s83, v130
	s_nop 1
	v_addc_co_u32_e32 v97, vcc, 0, v131, vcc
	global_store_dwordx4 v[96:97], v[100:103], off sc0 sc1
	ds_read_b128 v[96:99], v152 offset:49152
	ds_read_b128 v[100:103], v152 offset:50176
	ds_read_b128 v[104:107], v151 offset:49152
	ds_read_b128 v[108:111], v151 offset:50176
	ds_read_b128 v[112:115], v150 offset:49152
	ds_read_b128 v[116:119], v150 offset:50176
	ds_read_b128 v[120:123], v149 offset:49152
	ds_read_b128 v[124:127], v149 offset:50176
	s_barrier
	s_waitcnt lgkmcnt(0)
	s_setprio 1
	s_waitcnt lgkmcnt(0)
	v_mfma_f32_16x16x32_bf16 v[32:35], v[8:11], v[96:99], v[32:35]
	v_mfma_f32_16x16x32_bf16 v[36:39], v[76:79], v[96:99], v[36:39]
	v_mfma_f32_16x16x32_bf16 v[40:43], v[8:11], v[104:107], v[40:43]
	v_mfma_f32_16x16x32_bf16 v[130:133], v[76:79], v[104:107], v[44:47]
	v_mfma_f32_16x16x32_bf16 v[150:153], v[8:11], v[112:115], v[48:51]
	v_mfma_f32_16x16x32_bf16 v[52:55], v[76:79], v[112:115], v[52:55]
	v_mfma_f32_16x16x32_bf16 v[8:11], v[8:11], v[120:123], v[56:59]
	v_mfma_f32_16x16x32_bf16 v[60:63], v[76:79], v[120:123], v[60:63]
	v_mfma_f32_16x16x32_bf16 v[56:59], v[0:3], v[100:103], v[32:35]
	v_mfma_f32_16x16x32_bf16 v[48:51], v[72:75], v[100:103], v[36:39]
	v_mfma_f32_16x16x32_bf16 v[44:47], v[0:3], v[108:111], v[40:43]
	v_mfma_f32_16x16x32_bf16 v[40:43], v[72:75], v[108:111], v[130:133]
	v_mfma_f32_16x16x32_bf16 v[36:39], v[0:3], v[116:119], v[150:153]
	v_mfma_f32_16x16x32_bf16 v[32:35], v[72:75], v[116:119], v[52:55]
	v_mfma_f32_16x16x32_bf16 v[8:11], v[0:3], v[124:127], v[8:11]
	v_mfma_f32_16x16x32_bf16 v[0:3], v[72:75], v[124:127], v[60:63]
	s_setprio 0
	s_setprio 1
	v_mfma_f32_16x16x32_bf16 v[4:7], v[88:91], v[96:99], v[4:7]
	v_mfma_f32_16x16x32_bf16 v[12:15], v[92:95], v[96:99], v[12:15]
	v_mfma_f32_16x16x32_bf16 v[16:19], v[88:91], v[104:107], v[16:19]
	v_mfma_f32_16x16x32_bf16 v[20:23], v[92:95], v[104:107], v[20:23]
	v_mfma_f32_16x16x32_bf16 v[72:75], v[88:91], v[112:115], v[24:27]
	v_mfma_f32_16x16x32_bf16 v[76:79], v[92:95], v[112:115], v[28:31]
	v_mfma_f32_16x16x32_bf16 v[64:67], v[88:91], v[120:123], v[64:67]
	v_mfma_f32_16x16x32_bf16 v[68:71], v[92:95], v[120:123], v[68:71]
	v_mfma_f32_16x16x32_bf16 v[60:63], v[80:83], v[100:103], v[4:7]
	v_mfma_f32_16x16x32_bf16 v[52:55], v[84:87], v[100:103], v[12:15]
	v_mfma_f32_16x16x32_bf16 v[28:31], v[80:83], v[108:111], v[16:19]
	v_mfma_f32_16x16x32_bf16 v[24:27], v[84:87], v[108:111], v[20:23]
	v_mfma_f32_16x16x32_bf16 v[20:23], v[80:83], v[116:119], v[72:75]
	v_mfma_f32_16x16x32_bf16 v[16:19], v[84:87], v[116:119], v[76:79]
	v_mfma_f32_16x16x32_bf16 v[12:15], v[80:83], v[124:127], v[64:67]
	v_mfma_f32_16x16x32_bf16 v[4:7], v[84:87], v[124:127], v[68:71]
	s_setprio 0
	v_cmp_gt_u32_e32 vcc, s85, v135
	s_barrier
	s_and_saveexec_b64 s[64:65], vcc
	s_cbranch_execz .LBB0_277
	s_barrier

.LBB0_336:
	global_store_dwordx4 v76, v[64:67], s[10:11] sc0 sc1
	s_add_i32 s35, s35, 1
	s_mov_b64 s[14:15], 0
	s_andn2_b64 vcc, exec, s[24:25]
	s_mov_b32 s65, s71
	s_mov_b64 s[10:11], s[22:23]
	s_mov_b32 s64, s17
	s_cbranch_vccz .LBB0_416

.LBB0_364:
	v_cvt_pk_bf16_f32 v160, v148, v149
	v_cvt_pk_bf16_f32 v161, v150, v151
	v_cvt_pk_bf16_f32 v162, v144, v145
	v_cvt_pk_bf16_f32 v163, v146, v147
	global_store_dwordx4 v166, v[160:163], s[10:11] sc0 sc1
	v_add_u32_e32 v167, s17, v166
	s_nop 0
	v_cvt_pk_bf16_f32 v160, v156, v157
	v_cvt_pk_bf16_f32 v161, v158, v159
	v_cvt_pk_bf16_f32 v162, v152, v153
	v_cvt_pk_bf16_f32 v163, v154, v155
	global_store_dwordx4 v167, v[160:163], s[10:11] sc0 sc1
	v_add_u32_e32 v167, s22, v166
	v_add_u32_e32 v166, s24, v166
	v_cvt_pk_bf16_f32 v160, v132, v133
	v_cvt_pk_bf16_f32 v161, v134, v135
	v_cvt_pk_bf16_f32 v162, v128, v129
	v_cvt_pk_bf16_f32 v163, v130, v131
	global_store_dwordx4 v167, v[160:163], s[10:11] sc0 sc1
	v_add_u32_e32 v167, s17, v167
	s_nop 0
	v_cvt_pk_bf16_f32 v160, v140, v141
	v_cvt_pk_bf16_f32 v161, v142, v143
	v_cvt_pk_bf16_f32 v162, v136, v137
	v_cvt_pk_bf16_f32 v163, v138, v139
	global_store_dwordx4 v167, v[160:163], s[10:11] sc0 sc1
	v_add_u32_e32 v167, s17, v166
	s_nop 0
	v_cvt_pk_bf16_f32 v160, v116, v117
	v_cvt_pk_bf16_f32 v161, v118, v119
	v_cvt_pk_bf16_f32 v162, v112, v113
	v_cvt_pk_bf16_f32 v163, v114, v115
	global_store_dwordx4 v166, v[160:163], s[10:11] sc0 sc1
	v_add_u32_e32 v166, s22, v166
	v_add_u32_e32 v193, s17, v166
	v_cvt_pk_bf16_f32 v160, v124, v125
	v_cvt_pk_bf16_f32 v161, v126, v127
	v_cvt_pk_bf16_f32 v162, v120, v121
	v_cvt_pk_bf16_f32 v163, v122, v123
	global_store_dwordx4 v167, v[160:163], s[10:11] sc0 sc1
	s_nop 1
	v_cvt_pk_bf16_f32 v160, v100, v101
	v_cvt_pk_bf16_f32 v161, v102, v103
	v_cvt_pk_bf16_f32 v162, v24, v25
	v_cvt_pk_bf16_f32 v163, v26, v27
	global_store_dwordx4 v166, v[160:163], s[10:11] sc0 sc1
	s_nop 1
	v_cvt_pk_bf16_f32 v160, v108, v109
	v_cvt_pk_bf16_f32 v161, v110, v111
	v_cvt_pk_bf16_f32 v162, v104, v105
	v_cvt_pk_bf16_f32 v163, v106, v107
.LBB0_365:
	s_andn2_b64 vcc, exec, s[18:19]
	s_cbranch_vccnz .LBB0_367
	v_mul_lo_u32 v160, v192, s61
	v_bfe_u32 v162, v164, 3, 3
	v_lshlrev_b32_e32 v164, 4, v164
	v_add_u32_e32 v160, 0x20000, v160
	v_and_b32_e32 v164, 0x70, v164
	v_mul_u32_u24_e32 v166, 0x90, v188
	v_lshlrev_b32_e32 v167, 4, v189
	v_lshlrev_b32_e32 v161, 6, v190
	v_lshlrev_b32_e32 v163, 7, v191
	s_lshl_b32 s17, s66, 9
	v_add3_u32 v166, v160, v166, v167
	v_or_b32_e32 v160, v160, v164
	v_cvt_pk_bf16_f32 v148, v148, v149
	v_or3_b32 v161, v161, v162, s14
	v_mad_u32_u24 v160, v162, s62, v160
	v_cvt_pk_bf16_f32 v149, v150, v151
	v_cvt_pk_bf16_f32 v150, v144, v145
	v_cvt_pk_bf16_f32 v151, v146, v147
	ds_write_b128 v166, v[148:151]
	v_cvt_pk_bf16_f32 v144, v156, v157
	v_cvt_pk_bf16_f32 v145, v158, v159
	v_cvt_pk_bf16_f32 v146, v152, v153
	v_cvt_pk_bf16_f32 v147, v154, v155
	ds_write_b128 v166, v[144:147] offset:64
	v_or3_b32 v148, v163, s17, v164
	ds_read_b128 v[144:147], v160
	v_mad_u64_u32 v[152:153], s[18:19], v161, s15, v[148:149]
	ds_read_b128 v[148:151], v160 offset:1152
	s_lshl_b32 s17, s15, 3
	v_cvt_pk_bf16_f32 v132, v132, v133
	v_cvt_pk_bf16_f32 v133, v134, v135
	v_cvt_pk_bf16_f32 v134, v128, v129
	v_cvt_pk_bf16_f32 v135, v130, v131
	ds_write_b128 v166, v[132:135]
	v_cvt_pk_bf16_f32 v128, v140, v141
	v_cvt_pk_bf16_f32 v129, v142, v143
	v_cvt_pk_bf16_f32 v130, v136, v137
	v_cvt_pk_bf16_f32 v131, v138, v139
	ds_write_b128 v166, v[128:131] offset:64
	v_add_u32_e32 v132, s17, v152
	s_waitcnt lgkmcnt(0)
	global_store_dwordx4 v152, v[144:147], s[10:11] sc0 sc1
	ds_read_b128 v[128:131], v160
	global_store_dwordx4 v132, v[148:151], s[10:11] sc0 sc1
	v_add_u32_e32 v136, s17, v132
	ds_read_b128 v[132:135], v160 offset:1152
	v_cvt_pk_bf16_f32 v116, v116, v117
	v_cvt_pk_bf16_f32 v117, v118, v119
	v_cvt_pk_bf16_f32 v118, v112, v113
	v_cvt_pk_bf16_f32 v119, v114, v115
	ds_write_b128 v166, v[116:119]
	v_cvt_pk_bf16_f32 v112, v124, v125
	v_cvt_pk_bf16_f32 v113, v126, v127
	v_cvt_pk_bf16_f32 v114, v120, v121
	v_cvt_pk_bf16_f32 v115, v122, v123
	ds_write_b128 v166, v[112:115] offset:64
	v_add_u32_e32 v116, s17, v136
	s_waitcnt lgkmcnt(0)
	global_store_dwordx4 v136, v[128:131], s[10:11] sc0 sc1
	ds_read_b128 v[112:115], v160
	global_store_dwordx4 v116, v[132:135], s[10:11] sc0 sc1
	v_add_u32_e32 v120, s17, v116
	ds_read_b128 v[116:119], v160 offset:1152
	v_cvt_pk_bf16_f32 v100, v100, v101
	v_cvt_pk_bf16_f32 v101, v102, v103
	v_cvt_pk_bf16_f32 v102, v24, v25
	v_cvt_pk_bf16_f32 v103, v26, v27
	ds_write_b128 v166, v[100:103]
	v_cvt_pk_bf16_f32 v24, v108, v109
	v_cvt_pk_bf16_f32 v25, v110, v111
	v_cvt_pk_bf16_f32 v26, v104, v105
	v_cvt_pk_bf16_f32 v27, v106, v107
	ds_write_b128 v166, v[24:27] offset:64
	ds_read_b128 v[24:27], v160
	ds_read_b128 v[160:163], v160 offset:1152
	v_add_u32_e32 v100, s17, v120
	s_waitcnt lgkmcnt(0)
	global_store_dwordx4 v120, v[112:115], s[10:11] sc0 sc1
	global_store_dwordx4 v100, v[116:119], s[10:11] sc0 sc1
	v_add_u32_e32 v100, s17, v100
	v_add_u32_e32 v193, s17, v100
	global_store_dwordx4 v100, v[24:27], s[10:11] sc0 sc1
.LBB0_367:
	global_store_dwordx4 v193, v[160:163], s[10:11] sc0 sc1
	ds_read_b128 v[100:103], v187 offset:49152
	ds_read_b128 v[104:107], v187 offset:50176
	ds_read_b128 v[108:111], v186 offset:49152
	ds_read_b128 v[112:115], v186 offset:50176
	ds_read_b128 v[116:119], v185 offset:49152
	ds_read_b128 v[120:123], v185 offset:50176
	ds_read_b128 v[124:127], v184 offset:49152
	ds_read_b128 v[128:131], v184 offset:50176
	s_barrier
	s_waitcnt lgkmcnt(0)
	s_setprio 1
	s_waitcnt lgkmcnt(0)
	v_mfma_f32_16x16x32_bf16 v[24:27], v[8:11], v[100:103], v[32:35]
	v_mfma_f32_16x16x32_bf16 v[32:35], v[16:19], v[100:103], v[36:39]
	v_mfma_f32_16x16x32_bf16 v[36:39], v[8:11], v[108:111], v[40:43]
	v_mfma_f32_16x16x32_bf16 v[44:47], v[16:19], v[108:111], v[44:47]
	v_mfma_f32_16x16x32_bf16 v[132:135], v[8:11], v[116:119], v[48:51]
	v_mfma_f32_16x16x32_bf16 v[52:55], v[16:19], v[116:119], v[52:55]
	v_mfma_f32_16x16x32_bf16 v[8:11], v[8:11], v[124:127], v[56:59]
	v_mfma_f32_16x16x32_bf16 v[60:63], v[16:19], v[124:127], v[60:63]
	v_mfma_f32_16x16x32_bf16 v[56:59], v[0:3], v[104:107], v[24:27]
	v_mfma_f32_16x16x32_bf16 v[48:51], v[80:83], v[104:107], v[32:35]
	v_mfma_f32_16x16x32_bf16 v[40:43], v[0:3], v[112:115], v[36:39]
	v_mfma_f32_16x16x32_bf16 v[32:35], v[80:83], v[112:115], v[44:47]
	v_mfma_f32_16x16x32_bf16 v[24:27], v[0:3], v[120:123], v[132:135]
	v_mfma_f32_16x16x32_bf16 v[16:19], v[80:83], v[120:123], v[52:55]
	v_mfma_f32_16x16x32_bf16 v[8:11], v[0:3], v[128:131], v[8:11]
	v_mfma_f32_16x16x32_bf16 v[0:3], v[80:83], v[128:131], v[60:63]
	s_setprio 0
	s_setprio 1
	v_mfma_f32_16x16x32_bf16 v[4:7], v[92:95], v[100:103], v[4:7]
	v_mfma_f32_16x16x32_bf16 v[12:15], v[96:99], v[100:103], v[12:15]
	v_mfma_f32_16x16x32_bf16 v[20:23], v[92:95], v[108:111], v[20:23]
	v_mfma_f32_16x16x32_bf16 v[28:31], v[96:99], v[108:111], v[28:31]
	v_mfma_f32_16x16x32_bf16 v[64:67], v[92:95], v[116:119], v[64:67]
	v_mfma_f32_16x16x32_bf16 v[68:71], v[96:99], v[116:119], v[68:71]
	v_mfma_f32_16x16x32_bf16 v[72:75], v[92:95], v[124:127], v[72:75]
	v_mfma_f32_16x16x32_bf16 v[76:79], v[96:99], v[124:127], v[76:79]
	v_mfma_f32_16x16x32_bf16 v[60:63], v[84:87], v[104:107], v[4:7]
	v_mfma_f32_16x16x32_bf16 v[52:55], v[88:91], v[104:107], v[12:15]
	v_mfma_f32_16x16x32_bf16 v[44:47], v[84:87], v[112:115], v[20:23]
	v_mfma_f32_16x16x32_bf16 v[36:39], v[88:91], v[112:115], v[28:31]
	v_mfma_f32_16x16x32_bf16 v[28:31], v[84:87], v[120:123], v[64:67]
	v_mfma_f32_16x16x32_bf16 v[20:23], v[88:91], v[120:123], v[68:71]
	v_mfma_f32_16x16x32_bf16 v[12:15], v[84:87], v[128:131], v[72:75]
	v_mfma_f32_16x16x32_bf16 v[4:7], v[88:91], v[128:131], v[76:79]
	s_setprio 0
	v_cmp_gt_u32_e32 vcc, s63, v183
	s_barrier
	s_and_saveexec_b64 s[18:19], vcc
	s_cbranch_execz .LBB0_369
	s_barrier

.LBB0_379:
	s_cmp_gt_i32 s64, 1
	s_mov_b64 s[18:19], -1
	s_cbranch_scc0 .LBB0_381
	v_lshlrev_b32_e32 v160, 6, v190
	v_or3_b32 v161, v160, v188, s14
	v_lshlrev_b32_e32 v160, 6, v191
	v_lshlrev_b32_e32 v162, 4, v189
	v_or3_b32 v160, v162, v160, s16
	v_mad_u64_u32 v[166:167], s[18:19], v161, s15, v[160:161]
	v_mul_f32_e32 v160, v148, v144
	v_mul_f32_e32 v161, v149, v145
	v_cvt_pk_bf16_f32 v160, v160, v161
	v_mul_f32_e32 v161, v150, v146
	v_mul_f32_e32 v162, v151, v147
	v_cvt_pk_bf16_f32 v161, v161, v162
	v_mul_f32_e32 v162, v156, v152
	v_mul_f32_e32 v163, v157, v153
	v_cvt_pk_bf16_f32 v162, v162, v163
	v_mul_f32_e32 v163, v158, v154
	v_mul_f32_e32 v167, v159, v155
	v_cvt_pk_bf16_f32 v163, v163, v167
	global_store_dwordx4 v166, v[160:163], s[10:11] sc0 sc1
	s_lshl_b32 s17, s15, 4
	v_add_u32_e32 v166, s17, v166
	v_mul_f32_e32 v160, v132, v128
	v_mul_f32_e32 v161, v133, v129
	v_cvt_pk_bf16_f32 v160, v160, v161
	v_mul_f32_e32 v161, v134, v130
	v_mul_f32_e32 v162, v135, v131
	v_cvt_pk_bf16_f32 v161, v161, v162
	v_mul_f32_e32 v162, v140, v136
	v_mul_f32_e32 v163, v141, v137
	v_cvt_pk_bf16_f32 v162, v162, v163
	v_mul_f32_e32 v163, v142, v138
	v_mul_f32_e32 v167, v143, v139
	v_cvt_pk_bf16_f32 v163, v163, v167
	global_store_dwordx4 v166, v[160:163], s[10:11] sc0 sc1
	v_add_u32_e32 v166, s17, v166
	v_mul_f32_e32 v167, v127, v123
	v_mul_f32_e32 v160, v116, v112
	v_mul_f32_e32 v161, v117, v113
	v_cvt_pk_bf16_f32 v160, v160, v161
	v_mul_f32_e32 v161, v118, v114
	v_mul_f32_e32 v162, v119, v115
	v_cvt_pk_bf16_f32 v161, v161, v162
	v_mul_f32_e32 v162, v124, v120
	v_mul_f32_e32 v163, v125, v121
	v_cvt_pk_bf16_f32 v162, v162, v163
	v_mul_f32_e32 v163, v126, v122
	v_cvt_pk_bf16_f32 v163, v163, v167
	global_store_dwordx4 v166, v[160:163], s[10:11] sc0 sc1
	v_add_u32_e32 v193, s17, v166
	v_mul_f32_e32 v166, v111, v107
	v_mul_f32_e32 v160, v100, v24
	v_mul_f32_e32 v161, v101, v25
	v_cvt_pk_bf16_f32 v160, v160, v161
	v_mul_f32_e32 v161, v102, v26
	v_mul_f32_e32 v162, v103, v27
	v_cvt_pk_bf16_f32 v161, v161, v162
	v_mul_f32_e32 v162, v108, v104
	v_mul_f32_e32 v163, v109, v105
	v_cvt_pk_bf16_f32 v162, v162, v163
	v_mul_f32_e32 v163, v110, v106
	v_cvt_pk_bf16_f32 v163, v163, v166
	s_mov_b64 s[18:19], 0

.LBB0_402:
	v_add_u32_e32 v68, s72, v68
	v_cvt_pk_bf16_f32 v64, v56, v57
	v_cvt_pk_bf16_f32 v65, v58, v59
	v_cvt_pk_bf16_f32 v66, v48, v49
	v_cvt_pk_bf16_f32 v67, v50, v51
	global_store_dwordx4 v68, v[64:67], s[10:11] sc0 sc1
	v_add_u32_e32 v69, s67, v68
	s_nop 0
	v_cvt_pk_bf16_f32 v64, v60, v61
	v_cvt_pk_bf16_f32 v65, v62, v63
	v_cvt_pk_bf16_f32 v66, v52, v53
	v_cvt_pk_bf16_f32 v67, v54, v55
	global_store_dwordx4 v69, v[64:67], s[10:11] sc0 sc1
	v_add_u32_e32 v69, s30, v68
	v_add_u32_e32 v68, s68, v68
	v_cvt_pk_bf16_f32 v64, v40, v41
	v_cvt_pk_bf16_f32 v65, v42, v43
	v_cvt_pk_bf16_f32 v66, v32, v33
	v_cvt_pk_bf16_f32 v67, v34, v35
	global_store_dwordx4 v69, v[64:67], s[10:11] sc0 sc1
	v_add_u32_e32 v69, s67, v69
	s_nop 0
	v_cvt_pk_bf16_f32 v64, v44, v45
	v_cvt_pk_bf16_f32 v65, v46, v47
	v_cvt_pk_bf16_f32 v66, v36, v37
	v_cvt_pk_bf16_f32 v67, v38, v39
	global_store_dwordx4 v69, v[64:67], s[10:11] sc0 sc1
	v_add_u32_e32 v69, s67, v68
	s_nop 0
	v_cvt_pk_bf16_f32 v64, v24, v25
	v_cvt_pk_bf16_f32 v65, v26, v27
	v_cvt_pk_bf16_f32 v66, v16, v17
	v_cvt_pk_bf16_f32 v67, v18, v19
	global_store_dwordx4 v68, v[64:67], s[10:11] sc0 sc1
	v_add_u32_e32 v68, s30, v68
	v_add_u32_e32 v76, s67, v68
	v_cvt_pk_bf16_f32 v64, v28, v29
	v_cvt_pk_bf16_f32 v65, v30, v31
	v_cvt_pk_bf16_f32 v66, v20, v21
	v_cvt_pk_bf16_f32 v67, v22, v23
	global_store_dwordx4 v69, v[64:67], s[10:11] sc0 sc1
	s_nop 1
	v_cvt_pk_bf16_f32 v64, v8, v9
	v_cvt_pk_bf16_f32 v65, v10, v11
	v_cvt_pk_bf16_f32 v66, v0, v1
	v_cvt_pk_bf16_f32 v67, v2, v3
	global_store_dwordx4 v68, v[64:67], s[10:11] sc0 sc1
	s_nop 1
	v_cvt_pk_bf16_f32 v64, v12, v13
	v_cvt_pk_bf16_f32 v65, v14, v15
	v_cvt_pk_bf16_f32 v66, v4, v5
	v_cvt_pk_bf16_f32 v67, v6, v7
.LBB0_403:
	s_andn2_b64 vcc, exec, s[26:27]
	s_cbranch_vccnz .LBB0_336
	v_mul_lo_u32 v64, v75, s61
	v_lshlrev_b32_e32 v67, 4, v71
	v_add_u32_e32 v64, 0x20000, v64
	v_and_b32_e32 v67, 0x70, v67
	v_mul_u32_u24_e32 v68, 0x90, v72
	v_lshlrev_b32_e32 v69, 4, v73
	v_bfe_u32 v65, v71, 3, 3
	v_lshlrev_b32_e32 v66, 7, v74
	s_lshl_b32 s16, s66, 9
	v_add3_u32 v68, v64, v68, v69
	v_lshl_or_b32 v69, v70, 6, s14
	v_or_b32_e32 v64, v64, v67
	v_or3_b32 v69, v69, v65, s47
	v_mad_u32_u24 v64, v65, s62, v64
	v_cvt_pk_bf16_f32 v56, v56, v57
	v_cvt_pk_bf16_f32 v57, v58, v59
	v_cvt_pk_bf16_f32 v58, v48, v49
	v_cvt_pk_bf16_f32 v59, v50, v51
	ds_write_b128 v68, v[56:59]
	v_cvt_pk_bf16_f32 v48, v60, v61
	v_cvt_pk_bf16_f32 v49, v62, v63
	v_cvt_pk_bf16_f32 v50, v52, v53
	v_cvt_pk_bf16_f32 v51, v54, v55
	ds_write_b128 v68, v[48:51] offset:64
	v_or3_b32 v52, v66, s16, v67
	ds_read_b128 v[48:51], v64
	v_mad_u64_u32 v[56:57], s[26:27], v69, s15, v[52:53]
	ds_read_b128 v[52:55], v64 offset:1152
	s_lshl_b32 s14, s15, 3
	v_cvt_pk_bf16_f32 v40, v40, v41
	v_cvt_pk_bf16_f32 v41, v42, v43
	v_cvt_pk_bf16_f32 v42, v32, v33
	v_cvt_pk_bf16_f32 v43, v34, v35
	ds_write_b128 v68, v[40:43]
	v_cvt_pk_bf16_f32 v32, v44, v45
	v_cvt_pk_bf16_f32 v33, v46, v47
	v_cvt_pk_bf16_f32 v34, v36, v37
	v_cvt_pk_bf16_f32 v35, v38, v39
	ds_write_b128 v68, v[32:35] offset:64
	v_add_u32_e32 v36, s14, v56
	s_waitcnt lgkmcnt(0)
	global_store_dwordx4 v56, v[48:51], s[10:11] sc0 sc1
	ds_read_b128 v[32:35], v64
	global_store_dwordx4 v36, v[52:55], s[10:11] sc0 sc1
	v_add_u32_e32 v40, s14, v36
	ds_read_b128 v[36:39], v64 offset:1152
	v_cvt_pk_bf16_f32 v24, v24, v25
	v_cvt_pk_bf16_f32 v25, v26, v27
	v_cvt_pk_bf16_f32 v26, v16, v17
	v_cvt_pk_bf16_f32 v27, v18, v19
	ds_write_b128 v68, v[24:27]
	v_cvt_pk_bf16_f32 v16, v28, v29
	v_cvt_pk_bf16_f32 v17, v30, v31
	v_cvt_pk_bf16_f32 v18, v20, v21
	v_cvt_pk_bf16_f32 v19, v22, v23
	ds_write_b128 v68, v[16:19] offset:64
	v_add_u32_e32 v20, s14, v40
	s_waitcnt lgkmcnt(0)
	global_store_dwordx4 v40, v[32:35], s[10:11] sc0 sc1
	ds_read_b128 v[16:19], v64
	global_store_dwordx4 v20, v[36:39], s[10:11] sc0 sc1
	v_add_u32_e32 v24, s14, v20
	ds_read_b128 v[20:23], v64 offset:1152
	v_cvt_pk_bf16_f32 v8, v8, v9
	v_cvt_pk_bf16_f32 v9, v10, v11
	v_cvt_pk_bf16_f32 v10, v0, v1
	v_cvt_pk_bf16_f32 v11, v2, v3
	ds_write_b128 v68, v[8:11]
	v_cvt_pk_bf16_f32 v0, v12, v13
	v_cvt_pk_bf16_f32 v1, v14, v15
	v_cvt_pk_bf16_f32 v2, v4, v5
	v_cvt_pk_bf16_f32 v3, v6, v7
	ds_write_b128 v68, v[0:3] offset:64
	ds_read_b128 v[0:3], v64
	ds_read_b128 v[64:67], v64 offset:1152
	v_add_u32_e32 v4, s14, v24
	s_waitcnt lgkmcnt(0)
	global_store_dwordx4 v24, v[16:19], s[10:11] sc0 sc1
	global_store_dwordx4 v4, v[20:23], s[10:11] sc0 sc1
	v_add_u32_e32 v4, s14, v4
	v_add_u32_e32 v76, s14, v4
	global_store_dwordx4 v4, v[0:3], s[10:11] sc0 sc1
	s_branch .LBB0_336

.LBB0_408:
	s_cmp_gt_i32 s64, 1
	s_mov_b64 s[26:27], -1
	s_cbranch_scc0 .LBB0_410
	v_lshlrev_b32_e32 v64, 6, v74
	v_lshlrev_b32_e32 v65, 4, v73
	v_lshl_or_b32 v66, v70, 6, s14
	v_or3_b32 v66, v66, v72, s47
	v_or3_b32 v64, v65, v64, s16
	v_mad_u64_u32 v[68:69], s[26:27], v66, s15, v[64:65]
	v_mul_f32_e32 v64, v56, v48
	v_mul_f32_e32 v65, v57, v49
	v_cvt_pk_bf16_f32 v64, v64, v65
	v_mul_f32_e32 v65, v58, v50
	v_mul_f32_e32 v66, v59, v51
	v_cvt_pk_bf16_f32 v65, v65, v66
	v_mul_f32_e32 v66, v60, v52
	v_mul_f32_e32 v67, v61, v53
	v_cvt_pk_bf16_f32 v66, v66, v67
	v_mul_f32_e32 v67, v62, v54
	v_mul_f32_e32 v69, v63, v55
	v_cvt_pk_bf16_f32 v67, v67, v69
	global_store_dwordx4 v68, v[64:67], s[10:11] sc0 sc1
	s_lshl_b32 s16, s15, 4
	v_add_u32_e32 v68, s16, v68
	v_mul_f32_e32 v64, v40, v32
	v_mul_f32_e32 v65, v41, v33
	v_cvt_pk_bf16_f32 v64, v64, v65
	v_mul_f32_e32 v65, v42, v34
	v_mul_f32_e32 v66, v43, v35
	v_cvt_pk_bf16_f32 v65, v65, v66
	v_mul_f32_e32 v66, v44, v36
	v_mul_f32_e32 v67, v45, v37
	v_cvt_pk_bf16_f32 v66, v66, v67
	v_mul_f32_e32 v67, v46, v38
	v_mul_f32_e32 v69, v47, v39
	v_cvt_pk_bf16_f32 v67, v67, v69
	global_store_dwordx4 v68, v[64:67], s[10:11] sc0 sc1
	v_add_u32_e32 v68, s16, v68
	v_mul_f32_e32 v69, v31, v23
	v_mul_f32_e32 v64, v24, v16
	v_mul_f32_e32 v65, v25, v17
	v_cvt_pk_bf16_f32 v64, v64, v65
	v_mul_f32_e32 v65, v26, v18
	v_mul_f32_e32 v66, v27, v19
	v_cvt_pk_bf16_f32 v65, v65, v66
	v_mul_f32_e32 v66, v28, v20
	v_mul_f32_e32 v67, v29, v21
	v_cvt_pk_bf16_f32 v66, v66, v67
	v_mul_f32_e32 v67, v30, v22
	v_cvt_pk_bf16_f32 v67, v67, v69
	global_store_dwordx4 v68, v[64:67], s[10:11] sc0 sc1
	v_add_u32_e32 v76, s16, v68
	v_mul_f32_e32 v68, v15, v7
	v_mul_f32_e32 v64, v8, v0
	v_mul_f32_e32 v65, v9, v1
	v_cvt_pk_bf16_f32 v64, v64, v65
	v_mul_f32_e32 v65, v10, v2
	v_mul_f32_e32 v66, v11, v3
	v_cvt_pk_bf16_f32 v65, v65, v66
	v_mul_f32_e32 v66, v12, v4
	v_mul_f32_e32 v67, v13, v5
	v_cvt_pk_bf16_f32 v66, v66, v67
	v_mul_f32_e32 v67, v14, v6
	v_cvt_pk_bf16_f32 v67, v67, v68
	s_mov_b64 s[26:27], 0

.LBB0_453:
	v_mbcnt_lo_u32_b32 v64, -1, 0
	v_mbcnt_hi_u32_b32 v64, -1, v64
	v_cvt_pk_bf16_f32 v56, v56, v57
	v_cvt_pk_bf16_f32 v57, v58, v59
	v_cvt_pk_bf16_f32 v58, v48, v49
	v_cvt_pk_bf16_f32 v59, v50, v51
	v_cvt_pk_bf16_f32 v48, v60, v61
	s_nop 0
	v_add_u32_e32 v65, s74, v64
	v_ashrrev_i32_e32 v66, 6, v65
	v_and_b32_e32 v67, 15, v64
	v_and_b32_e32 v68, 48, v64
	v_mul_lo_u32 v69, v66, s79
	v_lshrrev_b32_e32 v65, 2, v65
	v_bfe_u32 v70, v64, 3, 3
	v_lshlrev_b32_e32 v64, 4, v64
	v_add_u32_e32 v69, 0x20000, v69
	v_and_b32_e32 v65, 64, v65
	v_and_b32_e32 v64, 0x70, v64
	v_mul_u32_u24_e32 v67, 0x90, v67
	v_add3_u32 v67, v69, v67, v68
	v_or_b32_e32 v68, v69, v64
	v_or3_b32 v65, s24, v65, v70
	v_lshlrev_b32_e32 v66, 7, v66
	v_mad_u32_u24 v68, v70, s80, v68
	ds_write_b128 v67, v[56:59]
	v_cvt_pk_bf16_f32 v49, v62, v63
	v_cvt_pk_bf16_f32 v50, v52, v53
	v_cvt_pk_bf16_f32 v51, v54, v55
	ds_write_b128 v67, v[48:51] offset:64
	v_lshlrev_b32_e32 v52, 12, v65
	ds_read_b128 v[48:51], v68
	v_and_or_b32 v52, v66, s81, v52
	v_or3_b32 v128, v52, s68, v64
	v_lshl_add_u64 v[56:57], s[0:1], 0, v[128:129]
	v_add_co_u32_e32 v58, vcc, s93, v56
	ds_read_b128 v[52:55], v68 offset:1152
	v_cvt_pk_bf16_f32 v44, v44, v45
	v_cvt_pk_bf16_f32 v45, v46, v47
	v_cvt_pk_bf16_f32 v46, v40, v41
	v_cvt_pk_bf16_f32 v47, v42, v43
	ds_write_b128 v67, v[44:47]
	v_cvt_pk_bf16_f32 v28, v28, v29
	v_cvt_pk_bf16_f32 v29, v30, v31
	v_cvt_pk_bf16_f32 v30, v24, v25
	v_cvt_pk_bf16_f32 v31, v26, v27
	ds_write_b128 v67, v[28:31] offset:64
	v_addc_co_u32_e32 v59, vcc, 0, v57, vcc
	ds_read_b128 v[24:27], v68
	ds_read_b128 v[28:31], v68 offset:1152
	s_waitcnt lgkmcnt(0)
	global_store_dwordx4 v[58:59], v[48:51], off sc0 sc1
	v_cvt_pk_bf16_f32 v20, v20, v21
	v_cvt_pk_bf16_f32 v21, v22, v23
	v_cvt_pk_bf16_f32 v22, v16, v17
	v_cvt_pk_bf16_f32 v23, v18, v19
	ds_write_b128 v67, v[20:23] offset:64
	s_nop 0
	v_add_co_u32_e32 v48, vcc, s94, v56
	v_cvt_pk_bf16_f32 v8, v8, v9
	v_cvt_pk_bf16_f32 v9, v10, v11
	v_cvt_pk_bf16_f32 v10, v0, v1
	v_cvt_pk_bf16_f32 v11, v2, v3
	s_nop 1
	v_addc_co_u32_e32 v49, vcc, 0, v57, vcc
	v_add_co_u32_e32 v40, vcc, s95, v56
	v_cvt_pk_bf16_f32 v0, v12, v13
	v_cvt_pk_bf16_f32 v1, v14, v15
	v_cvt_pk_bf16_f32 v2, v4, v5
	v_cvt_pk_bf16_f32 v3, v6, v7
	s_nop 1
	v_addc_co_u32_e32 v41, vcc, 0, v57, vcc
	global_store_dwordx4 v[40:41], v[24:27], off sc0 sc1
	s_add_i32 s75, s75, 1
	global_store_dwordx4 v[48:49], v[52:55], off sc0 sc1
	v_add_co_u32_e32 v24, vcc, s96, v56
	v_cvt_pk_bf16_f32 v26, v32, v33
	v_cvt_pk_bf16_f32 v27, v34, v35
	s_nop 1
	v_addc_co_u32_e32 v25, vcc, 0, v57, vcc
	global_store_dwordx4 v[24:25], v[28:31], off sc0 sc1
	v_cvt_pk_bf16_f32 v24, v36, v37
	v_cvt_pk_bf16_f32 v25, v38, v39
	ds_write_b128 v67, v[24:27]
	ds_read_b128 v[16:19], v68
	ds_read_b128 v[20:23], v68 offset:1152
	v_add_co_u32_e32 v24, vcc, s97, v56
	ds_write_b128 v67, v[8:11]
	ds_write_b128 v67, v[0:3] offset:64
	v_addc_co_u32_e32 v25, vcc, 0, v57, vcc
	ds_read_b128 v[0:3], v68
	ds_read_b128 v[4:7], v68 offset:1152
	s_waitcnt lgkmcnt(0)
	global_store_dwordx4 v[24:25], v[16:19], off sc0 sc1
	s_nop 1
	v_add_co_u32_e32 v16, vcc, s85, v56
	s_nop 1
	v_addc_co_u32_e32 v17, vcc, 0, v57, vcc
	v_add_co_u32_e32 v8, vcc, 0xb0000, v56
	global_store_dwordx4 v[16:17], v[20:23], off sc0 sc1
	s_nop 0
	v_addc_co_u32_e32 v9, vcc, 0, v57, vcc
	global_store_dwordx4 v[8:9], v[0:3], off sc0 sc1
	s_nop 1
	v_add_co_u32_e32 v0, vcc, 0xb8000, v56
	s_nop 1
	v_addc_co_u32_e32 v1, vcc, 0, v57, vcc
	s_andn2_b64 vcc, exec, s[66:67]
	s_mov_b64 s[66:67], 0
	global_store_dwordx4 v[0:1], v[4:7], off sc0 sc1
	s_cbranch_vccz .LBB0_470

.LBB0_465:
	ds_read_b128 v[164:167], v162
	ds_read_b128 v[168:171], v162 offset:1024
	ds_read_b128 v[172:175], v162 offset:2048
	ds_read_b128 v[176:179], v162 offset:3072
	v_lshl_add_u64 v[228:229], s[50:51], 0, v[132:133]
	s_mov_b64 s[68:69], 0xe080080
	v_readfirstlane_b32 s36, v161
	v_lshl_add_u64 v[212:213], v[228:229], 0, s[68:69]
	s_mov_b32 m0, s36
	s_mov_b64 s[68:69], 0xe0c0080
	v_readfirstlane_b32 s36, v160
	ds_read_b128 v[180:183], v153
	ds_read_b128 v[184:187], v153 offset:1024
	ds_read_b128 v[188:191], v152
	ds_read_b128 v[192:195], v152 offset:1024
	ds_read_b128 v[196:199], v151
	ds_read_b128 v[200:203], v151 offset:1024
	ds_read_b128 v[204:207], v150
	ds_read_b128 v[208:211], v150 offset:1024
	global_load_lds_dwordx4 v[212:213], off
	v_lshl_add_u64 v[212:213], v[228:229], 0, s[68:69]
	s_mov_b32 m0, s36
	s_nop 0
	global_load_lds_dwordx4 v[212:213], off
	s_waitcnt lgkmcnt(8)
	s_barrier
	s_waitcnt lgkmcnt(0)
	s_setprio 1
	s_waitcnt lgkmcnt(0)
	v_mfma_f32_16x16x32_bf16 v[124:127], v[164:167], v[180:183], v[124:127]
	v_mfma_f32_16x16x32_bf16 v[120:123], v[172:175], v[180:183], v[120:123]
	v_mfma_f32_16x16x32_bf16 v[116:119], v[164:167], v[188:191], v[116:119]
	v_mfma_f32_16x16x32_bf16 v[112:115], v[172:175], v[188:191], v[112:115]
	v_mfma_f32_16x16x32_bf16 v[108:111], v[164:167], v[196:199], v[108:111]
	v_mfma_f32_16x16x32_bf16 v[104:107], v[172:175], v[196:199], v[104:107]
	v_mfma_f32_16x16x32_bf16 v[100:103], v[164:167], v[204:207], v[100:103]
	v_mfma_f32_16x16x32_bf16 v[96:99], v[172:175], v[204:207], v[96:99]
	v_mfma_f32_16x16x32_bf16 v[124:127], v[168:171], v[184:187], v[124:127]
	v_mfma_f32_16x16x32_bf16 v[120:123], v[176:179], v[184:187], v[120:123]
	v_mfma_f32_16x16x32_bf16 v[116:119], v[168:171], v[192:195], v[116:119]
	v_mfma_f32_16x16x32_bf16 v[112:115], v[176:179], v[192:195], v[112:115]
	v_mfma_f32_16x16x32_bf16 v[108:111], v[168:171], v[200:203], v[108:111]
	v_mfma_f32_16x16x32_bf16 v[104:107], v[176:179], v[200:203], v[104:107]
	v_mfma_f32_16x16x32_bf16 v[100:103], v[168:171], v[208:211], v[100:103]
	v_mfma_f32_16x16x32_bf16 v[96:99], v[176:179], v[208:211], v[96:99]
	s_setprio 0
	s_barrier
	v_lshl_add_u64 v[230:231], s[50:51], 0, v[130:131]
	s_mov_b64 s[68:69], 0x3880000
	v_readfirstlane_b32 s36, v149
	v_lshl_add_u64 v[232:233], v[230:231], 0, s[68:69]
	s_mov_b32 m0, s36
	s_mov_b64 s[68:69], 0x3881000
	v_readfirstlane_b32 s36, v148
	ds_read_b128 v[212:215], v159
	ds_read_b128 v[216:219], v159 offset:1024
	ds_read_b128 v[220:223], v159 offset:2048
	ds_read_b128 v[224:227], v159 offset:3072
	global_load_lds_dwordx4 v[232:233], off
	v_lshl_add_u64 v[232:233], v[230:231], 0, s[68:69]
	s_mov_b32 m0, s36
	s_nop 0
	global_load_lds_dwordx4 v[232:233], off
	s_barrier
	s_waitcnt lgkmcnt(0)
	s_setprio 1
	s_waitcnt lgkmcnt(0)
	v_mfma_f32_16x16x32_bf16 v[92:95], v[212:215], v[180:183], v[92:95]
	v_mfma_f32_16x16x32_bf16 v[88:91], v[220:223], v[180:183], v[88:91]
	v_mfma_f32_16x16x32_bf16 v[84:87], v[212:215], v[188:191], v[84:87]
	v_mfma_f32_16x16x32_bf16 v[80:83], v[220:223], v[188:191], v[80:83]
	v_mfma_f32_16x16x32_bf16 v[76:79], v[212:215], v[196:199], v[76:79]
	v_mfma_f32_16x16x32_bf16 v[72:75], v[220:223], v[196:199], v[72:75]
	v_mfma_f32_16x16x32_bf16 v[68:71], v[212:215], v[204:207], v[68:71]
	v_mfma_f32_16x16x32_bf16 v[64:67], v[220:223], v[204:207], v[64:67]
	v_mfma_f32_16x16x32_bf16 v[92:95], v[216:219], v[184:187], v[92:95]
	v_mfma_f32_16x16x32_bf16 v[88:91], v[224:227], v[184:187], v[88:91]
	v_mfma_f32_16x16x32_bf16 v[84:87], v[216:219], v[192:195], v[84:87]
	v_mfma_f32_16x16x32_bf16 v[80:83], v[224:227], v[192:195], v[80:83]
	v_mfma_f32_16x16x32_bf16 v[76:79], v[216:219], v[200:203], v[76:79]
	v_mfma_f32_16x16x32_bf16 v[72:75], v[224:227], v[200:203], v[72:75]
	v_mfma_f32_16x16x32_bf16 v[68:71], v[216:219], v[208:211], v[68:71]
	v_mfma_f32_16x16x32_bf16 v[64:67], v[224:227], v[208:211], v[64:67]
	s_setprio 0
	s_mov_b64 s[68:69], 0xe000100
	v_readfirstlane_b32 s36, v135
	v_lshl_add_u64 v[232:233], v[228:229], 0, s[68:69]
	s_mov_b32 m0, s36
	s_mov_b64 s[68:69], 0xe040100
	v_readfirstlane_b32 s36, v147
	s_barrier
	ds_read_b128 v[180:183], v153 offset:16384
	ds_read_b128 v[184:187], v153 offset:17408
	ds_read_b128 v[188:191], v152 offset:16384
	ds_read_b128 v[192:195], v152 offset:17408
	ds_read_b128 v[196:199], v151 offset:16384
	ds_read_b128 v[200:203], v151 offset:17408
	ds_read_b128 v[204:207], v150 offset:16384
	ds_read_b128 v[208:211], v150 offset:17408
	global_load_lds_dwordx4 v[232:233], off
	v_lshl_add_u64 v[232:233], v[228:229], 0, s[68:69]
	s_mov_b32 m0, s36
	s_nop 0
	global_load_lds_dwordx4 v[232:233], off
	s_barrier
	s_waitcnt lgkmcnt(0)
	s_setprio 1
	s_waitcnt lgkmcnt(0)
	v_mfma_f32_16x16x32_bf16 v[60:63], v[164:167], v[180:183], v[60:63]
	v_mfma_f32_16x16x32_bf16 v[56:59], v[172:175], v[180:183], v[56:59]
	v_mfma_f32_16x16x32_bf16 v[52:55], v[164:167], v[188:191], v[52:55]
	v_mfma_f32_16x16x32_bf16 v[48:51], v[172:175], v[188:191], v[48:51]
	v_mfma_f32_16x16x32_bf16 v[44:47], v[164:167], v[196:199], v[44:47]
	v_mfma_f32_16x16x32_bf16 v[40:43], v[172:175], v[196:199], v[40:43]
	v_mfma_f32_16x16x32_bf16 v[36:39], v[164:167], v[204:207], v[36:39]
	v_mfma_f32_16x16x32_bf16 v[32:35], v[172:175], v[204:207], v[32:35]
	v_mfma_f32_16x16x32_bf16 v[60:63], v[168:171], v[184:187], v[60:63]
	v_mfma_f32_16x16x32_bf16 v[56:59], v[176:179], v[184:187], v[56:59]
	v_mfma_f32_16x16x32_bf16 v[52:55], v[168:171], v[192:195], v[52:55]
	v_mfma_f32_16x16x32_bf16 v[48:51], v[176:179], v[192:195], v[48:51]
	v_mfma_f32_16x16x32_bf16 v[44:47], v[168:171], v[200:203], v[44:47]
	v_mfma_f32_16x16x32_bf16 v[40:43], v[176:179], v[200:203], v[40:43]
	v_mfma_f32_16x16x32_bf16 v[36:39], v[168:171], v[208:211], v[36:39]
	v_mfma_f32_16x16x32_bf16 v[32:35], v[176:179], v[208:211], v[32:35]
	s_setprio 0
	s_barrier
	s_mov_b64 s[68:69], 0x3882000
	v_readfirstlane_b32 s36, v146
	v_lshl_add_u64 v[164:165], v[230:231], 0, s[68:69]
	s_mov_b32 m0, s36
	s_mov_b64 s[68:69], 0x3883000
	v_readfirstlane_b32 s36, v145
	global_load_lds_dwordx4 v[164:165], off
	v_lshl_add_u64 v[164:165], v[230:231], 0, s[68:69]
	s_mov_b32 m0, s36
	s_nop 0
	global_load_lds_dwordx4 v[164:165], off
	s_waitcnt vmcnt(6)
	s_barrier
	s_setprio 1
	v_mfma_f32_16x16x32_bf16 v[28:31], v[212:215], v[180:183], v[28:31]
	v_mfma_f32_16x16x32_bf16 v[24:27], v[220:223], v[180:183], v[24:27]
	v_mfma_f32_16x16x32_bf16 v[20:23], v[212:215], v[188:191], v[20:23]
	v_mfma_f32_16x16x32_bf16 v[16:19], v[220:223], v[188:191], v[16:19]
	v_mfma_f32_16x16x32_bf16 v[12:15], v[212:215], v[196:199], v[12:15]
	v_mfma_f32_16x16x32_bf16 v[8:11], v[220:223], v[196:199], v[8:11]
	v_mfma_f32_16x16x32_bf16 v[4:7], v[212:215], v[204:207], v[4:7]
	v_mfma_f32_16x16x32_bf16 v[0:3], v[220:223], v[204:207], v[0:3]
	v_mfma_f32_16x16x32_bf16 v[28:31], v[216:219], v[184:187], v[28:31]
	v_mfma_f32_16x16x32_bf16 v[24:27], v[224:227], v[184:187], v[24:27]
	v_mfma_f32_16x16x32_bf16 v[20:23], v[216:219], v[192:195], v[20:23]
	v_mfma_f32_16x16x32_bf16 v[16:19], v[224:227], v[192:195], v[16:19]
	v_mfma_f32_16x16x32_bf16 v[12:15], v[216:219], v[200:203], v[12:15]
	v_mfma_f32_16x16x32_bf16 v[8:11], v[224:227], v[200:203], v[8:11]
	v_mfma_f32_16x16x32_bf16 v[4:7], v[216:219], v[208:211], v[4:7]
	v_mfma_f32_16x16x32_bf16 v[0:3], v[224:227], v[208:211], v[0:3]
	s_setprio 0
	s_barrier
	ds_read_b128 v[164:167], v155
	ds_read_b128 v[168:171], v155 offset:1024
	ds_read_b128 v[172:175], v155 offset:2048
	ds_read_b128 v[176:179], v155 offset:3072
	v_readfirstlane_b32 s36, v144
	v_lshl_add_u64 v[212:213], v[228:229], 0, s[26:27]
	s_mov_b32 m0, s36
	v_readfirstlane_b32 s36, v143
	ds_read_b128 v[180:183], v153 offset:32768
	ds_read_b128 v[184:187], v153 offset:33792
	ds_read_b128 v[188:191], v152 offset:32768
	ds_read_b128 v[192:195], v152 offset:33792
	ds_read_b128 v[196:199], v151 offset:32768
	ds_read_b128 v[200:203], v151 offset:33792
	ds_read_b128 v[204:207], v150 offset:32768
	ds_read_b128 v[208:211], v150 offset:33792
	global_load_lds_dwordx4 v[212:213], off
	v_lshl_add_u64 v[212:213], v[228:229], 0, s[28:29]
	s_mov_b32 m0, s36
	s_nop 0
	global_load_lds_dwordx4 v[212:213], off
	s_waitcnt lgkmcnt(8)
	s_barrier
	s_waitcnt lgkmcnt(0)
	s_setprio 1
	s_waitcnt lgkmcnt(0)
	v_mfma_f32_16x16x32_bf16 v[124:127], v[164:167], v[180:183], v[124:127]
	v_mfma_f32_16x16x32_bf16 v[120:123], v[172:175], v[180:183], v[120:123]
	v_mfma_f32_16x16x32_bf16 v[116:119], v[164:167], v[188:191], v[116:119]
	v_mfma_f32_16x16x32_bf16 v[112:115], v[172:175], v[188:191], v[112:115]
	v_mfma_f32_16x16x32_bf16 v[108:111], v[164:167], v[196:199], v[108:111]
	v_mfma_f32_16x16x32_bf16 v[104:107], v[172:175], v[196:199], v[104:107]
	v_mfma_f32_16x16x32_bf16 v[100:103], v[164:167], v[204:207], v[100:103]
	v_mfma_f32_16x16x32_bf16 v[96:99], v[172:175], v[204:207], v[96:99]
	v_mfma_f32_16x16x32_bf16 v[124:127], v[168:171], v[184:187], v[124:127]
	v_mfma_f32_16x16x32_bf16 v[120:123], v[176:179], v[184:187], v[120:123]
	v_mfma_f32_16x16x32_bf16 v[116:119], v[168:171], v[192:195], v[116:119]
	v_mfma_f32_16x16x32_bf16 v[112:115], v[176:179], v[192:195], v[112:115]
	v_mfma_f32_16x16x32_bf16 v[108:111], v[168:171], v[200:203], v[108:111]
	v_mfma_f32_16x16x32_bf16 v[104:107], v[176:179], v[200:203], v[104:107]
	v_mfma_f32_16x16x32_bf16 v[100:103], v[168:171], v[208:211], v[100:103]
	v_mfma_f32_16x16x32_bf16 v[96:99], v[176:179], v[208:211], v[96:99]
	s_setprio 0
	s_barrier
	v_readfirstlane_b32 s36, v142
	v_lshl_add_u64 v[232:233], v[230:231], 0, s[30:31]
	s_mov_b32 m0, s36
	v_readfirstlane_b32 s36, v141
	ds_read_b128 v[212:215], v154
	ds_read_b128 v[216:219], v154 offset:1024
	ds_read_b128 v[220:223], v154 offset:2048
	ds_read_b128 v[224:227], v154 offset:3072
	global_load_lds_dwordx4 v[232:233], off
	v_lshl_add_u64 v[232:233], v[230:231], 0, s[34:35]
	s_mov_b32 m0, s36
	s_nop 0
	global_load_lds_dwordx4 v[232:233], off
	s_barrier
	s_waitcnt lgkmcnt(0)
	s_setprio 1
	s_waitcnt lgkmcnt(0)
	v_mfma_f32_16x16x32_bf16 v[92:95], v[212:215], v[180:183], v[92:95]
	v_mfma_f32_16x16x32_bf16 v[88:91], v[220:223], v[180:183], v[88:91]
	v_mfma_f32_16x16x32_bf16 v[84:87], v[212:215], v[188:191], v[84:87]
	v_mfma_f32_16x16x32_bf16 v[80:83], v[220:223], v[188:191], v[80:83]
	v_mfma_f32_16x16x32_bf16 v[76:79], v[212:215], v[196:199], v[76:79]
	v_mfma_f32_16x16x32_bf16 v[72:75], v[220:223], v[196:199], v[72:75]
	v_mfma_f32_16x16x32_bf16 v[68:71], v[212:215], v[204:207], v[68:71]
	v_mfma_f32_16x16x32_bf16 v[64:67], v[220:223], v[204:207], v[64:67]
	v_mfma_f32_16x16x32_bf16 v[92:95], v[216:219], v[184:187], v[92:95]
	v_mfma_f32_16x16x32_bf16 v[88:91], v[224:227], v[184:187], v[88:91]
	v_mfma_f32_16x16x32_bf16 v[84:87], v[216:219], v[192:195], v[84:87]
	v_mfma_f32_16x16x32_bf16 v[80:83], v[224:227], v[192:195], v[80:83]
	v_mfma_f32_16x16x32_bf16 v[76:79], v[216:219], v[200:203], v[76:79]
	v_mfma_f32_16x16x32_bf16 v[72:75], v[224:227], v[200:203], v[72:75]
	v_mfma_f32_16x16x32_bf16 v[68:71], v[216:219], v[208:211], v[68:71]
	v_mfma_f32_16x16x32_bf16 v[64:67], v[224:227], v[208:211], v[64:67]
	s_setprio 0
	v_readfirstlane_b32 s36, v140
	v_lshl_add_u64 v[232:233], v[228:229], 0, s[44:45]
	s_mov_b32 m0, s36
	v_readfirstlane_b32 s36, v139
	s_barrier
	ds_read_b128 v[180:183], v153 offset:49152
	ds_read_b128 v[184:187], v153 offset:50176
	ds_read_b128 v[188:191], v152 offset:49152
	ds_read_b128 v[192:195], v152 offset:50176
	ds_read_b128 v[196:199], v151 offset:49152
	ds_read_b128 v[200:203], v151 offset:50176
	ds_read_b128 v[204:207], v150 offset:49152
	ds_read_b128 v[208:211], v150 offset:50176
	global_load_lds_dwordx4 v[232:233], off
	v_lshl_add_u64 v[228:229], v[228:229], 0, s[46:47]
	s_mov_b32 m0, s36
	s_nop 0
	global_load_lds_dwordx4 v[228:229], off
	s_barrier
	s_waitcnt lgkmcnt(0)
	s_setprio 1
	s_waitcnt lgkmcnt(0)
	v_mfma_f32_16x16x32_bf16 v[60:63], v[164:167], v[180:183], v[60:63]
	v_mfma_f32_16x16x32_bf16 v[56:59], v[172:175], v[180:183], v[56:59]
	v_mfma_f32_16x16x32_bf16 v[52:55], v[164:167], v[188:191], v[52:55]
	v_mfma_f32_16x16x32_bf16 v[48:51], v[172:175], v[188:191], v[48:51]
	v_mfma_f32_16x16x32_bf16 v[44:47], v[164:167], v[196:199], v[44:47]
	v_mfma_f32_16x16x32_bf16 v[40:43], v[172:175], v[196:199], v[40:43]
	v_mfma_f32_16x16x32_bf16 v[36:39], v[164:167], v[204:207], v[36:39]
	v_mfma_f32_16x16x32_bf16 v[32:35], v[172:175], v[204:207], v[32:35]
	v_mfma_f32_16x16x32_bf16 v[60:63], v[168:171], v[184:187], v[60:63]
	v_mfma_f32_16x16x32_bf16 v[56:59], v[176:179], v[184:187], v[56:59]
	v_mfma_f32_16x16x32_bf16 v[52:55], v[168:171], v[192:195], v[52:55]
	v_mfma_f32_16x16x32_bf16 v[48:51], v[176:179], v[192:195], v[48:51]
	v_mfma_f32_16x16x32_bf16 v[44:47], v[168:171], v[200:203], v[44:47]
	v_mfma_f32_16x16x32_bf16 v[40:43], v[176:179], v[200:203], v[40:43]
	v_mfma_f32_16x16x32_bf16 v[36:39], v[168:171], v[208:211], v[36:39]
	v_mfma_f32_16x16x32_bf16 v[32:35], v[176:179], v[208:211], v[32:35]
	s_setprio 0
	s_barrier
	v_readfirstlane_b32 s36, v138
	v_lshl_add_u64 v[164:165], v[230:231], 0, s[56:57]
	s_mov_b32 m0, s36
	v_readfirstlane_b32 s36, v137
	global_load_lds_dwordx4 v[164:165], off
	v_lshl_add_u64 v[164:165], v[230:231], 0, s[58:59]
	s_mov_b32 m0, s36
	s_nop 0
	global_load_lds_dwordx4 v[164:165], off
	s_waitcnt vmcnt(6)
	s_barrier
	s_setprio 1
	v_mfma_f32_16x16x32_bf16 v[28:31], v[212:215], v[180:183], v[28:31]
	v_mfma_f32_16x16x32_bf16 v[24:27], v[220:223], v[180:183], v[24:27]
	v_mfma_f32_16x16x32_bf16 v[20:23], v[212:215], v[188:191], v[20:23]
	v_mfma_f32_16x16x32_bf16 v[16:19], v[220:223], v[188:191], v[16:19]
	v_mfma_f32_16x16x32_bf16 v[12:15], v[212:215], v[196:199], v[12:15]
	v_mfma_f32_16x16x32_bf16 v[8:11], v[220:223], v[196:199], v[8:11]
	v_mfma_f32_16x16x32_bf16 v[4:7], v[212:215], v[204:207], v[4:7]
	v_mfma_f32_16x16x32_bf16 v[0:3], v[220:223], v[204:207], v[0:3]
	v_mfma_f32_16x16x32_bf16 v[28:31], v[216:219], v[184:187], v[28:31]
	v_mfma_f32_16x16x32_bf16 v[24:27], v[224:227], v[184:187], v[24:27]
	v_mfma_f32_16x16x32_bf16 v[20:23], v[216:219], v[192:195], v[20:23]
	v_mfma_f32_16x16x32_bf16 v[16:19], v[224:227], v[192:195], v[16:19]
	v_mfma_f32_16x16x32_bf16 v[12:15], v[216:219], v[200:203], v[12:15]
	v_mfma_f32_16x16x32_bf16 v[8:11], v[224:227], v[200:203], v[8:11]
	v_mfma_f32_16x16x32_bf16 v[4:7], v[216:219], v[208:211], v[4:7]
	v_mfma_f32_16x16x32_bf16 v[0:3], v[224:227], v[208:211], v[0:3]
	s_setprio 0
	s_add_i32 s24, s24, 2
	v_lshl_add_u64 v[130:131], v[130:131], 0, s[10:11]
	s_cmp_lt_u32 s24, 28
	v_lshl_add_u64 v[132:133], v[132:133], 0, s[60:61]
	s_barrier
	s_cbranch_scc1 .LBB0_465
	s_lshl_b32 s24, s86, 5
	s_lshl_b32 s36, s86, 8
	s_and_b32 s24, s24, 0x1800
	s_and_b32 s36, s36, 0x700
	s_or_b32 s24, s36, s24
	v_lshlrev_b32_e32 v128, 3, v156
	v_lshlrev_b32_e32 v130, 5, v156
	v_and_b32_e32 v128, 0xffff0, v128
	v_and_b32_e32 v130, 32, v130
	s_lshl_b32 s36, s24, 12
	v_add_u32_e32 v130, v130, v158
	v_add_lshl_u32 v128, v157, v128, 12
	s_add_u32 s68, s70, s36
	v_lshl_add_u32 v128, v130, 1, v128
	s_addc_u32 s69, s71, 0
	v_lshl_add_u64 v[156:157], s[68:69], 0, v[128:129]
	v_readfirstlane_b32 s36, v161
	ds_read_b128 v[130:133], v162
	ds_read_b128 v[164:167], v162 offset:1024
	ds_read_b128 v[168:171], v162 offset:2048
	ds_read_b128 v[172:175], v162 offset:3072
	ds_read_b128 v[176:179], v153
	ds_read_b128 v[180:183], v153 offset:1024
	ds_read_b128 v[184:187], v152
	ds_read_b128 v[188:191], v152 offset:1024
	ds_read_b128 v[192:195], v151
	ds_read_b128 v[196:199], v151 offset:1024
	ds_read_b128 v[200:203], v150
	ds_read_b128 v[204:207], v150 offset:1024
	v_lshl_add_u64 v[162:163], v[156:157], 0, s[62:63]
	s_mov_b32 m0, s36
	v_readfirstlane_b32 s36, v160
	global_load_lds_dwordx4 v[162:163], off
	v_lshl_add_u64 v[156:157], v[156:157], 0, s[64:65]
	s_mov_b32 m0, s36
	s_nop 0
	global_load_lds_dwordx4 v[156:157], off
	s_barrier
	s_waitcnt lgkmcnt(0)
	s_setprio 1
	s_waitcnt lgkmcnt(0)
	v_mfma_f32_16x16x32_bf16 v[124:127], v[130:133], v[176:179], v[124:127]
	v_mfma_f32_16x16x32_bf16 v[120:123], v[168:171], v[176:179], v[120:123]
	v_mfma_f32_16x16x32_bf16 v[116:119], v[130:133], v[184:187], v[116:119]
	v_mfma_f32_16x16x32_bf16 v[112:115], v[168:171], v[184:187], v[112:115]
	v_mfma_f32_16x16x32_bf16 v[108:111], v[130:133], v[192:195], v[108:111]
	v_mfma_f32_16x16x32_bf16 v[104:107], v[168:171], v[192:195], v[104:107]
	v_mfma_f32_16x16x32_bf16 v[100:103], v[130:133], v[200:203], v[100:103]
	v_mfma_f32_16x16x32_bf16 v[96:99], v[168:171], v[200:203], v[96:99]
	v_mfma_f32_16x16x32_bf16 v[124:127], v[164:167], v[180:183], v[124:127]
	v_mfma_f32_16x16x32_bf16 v[120:123], v[172:175], v[180:183], v[120:123]
	v_mfma_f32_16x16x32_bf16 v[116:119], v[164:167], v[188:191], v[116:119]
	v_mfma_f32_16x16x32_bf16 v[112:115], v[172:175], v[188:191], v[112:115]
	v_mfma_f32_16x16x32_bf16 v[108:111], v[164:167], v[196:199], v[108:111]
	v_mfma_f32_16x16x32_bf16 v[104:107], v[172:175], v[196:199], v[104:107]
	v_mfma_f32_16x16x32_bf16 v[100:103], v[164:167], v[204:207], v[100:103]
	v_mfma_f32_16x16x32_bf16 v[96:99], v[172:175], v[204:207], v[96:99]
	s_setprio 0
	s_barrier
	ds_read_b128 v[160:163], v159
	ds_read_b128 v[208:211], v159 offset:1024
	ds_read_b128 v[212:215], v159 offset:2048
	ds_read_b128 v[156:159], v159 offset:3072
	s_barrier
	s_waitcnt lgkmcnt(0)
	s_setprio 1
	s_waitcnt lgkmcnt(0)
	v_mfma_f32_16x16x32_bf16 v[92:95], v[160:163], v[176:179], v[92:95]
	v_mfma_f32_16x16x32_bf16 v[88:91], v[212:215], v[176:179], v[88:91]
	v_mfma_f32_16x16x32_bf16 v[84:87], v[160:163], v[184:187], v[84:87]
	v_mfma_f32_16x16x32_bf16 v[80:83], v[212:215], v[184:187], v[80:83]
	v_mfma_f32_16x16x32_bf16 v[76:79], v[160:163], v[192:195], v[76:79]
	v_mfma_f32_16x16x32_bf16 v[72:75], v[212:215], v[192:195], v[72:75]
	v_mfma_f32_16x16x32_bf16 v[68:71], v[160:163], v[200:203], v[68:71]
	v_mfma_f32_16x16x32_bf16 v[64:67], v[212:215], v[200:203], v[64:67]
	v_mfma_f32_16x16x32_bf16 v[176:179], v[208:211], v[180:183], v[92:95]
	v_mfma_f32_16x16x32_bf16 v[180:183], v[156:159], v[180:183], v[88:91]
	v_mfma_f32_16x16x32_bf16 v[184:187], v[208:211], v[188:191], v[84:87]
	v_mfma_f32_16x16x32_bf16 v[188:191], v[156:159], v[188:191], v[80:83]
	v_mfma_f32_16x16x32_bf16 v[192:195], v[208:211], v[196:199], v[76:79]
	v_mfma_f32_16x16x32_bf16 v[196:199], v[156:159], v[196:199], v[72:75]
	v_mfma_f32_16x16x32_bf16 v[200:203], v[208:211], v[204:207], v[68:71]
	v_mfma_f32_16x16x32_bf16 v[204:207], v[156:159], v[204:207], v[64:67]
	s_setprio 0
	s_barrier
	s_nop 0
	ds_read_b128 v[64:67], v153 offset:16384
	ds_read_b128 v[68:71], v153 offset:17408
	ds_read_b128 v[72:75], v152 offset:16384
	ds_read_b128 v[76:79], v152 offset:17408
	ds_read_b128 v[80:83], v151 offset:16384
	ds_read_b128 v[84:87], v151 offset:17408
	ds_read_b128 v[88:91], v150 offset:16384
	ds_read_b128 v[92:95], v150 offset:17408
	s_waitcnt vmcnt(4)
	s_barrier
	s_waitcnt lgkmcnt(0)
	s_setprio 1
	s_waitcnt lgkmcnt(0)
	v_mfma_f32_16x16x32_bf16 v[60:63], v[130:133], v[64:67], v[60:63]
	v_mfma_f32_16x16x32_bf16 v[56:59], v[168:171], v[64:67], v[56:59]
	v_mfma_f32_16x16x32_bf16 v[52:55], v[130:133], v[72:75], v[52:55]
	v_mfma_f32_16x16x32_bf16 v[48:51], v[168:171], v[72:75], v[48:51]
	v_mfma_f32_16x16x32_bf16 v[216:219], v[130:133], v[80:83], v[44:47]
	v_mfma_f32_16x16x32_bf16 v[220:223], v[168:171], v[80:83], v[40:43]
	v_mfma_f32_16x16x32_bf16 v[130:133], v[130:133], v[88:91], v[36:39]
	v_mfma_f32_16x16x32_bf16 v[168:171], v[168:171], v[88:91], v[32:35]
	v_mfma_f32_16x16x32_bf16 v[32:35], v[164:167], v[68:71], v[60:63]
	v_mfma_f32_16x16x32_bf16 v[36:39], v[172:175], v[68:71], v[56:59]
	v_mfma_f32_16x16x32_bf16 v[40:43], v[164:167], v[76:79], v[52:55]
	v_mfma_f32_16x16x32_bf16 v[44:47], v[172:175], v[76:79], v[48:51]
	v_mfma_f32_16x16x32_bf16 v[48:51], v[164:167], v[84:87], v[216:219]
	v_mfma_f32_16x16x32_bf16 v[52:55], v[172:175], v[84:87], v[220:223]
	v_mfma_f32_16x16x32_bf16 v[56:59], v[164:167], v[92:95], v[130:133]
	v_mfma_f32_16x16x32_bf16 v[60:63], v[172:175], v[92:95], v[168:171]
	s_setprio 0
	s_setprio 1
	v_mfma_f32_16x16x32_bf16 v[28:31], v[160:163], v[64:67], v[28:31]
	v_mfma_f32_16x16x32_bf16 v[24:27], v[212:215], v[64:67], v[24:27]
	v_mfma_f32_16x16x32_bf16 v[20:23], v[160:163], v[72:75], v[20:23]
	v_mfma_f32_16x16x32_bf16 v[64:67], v[212:215], v[72:75], v[16:19]
	v_mfma_f32_16x16x32_bf16 v[72:75], v[160:163], v[80:83], v[12:15]
	v_mfma_f32_16x16x32_bf16 v[8:11], v[212:215], v[80:83], v[8:11]
	v_mfma_f32_16x16x32_bf16 v[80:83], v[160:163], v[88:91], v[4:7]
	v_mfma_f32_16x16x32_bf16 v[0:3], v[212:215], v[88:91], v[0:3]
	v_mfma_f32_16x16x32_bf16 v[4:7], v[208:211], v[68:71], v[28:31]
	v_mfma_f32_16x16x32_bf16 v[12:15], v[156:159], v[68:71], v[24:27]
	v_mfma_f32_16x16x32_bf16 v[16:19], v[208:211], v[76:79], v[20:23]
	v_mfma_f32_16x16x32_bf16 v[20:23], v[156:159], v[76:79], v[64:67]
	v_mfma_f32_16x16x32_bf16 v[24:27], v[208:211], v[84:87], v[72:75]
	v_mfma_f32_16x16x32_bf16 v[28:31], v[156:159], v[84:87], v[8:11]
	v_mfma_f32_16x16x32_bf16 v[64:67], v[208:211], v[92:95], v[80:83]
	v_mfma_f32_16x16x32_bf16 v[68:71], v[156:159], v[92:95], v[0:3]
	s_setprio 0
	s_barrier
	ds_read_b128 v[8:11], v155
	ds_read_b128 v[0:3], v155 offset:1024
	ds_read_b128 v[76:79], v155 offset:2048
	ds_read_b128 v[72:75], v155 offset:3072
	ds_read_b128 v[130:133], v153 offset:32768
	ds_read_b128 v[156:159], v153 offset:33792
	ds_read_b128 v[160:163], v152 offset:32768
	ds_read_b128 v[164:167], v152 offset:33792
	ds_read_b128 v[168:171], v151 offset:32768
	ds_read_b128 v[172:175], v151 offset:33792
	ds_read_b128 v[208:211], v150 offset:32768
	ds_read_b128 v[212:215], v150 offset:33792
	s_waitcnt vmcnt(2)
	s_barrier
	s_waitcnt lgkmcnt(0)
	s_setprio 1
	s_waitcnt lgkmcnt(0)
	v_mfma_f32_16x16x32_bf16 v[80:83], v[8:11], v[130:133], v[124:127]
	v_mfma_f32_16x16x32_bf16 v[84:87], v[76:79], v[130:133], v[120:123]
	v_mfma_f32_16x16x32_bf16 v[88:91], v[8:11], v[160:163], v[116:119]
	v_mfma_f32_16x16x32_bf16 v[92:95], v[76:79], v[160:163], v[112:115]
	v_mfma_f32_16x16x32_bf16 v[108:111], v[8:11], v[168:171], v[108:111]
	v_mfma_f32_16x16x32_bf16 v[104:107], v[76:79], v[168:171], v[104:107]
	v_mfma_f32_16x16x32_bf16 v[100:103], v[8:11], v[208:211], v[100:103]
	v_mfma_f32_16x16x32_bf16 v[96:99], v[76:79], v[208:211], v[96:99]
	v_mfma_f32_16x16x32_bf16 v[112:115], v[0:3], v[156:159], v[80:83]
	v_mfma_f32_16x16x32_bf16 v[116:119], v[72:75], v[156:159], v[84:87]
	v_mfma_f32_16x16x32_bf16 v[120:123], v[0:3], v[164:167], v[88:91]
	v_mfma_f32_16x16x32_bf16 v[124:127], v[72:75], v[164:167], v[92:95]
	v_mfma_f32_16x16x32_bf16 v[108:111], v[0:3], v[172:175], v[108:111]
	v_mfma_f32_16x16x32_bf16 v[104:107], v[72:75], v[172:175], v[104:107]
	v_mfma_f32_16x16x32_bf16 v[100:103], v[0:3], v[212:215], v[100:103]
	v_mfma_f32_16x16x32_bf16 v[96:99], v[72:75], v[212:215], v[96:99]
	s_setprio 0
	s_barrier
	ds_read_b128 v[88:91], v154
	ds_read_b128 v[80:83], v154 offset:1024
	ds_read_b128 v[92:95], v154 offset:2048
	ds_read_b128 v[84:87], v154 offset:3072
	s_waitcnt vmcnt(0)
	s_barrier
	s_waitcnt lgkmcnt(0)
	s_setprio 1
	s_waitcnt lgkmcnt(0)
	v_mfma_f32_16x16x32_bf16 v[176:179], v[88:91], v[130:133], v[176:179]
	v_mfma_f32_16x16x32_bf16 v[130:133], v[92:95], v[130:133], v[180:183]
	v_mfma_f32_16x16x32_bf16 v[180:183], v[88:91], v[160:163], v[184:187]
	v_mfma_f32_16x16x32_bf16 v[160:163], v[92:95], v[160:163], v[188:191]
	v_mfma_f32_16x16x32_bf16 v[184:187], v[88:91], v[168:171], v[192:195]
	v_mfma_f32_16x16x32_bf16 v[168:171], v[92:95], v[168:171], v[196:199]
	v_mfma_f32_16x16x32_bf16 v[188:191], v[88:91], v[208:211], v[200:203]
	v_mfma_f32_16x16x32_bf16 v[192:195], v[92:95], v[208:211], v[204:207]
	v_mfma_f32_16x16x32_bf16 v[176:179], v[80:83], v[156:159], v[176:179]
	v_mfma_f32_16x16x32_bf16 v[130:133], v[84:87], v[156:159], v[130:133]
	v_mfma_f32_16x16x32_bf16 v[154:157], v[80:83], v[164:167], v[180:183]
	v_mfma_f32_16x16x32_bf16 v[158:161], v[84:87], v[164:167], v[160:163]
	v_mfma_f32_16x16x32_bf16 v[162:165], v[80:83], v[172:175], v[184:187]
	v_mfma_f32_16x16x32_bf16 v[166:169], v[84:87], v[172:175], v[168:171]
	v_mfma_f32_16x16x32_bf16 v[170:173], v[80:83], v[212:215], v[188:191]
	v_mfma_f32_16x16x32_bf16 v[180:183], v[84:87], v[212:215], v[192:195]
	s_setprio 0
	s_barrier
	v_mbcnt_lo_u32_b32 v128, -1, 0
	v_mbcnt_hi_u32_b32 v128, -1, v128
	v_cvt_pk_bf16_f32 v112, v112, v113
	v_cvt_pk_bf16_f32 v113, v114, v115
	v_cvt_pk_bf16_f32 v114, v116, v117
	v_cvt_pk_bf16_f32 v115, v118, v119
	s_lshl_b32 s68, s66, 9
	v_add_u32_e32 v174, s74, v128
	v_ashrrev_i32_e32 v175, 6, v174
	v_and_b32_e32 v184, 15, v128
	v_and_b32_e32 v185, 48, v128
	v_mul_lo_u32 v186, v175, s79
	v_bfe_u32 v187, v128, 3, 3
	v_lshlrev_b32_e32 v128, 4, v128
	v_add_u32_e32 v186, 0x20000, v186
	v_lshrrev_b32_e32 v174, 2, v174
	v_and_b32_e32 v128, 0x70, v128
	v_mul_u32_u24_e32 v184, 0x90, v184
	v_and_b32_e32 v174, 64, v174
	v_add3_u32 v184, v186, v184, v185
	v_or_b32_e32 v185, v186, v128
	v_or3_b32 v174, s24, v174, v187
	v_mad_u32_u24 v185, v187, s80, v185
	ds_write_b128 v184, v[112:115]
	v_cvt_pk_bf16_f32 v112, v176, v177
	v_cvt_pk_bf16_f32 v113, v178, v179
	v_cvt_pk_bf16_f32 v114, v130, v131
	v_cvt_pk_bf16_f32 v115, v132, v133
	ds_write_b128 v184, v[112:115] offset:64
	v_lshlrev_b32_e32 v175, 7, v175
	ds_read_b128 v[112:115], v185
	v_lshlrev_b32_e32 v116, 12, v174
	v_and_or_b32 v116, v175, s81, v116
	v_or3_b32 v128, v116, s68, v128
	ds_read_b128 v[116:119], v185 offset:1152
	v_lshl_add_u64 v[130:131], s[0:1], 0, v[128:129]
	s_mov_b32 s36, 0x8000
	s_waitcnt lgkmcnt(0)
	global_store_dwordx4 v128, v[112:115], s[0:1] sc0 sc1
	v_cvt_pk_bf16_f32 v108, v108, v109
	v_cvt_pk_bf16_f32 v109, v110, v111
	v_cvt_pk_bf16_f32 v110, v104, v105
	v_cvt_pk_bf16_f32 v111, v106, v107
	v_cvt_pk_bf16_f32 v104, v162, v163
	s_nop 1
	v_add_co_u32_e32 v112, vcc, s36, v130
	v_cvt_pk_bf16_f32 v114, v124, v125
	v_cvt_pk_bf16_f32 v115, v126, v127
	v_cvt_pk_bf16_f32 v105, v164, v165
	v_cvt_pk_bf16_f32 v106, v166, v167
	s_nop 1
	v_addc_co_u32_e32 v113, vcc, 0, v131, vcc
	global_store_dwordx4 v[112:113], v[116:119], off sc0 sc1
	v_cvt_pk_bf16_f32 v112, v120, v121
	v_cvt_pk_bf16_f32 v113, v122, v123
	ds_write_b128 v184, v[112:115]
	v_cvt_pk_bf16_f32 v112, v154, v155
	v_cvt_pk_bf16_f32 v113, v156, v157
	v_cvt_pk_bf16_f32 v114, v158, v159
	v_cvt_pk_bf16_f32 v115, v160, v161
	ds_write_b128 v184, v[112:115] offset:64
	ds_read_b128 v[112:115], v185
	ds_read_b128 v[116:119], v185 offset:1152
	v_add_co_u32_e32 v120, vcc, s76, v130
	ds_write_b128 v184, v[108:111]
	v_cvt_pk_bf16_f32 v107, v168, v169
	ds_write_b128 v184, v[104:107] offset:64
	v_addc_co_u32_e32 v121, vcc, 0, v131, vcc
	ds_read_b128 v[104:107], v185
	ds_read_b128 v[108:111], v185 offset:1152
	s_waitcnt lgkmcnt(0)
	global_store_dwordx4 v[120:121], v[112:115], off sc0 sc1
	v_cvt_pk_bf16_f32 v100, v100, v101
	v_cvt_pk_bf16_f32 v101, v102, v103
	v_cvt_pk_bf16_f32 v102, v96, v97
	v_cvt_pk_bf16_f32 v103, v98, v99
	ds_write_b128 v184, v[100:103]
	s_nop 0
	v_add_co_u32_e32 v112, vcc, s77, v130
	v_cvt_pk_bf16_f32 v96, v170, v171
	v_cvt_pk_bf16_f32 v97, v172, v173
	v_cvt_pk_bf16_f32 v98, v180, v181
	v_cvt_pk_bf16_f32 v99, v182, v183
	s_nop 1
	v_addc_co_u32_e32 v113, vcc, 0, v131, vcc
	global_store_dwordx4 v[112:113], v[116:119], off sc0 sc1
	v_add_co_u32_e32 v112, vcc, s78, v130
	ds_write_b128 v184, v[96:99] offset:64
	s_nop 0
	v_addc_co_u32_e32 v113, vcc, 0, v131, vcc
	ds_read_b128 v[96:99], v185
	ds_read_b128 v[100:103], v185 offset:1152
	global_store_dwordx4 v[112:113], v[104:107], off sc0 sc1
	s_nop 1
	v_add_co_u32_e32 v104, vcc, s82, v130
	s_nop 1
	v_addc_co_u32_e32 v105, vcc, 0, v131, vcc
	global_store_dwordx4 v[104:105], v[108:111], off sc0 sc1
	v_add_co_u32_e32 v104, vcc, s83, v130
	s_nop 1
	v_addc_co_u32_e32 v105, vcc, 0, v131, vcc
	s_waitcnt lgkmcnt(0)
	global_store_dwordx4 v[104:105], v[96:99], off sc0 sc1
	s_nop 1
	v_add_co_u32_e32 v96, vcc, s91, v130
	s_nop 1
	v_addc_co_u32_e32 v97, vcc, 0, v131, vcc
	global_store_dwordx4 v[96:97], v[100:103], off sc0 sc1
	ds_read_b128 v[96:99], v153 offset:49152
	ds_read_b128 v[100:103], v153 offset:50176
	ds_read_b128 v[104:107], v152 offset:49152
	ds_read_b128 v[108:111], v152 offset:50176
	ds_read_b128 v[112:115], v151 offset:49152
	ds_read_b128 v[116:119], v151 offset:50176
	ds_read_b128 v[120:123], v150 offset:49152
	ds_read_b128 v[124:127], v150 offset:50176
	s_barrier
	s_waitcnt lgkmcnt(0)
	s_setprio 1
	s_waitcnt lgkmcnt(0)
	v_mfma_f32_16x16x32_bf16 v[32:35], v[8:11], v[96:99], v[32:35]
	v_mfma_f32_16x16x32_bf16 v[36:39], v[76:79], v[96:99], v[36:39]
	v_mfma_f32_16x16x32_bf16 v[40:43], v[8:11], v[104:107], v[40:43]
	v_mfma_f32_16x16x32_bf16 v[130:133], v[76:79], v[104:107], v[44:47]
	v_mfma_f32_16x16x32_bf16 v[150:153], v[8:11], v[112:115], v[48:51]
	v_mfma_f32_16x16x32_bf16 v[52:55], v[76:79], v[112:115], v[52:55]
	v_mfma_f32_16x16x32_bf16 v[8:11], v[8:11], v[120:123], v[56:59]
	v_mfma_f32_16x16x32_bf16 v[60:63], v[76:79], v[120:123], v[60:63]
	v_mfma_f32_16x16x32_bf16 v[56:59], v[0:3], v[100:103], v[32:35]
	v_mfma_f32_16x16x32_bf16 v[48:51], v[72:75], v[100:103], v[36:39]
	v_mfma_f32_16x16x32_bf16 v[44:47], v[0:3], v[108:111], v[40:43]
	v_mfma_f32_16x16x32_bf16 v[40:43], v[72:75], v[108:111], v[130:133]
	v_mfma_f32_16x16x32_bf16 v[36:39], v[0:3], v[116:119], v[150:153]
	v_mfma_f32_16x16x32_bf16 v[32:35], v[72:75], v[116:119], v[52:55]
	v_mfma_f32_16x16x32_bf16 v[8:11], v[0:3], v[124:127], v[8:11]
	v_mfma_f32_16x16x32_bf16 v[0:3], v[72:75], v[124:127], v[60:63]
	s_setprio 0
	s_setprio 1
	v_mfma_f32_16x16x32_bf16 v[4:7], v[88:91], v[96:99], v[4:7]
	v_mfma_f32_16x16x32_bf16 v[12:15], v[92:95], v[96:99], v[12:15]
	v_mfma_f32_16x16x32_bf16 v[16:19], v[88:91], v[104:107], v[16:19]
	v_mfma_f32_16x16x32_bf16 v[20:23], v[92:95], v[104:107], v[20:23]
	v_mfma_f32_16x16x32_bf16 v[72:75], v[88:91], v[112:115], v[24:27]
	v_mfma_f32_16x16x32_bf16 v[76:79], v[92:95], v[112:115], v[28:31]
	v_mfma_f32_16x16x32_bf16 v[64:67], v[88:91], v[120:123], v[64:67]
	v_mfma_f32_16x16x32_bf16 v[68:71], v[92:95], v[120:123], v[68:71]
	v_mfma_f32_16x16x32_bf16 v[60:63], v[80:83], v[100:103], v[4:7]
	v_mfma_f32_16x16x32_bf16 v[52:55], v[84:87], v[100:103], v[12:15]
	v_mfma_f32_16x16x32_bf16 v[28:31], v[80:83], v[108:111], v[16:19]
	v_mfma_f32_16x16x32_bf16 v[24:27], v[84:87], v[108:111], v[20:23]
	v_mfma_f32_16x16x32_bf16 v[20:23], v[80:83], v[116:119], v[72:75]
	v_mfma_f32_16x16x32_bf16 v[16:19], v[84:87], v[116:119], v[76:79]
	v_mfma_f32_16x16x32_bf16 v[12:15], v[80:83], v[124:127], v[64:67]
	v_mfma_f32_16x16x32_bf16 v[4:7], v[84:87], v[124:127], v[68:71]
	s_setprio 0
	v_cmp_gt_u32_e32 vcc, s92, v136
	s_barrier
	s_and_saveexec_b64 s[66:67], vcc
	s_cbranch_execz .LBB0_468
	s_barrier

.LBB0_508:
	v_mul_lo_u32 v64, v73, s73
	v_lshlrev_b32_e32 v67, 4, v69
	v_add_u32_e32 v64, 0x20000, v64
	v_bfe_u32 v65, v69, 3, 3
	v_and_b32_e32 v67, 0x70, v67
	v_mul_u32_u24_e32 v69, 0x90, v70
	v_add3_u32 v69, v64, v69, v72
	v_lshl_or_b32 v68, v68, 6, s46
	v_or_b32_e32 v64, v64, v67
	v_or3_b32 v68, v68, v65, s70
	v_mad_u32_u24 v70, v65, s74, v64
	s_waitcnt vmcnt(0)
	v_pk_mul_f32 v[62:63], v[172:173], v[62:63] op_sel_hi:[0,1]
	v_pk_mul_f32 v[60:61], v[172:173], v[60:61] op_sel_hi:[0,1]
	v_pk_mul_f32 v[64:65], v[172:173], v[58:59] op_sel_hi:[0,1]
	v_pk_mul_f32 v[58:59], v[172:173], v[56:57] op_sel_hi:[0,1]
	v_cvt_pk_bf16_f32 v56, v60, v61
	v_cvt_pk_bf16_f32 v57, v62, v63
	v_cvt_pk_bf16_f32 v58, v58, v59
	v_cvt_pk_bf16_f32 v59, v64, v65
	ds_write_b128 v69, v[56:59]
	v_pk_mul_f32 v[56:57], v[172:173], v[50:51] op_sel_hi:[0,1]
	v_pk_mul_f32 v[50:51], v[172:173], v[48:49] op_sel_hi:[0,1]
	v_pk_mul_f32 v[54:55], v[172:173], v[54:55] op_sel_hi:[0,1]
	v_pk_mul_f32 v[52:53], v[172:173], v[52:53] op_sel_hi:[0,1]
	v_cvt_pk_bf16_f32 v48, v52, v53
	v_cvt_pk_bf16_f32 v49, v54, v55
	v_cvt_pk_bf16_f32 v50, v50, v51
	v_cvt_pk_bf16_f32 v51, v56, v57
	ds_write_b128 v69, v[48:51] offset:64
	ds_read_b128 v[48:51], v70
	v_lshlrev_b32_e32 v66, 7, v71
	s_lshl_b32 s36, s78, 9
	v_or3_b32 v52, v66, s36, v67
	v_mad_u64_u32 v[56:57], s[46:47], v68, s77, v[52:53]
	ds_read_b128 v[52:55], v70 offset:1152
	s_waitcnt lgkmcnt(0)
	global_store_dwordx4 v56, v[48:51], s[0:1] sc0 sc1
	v_pk_mul_f32 v[46:47], v[170:171], v[46:47] op_sel_hi:[0,1]
	v_pk_mul_f32 v[44:45], v[170:171], v[44:45] op_sel_hi:[0,1]
	v_pk_mul_f32 v[48:49], v[170:171], v[42:43] op_sel_hi:[0,1]
	v_pk_mul_f32 v[42:43], v[170:171], v[40:41] op_sel_hi:[0,1]
	v_cvt_pk_bf16_f32 v40, v44, v45
	v_cvt_pk_bf16_f32 v41, v46, v47
	v_cvt_pk_bf16_f32 v42, v42, v43
	v_cvt_pk_bf16_f32 v43, v48, v49
	ds_write_b128 v69, v[40:43]
	v_pk_mul_f32 v[40:41], v[170:171], v[26:27] op_sel_hi:[0,1]
	v_pk_mul_f32 v[26:27], v[170:171], v[24:25] op_sel_hi:[0,1]
	v_pk_mul_f32 v[30:31], v[170:171], v[30:31] op_sel_hi:[0,1]
	v_pk_mul_f32 v[28:29], v[170:171], v[28:29] op_sel_hi:[0,1]
	v_cvt_pk_bf16_f32 v24, v28, v29
	v_cvt_pk_bf16_f32 v25, v30, v31
	v_cvt_pk_bf16_f32 v26, v26, v27
	v_cvt_pk_bf16_f32 v27, v40, v41
	ds_write_b128 v69, v[24:27] offset:64
	ds_read_b128 v[24:27], v70
	s_lshl_b32 s36, s77, 3
	v_add_u32_e32 v28, s36, v56
	v_add_u32_e32 v40, s36, v28
	global_store_dwordx4 v28, v[52:55], s[0:1] sc0 sc1
	ds_read_b128 v[28:31], v70 offset:1152
	s_waitcnt lgkmcnt(1)
	global_store_dwordx4 v40, v[24:27], s[0:1] sc0 sc1
	v_pk_mul_f32 v[34:35], v[168:169], v[34:35] op_sel_hi:[0,1]
	v_pk_mul_f32 v[32:33], v[168:169], v[32:33] op_sel_hi:[0,1]
	v_pk_mul_f32 v[24:25], v[168:169], v[36:37] op_sel_hi:[0,1]
	v_pk_mul_f32 v[26:27], v[168:169], v[38:39] op_sel_hi:[0,1]
	v_cvt_pk_bf16_f32 v24, v24, v25
	v_cvt_pk_bf16_f32 v25, v26, v27
	v_cvt_pk_bf16_f32 v26, v32, v33
	v_cvt_pk_bf16_f32 v27, v34, v35
	ds_write_b128 v69, v[24:27]
	v_pk_mul_f32 v[24:25], v[168:169], v[18:19] op_sel_hi:[0,1]
	v_pk_mul_f32 v[18:19], v[168:169], v[16:17] op_sel_hi:[0,1]
	v_pk_mul_f32 v[22:23], v[168:169], v[22:23] op_sel_hi:[0,1]
	v_pk_mul_f32 v[20:21], v[168:169], v[20:21] op_sel_hi:[0,1]
	v_cvt_pk_bf16_f32 v16, v20, v21
	v_cvt_pk_bf16_f32 v17, v22, v23
	v_cvt_pk_bf16_f32 v18, v18, v19
	v_cvt_pk_bf16_f32 v19, v24, v25
	ds_write_b128 v69, v[16:19] offset:64
	ds_read_b128 v[16:19], v70
	v_add_u32_e32 v20, s36, v40
	v_add_u32_e32 v24, s36, v20
	s_waitcnt lgkmcnt(3)
	global_store_dwordx4 v20, v[28:31], s[0:1] sc0 sc1
	ds_read_b128 v[20:23], v70 offset:1152
	s_waitcnt lgkmcnt(1)
	global_store_dwordx4 v24, v[16:19], s[0:1] sc0 sc1
	v_pk_mul_f32 v[14:15], v[166:167], v[14:15] op_sel_hi:[0,1]
	v_pk_mul_f32 v[12:13], v[166:167], v[12:13] op_sel_hi:[0,1]
	v_pk_mul_f32 v[16:17], v[166:167], v[10:11] op_sel_hi:[0,1]
	v_pk_mul_f32 v[10:11], v[166:167], v[8:9] op_sel_hi:[0,1]
	v_cvt_pk_bf16_f32 v8, v12, v13
	v_cvt_pk_bf16_f32 v9, v14, v15
	v_cvt_pk_bf16_f32 v10, v10, v11
	v_cvt_pk_bf16_f32 v11, v16, v17
	ds_write_b128 v69, v[8:11]
	v_pk_mul_f32 v[8:9], v[166:167], v[2:3] op_sel_hi:[0,1]
	v_pk_mul_f32 v[2:3], v[166:167], v[0:1] op_sel_hi:[0,1]
	v_pk_mul_f32 v[6:7], v[166:167], v[6:7] op_sel_hi:[0,1]
	v_pk_mul_f32 v[4:5], v[166:167], v[4:5] op_sel_hi:[0,1]
	v_cvt_pk_bf16_f32 v0, v4, v5
	v_cvt_pk_bf16_f32 v1, v6, v7
	v_cvt_pk_bf16_f32 v2, v2, v3
	v_cvt_pk_bf16_f32 v3, v8, v9
	ds_write_b128 v69, v[0:3] offset:64
	ds_read_b128 v[0:3], v70
	ds_read_b128 v[64:67], v70 offset:1152
	v_add_u32_e32 v4, s36, v24
	s_waitcnt lgkmcnt(4)
	global_store_dwordx4 v4, v[20:23], s[0:1] sc0 sc1
	v_add_u32_e32 v4, s36, v4
	v_add_u32_e32 v74, s36, v4
	s_waitcnt lgkmcnt(1)
	global_store_dwordx4 v4, v[0:3], s[0:1] sc0 sc1
.LBB0_509:
	s_add_i32 s76, s76, 1
	s_mov_b64 s[46:47], 0
	s_andn2_b64 vcc, exec, s[58:59]
	s_mov_b32 s77, s83
	s_waitcnt lgkmcnt(0)
	global_store_dwordx4 v74, v[64:67], s[0:1] sc0 sc1
	s_cbranch_vccz .LBB0_535

.LBB0_521:
	ds_read_b128 v[140:143], v138
	ds_read_b128 v[144:147], v138 offset:1024
	ds_read_b128 v[148:151], v138 offset:2048
	ds_read_b128 v[152:155], v138 offset:3072
	v_readfirstlane_b32 s36, v137
	v_lshl_add_u64 v[218:219], v[128:129], 0, s[18:19]
	s_mov_b32 m0, s36
	v_readfirstlane_b32 s36, v136
	ds_read_b128 v[156:159], v193
	ds_read_b128 v[160:163], v193 offset:1024
	ds_read_b128 v[194:197], v192
	ds_read_b128 v[198:201], v192 offset:1024
	ds_read_b128 v[202:205], v191
	ds_read_b128 v[206:209], v191 offset:1024
	ds_read_b128 v[210:213], v190
	ds_read_b128 v[214:217], v190 offset:1024
	global_load_lds_dwordx4 v[218:219], off
	v_lshl_add_u64 v[218:219], v[128:129], 0, s[20:21]
	s_mov_b32 m0, s36
	s_nop 0
	global_load_lds_dwordx4 v[218:219], off
	s_waitcnt lgkmcnt(8)
	s_barrier
	s_waitcnt lgkmcnt(0)
	s_setprio 1
	s_waitcnt lgkmcnt(0)
	v_mfma_f32_16x16x32_bf16 v[124:127], v[140:143], v[156:159], v[124:127]
	v_mfma_f32_16x16x32_bf16 v[120:123], v[148:151], v[156:159], v[120:123]
	v_mfma_f32_16x16x32_bf16 v[116:119], v[140:143], v[194:197], v[116:119]
	v_mfma_f32_16x16x32_bf16 v[112:115], v[148:151], v[194:197], v[112:115]
	v_mfma_f32_16x16x32_bf16 v[108:111], v[140:143], v[202:205], v[108:111]
	v_mfma_f32_16x16x32_bf16 v[104:107], v[148:151], v[202:205], v[104:107]
	v_mfma_f32_16x16x32_bf16 v[100:103], v[140:143], v[210:213], v[100:103]
	v_mfma_f32_16x16x32_bf16 v[96:99], v[148:151], v[210:213], v[96:99]
	v_mfma_f32_16x16x32_bf16 v[124:127], v[144:147], v[160:163], v[124:127]
	v_mfma_f32_16x16x32_bf16 v[120:123], v[152:155], v[160:163], v[120:123]
	v_mfma_f32_16x16x32_bf16 v[116:119], v[144:147], v[198:201], v[116:119]
	v_mfma_f32_16x16x32_bf16 v[112:115], v[152:155], v[198:201], v[112:115]
	v_mfma_f32_16x16x32_bf16 v[108:111], v[144:147], v[206:209], v[108:111]
	v_mfma_f32_16x16x32_bf16 v[104:107], v[152:155], v[206:209], v[104:107]
	v_mfma_f32_16x16x32_bf16 v[100:103], v[144:147], v[214:217], v[100:103]
	v_mfma_f32_16x16x32_bf16 v[96:99], v[152:155], v[214:217], v[96:99]
	s_setprio 0
	s_barrier
	v_readfirstlane_b32 s36, v189
	v_lshl_add_u64 v[234:235], s[58:59], 0, v[164:165]
	s_mov_b32 m0, s36
	v_readfirstlane_b32 s36, v188
	ds_read_b128 v[218:221], v135
	ds_read_b128 v[222:225], v135 offset:1024
	ds_read_b128 v[226:229], v135 offset:2048
	ds_read_b128 v[230:233], v135 offset:3072
	global_load_lds_dwordx4 v[234:235], off
	v_lshl_add_u64 v[236:237], v[234:235], 0, s[2:3]
	s_mov_b32 m0, s36
	s_nop 0
	global_load_lds_dwordx4 v[236:237], off
	s_barrier
	s_waitcnt lgkmcnt(0)
	s_setprio 1
	s_waitcnt lgkmcnt(0)
	v_mfma_f32_16x16x32_bf16 v[92:95], v[218:221], v[156:159], v[92:95]
	v_mfma_f32_16x16x32_bf16 v[88:91], v[226:229], v[156:159], v[88:91]
	v_mfma_f32_16x16x32_bf16 v[84:87], v[218:221], v[194:197], v[84:87]
	v_mfma_f32_16x16x32_bf16 v[80:83], v[226:229], v[194:197], v[80:83]
	v_mfma_f32_16x16x32_bf16 v[76:79], v[218:221], v[202:205], v[76:79]
	v_mfma_f32_16x16x32_bf16 v[72:75], v[226:229], v[202:205], v[72:75]
	v_mfma_f32_16x16x32_bf16 v[68:71], v[218:221], v[210:213], v[68:71]
	v_mfma_f32_16x16x32_bf16 v[64:67], v[226:229], v[210:213], v[64:67]
	v_mfma_f32_16x16x32_bf16 v[92:95], v[222:225], v[160:163], v[92:95]
	v_mfma_f32_16x16x32_bf16 v[88:91], v[230:233], v[160:163], v[88:91]
	v_mfma_f32_16x16x32_bf16 v[84:87], v[222:225], v[198:201], v[84:87]
	v_mfma_f32_16x16x32_bf16 v[80:83], v[230:233], v[198:201], v[80:83]
	v_mfma_f32_16x16x32_bf16 v[76:79], v[222:225], v[206:209], v[76:79]
	v_mfma_f32_16x16x32_bf16 v[72:75], v[230:233], v[206:209], v[72:75]
	v_mfma_f32_16x16x32_bf16 v[68:71], v[222:225], v[214:217], v[68:71]
	v_mfma_f32_16x16x32_bf16 v[64:67], v[230:233], v[214:217], v[64:67]
	s_setprio 0
	v_readfirstlane_b32 s36, v169
	v_lshl_add_u64 v[236:237], v[128:129], 0, s[22:23]
	s_mov_b32 m0, s36
	v_readfirstlane_b32 s36, v187
	s_barrier
	ds_read_b128 v[156:159], v193 offset:16384
	ds_read_b128 v[160:163], v193 offset:17408
	ds_read_b128 v[194:197], v192 offset:16384
	ds_read_b128 v[198:201], v192 offset:17408
	ds_read_b128 v[202:205], v191 offset:16384
	ds_read_b128 v[206:209], v191 offset:17408
	ds_read_b128 v[210:213], v190 offset:16384
	ds_read_b128 v[214:217], v190 offset:17408
	global_load_lds_dwordx4 v[236:237], off
	v_lshl_add_u64 v[236:237], v[128:129], 0, s[24:25]
	s_mov_b32 m0, s36
	s_nop 0
	global_load_lds_dwordx4 v[236:237], off
	s_barrier
	s_waitcnt lgkmcnt(0)
	s_setprio 1
	s_waitcnt lgkmcnt(0)
	v_mfma_f32_16x16x32_bf16 v[60:63], v[140:143], v[156:159], v[60:63]
	v_mfma_f32_16x16x32_bf16 v[56:59], v[148:151], v[156:159], v[56:59]
	v_mfma_f32_16x16x32_bf16 v[52:55], v[140:143], v[194:197], v[52:55]
	v_mfma_f32_16x16x32_bf16 v[48:51], v[148:151], v[194:197], v[48:51]
	v_mfma_f32_16x16x32_bf16 v[44:47], v[140:143], v[202:205], v[44:47]
	v_mfma_f32_16x16x32_bf16 v[40:43], v[148:151], v[202:205], v[40:43]
	v_mfma_f32_16x16x32_bf16 v[36:39], v[140:143], v[210:213], v[36:39]
	v_mfma_f32_16x16x32_bf16 v[32:35], v[148:151], v[210:213], v[32:35]
	v_mfma_f32_16x16x32_bf16 v[60:63], v[144:147], v[160:163], v[60:63]
	v_mfma_f32_16x16x32_bf16 v[56:59], v[152:155], v[160:163], v[56:59]
	v_mfma_f32_16x16x32_bf16 v[52:55], v[144:147], v[198:201], v[52:55]
	v_mfma_f32_16x16x32_bf16 v[48:51], v[152:155], v[198:201], v[48:51]
	v_mfma_f32_16x16x32_bf16 v[44:47], v[144:147], v[206:209], v[44:47]
	v_mfma_f32_16x16x32_bf16 v[40:43], v[152:155], v[206:209], v[40:43]
	v_mfma_f32_16x16x32_bf16 v[36:39], v[144:147], v[214:217], v[36:39]
	v_mfma_f32_16x16x32_bf16 v[32:35], v[152:155], v[214:217], v[32:35]
	s_setprio 0
	s_barrier
	v_readfirstlane_b32 s36, v186
	v_lshl_add_u64 v[140:141], v[234:235], 0, s[6:7]
	s_mov_b32 m0, s36
	v_readfirstlane_b32 s36, v185
	global_load_lds_dwordx4 v[140:141], off
	v_lshl_add_u64 v[140:141], v[234:235], 0, s[8:9]
	s_mov_b32 m0, s36
	s_nop 0
	global_load_lds_dwordx4 v[140:141], off
	s_waitcnt vmcnt(6)
	s_barrier
	s_setprio 1
	v_mfma_f32_16x16x32_bf16 v[28:31], v[218:221], v[156:159], v[28:31]
	v_mfma_f32_16x16x32_bf16 v[24:27], v[226:229], v[156:159], v[24:27]
	v_mfma_f32_16x16x32_bf16 v[20:23], v[218:221], v[194:197], v[20:23]
	v_mfma_f32_16x16x32_bf16 v[16:19], v[226:229], v[194:197], v[16:19]
	v_mfma_f32_16x16x32_bf16 v[12:15], v[218:221], v[202:205], v[12:15]
	v_mfma_f32_16x16x32_bf16 v[8:11], v[226:229], v[202:205], v[8:11]
	v_mfma_f32_16x16x32_bf16 v[4:7], v[218:221], v[210:213], v[4:7]
	v_mfma_f32_16x16x32_bf16 v[0:3], v[226:229], v[210:213], v[0:3]
	v_mfma_f32_16x16x32_bf16 v[28:31], v[222:225], v[160:163], v[28:31]
	v_mfma_f32_16x16x32_bf16 v[24:27], v[230:233], v[160:163], v[24:27]
	v_mfma_f32_16x16x32_bf16 v[20:23], v[222:225], v[198:201], v[20:23]
	v_mfma_f32_16x16x32_bf16 v[16:19], v[230:233], v[198:201], v[16:19]
	v_mfma_f32_16x16x32_bf16 v[12:15], v[222:225], v[206:209], v[12:15]
	v_mfma_f32_16x16x32_bf16 v[8:11], v[230:233], v[206:209], v[8:11]
	v_mfma_f32_16x16x32_bf16 v[4:7], v[222:225], v[214:217], v[4:7]
	v_mfma_f32_16x16x32_bf16 v[0:3], v[230:233], v[214:217], v[0:3]
	s_setprio 0
	s_barrier
	ds_read_b128 v[140:143], v130
	ds_read_b128 v[144:147], v130 offset:1024
	ds_read_b128 v[148:151], v130 offset:2048
	ds_read_b128 v[152:155], v130 offset:3072
	v_readfirstlane_b32 s36, v184
	v_lshl_add_u64 v[218:219], v[128:129], 0, s[26:27]
	s_mov_b32 m0, s36
	v_readfirstlane_b32 s36, v183
	ds_read_b128 v[156:159], v193 offset:32768
	ds_read_b128 v[160:163], v193 offset:33792
	ds_read_b128 v[194:197], v192 offset:32768
	ds_read_b128 v[198:201], v192 offset:33792
	ds_read_b128 v[202:205], v191 offset:32768
	ds_read_b128 v[206:209], v191 offset:33792
	ds_read_b128 v[210:213], v190 offset:32768
	ds_read_b128 v[214:217], v190 offset:33792
	global_load_lds_dwordx4 v[218:219], off
	s_mov_b32 m0, s36
	s_nop 0
	global_load_lds_dwordx4 v[128:129], off
	s_waitcnt lgkmcnt(8)
	s_barrier
	s_waitcnt lgkmcnt(0)
	s_setprio 1
	s_waitcnt lgkmcnt(0)
	v_mfma_f32_16x16x32_bf16 v[124:127], v[140:143], v[156:159], v[124:127]
	v_mfma_f32_16x16x32_bf16 v[120:123], v[148:151], v[156:159], v[120:123]
	v_mfma_f32_16x16x32_bf16 v[116:119], v[140:143], v[194:197], v[116:119]
	v_mfma_f32_16x16x32_bf16 v[112:115], v[148:151], v[194:197], v[112:115]
	v_mfma_f32_16x16x32_bf16 v[108:111], v[140:143], v[202:205], v[108:111]
	v_mfma_f32_16x16x32_bf16 v[104:107], v[148:151], v[202:205], v[104:107]
	v_mfma_f32_16x16x32_bf16 v[100:103], v[140:143], v[210:213], v[100:103]
	v_mfma_f32_16x16x32_bf16 v[96:99], v[148:151], v[210:213], v[96:99]
	v_mfma_f32_16x16x32_bf16 v[124:127], v[144:147], v[160:163], v[124:127]
	v_mfma_f32_16x16x32_bf16 v[120:123], v[152:155], v[160:163], v[120:123]
	v_mfma_f32_16x16x32_bf16 v[116:119], v[144:147], v[198:201], v[116:119]
	v_mfma_f32_16x16x32_bf16 v[112:115], v[152:155], v[198:201], v[112:115]
	v_mfma_f32_16x16x32_bf16 v[108:111], v[144:147], v[206:209], v[108:111]
	v_mfma_f32_16x16x32_bf16 v[104:107], v[152:155], v[206:209], v[104:107]
	v_mfma_f32_16x16x32_bf16 v[100:103], v[144:147], v[214:217], v[100:103]
	v_mfma_f32_16x16x32_bf16 v[96:99], v[152:155], v[214:217], v[96:99]
	s_setprio 0
	s_barrier
	v_readfirstlane_b32 s36, v182
	v_lshl_add_u64 v[234:235], s[46:47], 0, v[164:165]
	s_mov_b32 m0, s36
	v_readfirstlane_b32 s36, v181
	ds_read_b128 v[218:221], v132
	ds_read_b128 v[222:225], v132 offset:1024
	ds_read_b128 v[226:229], v132 offset:2048
	ds_read_b128 v[230:233], v132 offset:3072
	global_load_lds_dwordx4 v[234:235], off
	v_lshl_add_u64 v[236:237], v[234:235], 0, s[2:3]
	s_mov_b32 m0, s36
	s_nop 0
	global_load_lds_dwordx4 v[236:237], off
	s_barrier
	s_waitcnt lgkmcnt(0)
	s_setprio 1
	s_waitcnt lgkmcnt(0)
	v_mfma_f32_16x16x32_bf16 v[92:95], v[218:221], v[156:159], v[92:95]
	v_mfma_f32_16x16x32_bf16 v[88:91], v[226:229], v[156:159], v[88:91]
	v_mfma_f32_16x16x32_bf16 v[84:87], v[218:221], v[194:197], v[84:87]
	v_mfma_f32_16x16x32_bf16 v[80:83], v[226:229], v[194:197], v[80:83]
	v_mfma_f32_16x16x32_bf16 v[76:79], v[218:221], v[202:205], v[76:79]
	v_mfma_f32_16x16x32_bf16 v[72:75], v[226:229], v[202:205], v[72:75]
	v_mfma_f32_16x16x32_bf16 v[68:71], v[218:221], v[210:213], v[68:71]
	v_mfma_f32_16x16x32_bf16 v[64:67], v[226:229], v[210:213], v[64:67]
	v_mfma_f32_16x16x32_bf16 v[92:95], v[222:225], v[160:163], v[92:95]
	v_mfma_f32_16x16x32_bf16 v[88:91], v[230:233], v[160:163], v[88:91]
	v_mfma_f32_16x16x32_bf16 v[84:87], v[222:225], v[198:201], v[84:87]
	v_mfma_f32_16x16x32_bf16 v[80:83], v[230:233], v[198:201], v[80:83]
	v_mfma_f32_16x16x32_bf16 v[76:79], v[222:225], v[206:209], v[76:79]
	v_mfma_f32_16x16x32_bf16 v[72:75], v[230:233], v[206:209], v[72:75]
	v_mfma_f32_16x16x32_bf16 v[68:71], v[222:225], v[214:217], v[68:71]
	v_mfma_f32_16x16x32_bf16 v[64:67], v[230:233], v[214:217], v[64:67]
	s_setprio 0
	v_readfirstlane_b32 s36, v177
	v_lshl_add_u64 v[236:237], v[128:129], 0, s[28:29]
	s_mov_b32 m0, s36
	v_readfirstlane_b32 s36, v175
	s_barrier
	ds_read_b128 v[156:159], v193 offset:49152
	ds_read_b128 v[160:163], v193 offset:50176
	ds_read_b128 v[194:197], v192 offset:49152
	ds_read_b128 v[198:201], v192 offset:50176
	ds_read_b128 v[202:205], v191 offset:49152
	ds_read_b128 v[206:209], v191 offset:50176
	ds_read_b128 v[210:213], v190 offset:49152
	ds_read_b128 v[214:217], v190 offset:50176
	global_load_lds_dwordx4 v[236:237], off
	v_lshl_add_u64 v[236:237], v[128:129], 0, s[30:31]
	s_mov_b32 m0, s36
	s_nop 0
	global_load_lds_dwordx4 v[236:237], off
	s_barrier
	s_waitcnt lgkmcnt(0)
	s_setprio 1
	s_waitcnt lgkmcnt(0)
	v_mfma_f32_16x16x32_bf16 v[60:63], v[140:143], v[156:159], v[60:63]
	v_mfma_f32_16x16x32_bf16 v[56:59], v[148:151], v[156:159], v[56:59]
	v_mfma_f32_16x16x32_bf16 v[52:55], v[140:143], v[194:197], v[52:55]
	v_mfma_f32_16x16x32_bf16 v[48:51], v[148:151], v[194:197], v[48:51]
	v_mfma_f32_16x16x32_bf16 v[44:47], v[140:143], v[202:205], v[44:47]
	v_mfma_f32_16x16x32_bf16 v[40:43], v[148:151], v[202:205], v[40:43]
	v_mfma_f32_16x16x32_bf16 v[36:39], v[140:143], v[210:213], v[36:39]
	v_mfma_f32_16x16x32_bf16 v[32:35], v[148:151], v[210:213], v[32:35]
	v_mfma_f32_16x16x32_bf16 v[60:63], v[144:147], v[160:163], v[60:63]
	v_mfma_f32_16x16x32_bf16 v[56:59], v[152:155], v[160:163], v[56:59]
	v_mfma_f32_16x16x32_bf16 v[52:55], v[144:147], v[198:201], v[52:55]
	v_mfma_f32_16x16x32_bf16 v[48:51], v[152:155], v[198:201], v[48:51]
	v_mfma_f32_16x16x32_bf16 v[44:47], v[144:147], v[206:209], v[44:47]
	v_mfma_f32_16x16x32_bf16 v[40:43], v[152:155], v[206:209], v[40:43]
	v_mfma_f32_16x16x32_bf16 v[36:39], v[144:147], v[214:217], v[36:39]
	v_mfma_f32_16x16x32_bf16 v[32:35], v[152:155], v[214:217], v[32:35]
	s_setprio 0
	s_barrier
	v_readfirstlane_b32 s36, v173
	v_lshl_add_u64 v[140:141], v[234:235], 0, s[6:7]
	s_mov_b32 m0, s36
	v_readfirstlane_b32 s36, v171
	global_load_lds_dwordx4 v[140:141], off
	v_lshl_add_u64 v[140:141], v[234:235], 0, s[8:9]
	s_mov_b32 m0, s36
	s_nop 0
	global_load_lds_dwordx4 v[140:141], off
	s_waitcnt vmcnt(6)
	s_barrier
	s_setprio 1
	v_mfma_f32_16x16x32_bf16 v[28:31], v[218:221], v[156:159], v[28:31]
	v_mfma_f32_16x16x32_bf16 v[24:27], v[226:229], v[156:159], v[24:27]
	v_mfma_f32_16x16x32_bf16 v[20:23], v[218:221], v[194:197], v[20:23]
	v_mfma_f32_16x16x32_bf16 v[16:19], v[226:229], v[194:197], v[16:19]
	v_mfma_f32_16x16x32_bf16 v[12:15], v[218:221], v[202:205], v[12:15]
	v_mfma_f32_16x16x32_bf16 v[8:11], v[226:229], v[202:205], v[8:11]
	v_mfma_f32_16x16x32_bf16 v[4:7], v[218:221], v[210:213], v[4:7]
	v_mfma_f32_16x16x32_bf16 v[0:3], v[226:229], v[210:213], v[0:3]
	v_mfma_f32_16x16x32_bf16 v[28:31], v[222:225], v[160:163], v[28:31]
	v_mfma_f32_16x16x32_bf16 v[24:27], v[230:233], v[160:163], v[24:27]
	v_mfma_f32_16x16x32_bf16 v[20:23], v[222:225], v[198:201], v[20:23]
	v_mfma_f32_16x16x32_bf16 v[16:19], v[230:233], v[198:201], v[16:19]
	v_mfma_f32_16x16x32_bf16 v[12:15], v[222:225], v[206:209], v[12:15]
	v_mfma_f32_16x16x32_bf16 v[8:11], v[230:233], v[206:209], v[8:11]
	v_mfma_f32_16x16x32_bf16 v[4:7], v[222:225], v[214:217], v[4:7]
	v_mfma_f32_16x16x32_bf16 v[0:3], v[230:233], v[214:217], v[0:3]
	s_setprio 0
	s_add_i32 s14, s14, 2
	s_add_u32 s46, s46, s56
	s_addc_u32 s47, s47, s57
	s_add_u32 s58, s58, s56
	s_addc_u32 s59, s59, s57
	s_cmp_lt_u32 s14, 28
	v_lshl_add_u64 v[128:129], v[128:129], 0, s[34:35]
	s_barrier
	s_cbranch_scc1 .LBB0_521
	s_lshl_b32 s14, s60, 3
	s_or_b32 s80, s61, s14
	s_lshl_b32 s46, s80, 8
	v_lshlrev_b32_e32 v128, 3, v131
	v_lshlrev_b32_e32 v129, 5, v131
	s_or_b32 s14, s46, 0x80
	v_and_b32_e32 v128, 0x7fff0, v128
	v_and_b32_e32 v129, 32, v129
	s_lshl_b64 s[56:57], s[14:15], 13
	v_add_u32_e32 v129, v129, v134
	v_add_lshl_u32 v128, v133, v128, 13
	s_add_u32 s56, s40, s56
	v_lshl_add_u32 v164, v129, 1, v128
	s_addc_u32 s57, s41, s57
	v_lshl_add_u64 v[128:129], s[56:57], 0, v[164:165]
	v_readfirstlane_b32 s14, v137
	ds_read_b128 v[140:143], v138
	ds_read_b128 v[144:147], v138 offset:1024
	ds_read_b128 v[148:151], v138 offset:2048
	ds_read_b128 v[152:155], v138 offset:3072
	ds_read_b128 v[156:159], v193
	ds_read_b128 v[160:163], v193 offset:1024
	ds_read_b128 v[194:197], v192
	ds_read_b128 v[198:201], v192 offset:1024
	ds_read_b128 v[202:205], v191
	ds_read_b128 v[206:209], v191 offset:1024
	ds_read_b128 v[210:213], v190
	ds_read_b128 v[214:217], v190 offset:1024
	v_lshl_add_u64 v[138:139], v[128:129], 0, s[38:39]
	s_mov_b32 m0, s14
	v_readfirstlane_b32 s14, v136
	global_load_lds_dwordx4 v[138:139], off
	v_lshl_add_u64 v[128:129], v[128:129], 0, s[44:45]
	s_mov_b32 m0, s14
	s_mov_b32 s47, s15
	global_load_lds_dwordx4 v[128:129], off
	s_barrier
	s_waitcnt lgkmcnt(0)
	s_setprio 1
	s_waitcnt lgkmcnt(0)
	v_mfma_f32_16x16x32_bf16 v[124:127], v[140:143], v[156:159], v[124:127]
	v_mfma_f32_16x16x32_bf16 v[120:123], v[148:151], v[156:159], v[120:123]
	v_mfma_f32_16x16x32_bf16 v[116:119], v[140:143], v[194:197], v[116:119]
	v_mfma_f32_16x16x32_bf16 v[112:115], v[148:151], v[194:197], v[112:115]
	v_mfma_f32_16x16x32_bf16 v[108:111], v[140:143], v[202:205], v[108:111]
	v_mfma_f32_16x16x32_bf16 v[104:107], v[148:151], v[202:205], v[104:107]
	v_mfma_f32_16x16x32_bf16 v[100:103], v[140:143], v[210:213], v[100:103]
	v_mfma_f32_16x16x32_bf16 v[96:99], v[148:151], v[210:213], v[96:99]
	v_mfma_f32_16x16x32_bf16 v[124:127], v[144:147], v[160:163], v[124:127]
	v_mfma_f32_16x16x32_bf16 v[120:123], v[152:155], v[160:163], v[120:123]
	v_mfma_f32_16x16x32_bf16 v[116:119], v[144:147], v[198:201], v[116:119]
	v_mfma_f32_16x16x32_bf16 v[112:115], v[152:155], v[198:201], v[112:115]
	v_mfma_f32_16x16x32_bf16 v[108:111], v[144:147], v[206:209], v[108:111]
	v_mfma_f32_16x16x32_bf16 v[104:107], v[152:155], v[206:209], v[104:107]
	v_mfma_f32_16x16x32_bf16 v[100:103], v[144:147], v[214:217], v[100:103]
	v_mfma_f32_16x16x32_bf16 v[96:99], v[152:155], v[214:217], v[96:99]
	s_setprio 0
	s_barrier
	ds_read_b128 v[136:139], v135
	ds_read_b128 v[218:221], v135 offset:1024
	ds_read_b128 v[222:225], v135 offset:2048
	ds_read_b128 v[226:229], v135 offset:3072
	s_barrier
	s_waitcnt lgkmcnt(0)
	s_setprio 1
	s_waitcnt lgkmcnt(0)
	v_mfma_f32_16x16x32_bf16 v[92:95], v[136:139], v[156:159], v[92:95]
	v_mfma_f32_16x16x32_bf16 v[84:87], v[136:139], v[194:197], v[84:87]
	v_mfma_f32_16x16x32_bf16 v[80:83], v[222:225], v[194:197], v[80:83]
	v_mfma_f32_16x16x32_bf16 v[88:91], v[222:225], v[156:159], v[88:91]
	v_mfma_f32_16x16x32_bf16 v[76:79], v[136:139], v[202:205], v[76:79]
	v_mfma_f32_16x16x32_bf16 v[72:75], v[222:225], v[202:205], v[72:75]
	v_mfma_f32_16x16x32_bf16 v[68:71], v[136:139], v[210:213], v[68:71]
	v_mfma_f32_16x16x32_bf16 v[64:67], v[222:225], v[210:213], v[64:67]
	v_mfma_f32_16x16x32_bf16 v[156:159], v[218:221], v[160:163], v[92:95]
	v_mfma_f32_16x16x32_bf16 v[194:197], v[218:221], v[198:201], v[84:87]
	v_mfma_f32_16x16x32_bf16 v[198:201], v[226:229], v[198:201], v[80:83]
	v_mfma_f32_16x16x32_bf16 v[160:163], v[226:229], v[160:163], v[88:91]
	v_mfma_f32_16x16x32_bf16 v[202:205], v[218:221], v[206:209], v[76:79]
	v_mfma_f32_16x16x32_bf16 v[206:209], v[226:229], v[206:209], v[72:75]
	v_mfma_f32_16x16x32_bf16 v[210:213], v[218:221], v[214:217], v[68:71]
	v_mfma_f32_16x16x32_bf16 v[214:217], v[226:229], v[214:217], v[64:67]
	s_setprio 0
	s_barrier
	s_nop 0
	ds_read_b128 v[64:67], v193 offset:16384
	ds_read_b128 v[68:71], v193 offset:17408
	ds_read_b128 v[72:75], v192 offset:16384
	ds_read_b128 v[76:79], v192 offset:17408
	ds_read_b128 v[80:83], v191 offset:16384
	ds_read_b128 v[84:87], v191 offset:17408
	ds_read_b128 v[88:91], v190 offset:16384
	ds_read_b128 v[92:95], v190 offset:17408
	s_waitcnt vmcnt(4)
	s_barrier
	s_waitcnt lgkmcnt(0)
	s_setprio 1
	s_waitcnt lgkmcnt(0)
	v_mfma_f32_16x16x32_bf16 v[60:63], v[140:143], v[64:67], v[60:63]
	v_mfma_f32_16x16x32_bf16 v[56:59], v[148:151], v[64:67], v[56:59]
	v_mfma_f32_16x16x32_bf16 v[52:55], v[140:143], v[72:75], v[52:55]
	v_mfma_f32_16x16x32_bf16 v[48:51], v[148:151], v[72:75], v[48:51]
	v_mfma_f32_16x16x32_bf16 v[230:233], v[140:143], v[80:83], v[44:47]
	v_mfma_f32_16x16x32_bf16 v[234:237], v[148:151], v[80:83], v[40:43]
	v_mfma_f32_16x16x32_bf16 v[140:143], v[140:143], v[88:91], v[36:39]
	v_mfma_f32_16x16x32_bf16 v[148:151], v[148:151], v[88:91], v[32:35]
	v_mfma_f32_16x16x32_bf16 v[32:35], v[144:147], v[68:71], v[60:63]
	v_mfma_f32_16x16x32_bf16 v[36:39], v[152:155], v[68:71], v[56:59]
	v_mfma_f32_16x16x32_bf16 v[40:43], v[144:147], v[76:79], v[52:55]
	v_mfma_f32_16x16x32_bf16 v[44:47], v[152:155], v[76:79], v[48:51]
	v_mfma_f32_16x16x32_bf16 v[48:51], v[144:147], v[84:87], v[230:233]
	v_mfma_f32_16x16x32_bf16 v[52:55], v[152:155], v[84:87], v[234:237]
	v_mfma_f32_16x16x32_bf16 v[56:59], v[144:147], v[92:95], v[140:143]
	v_mfma_f32_16x16x32_bf16 v[60:63], v[152:155], v[92:95], v[148:151]
	s_setprio 0
	s_setprio 1
	v_mfma_f32_16x16x32_bf16 v[28:31], v[136:139], v[64:67], v[28:31]
	v_mfma_f32_16x16x32_bf16 v[24:27], v[222:225], v[64:67], v[24:27]
	v_mfma_f32_16x16x32_bf16 v[20:23], v[136:139], v[72:75], v[20:23]
	v_mfma_f32_16x16x32_bf16 v[64:67], v[222:225], v[72:75], v[16:19]
	v_mfma_f32_16x16x32_bf16 v[12:15], v[136:139], v[80:83], v[12:15]
	v_mfma_f32_16x16x32_bf16 v[8:11], v[222:225], v[80:83], v[8:11]
	v_mfma_f32_16x16x32_bf16 v[72:75], v[136:139], v[88:91], v[4:7]
	v_mfma_f32_16x16x32_bf16 v[80:83], v[222:225], v[88:91], v[0:3]
	v_mfma_f32_16x16x32_bf16 v[0:3], v[218:221], v[68:71], v[28:31]
	v_mfma_f32_16x16x32_bf16 v[4:7], v[226:229], v[68:71], v[24:27]
	v_mfma_f32_16x16x32_bf16 v[16:19], v[218:221], v[76:79], v[20:23]
	v_mfma_f32_16x16x32_bf16 v[20:23], v[226:229], v[76:79], v[64:67]
	v_mfma_f32_16x16x32_bf16 v[24:27], v[218:221], v[84:87], v[12:15]
	v_mfma_f32_16x16x32_bf16 v[28:31], v[226:229], v[84:87], v[8:11]
	v_mfma_f32_16x16x32_bf16 v[64:67], v[218:221], v[92:95], v[72:75]
	v_mfma_f32_16x16x32_bf16 v[68:71], v[226:229], v[92:95], v[80:83]
	s_setprio 0
	s_barrier
	ds_read_b128 v[12:15], v130
	ds_read_b128 v[8:11], v130 offset:1024
	ds_read_b128 v[76:79], v130 offset:2048
	ds_read_b128 v[72:75], v130 offset:3072
	ds_read_b128 v[140:143], v193 offset:32768
	ds_read_b128 v[148:151], v193 offset:33792
	ds_read_b128 v[218:221], v192 offset:32768
	ds_read_b128 v[222:225], v192 offset:33792
	ds_read_b128 v[226:229], v191 offset:32768
	ds_read_b128 v[230:233], v191 offset:33792
	ds_read_b128 v[234:237], v190 offset:32768
	ds_read_b128 v[238:241], v190 offset:33792
	s_waitcnt vmcnt(2)
	s_barrier
	s_waitcnt lgkmcnt(0)
	s_setprio 1
	s_waitcnt lgkmcnt(0)
	v_mfma_f32_16x16x32_bf16 v[80:83], v[12:15], v[140:143], v[124:127]
	v_mfma_f32_16x16x32_bf16 v[84:87], v[76:79], v[140:143], v[120:123]
	v_mfma_f32_16x16x32_bf16 v[88:91], v[12:15], v[218:221], v[116:119]
	v_mfma_f32_16x16x32_bf16 v[92:95], v[76:79], v[218:221], v[112:115]
	v_mfma_f32_16x16x32_bf16 v[108:111], v[12:15], v[226:229], v[108:111]
	v_mfma_f32_16x16x32_bf16 v[104:107], v[76:79], v[226:229], v[104:107]
	v_mfma_f32_16x16x32_bf16 v[100:103], v[12:15], v[234:237], v[100:103]
	v_mfma_f32_16x16x32_bf16 v[96:99], v[76:79], v[234:237], v[96:99]
	v_mfma_f32_16x16x32_bf16 v[152:155], v[8:11], v[148:151], v[80:83]
	v_mfma_f32_16x16x32_bf16 v[144:147], v[72:75], v[148:151], v[84:87]
	v_mfma_f32_16x16x32_bf16 v[136:139], v[8:11], v[222:225], v[88:91]
	v_mfma_f32_16x16x32_bf16 v[128:131], v[72:75], v[222:225], v[92:95]
	v_mfma_f32_16x16x32_bf16 v[120:123], v[8:11], v[230:233], v[108:111]
	v_mfma_f32_16x16x32_bf16 v[112:115], v[72:75], v[230:233], v[104:107]
	v_mfma_f32_16x16x32_bf16 v[104:107], v[8:11], v[238:241], v[100:103]
	v_mfma_f32_16x16x32_bf16 v[96:99], v[72:75], v[238:241], v[96:99]
	s_setprio 0
	s_barrier
	ds_read_b128 v[88:91], v132
	ds_read_b128 v[80:83], v132 offset:1024
	ds_read_b128 v[92:95], v132 offset:2048
	ds_read_b128 v[84:87], v132 offset:3072
	s_waitcnt vmcnt(0)
	s_barrier
	s_waitcnt lgkmcnt(0)
	s_setprio 1
	s_waitcnt lgkmcnt(0)
	v_mfma_f32_16x16x32_bf16 v[100:103], v[88:91], v[140:143], v[156:159]
	v_mfma_f32_16x16x32_bf16 v[108:111], v[92:95], v[140:143], v[160:163]
	v_mfma_f32_16x16x32_bf16 v[116:119], v[88:91], v[218:221], v[194:197]
	v_mfma_f32_16x16x32_bf16 v[124:127], v[92:95], v[218:221], v[198:201]
	v_mfma_f32_16x16x32_bf16 v[160:163], v[88:91], v[226:229], v[202:205]
	v_mfma_f32_16x16x32_bf16 v[194:197], v[92:95], v[226:229], v[206:209]
	v_mfma_f32_16x16x32_bf16 v[198:201], v[88:91], v[234:237], v[210:213]
	v_mfma_f32_16x16x32_bf16 v[202:205], v[92:95], v[234:237], v[214:217]
	v_mfma_f32_16x16x32_bf16 v[156:159], v[80:83], v[148:151], v[100:103]
	v_mfma_f32_16x16x32_bf16 v[148:151], v[84:87], v[148:151], v[108:111]
	v_mfma_f32_16x16x32_bf16 v[140:143], v[80:83], v[222:225], v[116:119]
	v_mfma_f32_16x16x32_bf16 v[132:135], v[84:87], v[222:225], v[124:127]
	v_mfma_f32_16x16x32_bf16 v[124:127], v[80:83], v[230:233], v[160:163]
	v_mfma_f32_16x16x32_bf16 v[116:119], v[84:87], v[230:233], v[194:197]
	v_mfma_f32_16x16x32_bf16 v[108:111], v[80:83], v[238:241], v[198:201]
	v_mfma_f32_16x16x32_bf16 v[100:103], v[84:87], v[238:241], v[202:205]
	s_setprio 0
	s_lshl_b64 s[56:57], s[46:47], 2
	s_barrier
	v_mbcnt_lo_u32_b32 v162, -1, 0
	v_mbcnt_hi_u32_b32 v162, -1, v162
	s_add_u32 s56, s87, s56
	v_add_u32_e32 v160, s64, v162
	s_addc_u32 s57, s88, s57
	v_and_b32_e32 v164, 0x100, v160
	v_and_b32_e32 v162, 15, v162
	v_lshl_add_u64 v[160:161], s[56:57], 0, v[164:165]
	v_lshlrev_b32_e32 v164, 2, v162
	v_lshl_add_u64 v[160:161], v[160:161], 0, v[164:165]
	global_load_dword v180, v[160:161], off
	global_load_dword v178, v[160:161], off offset:64
	global_load_dword v176, v[160:161], off offset:128
	global_load_dword v174, v[160:161], off offset:192
	global_load_dword v172, v[160:161], off offset:512
	global_load_dword v170, v[160:161], off offset:576
	global_load_dword v168, v[160:161], off offset:640
	global_load_dword v166, v[160:161], off offset:704
	v_mbcnt_lo_u32_b32 v194, -1, 0
	v_mbcnt_hi_u32_b32 v194, -1, v194
	s_cmp_lg_u32 s79, 0
	v_add_u32_e32 v160, s64, v194
	v_bfe_u32 v196, v160, 8, 1
	v_ashrrev_i32_e32 v199, 6, v160
	v_bfe_u32 v160, v194, 4, 2
	s_cselect_b64 s[56:57], -1, 0
	v_and_b32_e32 v197, 3, v199
	v_and_b32_e32 v195, 15, v194
	s_and_b64 vcc, exec, s[56:57]
	v_lshlrev_b32_e32 v198, 4, v160
	s_cbranch_vccz .LBB0_533
	s_lshl_b32 s14, s78, 22
	s_lshl_b32 s36, s80, 14
	s_add_i32 s36, s36, s14
	v_lshlrev_b32_e32 v160, 6, v195
	v_or3_b32 v160, s36, v160, v198
	v_lshl_add_u32 v160, v197, 20, v160
	v_lshl_or_b32 v164, v196, 12, v160
	s_waitcnt vmcnt(0)
	v_pk_mul_f32 v[160:161], v[154:155], v[180:181] op_sel_hi:[1,0]
	v_pk_mul_f32 v[200:201], v[146:147], v[180:181] op_sel_hi:[1,0]
	v_max_f32_e32 v160, 0, v160
	v_mul_f32_e32 v204, v160, v160
	v_max_f32_e32 v160, 0, v200
	v_pk_mul_f32 v[162:163], v[152:153], v[180:181] op_sel_hi:[1,0]
	v_mul_f32_e32 v200, v160, v160
	v_max_f32_e32 v160, 0, v161
	v_pk_mul_f32 v[202:203], v[144:145], v[180:181] op_sel_hi:[1,0]
	v_max_f32_e32 v162, 0, v162
	v_max_f32_e32 v163, 0, v163
	v_mul_f32_e32 v161, v160, v160
	v_max_f32_e32 v160, 0, v201
	v_mul_f32_e32 v162, v162, v162
	v_max_f32_e32 v202, 0, v202
	v_mul_f32_e32 v163, v163, v163
	v_max_f32_e32 v203, 0, v203
	v_mul_f32_e32 v201, v160, v160
	v_cvt_pk_bf16_f32 v160, v162, v163
	v_cvt_pk_bf16_f32 v161, v204, v161
	v_mul_f32_e32 v202, v202, v202
	v_mul_f32_e32 v203, v203, v203
	v_cvt_pk_bf16_f32 v162, v202, v203
	v_cvt_pk_bf16_f32 v163, v200, v201
	global_store_dwordx4 v164, v[160:163], s[0:1] sc0 sc1
	v_pk_mul_f32 v[202:203], v[150:151], v[180:181] op_sel_hi:[1,0]
	v_lshl_add_u64 v[200:201], s[0:1], 0, v[164:165]
	v_pk_mul_f32 v[160:161], v[158:159], v[180:181] op_sel_hi:[1,0]
	v_pk_mul_f32 v[162:163], v[156:157], v[180:181] op_sel_hi:[1,0]
	v_max_f32_e32 v160, 0, v160
	v_mul_f32_e32 v206, v160, v160
	v_max_f32_e32 v160, 0, v202
	v_mul_f32_e32 v202, v160, v160
	v_max_f32_e32 v160, 0, v161
	v_pk_mul_f32 v[204:205], v[148:149], v[180:181] op_sel_hi:[1,0]
	v_max_f32_e32 v162, 0, v162
	v_max_f32_e32 v163, 0, v163
	v_mul_f32_e32 v161, v160, v160
	v_max_f32_e32 v160, 0, v203
	v_add_co_u32_e32 v200, vcc, s72, v200
	v_mul_f32_e32 v162, v162, v162
	v_max_f32_e32 v204, 0, v204
	v_mul_f32_e32 v163, v163, v163
	v_max_f32_e32 v205, 0, v205
	v_mul_f32_e32 v203, v160, v160
	v_cvt_pk_bf16_f32 v160, v162, v163
	v_cvt_pk_bf16_f32 v161, v206, v161
	v_addc_co_u32_e32 v201, vcc, 0, v201, vcc
	v_mul_f32_e32 v204, v204, v204
	v_mul_f32_e32 v205, v205, v205
	v_cvt_pk_bf16_f32 v162, v204, v205
	v_cvt_pk_bf16_f32 v163, v202, v203
	global_store_dwordx4 v[200:201], v[160:163], off sc0 sc1
	v_pk_mul_f32 v[202:203], v[130:131], v[178:179] op_sel_hi:[1,0]
	v_pk_mul_f32 v[204:205], v[128:129], v[178:179] op_sel_hi:[1,0]
	v_pk_mul_f32 v[160:161], v[138:139], v[178:179] op_sel_hi:[1,0]
	v_pk_mul_f32 v[162:163], v[136:137], v[178:179] op_sel_hi:[1,0]
	v_max_f32_e32 v160, 0, v160
	v_mul_f32_e32 v206, v160, v160
	v_max_f32_e32 v160, 0, v202
	v_mul_f32_e32 v202, v160, v160
	v_max_f32_e32 v160, 0, v161
	v_max_f32_e32 v162, 0, v162
	v_max_f32_e32 v163, 0, v163
	v_mul_f32_e32 v161, v160, v160
	v_max_f32_e32 v160, 0, v203
	v_mul_f32_e32 v162, v162, v162
	v_max_f32_e32 v204, 0, v204
	v_mul_f32_e32 v163, v163, v163
	v_max_f32_e32 v205, 0, v205
	v_mul_f32_e32 v203, v160, v160
	v_cvt_pk_bf16_f32 v160, v162, v163
	v_cvt_pk_bf16_f32 v161, v206, v161
	v_mul_f32_e32 v204, v204, v204
	v_mul_f32_e32 v205, v205, v205
	v_cvt_pk_bf16_f32 v162, v204, v205
	v_cvt_pk_bf16_f32 v163, v202, v203
	global_store_dwordx4 v164, v[160:163], s[0:1] offset:1024 sc0 sc1
	v_pk_mul_f32 v[202:203], v[134:135], v[178:179] op_sel_hi:[1,0]
	v_pk_mul_f32 v[204:205], v[132:133], v[178:179] op_sel_hi:[1,0]
	v_pk_mul_f32 v[160:161], v[142:143], v[178:179] op_sel_hi:[1,0]
	v_pk_mul_f32 v[162:163], v[140:141], v[178:179] op_sel_hi:[1,0]
	v_max_f32_e32 v160, 0, v160
	v_mul_f32_e32 v206, v160, v160
	v_max_f32_e32 v160, 0, v202
	v_mul_f32_e32 v202, v160, v160
	v_max_f32_e32 v160, 0, v161
	v_max_f32_e32 v162, 0, v162
	v_max_f32_e32 v163, 0, v163
	v_mul_f32_e32 v161, v160, v160
	v_max_f32_e32 v160, 0, v203
	v_mul_f32_e32 v162, v162, v162
	v_max_f32_e32 v204, 0, v204
	v_mul_f32_e32 v163, v163, v163
	v_max_f32_e32 v205, 0, v205
	v_mul_f32_e32 v203, v160, v160
	v_cvt_pk_bf16_f32 v160, v162, v163
	v_cvt_pk_bf16_f32 v161, v206, v161
	v_mul_f32_e32 v204, v204, v204
	v_mul_f32_e32 v205, v205, v205
	v_cvt_pk_bf16_f32 v162, v204, v205
	v_cvt_pk_bf16_f32 v163, v202, v203
	global_store_dwordx4 v[200:201], v[160:163], off offset:1024 sc0 sc1
	v_pk_mul_f32 v[202:203], v[114:115], v[176:177] op_sel_hi:[1,0]
	v_pk_mul_f32 v[204:205], v[112:113], v[176:177] op_sel_hi:[1,0]
	v_pk_mul_f32 v[160:161], v[122:123], v[176:177] op_sel_hi:[1,0]
	v_pk_mul_f32 v[162:163], v[120:121], v[176:177] op_sel_hi:[1,0]
	v_max_f32_e32 v160, 0, v160
	v_mul_f32_e32 v206, v160, v160
	v_max_f32_e32 v160, 0, v202
	v_mul_f32_e32 v202, v160, v160
	v_max_f32_e32 v160, 0, v161
	v_max_f32_e32 v162, 0, v162
	v_max_f32_e32 v163, 0, v163
	v_mul_f32_e32 v161, v160, v160
	v_max_f32_e32 v160, 0, v203
	v_mul_f32_e32 v162, v162, v162
	v_max_f32_e32 v204, 0, v204
	v_mul_f32_e32 v163, v163, v163
	v_max_f32_e32 v205, 0, v205
	v_mul_f32_e32 v203, v160, v160
	v_cvt_pk_bf16_f32 v160, v162, v163
	v_cvt_pk_bf16_f32 v161, v206, v161
	v_mul_f32_e32 v204, v204, v204
	v_mul_f32_e32 v205, v205, v205
	v_cvt_pk_bf16_f32 v162, v204, v205
	v_cvt_pk_bf16_f32 v163, v202, v203
	global_store_dwordx4 v164, v[160:163], s[0:1] offset:2048 sc0 sc1
	v_pk_mul_f32 v[202:203], v[118:119], v[176:177] op_sel_hi:[1,0]
	v_pk_mul_f32 v[204:205], v[116:117], v[176:177] op_sel_hi:[1,0]
	v_pk_mul_f32 v[160:161], v[126:127], v[176:177] op_sel_hi:[1,0]
	v_pk_mul_f32 v[162:163], v[124:125], v[176:177] op_sel_hi:[1,0]
	v_max_f32_e32 v160, 0, v160
	v_mul_f32_e32 v206, v160, v160
	v_max_f32_e32 v160, 0, v202
	v_mul_f32_e32 v202, v160, v160
	v_max_f32_e32 v160, 0, v161
	v_max_f32_e32 v162, 0, v162
	v_max_f32_e32 v163, 0, v163
	v_mul_f32_e32 v161, v160, v160
	v_max_f32_e32 v160, 0, v203
	v_mul_f32_e32 v162, v162, v162
	v_max_f32_e32 v204, 0, v204
	v_mul_f32_e32 v163, v163, v163
	v_max_f32_e32 v205, 0, v205
	v_mul_f32_e32 v203, v160, v160
	v_cvt_pk_bf16_f32 v160, v162, v163
	v_cvt_pk_bf16_f32 v161, v206, v161
	v_mul_f32_e32 v204, v204, v204
	v_mul_f32_e32 v205, v205, v205
	v_cvt_pk_bf16_f32 v162, v204, v205
	v_cvt_pk_bf16_f32 v163, v202, v203
	global_store_dwordx4 v[200:201], v[160:163], off offset:2048 sc0 sc1
	v_pk_mul_f32 v[200:201], v[98:99], v[174:175] op_sel_hi:[1,0]
	v_pk_mul_f32 v[202:203], v[96:97], v[174:175] op_sel_hi:[1,0]
	v_pk_mul_f32 v[160:161], v[106:107], v[174:175] op_sel_hi:[1,0]
	v_pk_mul_f32 v[162:163], v[104:105], v[174:175] op_sel_hi:[1,0]
	v_max_f32_e32 v160, 0, v160
	v_mul_f32_e32 v204, v160, v160
	v_max_f32_e32 v160, 0, v200
	v_mul_f32_e32 v200, v160, v160
	v_max_f32_e32 v160, 0, v161
	v_max_f32_e32 v162, 0, v162
	v_max_f32_e32 v163, 0, v163
	v_mul_f32_e32 v161, v160, v160
	v_max_f32_e32 v160, 0, v201
	v_mul_f32_e32 v162, v162, v162
	v_max_f32_e32 v202, 0, v202
	v_mul_f32_e32 v163, v163, v163
	v_max_f32_e32 v203, 0, v203
	v_mul_f32_e32 v201, v160, v160
	v_cvt_pk_bf16_f32 v160, v162, v163
	v_cvt_pk_bf16_f32 v161, v204, v161
	v_mul_f32_e32 v202, v202, v202
	v_mul_f32_e32 v203, v203, v203
	v_cvt_pk_bf16_f32 v162, v202, v203
	v_cvt_pk_bf16_f32 v163, v200, v201
	global_store_dwordx4 v164, v[160:163], s[0:1] offset:3072 sc0 sc1
	v_pk_mul_f32 v[200:201], v[102:103], v[174:175] op_sel_hi:[1,0]
	v_pk_mul_f32 v[202:203], v[100:101], v[174:175] op_sel_hi:[1,0]
	v_pk_mul_f32 v[160:161], v[110:111], v[174:175] op_sel_hi:[1,0]
	v_pk_mul_f32 v[162:163], v[108:109], v[174:175] op_sel_hi:[1,0]
	v_max_f32_e32 v160, 0, v160
	v_mul_f32_e32 v204, v160, v160
	v_max_f32_e32 v160, 0, v200
	v_max_f32_e32 v162, 0, v162
	v_max_f32_e32 v163, 0, v163
	v_mul_f32_e32 v200, v160, v160
	v_max_f32_e32 v160, 0, v161
	v_mul_f32_e32 v162, v162, v162
	v_max_f32_e32 v202, 0, v202
	v_mul_f32_e32 v163, v163, v163
	v_max_f32_e32 v203, 0, v203
	v_mul_f32_e32 v161, v160, v160
	v_max_f32_e32 v160, 0, v201
	v_mul_f32_e32 v202, v202, v202
	v_mul_f32_e32 v203, v203, v203
	v_mul_f32_e32 v201, v160, v160
	v_cvt_pk_bf16_f32 v160, v162, v163
	v_cvt_pk_bf16_f32 v161, v204, v161
	v_cvt_pk_bf16_f32 v162, v202, v203
	v_cvt_pk_bf16_f32 v163, v200, v201
	v_add_u32_e32 v164, 0x80c00, v164
	s_cbranch_execnz .LBB0_525
.LBB0_524:
	v_mul_lo_u32 v160, v199, s73
	v_lshlrev_b32_e32 v164, 4, v194
	v_add_u32_e32 v160, 0x20000, v160
	v_bfe_u32 v162, v194, 3, 3
	v_and_b32_e32 v164, 0x70, v164
	v_mul_u32_u24_e32 v194, 0x90, v195
	v_lshlrev_b32_e32 v161, 6, v196
	v_add3_u32 v194, v160, v194, v198
	v_or_b32_e32 v160, v160, v164
	v_or3_b32 v195, v161, v162, s46
	v_mad_u32_u24 v162, v162, s74, v160
	s_waitcnt vmcnt(0)
	v_pk_mul_f32 v[160:161], v[146:147], v[180:181] op_sel_hi:[1,0]
	v_pk_mul_f32 v[146:147], v[144:145], v[180:181] op_sel_hi:[1,0]
	v_pk_mul_f32 v[154:155], v[154:155], v[180:181] op_sel_hi:[1,0]
	v_pk_mul_f32 v[152:153], v[152:153], v[180:181] op_sel_hi:[1,0]
	v_cvt_pk_bf16_f32 v145, v154, v155
	v_cvt_pk_bf16_f32 v146, v146, v147
	v_cvt_pk_bf16_f32 v147, v160, v161
	v_pk_mul_f32 v[150:151], v[150:151], v[180:181] op_sel_hi:[1,0]
	v_cvt_pk_bf16_f32 v144, v152, v153
	ds_write_b128 v194, v[144:147]
	v_pk_mul_f32 v[146:147], v[158:159], v[180:181] op_sel_hi:[1,0]
	v_pk_mul_f32 v[144:145], v[156:157], v[180:181] op_sel_hi:[1,0]
	v_pk_mul_f32 v[148:149], v[148:149], v[180:181] op_sel_hi:[1,0]
	v_cvt_pk_bf16_f32 v144, v144, v145
	v_cvt_pk_bf16_f32 v145, v146, v147
	v_cvt_pk_bf16_f32 v147, v150, v151
	v_lshlrev_b32_e32 v163, 7, v197
	v_cvt_pk_bf16_f32 v146, v148, v149
	ds_write_b128 v194, v[144:147] offset:64
	ds_read_b128 v[144:147], v162
	s_lshl_b32 s14, s78, 9
	v_or3_b32 v148, v163, s14, v164
	v_mad_u64_u32 v[152:153], s[58:59], v195, s77, v[148:149]
	ds_read_b128 v[148:151], v162 offset:1152
	s_waitcnt lgkmcnt(1)
	global_store_dwordx4 v152, v[144:147], s[0:1] sc0 sc1
	v_pk_mul_f32 v[138:139], v[138:139], v[178:179] op_sel_hi:[1,0]
	v_pk_mul_f32 v[136:137], v[136:137], v[178:179] op_sel_hi:[1,0]
	v_pk_mul_f32 v[144:145], v[130:131], v[178:179] op_sel_hi:[1,0]
	v_pk_mul_f32 v[130:131], v[128:129], v[178:179] op_sel_hi:[1,0]
	v_cvt_pk_bf16_f32 v128, v136, v137
	v_cvt_pk_bf16_f32 v129, v138, v139
	v_pk_mul_f32 v[134:135], v[134:135], v[178:179] op_sel_hi:[1,0]
	v_cvt_pk_bf16_f32 v130, v130, v131
	v_cvt_pk_bf16_f32 v131, v144, v145
	ds_write_b128 v194, v[128:131]
	v_pk_mul_f32 v[130:131], v[142:143], v[178:179] op_sel_hi:[1,0]
	v_pk_mul_f32 v[128:129], v[140:141], v[178:179] op_sel_hi:[1,0]
	v_pk_mul_f32 v[132:133], v[132:133], v[178:179] op_sel_hi:[1,0]
	v_cvt_pk_bf16_f32 v128, v128, v129
	v_cvt_pk_bf16_f32 v129, v130, v131
	v_cvt_pk_bf16_f32 v131, v134, v135
	s_lshl_b32 s14, s77, 3
	v_cvt_pk_bf16_f32 v130, v132, v133
	ds_write_b128 v194, v[128:131] offset:64
	ds_read_b128 v[128:131], v162
	v_add_u32_e32 v132, s14, v152
	v_add_u32_e32 v136, s14, v132
	s_waitcnt lgkmcnt(3)
	global_store_dwordx4 v132, v[148:151], s[0:1] sc0 sc1
	ds_read_b128 v[132:135], v162 offset:1152
	s_waitcnt lgkmcnt(1)
	global_store_dwordx4 v136, v[128:131], s[0:1] sc0 sc1
	v_pk_mul_f32 v[122:123], v[122:123], v[176:177] op_sel_hi:[1,0]
	v_pk_mul_f32 v[120:121], v[120:121], v[176:177] op_sel_hi:[1,0]
	v_pk_mul_f32 v[128:129], v[114:115], v[176:177] op_sel_hi:[1,0]
	v_pk_mul_f32 v[114:115], v[112:113], v[176:177] op_sel_hi:[1,0]
	v_cvt_pk_bf16_f32 v112, v120, v121
	v_cvt_pk_bf16_f32 v113, v122, v123
	v_pk_mul_f32 v[118:119], v[118:119], v[176:177] op_sel_hi:[1,0]
	v_cvt_pk_bf16_f32 v114, v114, v115
	v_cvt_pk_bf16_f32 v115, v128, v129
	ds_write_b128 v194, v[112:115]
	v_pk_mul_f32 v[114:115], v[126:127], v[176:177] op_sel_hi:[1,0]
	v_pk_mul_f32 v[112:113], v[124:125], v[176:177] op_sel_hi:[1,0]
	v_pk_mul_f32 v[116:117], v[116:117], v[176:177] op_sel_hi:[1,0]
	v_cvt_pk_bf16_f32 v112, v112, v113
	v_cvt_pk_bf16_f32 v113, v114, v115
	v_cvt_pk_bf16_f32 v115, v118, v119
	v_pk_mul_f32 v[106:107], v[106:107], v[174:175] op_sel_hi:[1,0]
	v_cvt_pk_bf16_f32 v114, v116, v117
	ds_write_b128 v194, v[112:115] offset:64
	ds_read_b128 v[112:115], v162
	v_add_u32_e32 v116, s14, v136
	v_add_u32_e32 v120, s14, v116
	s_waitcnt lgkmcnt(3)
	global_store_dwordx4 v116, v[132:135], s[0:1] sc0 sc1
	ds_read_b128 v[116:119], v162 offset:1152
	s_waitcnt lgkmcnt(1)
	global_store_dwordx4 v120, v[112:115], s[0:1] sc0 sc1
	v_pk_mul_f32 v[104:105], v[104:105], v[174:175] op_sel_hi:[1,0]
	v_pk_mul_f32 v[102:103], v[102:103], v[174:175] op_sel_hi:[1,0]
	v_pk_mul_f32 v[112:113], v[98:99], v[174:175] op_sel_hi:[1,0]
	v_pk_mul_f32 v[98:99], v[96:97], v[174:175] op_sel_hi:[1,0]
	v_cvt_pk_bf16_f32 v96, v104, v105
	v_cvt_pk_bf16_f32 v97, v106, v107
	v_pk_mul_f32 v[100:101], v[100:101], v[174:175] op_sel_hi:[1,0]
	v_cvt_pk_bf16_f32 v98, v98, v99
	v_cvt_pk_bf16_f32 v99, v112, v113
	ds_write_b128 v194, v[96:99]
	v_pk_mul_f32 v[98:99], v[110:111], v[174:175] op_sel_hi:[1,0]
	v_pk_mul_f32 v[96:97], v[108:109], v[174:175] op_sel_hi:[1,0]
	s_nop 0
	v_cvt_pk_bf16_f32 v96, v96, v97
	v_cvt_pk_bf16_f32 v97, v98, v99
	v_cvt_pk_bf16_f32 v98, v100, v101
	v_cvt_pk_bf16_f32 v99, v102, v103
	ds_write_b128 v194, v[96:99] offset:64
	ds_read_b128 v[96:99], v162
	ds_read_b128 v[160:163], v162 offset:1152
	v_add_u32_e32 v100, s14, v120
	s_waitcnt lgkmcnt(4)
	global_store_dwordx4 v100, v[116:119], s[0:1] sc0 sc1
	v_add_u32_e32 v100, s14, v100
	v_add_u32_e32 v164, s14, v100
	s_waitcnt lgkmcnt(1)
	global_store_dwordx4 v100, v[96:99], s[0:1] sc0 sc1
.LBB0_525:
	s_waitcnt lgkmcnt(0)
	global_store_dwordx4 v164, v[160:163], s[0:1] sc0 sc1
	ds_read_b128 v[96:99], v193 offset:49152
	ds_read_b128 v[100:103], v193 offset:50176
	ds_read_b128 v[104:107], v192 offset:49152
	ds_read_b128 v[108:111], v192 offset:50176
	ds_read_b128 v[112:115], v191 offset:49152
	ds_read_b128 v[116:119], v191 offset:50176
	ds_read_b128 v[120:123], v190 offset:49152
	ds_read_b128 v[124:127], v190 offset:50176
	s_barrier
	s_waitcnt lgkmcnt(0)
	s_setprio 1
	s_waitcnt lgkmcnt(0)
	v_mfma_f32_16x16x32_bf16 v[32:35], v[12:15], v[96:99], v[32:35]
	v_mfma_f32_16x16x32_bf16 v[36:39], v[76:79], v[96:99], v[36:39]
	v_mfma_f32_16x16x32_bf16 v[40:43], v[12:15], v[104:107], v[40:43]
	v_mfma_f32_16x16x32_bf16 v[128:131], v[76:79], v[104:107], v[44:47]
	v_mfma_f32_16x16x32_bf16 v[48:51], v[12:15], v[112:115], v[48:51]
	v_mfma_f32_16x16x32_bf16 v[52:55], v[76:79], v[112:115], v[52:55]
	v_mfma_f32_16x16x32_bf16 v[12:15], v[12:15], v[120:123], v[56:59]
	v_mfma_f32_16x16x32_bf16 v[76:79], v[76:79], v[120:123], v[60:63]
	v_mfma_f32_16x16x32_bf16 v[60:63], v[8:11], v[100:103], v[32:35]
	v_mfma_f32_16x16x32_bf16 v[56:59], v[72:75], v[100:103], v[36:39]
	v_mfma_f32_16x16x32_bf16 v[44:47], v[8:11], v[108:111], v[40:43]
	v_mfma_f32_16x16x32_bf16 v[40:43], v[72:75], v[108:111], v[128:131]
	v_mfma_f32_16x16x32_bf16 v[36:39], v[8:11], v[116:119], v[48:51]
	v_mfma_f32_16x16x32_bf16 v[32:35], v[72:75], v[116:119], v[52:55]
	v_mfma_f32_16x16x32_bf16 v[12:15], v[8:11], v[124:127], v[12:15]
	v_mfma_f32_16x16x32_bf16 v[8:11], v[72:75], v[124:127], v[76:79]
	s_setprio 0
	s_setprio 1
	v_mfma_f32_16x16x32_bf16 v[0:3], v[88:91], v[96:99], v[0:3]
	v_mfma_f32_16x16x32_bf16 v[4:7], v[92:95], v[96:99], v[4:7]
	v_mfma_f32_16x16x32_bf16 v[16:19], v[88:91], v[104:107], v[16:19]
	v_mfma_f32_16x16x32_bf16 v[20:23], v[92:95], v[104:107], v[20:23]
	v_mfma_f32_16x16x32_bf16 v[72:75], v[88:91], v[112:115], v[24:27]
	v_mfma_f32_16x16x32_bf16 v[76:79], v[92:95], v[112:115], v[28:31]
	v_mfma_f32_16x16x32_bf16 v[64:67], v[88:91], v[120:123], v[64:67]
	v_mfma_f32_16x16x32_bf16 v[68:71], v[92:95], v[120:123], v[68:71]
	v_mfma_f32_16x16x32_bf16 v[52:55], v[80:83], v[100:103], v[0:3]
	v_mfma_f32_16x16x32_bf16 v[48:51], v[84:87], v[100:103], v[4:7]
	v_mfma_f32_16x16x32_bf16 v[28:31], v[80:83], v[108:111], v[16:19]
	v_mfma_f32_16x16x32_bf16 v[24:27], v[84:87], v[108:111], v[20:23]
	v_mfma_f32_16x16x32_bf16 v[20:23], v[80:83], v[116:119], v[72:75]
	v_mfma_f32_16x16x32_bf16 v[16:19], v[84:87], v[116:119], v[76:79]
	v_mfma_f32_16x16x32_bf16 v[4:7], v[80:83], v[124:127], v[64:67]
	v_mfma_f32_16x16x32_bf16 v[0:3], v[84:87], v[124:127], v[68:71]
	s_setprio 0
	v_cmp_gt_u32_e32 vcc, s71, v179
	s_barrier
	s_and_saveexec_b64 s[58:59], vcc
	s_cbranch_execz .LBB0_527
	s_barrier

.LBB0_531:
	v_mbcnt_lo_u32_b32 v69, -1, 0
	v_mbcnt_hi_u32_b32 v69, -1, v69
	s_and_b64 vcc, exec, s[56:57]
	v_add_u32_e32 v64, s64, v69
	v_bfe_u32 v68, v64, 8, 1
	v_ashrrev_i32_e32 v73, 6, v64
	v_bfe_u32 v64, v69, 4, 2
	v_and_b32_e32 v71, 3, v73
	v_and_b32_e32 v70, 15, v69
	v_lshlrev_b32_e32 v72, 4, v64
	s_cbranch_vccz .LBB0_534
	s_lshl_b32 s36, s80, 14
	s_lshl_b32 s37, s78, 22
	s_add_i32 s36, s36, s37
	v_lshlrev_b32_e32 v64, 6, v70
	v_or3_b32 v64, s36, v64, v72
	v_lshl_add_u32 v64, v71, 20, v64
	v_lshl_or_b32 v164, v68, 12, v64
	s_waitcnt vmcnt(0)
	v_pk_mul_f32 v[64:65], v[172:173], v[58:59] op_sel_hi:[0,1]
	v_pk_mul_f32 v[66:67], v[172:173], v[56:57] op_sel_hi:[0,1]
	v_max_f32_e32 v66, 0, v66
	v_max_f32_e32 v64, 0, v64
	v_mul_f32_e32 v74, v66, v66
	v_max_f32_e32 v66, 0, v67
	v_mul_f32_e32 v76, v64, v64
	v_max_f32_e32 v64, 0, v65
	v_mul_f32_e32 v75, v66, v66
	v_mul_f32_e32 v77, v64, v64
	v_pk_mul_f32 v[64:65], v[172:173], v[62:63] op_sel_hi:[0,1]
	v_pk_mul_f32 v[66:67], v[172:173], v[60:61] op_sel_hi:[0,1]
	v_max_f32_e32 v66, 0, v66
	v_max_f32_e32 v64, 0, v64
	v_mul_f32_e32 v66, v66, v66
	v_max_f32_e32 v67, 0, v67
	v_mul_f32_e32 v78, v64, v64
	v_max_f32_e32 v64, 0, v65
	v_mul_f32_e32 v67, v67, v67
	v_mul_f32_e32 v65, v64, v64
	v_cvt_pk_bf16_f32 v64, v66, v67
	v_cvt_pk_bf16_f32 v66, v74, v75
	v_lshl_add_u64 v[74:75], s[0:1], 0, v[164:165]
	v_cvt_pk_bf16_f32 v67, v76, v77
	v_add_co_u32_e32 v76, vcc, s66, v74
	v_cvt_pk_bf16_f32 v65, v78, v65
	s_nop 1
	v_addc_co_u32_e32 v77, vcc, 0, v75, vcc
	global_store_dwordx4 v[76:77], v[64:67], off sc0 sc1
	v_add_co_u32_e32 v74, vcc, s75, v74
	s_nop 0
	v_pk_mul_f32 v[64:65], v[172:173], v[50:51] op_sel_hi:[0,1]
	v_max_f32_e32 v64, 0, v64
	v_pk_mul_f32 v[66:67], v[172:173], v[48:49] op_sel_hi:[0,1]
	v_mul_f32_e32 v80, v64, v64
	v_max_f32_e32 v64, 0, v65
	v_max_f32_e32 v66, 0, v66
	v_mul_f32_e32 v81, v64, v64
	v_pk_mul_f32 v[64:65], v[172:173], v[54:55] op_sel_hi:[0,1]
	v_mul_f32_e32 v78, v66, v66
	v_max_f32_e32 v66, 0, v67
	v_max_f32_e32 v64, 0, v64
	v_mul_f32_e32 v79, v66, v66
	v_pk_mul_f32 v[66:67], v[172:173], v[52:53] op_sel_hi:[0,1]
	v_mul_f32_e32 v82, v64, v64
	v_max_f32_e32 v64, 0, v65
	v_max_f32_e32 v66, 0, v66
	v_max_f32_e32 v67, 0, v67
	v_mul_f32_e32 v65, v64, v64
	v_mul_f32_e32 v66, v66, v66
	v_mul_f32_e32 v67, v67, v67
	v_cvt_pk_bf16_f32 v64, v66, v67
	v_cvt_pk_bf16_f32 v65, v82, v65
	v_addc_co_u32_e32 v75, vcc, 0, v75, vcc
	v_cvt_pk_bf16_f32 v66, v78, v79
	v_cvt_pk_bf16_f32 v67, v80, v81
	global_store_dwordx4 v[74:75], v[64:67], off sc0 sc1
	s_nop 1
	v_pk_mul_f32 v[64:65], v[170:171], v[42:43] op_sel_hi:[0,1]
	v_max_f32_e32 v64, 0, v64
	v_pk_mul_f32 v[66:67], v[170:171], v[40:41] op_sel_hi:[0,1]
	v_mul_f32_e32 v80, v64, v64
	v_max_f32_e32 v64, 0, v65
	v_max_f32_e32 v66, 0, v66
	v_mul_f32_e32 v81, v64, v64
	v_pk_mul_f32 v[64:65], v[170:171], v[46:47] op_sel_hi:[0,1]
	v_mul_f32_e32 v78, v66, v66
	v_max_f32_e32 v66, 0, v67
	v_max_f32_e32 v64, 0, v64
	v_mul_f32_e32 v79, v66, v66
	v_pk_mul_f32 v[66:67], v[170:171], v[44:45] op_sel_hi:[0,1]
	v_mul_f32_e32 v82, v64, v64
	v_max_f32_e32 v64, 0, v65
	v_max_f32_e32 v66, 0, v66
	v_max_f32_e32 v67, 0, v67
	v_mul_f32_e32 v65, v64, v64
	v_mul_f32_e32 v66, v66, v66
	v_mul_f32_e32 v67, v67, v67
	v_cvt_pk_bf16_f32 v64, v66, v67
	v_cvt_pk_bf16_f32 v65, v82, v65
	v_cvt_pk_bf16_f32 v66, v78, v79
	v_cvt_pk_bf16_f32 v67, v80, v81
	global_store_dwordx4 v[76:77], v[64:67], off offset:1024 sc0 sc1
	s_nop 1
	v_pk_mul_f32 v[64:65], v[170:171], v[26:27] op_sel_hi:[0,1]
	v_max_f32_e32 v64, 0, v64
	v_pk_mul_f32 v[66:67], v[170:171], v[24:25] op_sel_hi:[0,1]
	v_mul_f32_e32 v80, v64, v64
	v_max_f32_e32 v64, 0, v65
	v_max_f32_e32 v66, 0, v66
	v_mul_f32_e32 v81, v64, v64
	v_pk_mul_f32 v[64:65], v[170:171], v[30:31] op_sel_hi:[0,1]
	v_mul_f32_e32 v78, v66, v66
	v_max_f32_e32 v66, 0, v67
	v_max_f32_e32 v64, 0, v64
	v_mul_f32_e32 v79, v66, v66
	v_pk_mul_f32 v[66:67], v[170:171], v[28:29] op_sel_hi:[0,1]
	v_mul_f32_e32 v82, v64, v64
	v_max_f32_e32 v64, 0, v65
	v_max_f32_e32 v66, 0, v66
	v_max_f32_e32 v67, 0, v67
	v_mul_f32_e32 v65, v64, v64
	v_mul_f32_e32 v66, v66, v66
	v_mul_f32_e32 v67, v67, v67
	v_cvt_pk_bf16_f32 v64, v66, v67
	v_cvt_pk_bf16_f32 v65, v82, v65
	v_cvt_pk_bf16_f32 v66, v78, v79
	v_cvt_pk_bf16_f32 v67, v80, v81
	global_store_dwordx4 v[74:75], v[64:67], off offset:1024 sc0 sc1
	s_nop 1
	v_pk_mul_f32 v[64:65], v[168:169], v[34:35] op_sel_hi:[0,1]
	v_max_f32_e32 v64, 0, v64
	v_pk_mul_f32 v[66:67], v[168:169], v[32:33] op_sel_hi:[0,1]
	v_mul_f32_e32 v80, v64, v64
	v_max_f32_e32 v64, 0, v65
	v_max_f32_e32 v66, 0, v66
	v_mul_f32_e32 v81, v64, v64
	v_pk_mul_f32 v[64:65], v[168:169], v[38:39] op_sel_hi:[0,1]
	v_mul_f32_e32 v78, v66, v66
	v_max_f32_e32 v66, 0, v67
	v_max_f32_e32 v64, 0, v64
	v_mul_f32_e32 v79, v66, v66
	v_pk_mul_f32 v[66:67], v[168:169], v[36:37] op_sel_hi:[0,1]
	v_mul_f32_e32 v82, v64, v64
	v_max_f32_e32 v64, 0, v65
	v_max_f32_e32 v66, 0, v66
	v_max_f32_e32 v67, 0, v67
	v_mul_f32_e32 v65, v64, v64
	v_mul_f32_e32 v66, v66, v66
	v_mul_f32_e32 v67, v67, v67
	v_cvt_pk_bf16_f32 v64, v66, v67
	v_cvt_pk_bf16_f32 v65, v82, v65
	v_cvt_pk_bf16_f32 v66, v78, v79
	v_cvt_pk_bf16_f32 v67, v80, v81
	global_store_dwordx4 v[76:77], v[64:67], off offset:2048 sc0 sc1
	s_nop 1
	v_pk_mul_f32 v[64:65], v[168:169], v[18:19] op_sel_hi:[0,1]
	v_max_f32_e32 v64, 0, v64
	v_pk_mul_f32 v[66:67], v[168:169], v[16:17] op_sel_hi:[0,1]
	v_mul_f32_e32 v80, v64, v64
	v_max_f32_e32 v64, 0, v65
	v_max_f32_e32 v66, 0, v66
	v_mul_f32_e32 v81, v64, v64
	v_pk_mul_f32 v[64:65], v[168:169], v[22:23] op_sel_hi:[0,1]
	v_mul_f32_e32 v78, v66, v66
	v_max_f32_e32 v66, 0, v67
	v_max_f32_e32 v64, 0, v64
	v_mul_f32_e32 v79, v66, v66
	v_pk_mul_f32 v[66:67], v[168:169], v[20:21] op_sel_hi:[0,1]
	v_mul_f32_e32 v82, v64, v64
	v_max_f32_e32 v64, 0, v65
	v_max_f32_e32 v66, 0, v66
	v_max_f32_e32 v67, 0, v67
	v_mul_f32_e32 v65, v64, v64
	v_mul_f32_e32 v66, v66, v66
	v_mul_f32_e32 v67, v67, v67
	v_cvt_pk_bf16_f32 v64, v66, v67
	v_cvt_pk_bf16_f32 v65, v82, v65
	v_cvt_pk_bf16_f32 v66, v78, v79
	v_cvt_pk_bf16_f32 v67, v80, v81
	global_store_dwordx4 v[74:75], v[64:67], off offset:2048 sc0 sc1
	s_nop 1
	v_pk_mul_f32 v[64:65], v[166:167], v[10:11] op_sel_hi:[0,1]
	v_max_f32_e32 v64, 0, v64
	v_pk_mul_f32 v[66:67], v[166:167], v[8:9] op_sel_hi:[0,1]
	v_mul_f32_e32 v78, v64, v64
	v_max_f32_e32 v64, 0, v65
	v_max_f32_e32 v66, 0, v66
	v_mul_f32_e32 v79, v64, v64
	v_pk_mul_f32 v[64:65], v[166:167], v[14:15] op_sel_hi:[0,1]
	v_mul_f32_e32 v74, v66, v66
	v_max_f32_e32 v66, 0, v67
	v_max_f32_e32 v64, 0, v64
	v_mul_f32_e32 v75, v66, v66
	v_pk_mul_f32 v[66:67], v[166:167], v[12:13] op_sel_hi:[0,1]
	v_mul_f32_e32 v80, v64, v64
	v_max_f32_e32 v64, 0, v65
	v_max_f32_e32 v66, 0, v66
	v_max_f32_e32 v67, 0, v67
	v_mul_f32_e32 v65, v64, v64
	v_mul_f32_e32 v66, v66, v66
	v_mul_f32_e32 v67, v67, v67
	v_cvt_pk_bf16_f32 v64, v66, v67
	v_cvt_pk_bf16_f32 v65, v80, v65
	v_cvt_pk_bf16_f32 v66, v74, v75
	v_cvt_pk_bf16_f32 v67, v78, v79
	global_store_dwordx4 v[76:77], v[64:67], off offset:3072 sc0 sc1
	s_nop 1
	v_pk_mul_f32 v[64:65], v[166:167], v[2:3] op_sel_hi:[0,1]
	v_pk_mul_f32 v[66:67], v[166:167], v[0:1] op_sel_hi:[0,1]
	v_max_f32_e32 v64, 0, v64
	v_max_f32_e32 v66, 0, v66
	v_mul_f32_e32 v76, v64, v64
	v_max_f32_e32 v64, 0, v65
	v_mul_f32_e32 v74, v66, v66
	v_max_f32_e32 v66, 0, v67
	v_mul_f32_e32 v77, v64, v64
	v_pk_mul_f32 v[64:65], v[166:167], v[6:7] op_sel_hi:[0,1]
	v_mul_f32_e32 v75, v66, v66
	v_pk_mul_f32 v[66:67], v[166:167], v[4:5] op_sel_hi:[0,1]
	v_max_f32_e32 v64, 0, v64
	v_max_f32_e32 v66, 0, v66
	v_max_f32_e32 v67, 0, v67
	v_mul_f32_e32 v78, v64, v64
	v_max_f32_e32 v64, 0, v65
	v_mul_f32_e32 v66, v66, v66
	v_mul_f32_e32 v67, v67, v67
	v_mul_f32_e32 v65, v64, v64
	v_cvt_pk_bf16_f32 v64, v66, v67
	v_cvt_pk_bf16_f32 v65, v78, v65
	v_cvt_pk_bf16_f32 v66, v74, v75
	v_cvt_pk_bf16_f32 v67, v76, v77
	v_add_u32_e32 v74, 0x82c00, v164
	s_cbranch_execnz .LBB0_509
	s_branch .LBB0_508

.LBB0_549:
	v_mbcnt_lo_u32_b32 v64, -1, 0
	v_mbcnt_hi_u32_b32 v64, -1, v64
	v_cvt_pk_bf16_f32 v56, v56, v57
	v_cvt_pk_bf16_f32 v57, v58, v59
	v_cvt_pk_bf16_f32 v58, v48, v49
	v_cvt_pk_bf16_f32 v59, v50, v51
	v_cvt_pk_bf16_f32 v48, v60, v61
	s_nop 0
	v_add_u32_e32 v65, s74, v64
	v_ashrrev_i32_e32 v66, 6, v65
	v_and_b32_e32 v67, 15, v64
	v_and_b32_e32 v68, 48, v64
	v_mul_lo_u32 v69, v66, s79
	v_lshrrev_b32_e32 v65, 2, v65
	v_bfe_u32 v70, v64, 3, 3
	v_lshlrev_b32_e32 v64, 4, v64
	v_add_u32_e32 v69, 0x20000, v69
	v_and_b32_e32 v65, 64, v65
	v_and_b32_e32 v64, 0x70, v64
	v_mul_u32_u24_e32 v67, 0x90, v67
	v_add3_u32 v67, v69, v67, v68
	v_or_b32_e32 v68, v69, v64
	v_or3_b32 v65, s96, v65, v70
	v_lshlrev_b32_e32 v66, 7, v66
	v_mad_u32_u24 v68, v70, s81, v68
	ds_write_b128 v67, v[56:59]
	v_cvt_pk_bf16_f32 v49, v62, v63
	v_cvt_pk_bf16_f32 v50, v52, v53
	v_cvt_pk_bf16_f32 v51, v54, v55
	ds_write_b128 v67, v[48:51] offset:64
	v_lshlrev_b32_e32 v52, 12, v65
	ds_read_b128 v[48:51], v68
	v_and_or_b32 v52, v66, s82, v52
	v_or3_b32 v128, v52, s89, v64
	v_lshl_add_u64 v[56:57], s[0:1], 0, v[128:129]
	v_add_co_u32_e32 v58, vcc, s90, v56
	ds_read_b128 v[52:55], v68 offset:1152
	v_cvt_pk_bf16_f32 v44, v44, v45
	v_cvt_pk_bf16_f32 v45, v46, v47
	v_cvt_pk_bf16_f32 v46, v40, v41
	v_cvt_pk_bf16_f32 v47, v42, v43
	ds_write_b128 v67, v[44:47]
	v_cvt_pk_bf16_f32 v28, v28, v29
	v_cvt_pk_bf16_f32 v29, v30, v31
	v_cvt_pk_bf16_f32 v30, v24, v25
	v_cvt_pk_bf16_f32 v31, v26, v27
	ds_write_b128 v67, v[28:31] offset:64
	v_addc_co_u32_e32 v59, vcc, 0, v57, vcc
	ds_read_b128 v[24:27], v68
	ds_read_b128 v[28:31], v68 offset:1152
	s_waitcnt lgkmcnt(0)
	global_store_dwordx4 v[58:59], v[48:51], off sc0 sc1
	v_cvt_pk_bf16_f32 v20, v20, v21
	v_cvt_pk_bf16_f32 v21, v22, v23
	v_cvt_pk_bf16_f32 v22, v16, v17
	v_cvt_pk_bf16_f32 v23, v18, v19
	ds_write_b128 v67, v[20:23] offset:64
	s_nop 0
	v_add_co_u32_e32 v48, vcc, s91, v56
	v_cvt_pk_bf16_f32 v8, v8, v9
	v_cvt_pk_bf16_f32 v9, v10, v11
	v_cvt_pk_bf16_f32 v10, v0, v1
	v_cvt_pk_bf16_f32 v11, v2, v3
	s_nop 1
	v_addc_co_u32_e32 v49, vcc, 0, v57, vcc
	v_add_co_u32_e32 v40, vcc, s92, v56
	v_cvt_pk_bf16_f32 v0, v12, v13
	v_cvt_pk_bf16_f32 v1, v14, v15
	v_cvt_pk_bf16_f32 v2, v4, v5
	v_cvt_pk_bf16_f32 v3, v6, v7
	s_nop 1
	v_addc_co_u32_e32 v41, vcc, 0, v57, vcc
	global_store_dwordx4 v[40:41], v[24:27], off sc0 sc1
	s_add_i32 s78, s78, 1
	global_store_dwordx4 v[48:49], v[52:55], off sc0 sc1
	v_add_co_u32_e32 v24, vcc, s93, v56
	v_cvt_pk_bf16_f32 v26, v32, v33
	v_cvt_pk_bf16_f32 v27, v34, v35
	s_nop 1
	v_addc_co_u32_e32 v25, vcc, 0, v57, vcc
	global_store_dwordx4 v[24:25], v[28:31], off sc0 sc1
	v_cvt_pk_bf16_f32 v24, v36, v37
	v_cvt_pk_bf16_f32 v25, v38, v39
	ds_write_b128 v67, v[24:27]
	ds_read_b128 v[16:19], v68
	ds_read_b128 v[20:23], v68 offset:1152
	v_add_co_u32_e32 v24, vcc, s94, v56
	ds_write_b128 v67, v[8:11]
	ds_write_b128 v67, v[0:3] offset:64
	v_addc_co_u32_e32 v25, vcc, 0, v57, vcc
	ds_read_b128 v[0:3], v68
	ds_read_b128 v[4:7], v68 offset:1152
	s_waitcnt lgkmcnt(0)
	global_store_dwordx4 v[24:25], v[16:19], off sc0 sc1
	s_nop 1
	v_add_co_u32_e32 v16, vcc, s95, v56
	s_nop 1
	v_addc_co_u32_e32 v17, vcc, 0, v57, vcc
	v_add_co_u32_e32 v8, vcc, 0xb0000, v56
	global_store_dwordx4 v[16:17], v[20:23], off sc0 sc1
	s_nop 0
	v_addc_co_u32_e32 v9, vcc, 0, v57, vcc
	global_store_dwordx4 v[8:9], v[0:3], off sc0 sc1
	s_nop 1
	v_add_co_u32_e32 v0, vcc, 0xb8000, v56
	s_nop 1
	v_addc_co_u32_e32 v1, vcc, 0, v57, vcc
	s_andn2_b64 vcc, exec, s[66:67]
	s_mov_b64 s[66:67], 0
	global_store_dwordx4 v[0:1], v[4:7], off sc0 sc1
	s_cbranch_vccz .LBB0_568

.LBB0_561:
	ds_read_b128 v[162:165], v161
	ds_read_b128 v[166:169], v161 offset:1024
	ds_read_b128 v[170:173], v161 offset:2048
	ds_read_b128 v[174:177], v161 offset:3072
	v_readfirstlane_b32 s36, v160
	v_lshl_add_u64 v[210:211], v[132:133], 0, s[22:23]
	s_mov_b32 m0, s36
	v_readfirstlane_b32 s36, v159
	ds_read_b128 v[178:181], v152
	ds_read_b128 v[182:185], v152 offset:1024
	ds_read_b128 v[186:189], v151
	ds_read_b128 v[190:193], v151 offset:1024
	ds_read_b128 v[194:197], v150
	ds_read_b128 v[198:201], v150 offset:1024
	ds_read_b128 v[202:205], v149
	ds_read_b128 v[206:209], v149 offset:1024
	global_load_lds_dwordx4 v[210:211], off
	v_lshl_add_u64 v[210:211], v[132:133], 0, s[24:25]
	s_mov_b32 m0, s36
	s_nop 0
	global_load_lds_dwordx4 v[210:211], off
	s_waitcnt lgkmcnt(8)
	s_barrier
	s_waitcnt lgkmcnt(0)
	s_setprio 1
	s_waitcnt lgkmcnt(0)
	v_mfma_f32_16x16x32_bf16 v[124:127], v[162:165], v[178:181], v[124:127]
	v_mfma_f32_16x16x32_bf16 v[120:123], v[170:173], v[178:181], v[120:123]
	v_mfma_f32_16x16x32_bf16 v[116:119], v[162:165], v[186:189], v[116:119]
	v_mfma_f32_16x16x32_bf16 v[112:115], v[170:173], v[186:189], v[112:115]
	v_mfma_f32_16x16x32_bf16 v[108:111], v[162:165], v[194:197], v[108:111]
	v_mfma_f32_16x16x32_bf16 v[104:107], v[170:173], v[194:197], v[104:107]
	v_mfma_f32_16x16x32_bf16 v[100:103], v[162:165], v[202:205], v[100:103]
	v_mfma_f32_16x16x32_bf16 v[96:99], v[170:173], v[202:205], v[96:99]
	v_mfma_f32_16x16x32_bf16 v[124:127], v[166:169], v[182:185], v[124:127]
	v_mfma_f32_16x16x32_bf16 v[120:123], v[174:177], v[182:185], v[120:123]
	v_mfma_f32_16x16x32_bf16 v[116:119], v[166:169], v[190:193], v[116:119]
	v_mfma_f32_16x16x32_bf16 v[112:115], v[174:177], v[190:193], v[112:115]
	v_mfma_f32_16x16x32_bf16 v[108:111], v[166:169], v[198:201], v[108:111]
	v_mfma_f32_16x16x32_bf16 v[104:107], v[174:177], v[198:201], v[104:107]
	v_mfma_f32_16x16x32_bf16 v[100:103], v[166:169], v[206:209], v[100:103]
	v_mfma_f32_16x16x32_bf16 v[96:99], v[174:177], v[206:209], v[96:99]
	s_setprio 0
	s_barrier
	v_readfirstlane_b32 s36, v148
	v_lshl_add_u64 v[226:227], v[130:131], 0, s[26:27]
	s_mov_b32 m0, s36
	v_readfirstlane_b32 s36, v147
	ds_read_b128 v[210:213], v158
	ds_read_b128 v[214:217], v158 offset:1024
	ds_read_b128 v[218:221], v158 offset:2048
	ds_read_b128 v[222:225], v158 offset:3072
	global_load_lds_dwordx4 v[226:227], off
	v_lshl_add_u64 v[226:227], v[130:131], 0, s[28:29]
	s_mov_b32 m0, s36
	s_add_i32 s68, s68, 2
	global_load_lds_dwordx4 v[226:227], off
	s_barrier
	s_waitcnt lgkmcnt(0)
	s_setprio 1
	s_waitcnt lgkmcnt(0)
	v_mfma_f32_16x16x32_bf16 v[92:95], v[210:213], v[178:181], v[92:95]
	v_mfma_f32_16x16x32_bf16 v[88:91], v[218:221], v[178:181], v[88:91]
	v_mfma_f32_16x16x32_bf16 v[84:87], v[210:213], v[186:189], v[84:87]
	v_mfma_f32_16x16x32_bf16 v[80:83], v[218:221], v[186:189], v[80:83]
	v_mfma_f32_16x16x32_bf16 v[76:79], v[210:213], v[194:197], v[76:79]
	v_mfma_f32_16x16x32_bf16 v[72:75], v[218:221], v[194:197], v[72:75]
	v_mfma_f32_16x16x32_bf16 v[68:71], v[210:213], v[202:205], v[68:71]
	v_mfma_f32_16x16x32_bf16 v[64:67], v[218:221], v[202:205], v[64:67]
	v_mfma_f32_16x16x32_bf16 v[92:95], v[214:217], v[182:185], v[92:95]
	v_mfma_f32_16x16x32_bf16 v[88:91], v[222:225], v[182:185], v[88:91]
	v_mfma_f32_16x16x32_bf16 v[84:87], v[214:217], v[190:193], v[84:87]
	v_mfma_f32_16x16x32_bf16 v[80:83], v[222:225], v[190:193], v[80:83]
	v_mfma_f32_16x16x32_bf16 v[76:79], v[214:217], v[198:201], v[76:79]
	v_mfma_f32_16x16x32_bf16 v[72:75], v[222:225], v[198:201], v[72:75]
	v_mfma_f32_16x16x32_bf16 v[68:71], v[214:217], v[206:209], v[68:71]
	v_mfma_f32_16x16x32_bf16 v[64:67], v[222:225], v[206:209], v[64:67]
	s_setprio 0
	v_readfirstlane_b32 s36, v134
	v_lshl_add_u64 v[226:227], v[132:133], 0, s[30:31]
	s_mov_b32 m0, s36
	v_readfirstlane_b32 s36, v146
	s_barrier
	ds_read_b128 v[178:181], v152 offset:16384
	ds_read_b128 v[182:185], v152 offset:17408
	ds_read_b128 v[186:189], v151 offset:16384
	ds_read_b128 v[190:193], v151 offset:17408
	ds_read_b128 v[194:197], v150 offset:16384
	ds_read_b128 v[198:201], v150 offset:17408
	ds_read_b128 v[202:205], v149 offset:16384
	ds_read_b128 v[206:209], v149 offset:17408
	global_load_lds_dwordx4 v[226:227], off
	v_lshl_add_u64 v[226:227], v[132:133], 0, s[34:35]
	s_mov_b32 m0, s36
	s_nop 0
	global_load_lds_dwordx4 v[226:227], off
	s_barrier
	s_waitcnt lgkmcnt(0)
	s_setprio 1
	s_waitcnt lgkmcnt(0)
	v_mfma_f32_16x16x32_bf16 v[60:63], v[162:165], v[178:181], v[60:63]
	v_mfma_f32_16x16x32_bf16 v[56:59], v[170:173], v[178:181], v[56:59]
	v_mfma_f32_16x16x32_bf16 v[52:55], v[162:165], v[186:189], v[52:55]
	v_mfma_f32_16x16x32_bf16 v[48:51], v[170:173], v[186:189], v[48:51]
	v_mfma_f32_16x16x32_bf16 v[44:47], v[162:165], v[194:197], v[44:47]
	v_mfma_f32_16x16x32_bf16 v[40:43], v[170:173], v[194:197], v[40:43]
	v_mfma_f32_16x16x32_bf16 v[36:39], v[162:165], v[202:205], v[36:39]
	v_mfma_f32_16x16x32_bf16 v[32:35], v[170:173], v[202:205], v[32:35]
	v_mfma_f32_16x16x32_bf16 v[60:63], v[166:169], v[182:185], v[60:63]
	v_mfma_f32_16x16x32_bf16 v[56:59], v[174:177], v[182:185], v[56:59]
	v_mfma_f32_16x16x32_bf16 v[52:55], v[166:169], v[190:193], v[52:55]
	v_mfma_f32_16x16x32_bf16 v[48:51], v[174:177], v[190:193], v[48:51]
	v_mfma_f32_16x16x32_bf16 v[44:47], v[166:169], v[198:201], v[44:47]
	v_mfma_f32_16x16x32_bf16 v[40:43], v[174:177], v[198:201], v[40:43]
	v_mfma_f32_16x16x32_bf16 v[36:39], v[166:169], v[206:209], v[36:39]
	v_mfma_f32_16x16x32_bf16 v[32:35], v[174:177], v[206:209], v[32:35]
	s_setprio 0
	s_barrier
	v_readfirstlane_b32 s36, v145
	v_lshl_add_u64 v[162:163], v[130:131], 0, s[38:39]
	s_mov_b32 m0, s36
	v_readfirstlane_b32 s36, v144
	global_load_lds_dwordx4 v[162:163], off
	v_lshl_add_u64 v[162:163], v[130:131], 0, s[44:45]
	s_mov_b32 m0, s36
	s_nop 0
	global_load_lds_dwordx4 v[162:163], off
	s_waitcnt vmcnt(6)
	s_barrier
	s_setprio 1
	v_mfma_f32_16x16x32_bf16 v[28:31], v[210:213], v[178:181], v[28:31]
	v_mfma_f32_16x16x32_bf16 v[24:27], v[218:221], v[178:181], v[24:27]
	v_mfma_f32_16x16x32_bf16 v[20:23], v[210:213], v[186:189], v[20:23]
	v_mfma_f32_16x16x32_bf16 v[16:19], v[218:221], v[186:189], v[16:19]
	v_mfma_f32_16x16x32_bf16 v[12:15], v[210:213], v[194:197], v[12:15]
	v_mfma_f32_16x16x32_bf16 v[8:11], v[218:221], v[194:197], v[8:11]
	v_mfma_f32_16x16x32_bf16 v[4:7], v[210:213], v[202:205], v[4:7]
	v_mfma_f32_16x16x32_bf16 v[0:3], v[218:221], v[202:205], v[0:3]
	v_mfma_f32_16x16x32_bf16 v[28:31], v[214:217], v[182:185], v[28:31]
	v_mfma_f32_16x16x32_bf16 v[24:27], v[222:225], v[182:185], v[24:27]
	v_mfma_f32_16x16x32_bf16 v[20:23], v[214:217], v[190:193], v[20:23]
	v_mfma_f32_16x16x32_bf16 v[16:19], v[222:225], v[190:193], v[16:19]
	v_mfma_f32_16x16x32_bf16 v[12:15], v[214:217], v[198:201], v[12:15]
	v_mfma_f32_16x16x32_bf16 v[8:11], v[222:225], v[198:201], v[8:11]
	v_mfma_f32_16x16x32_bf16 v[4:7], v[214:217], v[206:209], v[4:7]
	v_mfma_f32_16x16x32_bf16 v[0:3], v[222:225], v[206:209], v[0:3]
	s_setprio 0
	s_barrier
	ds_read_b128 v[162:165], v154
	ds_read_b128 v[166:169], v154 offset:1024
	ds_read_b128 v[170:173], v154 offset:2048
	ds_read_b128 v[174:177], v154 offset:3072
	v_readfirstlane_b32 s36, v143
	v_lshl_add_u64 v[210:211], v[132:133], 0, s[46:47]
	s_mov_b32 m0, s36
	v_readfirstlane_b32 s36, v142
	ds_read_b128 v[178:181], v152 offset:32768
	ds_read_b128 v[182:185], v152 offset:33792
	ds_read_b128 v[186:189], v151 offset:32768
	ds_read_b128 v[190:193], v151 offset:33792
	ds_read_b128 v[194:197], v150 offset:32768
	ds_read_b128 v[198:201], v150 offset:33792
	ds_read_b128 v[202:205], v149 offset:32768
	ds_read_b128 v[206:209], v149 offset:33792
	global_load_lds_dwordx4 v[210:211], off
	v_lshl_add_u64 v[210:211], v[132:133], 0, s[50:51]
	s_mov_b32 m0, s36
	s_nop 0
	global_load_lds_dwordx4 v[210:211], off
	s_waitcnt lgkmcnt(8)
	s_barrier
	s_waitcnt lgkmcnt(0)
	s_setprio 1
	s_waitcnt lgkmcnt(0)
	v_mfma_f32_16x16x32_bf16 v[124:127], v[162:165], v[178:181], v[124:127]
	v_mfma_f32_16x16x32_bf16 v[120:123], v[170:173], v[178:181], v[120:123]
	v_mfma_f32_16x16x32_bf16 v[116:119], v[162:165], v[186:189], v[116:119]
	v_mfma_f32_16x16x32_bf16 v[112:115], v[170:173], v[186:189], v[112:115]
	v_mfma_f32_16x16x32_bf16 v[108:111], v[162:165], v[194:197], v[108:111]
	v_mfma_f32_16x16x32_bf16 v[104:107], v[170:173], v[194:197], v[104:107]
	v_mfma_f32_16x16x32_bf16 v[100:103], v[162:165], v[202:205], v[100:103]
	v_mfma_f32_16x16x32_bf16 v[96:99], v[170:173], v[202:205], v[96:99]
	v_mfma_f32_16x16x32_bf16 v[124:127], v[166:169], v[182:185], v[124:127]
	v_mfma_f32_16x16x32_bf16 v[120:123], v[174:177], v[182:185], v[120:123]
	v_mfma_f32_16x16x32_bf16 v[116:119], v[166:169], v[190:193], v[116:119]
	v_mfma_f32_16x16x32_bf16 v[112:115], v[174:177], v[190:193], v[112:115]
	v_mfma_f32_16x16x32_bf16 v[108:111], v[166:169], v[198:201], v[108:111]
	v_mfma_f32_16x16x32_bf16 v[104:107], v[174:177], v[198:201], v[104:107]
	v_mfma_f32_16x16x32_bf16 v[100:103], v[166:169], v[206:209], v[100:103]
	v_mfma_f32_16x16x32_bf16 v[96:99], v[174:177], v[206:209], v[96:99]
	s_setprio 0
	s_barrier
	v_readfirstlane_b32 s36, v141
	v_lshl_add_u64 v[226:227], v[130:131], 0, s[56:57]
	s_mov_b32 m0, s36
	v_readfirstlane_b32 s36, v140
	ds_read_b128 v[210:213], v153
	ds_read_b128 v[214:217], v153 offset:1024
	ds_read_b128 v[218:221], v153 offset:2048
	ds_read_b128 v[222:225], v153 offset:3072
	global_load_lds_dwordx4 v[226:227], off
	v_lshl_add_u64 v[226:227], v[130:131], 0, s[58:59]
	s_mov_b32 m0, s36
	s_nop 0
	global_load_lds_dwordx4 v[226:227], off
	s_barrier
	s_waitcnt lgkmcnt(0)
	s_setprio 1
	s_waitcnt lgkmcnt(0)
	v_mfma_f32_16x16x32_bf16 v[92:95], v[210:213], v[178:181], v[92:95]
	v_mfma_f32_16x16x32_bf16 v[88:91], v[218:221], v[178:181], v[88:91]
	v_mfma_f32_16x16x32_bf16 v[84:87], v[210:213], v[186:189], v[84:87]
	v_mfma_f32_16x16x32_bf16 v[80:83], v[218:221], v[186:189], v[80:83]
	v_mfma_f32_16x16x32_bf16 v[76:79], v[210:213], v[194:197], v[76:79]
	v_mfma_f32_16x16x32_bf16 v[72:75], v[218:221], v[194:197], v[72:75]
	v_mfma_f32_16x16x32_bf16 v[68:71], v[210:213], v[202:205], v[68:71]
	v_mfma_f32_16x16x32_bf16 v[64:67], v[218:221], v[202:205], v[64:67]
	v_mfma_f32_16x16x32_bf16 v[92:95], v[214:217], v[182:185], v[92:95]
	v_mfma_f32_16x16x32_bf16 v[88:91], v[222:225], v[182:185], v[88:91]
	v_mfma_f32_16x16x32_bf16 v[84:87], v[214:217], v[190:193], v[84:87]
	v_mfma_f32_16x16x32_bf16 v[80:83], v[222:225], v[190:193], v[80:83]
	v_mfma_f32_16x16x32_bf16 v[76:79], v[214:217], v[198:201], v[76:79]
	v_mfma_f32_16x16x32_bf16 v[72:75], v[222:225], v[198:201], v[72:75]
	v_mfma_f32_16x16x32_bf16 v[68:71], v[214:217], v[206:209], v[68:71]
	v_mfma_f32_16x16x32_bf16 v[64:67], v[222:225], v[206:209], v[64:67]
	s_setprio 0
	v_readfirstlane_b32 s36, v139
	v_lshl_add_u64 v[226:227], v[132:133], 0, s[60:61]
	s_mov_b32 m0, s36
	v_readfirstlane_b32 s36, v138
	s_barrier
	ds_read_b128 v[178:181], v152 offset:49152
	ds_read_b128 v[182:185], v152 offset:50176
	ds_read_b128 v[186:189], v151 offset:49152
	ds_read_b128 v[190:193], v151 offset:50176
	ds_read_b128 v[194:197], v150 offset:49152
	ds_read_b128 v[198:201], v150 offset:50176
	ds_read_b128 v[202:205], v149 offset:49152
	ds_read_b128 v[206:209], v149 offset:50176
	global_load_lds_dwordx4 v[226:227], off
	s_mov_b32 m0, s36
	s_nop 0
	global_load_lds_dwordx4 v[132:133], off
	s_barrier
	s_waitcnt lgkmcnt(0)
	s_setprio 1
	s_waitcnt lgkmcnt(0)
	v_mfma_f32_16x16x32_bf16 v[60:63], v[162:165], v[178:181], v[60:63]
	v_mfma_f32_16x16x32_bf16 v[56:59], v[170:173], v[178:181], v[56:59]
	v_mfma_f32_16x16x32_bf16 v[52:55], v[162:165], v[186:189], v[52:55]
	v_mfma_f32_16x16x32_bf16 v[48:51], v[170:173], v[186:189], v[48:51]
	v_mfma_f32_16x16x32_bf16 v[44:47], v[162:165], v[194:197], v[44:47]
	v_mfma_f32_16x16x32_bf16 v[40:43], v[170:173], v[194:197], v[40:43]
	v_mfma_f32_16x16x32_bf16 v[36:39], v[162:165], v[202:205], v[36:39]
	v_mfma_f32_16x16x32_bf16 v[32:35], v[170:173], v[202:205], v[32:35]
	v_mfma_f32_16x16x32_bf16 v[60:63], v[166:169], v[182:185], v[60:63]
	v_mfma_f32_16x16x32_bf16 v[56:59], v[174:177], v[182:185], v[56:59]
	v_mfma_f32_16x16x32_bf16 v[52:55], v[166:169], v[190:193], v[52:55]
	v_mfma_f32_16x16x32_bf16 v[48:51], v[174:177], v[190:193], v[48:51]
	v_mfma_f32_16x16x32_bf16 v[44:47], v[166:169], v[198:201], v[44:47]
	v_mfma_f32_16x16x32_bf16 v[40:43], v[174:177], v[198:201], v[40:43]
	v_mfma_f32_16x16x32_bf16 v[36:39], v[166:169], v[206:209], v[36:39]
	v_mfma_f32_16x16x32_bf16 v[32:35], v[174:177], v[206:209], v[32:35]
	s_setprio 0
	s_barrier
	v_readfirstlane_b32 s36, v137
	v_lshl_add_u64 v[162:163], v[130:131], 0, s[60:61]
	s_mov_b32 m0, s36
	v_readfirstlane_b32 s36, v136
	global_load_lds_dwordx4 v[162:163], off
	s_mov_b32 m0, s36
	s_nop 0
	global_load_lds_dwordx4 v[130:131], off
	s_waitcnt vmcnt(6)
	s_barrier
	s_setprio 1
	v_mfma_f32_16x16x32_bf16 v[28:31], v[210:213], v[178:181], v[28:31]
	v_mfma_f32_16x16x32_bf16 v[24:27], v[218:221], v[178:181], v[24:27]
	v_mfma_f32_16x16x32_bf16 v[20:23], v[210:213], v[186:189], v[20:23]
	v_mfma_f32_16x16x32_bf16 v[16:19], v[218:221], v[186:189], v[16:19]
	v_mfma_f32_16x16x32_bf16 v[12:15], v[210:213], v[194:197], v[12:15]
	v_mfma_f32_16x16x32_bf16 v[8:11], v[218:221], v[194:197], v[8:11]
	v_mfma_f32_16x16x32_bf16 v[4:7], v[210:213], v[202:205], v[4:7]
	v_mfma_f32_16x16x32_bf16 v[0:3], v[218:221], v[202:205], v[0:3]
	v_mfma_f32_16x16x32_bf16 v[28:31], v[214:217], v[182:185], v[28:31]
	v_mfma_f32_16x16x32_bf16 v[24:27], v[222:225], v[182:185], v[24:27]
	v_mfma_f32_16x16x32_bf16 v[20:23], v[214:217], v[190:193], v[20:23]
	v_mfma_f32_16x16x32_bf16 v[16:19], v[222:225], v[190:193], v[16:19]
	v_mfma_f32_16x16x32_bf16 v[12:15], v[214:217], v[198:201], v[12:15]
	v_mfma_f32_16x16x32_bf16 v[8:11], v[222:225], v[198:201], v[8:11]
	v_mfma_f32_16x16x32_bf16 v[4:7], v[214:217], v[206:209], v[4:7]
	v_mfma_f32_16x16x32_bf16 v[0:3], v[222:225], v[206:209], v[0:3]
	s_setprio 0
	v_lshl_add_u64 v[130:131], v[130:131], 0, s[62:63]
	s_cmp_lt_u32 s68, s67
	v_lshl_add_u64 v[132:133], v[132:133], 0, s[64:65]
	s_barrier
	s_cbranch_scc1 .LBB0_561
	s_lshl_b32 s36, s86, 5
	s_lshl_b32 s37, s86, 8
	s_and_b32 s36, s36, 0x1800
	s_and_b32 s37, s37, 0x700
	s_or_b32 s96, s37, s36
	s_lshl_b32 s36, s96, 6
	s_add_u32 s36, s70, s36
	s_addc_u32 s37, s71, 0
	s_add_i32 s20, s20, -1
	s_lshl_b64 s[68:69], s[20:21], 20
	v_add_u32_e32 v128, v156, v157
	s_add_u32 s68, s36, s68
	v_or_b32_e32 v128, v128, v155
	s_addc_u32 s69, s37, s69
	v_lshl_add_u64 v[156:157], s[68:69], 0, v[128:129]
	v_readfirstlane_b32 s20, v160
	v_lshl_add_u64 v[206:207], v[156:157], 0, s[4:5]
	s_mov_b32 m0, s20
	v_readfirstlane_b32 s20, v159
	ds_read_b128 v[130:133], v161
	ds_read_b128 v[162:165], v161 offset:1024
	ds_read_b128 v[166:169], v161 offset:2048
	ds_read_b128 v[170:173], v161 offset:3072
	ds_read_b128 v[174:177], v152
	ds_read_b128 v[178:181], v152 offset:1024
	ds_read_b128 v[182:185], v151
	ds_read_b128 v[186:189], v151 offset:1024
	ds_read_b128 v[190:193], v150
	ds_read_b128 v[194:197], v150 offset:1024
	ds_read_b128 v[198:201], v149
	ds_read_b128 v[202:205], v149 offset:1024
	global_load_lds_dwordx4 v[206:207], off
	v_lshl_add_u64 v[156:157], v[156:157], 0, s[6:7]
	s_mov_b32 m0, s20
	s_nop 0
	global_load_lds_dwordx4 v[156:157], off
	s_barrier
	s_waitcnt lgkmcnt(0)
	s_setprio 1
	s_waitcnt lgkmcnt(0)
	v_mfma_f32_16x16x32_bf16 v[124:127], v[130:133], v[174:177], v[124:127]
	v_mfma_f32_16x16x32_bf16 v[120:123], v[166:169], v[174:177], v[120:123]
	v_mfma_f32_16x16x32_bf16 v[116:119], v[130:133], v[182:185], v[116:119]
	v_mfma_f32_16x16x32_bf16 v[112:115], v[166:169], v[182:185], v[112:115]
	v_mfma_f32_16x16x32_bf16 v[108:111], v[130:133], v[190:193], v[108:111]
	v_mfma_f32_16x16x32_bf16 v[104:107], v[166:169], v[190:193], v[104:107]
	v_mfma_f32_16x16x32_bf16 v[100:103], v[130:133], v[198:201], v[100:103]
	v_mfma_f32_16x16x32_bf16 v[96:99], v[166:169], v[198:201], v[96:99]
	v_mfma_f32_16x16x32_bf16 v[124:127], v[162:165], v[178:181], v[124:127]
	v_mfma_f32_16x16x32_bf16 v[120:123], v[170:173], v[178:181], v[120:123]
	v_mfma_f32_16x16x32_bf16 v[116:119], v[162:165], v[186:189], v[116:119]
	v_mfma_f32_16x16x32_bf16 v[112:115], v[170:173], v[186:189], v[112:115]
	v_mfma_f32_16x16x32_bf16 v[108:111], v[162:165], v[194:197], v[108:111]
	v_mfma_f32_16x16x32_bf16 v[104:107], v[170:173], v[194:197], v[104:107]
	v_mfma_f32_16x16x32_bf16 v[100:103], v[162:165], v[202:205], v[100:103]
	v_mfma_f32_16x16x32_bf16 v[96:99], v[170:173], v[202:205], v[96:99]
	s_setprio 0
	s_barrier
	ds_read_b128 v[206:209], v158
	ds_read_b128 v[210:213], v158 offset:1024
	ds_read_b128 v[214:217], v158 offset:2048
	ds_read_b128 v[156:159], v158 offset:3072
	s_barrier
	s_waitcnt lgkmcnt(0)
	s_setprio 1
	s_waitcnt lgkmcnt(0)
	v_mfma_f32_16x16x32_bf16 v[92:95], v[206:209], v[174:177], v[92:95]
	v_mfma_f32_16x16x32_bf16 v[88:91], v[214:217], v[174:177], v[88:91]
	v_mfma_f32_16x16x32_bf16 v[84:87], v[206:209], v[182:185], v[84:87]
	v_mfma_f32_16x16x32_bf16 v[80:83], v[214:217], v[182:185], v[80:83]
	v_mfma_f32_16x16x32_bf16 v[76:79], v[206:209], v[190:193], v[76:79]
	v_mfma_f32_16x16x32_bf16 v[72:75], v[214:217], v[190:193], v[72:75]
	v_mfma_f32_16x16x32_bf16 v[68:71], v[206:209], v[198:201], v[68:71]
	v_mfma_f32_16x16x32_bf16 v[64:67], v[214:217], v[198:201], v[64:67]
	v_mfma_f32_16x16x32_bf16 v[174:177], v[210:213], v[178:181], v[92:95]
	v_mfma_f32_16x16x32_bf16 v[178:181], v[156:159], v[178:181], v[88:91]
	v_mfma_f32_16x16x32_bf16 v[182:185], v[210:213], v[186:189], v[84:87]
	v_mfma_f32_16x16x32_bf16 v[186:189], v[156:159], v[186:189], v[80:83]
	v_mfma_f32_16x16x32_bf16 v[190:193], v[210:213], v[194:197], v[76:79]
	v_mfma_f32_16x16x32_bf16 v[194:197], v[156:159], v[194:197], v[72:75]
	v_mfma_f32_16x16x32_bf16 v[198:201], v[210:213], v[202:205], v[68:71]
	v_mfma_f32_16x16x32_bf16 v[202:205], v[156:159], v[202:205], v[64:67]
	s_setprio 0
	s_barrier
	s_nop 0
	ds_read_b128 v[64:67], v152 offset:16384
	ds_read_b128 v[68:71], v152 offset:17408
	ds_read_b128 v[72:75], v151 offset:16384
	ds_read_b128 v[76:79], v151 offset:17408
	ds_read_b128 v[80:83], v150 offset:16384
	ds_read_b128 v[84:87], v150 offset:17408
	ds_read_b128 v[88:91], v149 offset:16384
	ds_read_b128 v[92:95], v149 offset:17408
	s_waitcnt vmcnt(4)
	s_barrier
	s_waitcnt lgkmcnt(0)
	s_setprio 1
	s_waitcnt lgkmcnt(0)
	v_mfma_f32_16x16x32_bf16 v[60:63], v[130:133], v[64:67], v[60:63]
	v_mfma_f32_16x16x32_bf16 v[56:59], v[166:169], v[64:67], v[56:59]
	v_mfma_f32_16x16x32_bf16 v[52:55], v[130:133], v[72:75], v[52:55]
	v_mfma_f32_16x16x32_bf16 v[48:51], v[166:169], v[72:75], v[48:51]
	v_mfma_f32_16x16x32_bf16 v[218:221], v[130:133], v[80:83], v[44:47]
	v_mfma_f32_16x16x32_bf16 v[222:225], v[166:169], v[80:83], v[40:43]
	v_mfma_f32_16x16x32_bf16 v[130:133], v[130:133], v[88:91], v[36:39]
	v_mfma_f32_16x16x32_bf16 v[166:169], v[166:169], v[88:91], v[32:35]
	v_mfma_f32_16x16x32_bf16 v[32:35], v[162:165], v[68:71], v[60:63]
	v_mfma_f32_16x16x32_bf16 v[36:39], v[170:173], v[68:71], v[56:59]
	v_mfma_f32_16x16x32_bf16 v[40:43], v[162:165], v[76:79], v[52:55]
	v_mfma_f32_16x16x32_bf16 v[44:47], v[170:173], v[76:79], v[48:51]
	v_mfma_f32_16x16x32_bf16 v[48:51], v[162:165], v[84:87], v[218:221]
	v_mfma_f32_16x16x32_bf16 v[52:55], v[170:173], v[84:87], v[222:225]
	v_mfma_f32_16x16x32_bf16 v[56:59], v[162:165], v[92:95], v[130:133]
	v_mfma_f32_16x16x32_bf16 v[60:63], v[170:173], v[92:95], v[166:169]
	s_setprio 0
	s_setprio 1
	v_mfma_f32_16x16x32_bf16 v[28:31], v[206:209], v[64:67], v[28:31]
	v_mfma_f32_16x16x32_bf16 v[24:27], v[214:217], v[64:67], v[24:27]
	v_mfma_f32_16x16x32_bf16 v[20:23], v[206:209], v[72:75], v[20:23]
	v_mfma_f32_16x16x32_bf16 v[64:67], v[214:217], v[72:75], v[16:19]
	v_mfma_f32_16x16x32_bf16 v[72:75], v[206:209], v[80:83], v[12:15]
	v_mfma_f32_16x16x32_bf16 v[8:11], v[214:217], v[80:83], v[8:11]
	v_mfma_f32_16x16x32_bf16 v[80:83], v[206:209], v[88:91], v[4:7]
	v_mfma_f32_16x16x32_bf16 v[0:3], v[214:217], v[88:91], v[0:3]
	v_mfma_f32_16x16x32_bf16 v[4:7], v[210:213], v[68:71], v[28:31]
	v_mfma_f32_16x16x32_bf16 v[12:15], v[156:159], v[68:71], v[24:27]
	v_mfma_f32_16x16x32_bf16 v[16:19], v[210:213], v[76:79], v[20:23]
	v_mfma_f32_16x16x32_bf16 v[20:23], v[156:159], v[76:79], v[64:67]
	v_mfma_f32_16x16x32_bf16 v[24:27], v[210:213], v[84:87], v[72:75]
	v_mfma_f32_16x16x32_bf16 v[28:31], v[156:159], v[84:87], v[8:11]
	v_mfma_f32_16x16x32_bf16 v[64:67], v[210:213], v[92:95], v[80:83]
	v_mfma_f32_16x16x32_bf16 v[68:71], v[156:159], v[92:95], v[0:3]
	s_setprio 0
	s_barrier
	ds_read_b128 v[8:11], v154
	ds_read_b128 v[0:3], v154 offset:1024
	ds_read_b128 v[76:79], v154 offset:2048
	ds_read_b128 v[72:75], v154 offset:3072
	ds_read_b128 v[130:133], v152 offset:32768
	ds_read_b128 v[154:157], v152 offset:33792
	ds_read_b128 v[158:161], v151 offset:32768
	ds_read_b128 v[162:165], v151 offset:33792
	ds_read_b128 v[166:169], v150 offset:32768
	ds_read_b128 v[170:173], v150 offset:33792
	ds_read_b128 v[206:209], v149 offset:32768
	ds_read_b128 v[210:213], v149 offset:33792
	s_waitcnt vmcnt(2)
	s_barrier
	s_waitcnt lgkmcnt(0)
	s_setprio 1
	s_waitcnt lgkmcnt(0)
	v_mfma_f32_16x16x32_bf16 v[80:83], v[8:11], v[130:133], v[124:127]
	v_mfma_f32_16x16x32_bf16 v[84:87], v[76:79], v[130:133], v[120:123]
	v_mfma_f32_16x16x32_bf16 v[88:91], v[8:11], v[158:161], v[116:119]
	v_mfma_f32_16x16x32_bf16 v[92:95], v[76:79], v[158:161], v[112:115]
	v_mfma_f32_16x16x32_bf16 v[108:111], v[8:11], v[166:169], v[108:111]
	v_mfma_f32_16x16x32_bf16 v[104:107], v[76:79], v[166:169], v[104:107]
	v_mfma_f32_16x16x32_bf16 v[100:103], v[8:11], v[206:209], v[100:103]
	v_mfma_f32_16x16x32_bf16 v[96:99], v[76:79], v[206:209], v[96:99]
	v_mfma_f32_16x16x32_bf16 v[112:115], v[0:3], v[154:157], v[80:83]
	v_mfma_f32_16x16x32_bf16 v[116:119], v[72:75], v[154:157], v[84:87]
	v_mfma_f32_16x16x32_bf16 v[120:123], v[0:3], v[162:165], v[88:91]
	v_mfma_f32_16x16x32_bf16 v[124:127], v[72:75], v[162:165], v[92:95]
	v_mfma_f32_16x16x32_bf16 v[108:111], v[0:3], v[170:173], v[108:111]
	v_mfma_f32_16x16x32_bf16 v[104:107], v[72:75], v[170:173], v[104:107]
	v_mfma_f32_16x16x32_bf16 v[100:103], v[0:3], v[210:213], v[100:103]
	v_mfma_f32_16x16x32_bf16 v[96:99], v[72:75], v[210:213], v[96:99]
	s_setprio 0
	s_barrier
	ds_read_b128 v[88:91], v153
	ds_read_b128 v[80:83], v153 offset:1024
	ds_read_b128 v[92:95], v153 offset:2048
	ds_read_b128 v[84:87], v153 offset:3072
	s_waitcnt vmcnt(0)
	s_barrier
	s_waitcnt lgkmcnt(0)
	s_setprio 1
	s_waitcnt lgkmcnt(0)
	v_mfma_f32_16x16x32_bf16 v[174:177], v[88:91], v[130:133], v[174:177]
	v_mfma_f32_16x16x32_bf16 v[130:133], v[92:95], v[130:133], v[178:181]
	v_mfma_f32_16x16x32_bf16 v[178:181], v[88:91], v[158:161], v[182:185]
	v_mfma_f32_16x16x32_bf16 v[158:161], v[92:95], v[158:161], v[186:189]
	v_mfma_f32_16x16x32_bf16 v[182:185], v[88:91], v[166:169], v[190:193]
	v_mfma_f32_16x16x32_bf16 v[166:169], v[92:95], v[166:169], v[194:197]
	v_mfma_f32_16x16x32_bf16 v[186:189], v[88:91], v[206:209], v[198:201]
	v_mfma_f32_16x16x32_bf16 v[190:193], v[92:95], v[206:209], v[202:205]
	v_mfma_f32_16x16x32_bf16 v[174:177], v[80:83], v[154:157], v[174:177]
	v_mfma_f32_16x16x32_bf16 v[130:133], v[84:87], v[154:157], v[130:133]
	v_mfma_f32_16x16x32_bf16 v[154:157], v[80:83], v[162:165], v[178:181]
	v_mfma_f32_16x16x32_bf16 v[158:161], v[84:87], v[162:165], v[158:161]
	v_mfma_f32_16x16x32_bf16 v[162:165], v[80:83], v[170:173], v[182:185]
	v_mfma_f32_16x16x32_bf16 v[166:169], v[84:87], v[170:173], v[166:169]
	v_mfma_f32_16x16x32_bf16 v[170:173], v[80:83], v[210:213], v[186:189]
	v_mfma_f32_16x16x32_bf16 v[178:181], v[84:87], v[210:213], v[190:193]
	s_setprio 0
	s_barrier
	v_mbcnt_lo_u32_b32 v128, -1, 0
	v_mbcnt_hi_u32_b32 v128, -1, v128
	v_cvt_pk_bf16_f32 v112, v112, v113
	v_cvt_pk_bf16_f32 v113, v114, v115
	v_cvt_pk_bf16_f32 v114, v116, v117
	v_cvt_pk_bf16_f32 v115, v118, v119
	s_lshl_b32 s89, s66, 9
	v_add_u32_e32 v153, s74, v128
	v_ashrrev_i32_e32 v182, 6, v153
	v_and_b32_e32 v183, 15, v128
	v_and_b32_e32 v184, 48, v128
	v_mul_lo_u32 v185, v182, s79
	v_bfe_u32 v186, v128, 3, 3
	v_lshlrev_b32_e32 v128, 4, v128
	v_add_u32_e32 v185, 0x20000, v185
	v_lshrrev_b32_e32 v153, 2, v153
	v_and_b32_e32 v128, 0x70, v128
	v_mul_u32_u24_e32 v183, 0x90, v183
	v_and_b32_e32 v153, 64, v153
	v_add3_u32 v183, v185, v183, v184
	v_or_b32_e32 v184, v185, v128
	v_or3_b32 v153, s96, v153, v186
	v_mad_u32_u24 v184, v186, s81, v184
	ds_write_b128 v183, v[112:115]
	v_cvt_pk_bf16_f32 v112, v174, v175
	v_cvt_pk_bf16_f32 v113, v176, v177
	v_cvt_pk_bf16_f32 v114, v130, v131
	v_cvt_pk_bf16_f32 v115, v132, v133
	ds_write_b128 v183, v[112:115] offset:64
	v_lshlrev_b32_e32 v182, 7, v182
	ds_read_b128 v[112:115], v184
	v_lshlrev_b32_e32 v116, 12, v153
	v_and_or_b32 v116, v182, s82, v116
	v_or3_b32 v128, v116, s89, v128
	ds_read_b128 v[116:119], v184 offset:1152
	v_lshl_add_u64 v[130:131], s[0:1], 0, v[128:129]
	s_mov_b32 s20, 0x8000
	s_waitcnt lgkmcnt(0)
	global_store_dwordx4 v128, v[112:115], s[0:1] sc0 sc1
	v_cvt_pk_bf16_f32 v108, v108, v109
	v_cvt_pk_bf16_f32 v109, v110, v111
	v_cvt_pk_bf16_f32 v110, v104, v105
	v_cvt_pk_bf16_f32 v111, v106, v107
	v_cvt_pk_bf16_f32 v104, v162, v163
	s_nop 1
	v_add_co_u32_e32 v112, vcc, s20, v130
	v_cvt_pk_bf16_f32 v114, v124, v125
	v_cvt_pk_bf16_f32 v115, v126, v127
	v_cvt_pk_bf16_f32 v105, v164, v165
	v_cvt_pk_bf16_f32 v106, v166, v167
	s_nop 1
	v_addc_co_u32_e32 v113, vcc, 0, v131, vcc
	global_store_dwordx4 v[112:113], v[116:119], off sc0 sc1
	v_cvt_pk_bf16_f32 v112, v120, v121
	v_cvt_pk_bf16_f32 v113, v122, v123
	ds_write_b128 v183, v[112:115]
	v_cvt_pk_bf16_f32 v112, v154, v155
	v_cvt_pk_bf16_f32 v113, v156, v157
	v_cvt_pk_bf16_f32 v114, v158, v159
	v_cvt_pk_bf16_f32 v115, v160, v161
	ds_write_b128 v183, v[112:115] offset:64
	ds_read_b128 v[112:115], v184
	ds_read_b128 v[116:119], v184 offset:1152
	v_add_co_u32_e32 v120, vcc, s76, v130
	ds_write_b128 v183, v[108:111]
	v_cvt_pk_bf16_f32 v107, v168, v169
	ds_write_b128 v183, v[104:107] offset:64
	v_addc_co_u32_e32 v121, vcc, 0, v131, vcc
	ds_read_b128 v[104:107], v184
	ds_read_b128 v[108:111], v184 offset:1152
	s_waitcnt lgkmcnt(0)
	global_store_dwordx4 v[120:121], v[112:115], off sc0 sc1
	v_cvt_pk_bf16_f32 v100, v100, v101
	v_cvt_pk_bf16_f32 v101, v102, v103
	v_cvt_pk_bf16_f32 v102, v96, v97
	v_cvt_pk_bf16_f32 v103, v98, v99
	ds_write_b128 v183, v[100:103]
	s_nop 0
	v_add_co_u32_e32 v112, vcc, s77, v130
	v_cvt_pk_bf16_f32 v96, v170, v171
	v_cvt_pk_bf16_f32 v97, v172, v173
	v_cvt_pk_bf16_f32 v98, v178, v179
	v_cvt_pk_bf16_f32 v99, v180, v181
	s_nop 1
	v_addc_co_u32_e32 v113, vcc, 0, v131, vcc
	global_store_dwordx4 v[112:113], v[116:119], off sc0 sc1
	v_add_co_u32_e32 v112, vcc, s80, v130
	ds_write_b128 v183, v[96:99] offset:64
	s_nop 0
	v_addc_co_u32_e32 v113, vcc, 0, v131, vcc
	ds_read_b128 v[96:99], v184
	ds_read_b128 v[100:103], v184 offset:1152
	global_store_dwordx4 v[112:113], v[104:107], off sc0 sc1
	s_nop 1
	v_add_co_u32_e32 v104, vcc, s83, v130
	s_nop 1
	v_addc_co_u32_e32 v105, vcc, 0, v131, vcc
	global_store_dwordx4 v[104:105], v[108:111], off sc0 sc1
	v_add_co_u32_e32 v104, vcc, s85, v130
	s_nop 1
	v_addc_co_u32_e32 v105, vcc, 0, v131, vcc
	s_waitcnt lgkmcnt(0)
	global_store_dwordx4 v[104:105], v[96:99], off sc0 sc1
	s_nop 1
	v_add_co_u32_e32 v96, vcc, s87, v130
	s_nop 1
	v_addc_co_u32_e32 v97, vcc, 0, v131, vcc
	global_store_dwordx4 v[96:97], v[100:103], off sc0 sc1
	ds_read_b128 v[96:99], v152 offset:49152
	ds_read_b128 v[100:103], v152 offset:50176
	ds_read_b128 v[104:107], v151 offset:49152
	ds_read_b128 v[108:111], v151 offset:50176
	ds_read_b128 v[112:115], v150 offset:49152
	ds_read_b128 v[116:119], v150 offset:50176
	ds_read_b128 v[120:123], v149 offset:49152
	ds_read_b128 v[124:127], v149 offset:50176
	s_barrier
	s_waitcnt lgkmcnt(0)
	s_setprio 1
	s_waitcnt lgkmcnt(0)
	v_mfma_f32_16x16x32_bf16 v[32:35], v[8:11], v[96:99], v[32:35]
	v_mfma_f32_16x16x32_bf16 v[36:39], v[76:79], v[96:99], v[36:39]
	v_mfma_f32_16x16x32_bf16 v[40:43], v[8:11], v[104:107], v[40:43]
	v_mfma_f32_16x16x32_bf16 v[130:133], v[76:79], v[104:107], v[44:47]
	v_mfma_f32_16x16x32_bf16 v[150:153], v[8:11], v[112:115], v[48:51]
	v_mfma_f32_16x16x32_bf16 v[52:55], v[76:79], v[112:115], v[52:55]
	v_mfma_f32_16x16x32_bf16 v[8:11], v[8:11], v[120:123], v[56:59]
	v_mfma_f32_16x16x32_bf16 v[60:63], v[76:79], v[120:123], v[60:63]
	v_mfma_f32_16x16x32_bf16 v[56:59], v[0:3], v[100:103], v[32:35]
	v_mfma_f32_16x16x32_bf16 v[48:51], v[72:75], v[100:103], v[36:39]
	v_mfma_f32_16x16x32_bf16 v[44:47], v[0:3], v[108:111], v[40:43]
	v_mfma_f32_16x16x32_bf16 v[40:43], v[72:75], v[108:111], v[130:133]
	v_mfma_f32_16x16x32_bf16 v[36:39], v[0:3], v[116:119], v[150:153]
	v_mfma_f32_16x16x32_bf16 v[32:35], v[72:75], v[116:119], v[52:55]
	v_mfma_f32_16x16x32_bf16 v[8:11], v[0:3], v[124:127], v[8:11]
	v_mfma_f32_16x16x32_bf16 v[0:3], v[72:75], v[124:127], v[60:63]
	s_setprio 0
	s_setprio 1
	v_mfma_f32_16x16x32_bf16 v[4:7], v[88:91], v[96:99], v[4:7]
	v_mfma_f32_16x16x32_bf16 v[12:15], v[92:95], v[96:99], v[12:15]
	v_mfma_f32_16x16x32_bf16 v[16:19], v[88:91], v[104:107], v[16:19]
	v_mfma_f32_16x16x32_bf16 v[20:23], v[92:95], v[104:107], v[20:23]
	v_mfma_f32_16x16x32_bf16 v[72:75], v[88:91], v[112:115], v[24:27]
	v_mfma_f32_16x16x32_bf16 v[76:79], v[92:95], v[112:115], v[28:31]
	v_mfma_f32_16x16x32_bf16 v[64:67], v[88:91], v[120:123], v[64:67]
	v_mfma_f32_16x16x32_bf16 v[68:71], v[92:95], v[120:123], v[68:71]
	v_mfma_f32_16x16x32_bf16 v[60:63], v[80:83], v[100:103], v[4:7]
	v_mfma_f32_16x16x32_bf16 v[52:55], v[84:87], v[100:103], v[12:15]
	v_mfma_f32_16x16x32_bf16 v[28:31], v[80:83], v[108:111], v[16:19]
	v_mfma_f32_16x16x32_bf16 v[24:27], v[84:87], v[108:111], v[20:23]
	v_mfma_f32_16x16x32_bf16 v[20:23], v[80:83], v[116:119], v[72:75]
	v_mfma_f32_16x16x32_bf16 v[16:19], v[84:87], v[116:119], v[76:79]
	v_mfma_f32_16x16x32_bf16 v[12:15], v[80:83], v[124:127], v[64:67]
	v_mfma_f32_16x16x32_bf16 v[4:7], v[84:87], v[124:127], v[68:71]
	s_setprio 0
	v_cmp_gt_u32_e32 vcc, s88, v135
	s_barrier
	s_and_saveexec_b64 s[66:67], vcc
	s_cbranch_execz .LBB0_564
	s_barrier
